# y outputs of the generated mLSTM/HGRN2 step sections written only from the l16==0 lanes (exec-masked) instead of all lanes
# speedup vs baseline: 1.1824x; 1.0078x over previous
.LBB0_1156:
	s_or_b64 exec, exec, s[8:9]
	s_waitcnt lgkmcnt(0)
	s_barrier
	v_mov_b32_e32 v196, v88
	v_mov_b32_e32 v197, v89
	v_mov_b32_e32 v198, v90
	v_mov_b32_e32 v199, v100
	v_mov_b32_e32 v200, v91
	v_mov_b32_e32 v201, v101
	v_mov_b32_e32 v202, v102
	v_mov_b32_e32 v203, v104
	v_mov_b32_e32 v204, v103
	v_mov_b32_e32 v205, v105
	v_mov_b32_e32 v206, v106
	v_mov_b32_e32 v207, v109
	v_mov_b32_e32 v208, v107
	v_mov_b32_e32 v209, v110
	v_mov_b32_e32 v210, v108
	v_mov_b32_e32 v211, v111
	v_mov_b32_e32 v214, 0
	v_mov_b32_e32 v215, 0
	ds_read_b128 v[80:83], v194 offset:8192
	ds_read_b128 v[84:87], v194 offset:8448
	ds_read_b128 v[88:91], v194 offset:8704
	ds_read_b128 v[92:95], v194 offset:8960
	ds_read_b32 v134, v140 offset:35136
	ds_read_b32 v135, v190 offset:16384
	ds_read_b32 v132, v140 offset:35072
	ds_read_b128 v[64:67], v194
	ds_read_b128 v[68:71], v194 offset:256
	ds_read_b128 v[72:75], v194 offset:512
	ds_read_b128 v[76:79], v194 offset:768
	ds_read_b128 v[112:115], v194 offset:9216
	ds_read_b128 v[116:119], v194 offset:9472
	ds_read_b128 v[120:123], v194 offset:9728
	ds_read_b128 v[124:127], v194 offset:9984
	ds_read_b32 v156, v140 offset:35140
	ds_read_b32 v157, v190 offset:16448
	ds_read_b32 v154, v140 offset:35076
	ds_read_b128 v[96:99], v194 offset:1024
	ds_read_b128 v[100:103], v194 offset:1280
	ds_read_b128 v[104:107], v194 offset:1536
	ds_read_b128 v[108:111], v194 offset:1792
	s_waitcnt lgkmcnt(15)
	v_mul_f32_e32 v133, v134, v135
	v_pk_mul_f32 v[80:81], v[80:81], v[132:133] op_sel:[0,1] op_sel_hi:[1,1]
	v_pk_mul_f32 v[82:83], v[82:83], v[132:133] op_sel:[0,1] op_sel_hi:[1,1]
	v_pk_mul_f32 v[84:85], v[84:85], v[132:133] op_sel:[0,1] op_sel_hi:[1,1]
	v_pk_mul_f32 v[86:87], v[86:87], v[132:133] op_sel:[0,1] op_sel_hi:[1,1]
	v_pk_mul_f32 v[88:89], v[88:89], v[132:133] op_sel:[0,1] op_sel_hi:[1,1]
	v_pk_mul_f32 v[90:91], v[90:91], v[132:133] op_sel:[0,1] op_sel_hi:[1,1]
	v_pk_mul_f32 v[92:93], v[92:93], v[132:133] op_sel:[0,1] op_sel_hi:[1,1]
	v_pk_mul_f32 v[94:95], v[94:95], v[132:133] op_sel:[0,1] op_sel_hi:[1,1]
	v_pk_fma_f32 v[196:197], v[132:133], v[196:197], v[80:81] op_sel_hi:[0,1,1]
	v_pk_fma_f32 v[198:199], v[132:133], v[198:199], v[82:83] op_sel_hi:[0,1,1]
	v_pk_fma_f32 v[200:201], v[132:133], v[200:201], v[84:85] op_sel_hi:[0,1,1]
	v_pk_fma_f32 v[202:203], v[132:133], v[202:203], v[86:87] op_sel_hi:[0,1,1]
	v_pk_fma_f32 v[204:205], v[132:133], v[204:205], v[88:89] op_sel_hi:[0,1,1]
	v_pk_fma_f32 v[206:207], v[132:133], v[206:207], v[90:91] op_sel_hi:[0,1,1]
	v_pk_fma_f32 v[208:209], v[132:133], v[208:209], v[92:93] op_sel_hi:[0,1,1]
	v_pk_fma_f32 v[210:211], v[132:133], v[210:211], v[94:95] op_sel_hi:[0,1,1]
	s_waitcnt lgkmcnt(14)
	v_pk_fma_f32 v[128:129], v[64:65], v[196:197], v[214:215]
	v_pk_fma_f32 v[130:131], v[66:67], v[198:199], v[214:215]
	s_waitcnt lgkmcnt(13)
	v_pk_fma_f32 v[128:129], v[68:69], v[200:201], v[128:129]
	v_pk_fma_f32 v[130:131], v[70:71], v[202:203], v[130:131]
	s_waitcnt lgkmcnt(12)
	v_pk_fma_f32 v[128:129], v[72:73], v[204:205], v[128:129]
	v_pk_fma_f32 v[130:131], v[74:75], v[206:207], v[130:131]
	s_waitcnt lgkmcnt(11)
	v_pk_fma_f32 v[128:129], v[76:77], v[208:209], v[128:129]
	v_pk_fma_f32 v[130:131], v[78:79], v[210:211], v[130:131]
	v_add_f32_e32 v128, v128, v129
	v_add_f32_e32 v130, v130, v131
	v_add_f32_e32 v212, v128, v130
	ds_read_b128 v[80:83], v194 offset:10240
	ds_read_b128 v[84:87], v194 offset:10496
	ds_read_b128 v[88:91], v194 offset:10752
	ds_read_b128 v[92:95], v194 offset:11008
	ds_read_b32 v134, v140 offset:35144
	ds_read_b32 v135, v190 offset:16512
	ds_read_b32 v132, v140 offset:35080
	ds_read_b128 v[64:67], v194 offset:2048
	ds_read_b128 v[68:71], v194 offset:2304
	ds_read_b128 v[72:75], v194 offset:2560
	ds_read_b128 v[76:79], v194 offset:2816
	s_waitcnt lgkmcnt(15)
	v_mul_f32_e32 v155, v156, v157
	v_pk_mul_f32 v[112:113], v[112:113], v[154:155] op_sel:[0,1] op_sel_hi:[1,1]
	v_add_f32_dpp v212, v212, v212 row_ror:8 row_mask:0xf bank_mask:0xf bound_ctrl:1
	v_pk_mul_f32 v[114:115], v[114:115], v[154:155] op_sel:[0,1] op_sel_hi:[1,1]
	v_pk_mul_f32 v[116:117], v[116:117], v[154:155] op_sel:[0,1] op_sel_hi:[1,1]
	v_add_f32_dpp v212, v212, v212 row_ror:4 row_mask:0xf bank_mask:0xf bound_ctrl:1
	v_pk_mul_f32 v[118:119], v[118:119], v[154:155] op_sel:[0,1] op_sel_hi:[1,1]
	v_pk_mul_f32 v[120:121], v[120:121], v[154:155] op_sel:[0,1] op_sel_hi:[1,1]
	v_add_f32_dpp v212, v212, v212 row_ror:2 row_mask:0xf bank_mask:0xf bound_ctrl:1
	v_pk_mul_f32 v[122:123], v[122:123], v[154:155] op_sel:[0,1] op_sel_hi:[1,1]
	v_pk_mul_f32 v[124:125], v[124:125], v[154:155] op_sel:[0,1] op_sel_hi:[1,1]
	v_add_f32_dpp v212, v212, v212 row_ror:1 row_mask:0xf bank_mask:0xf bound_ctrl:1
	v_pk_mul_f32 v[126:127], v[126:127], v[154:155] op_sel:[0,1] op_sel_hi:[1,1]
	v_pk_fma_f32 v[196:197], v[154:155], v[196:197], v[112:113] op_sel_hi:[0,1,1]
	s_and_saveexec_b64 s[8:9], s[44:45]
	ds_write_b32 v190, v212 offset:34048
	s_mov_b64 exec, s[8:9]
	v_pk_fma_f32 v[198:199], v[154:155], v[198:199], v[114:115] op_sel_hi:[0,1,1]
	v_pk_fma_f32 v[200:201], v[154:155], v[200:201], v[116:117] op_sel_hi:[0,1,1]
	v_pk_fma_f32 v[202:203], v[154:155], v[202:203], v[118:119] op_sel_hi:[0,1,1]
	v_pk_fma_f32 v[204:205], v[154:155], v[204:205], v[120:121] op_sel_hi:[0,1,1]
	v_pk_fma_f32 v[206:207], v[154:155], v[206:207], v[122:123] op_sel_hi:[0,1,1]
	v_pk_fma_f32 v[208:209], v[154:155], v[208:209], v[124:125] op_sel_hi:[0,1,1]
	v_pk_fma_f32 v[210:211], v[154:155], v[210:211], v[126:127] op_sel_hi:[0,1,1]
	s_waitcnt lgkmcnt(15)
	v_pk_fma_f32 v[128:129], v[96:97], v[196:197], v[214:215]
	v_pk_fma_f32 v[130:131], v[98:99], v[198:199], v[214:215]
	s_waitcnt lgkmcnt(14)
	v_pk_fma_f32 v[128:129], v[100:101], v[200:201], v[128:129]
	v_pk_fma_f32 v[130:131], v[102:103], v[202:203], v[130:131]
	s_waitcnt lgkmcnt(13)
	v_pk_fma_f32 v[128:129], v[104:105], v[204:205], v[128:129]
	v_pk_fma_f32 v[130:131], v[106:107], v[206:207], v[130:131]
	s_waitcnt lgkmcnt(12)
	v_pk_fma_f32 v[128:129], v[108:109], v[208:209], v[128:129]
	v_pk_fma_f32 v[130:131], v[110:111], v[210:211], v[130:131]
	v_add_f32_e32 v128, v128, v129
	v_add_f32_e32 v130, v130, v131
	v_add_f32_e32 v213, v128, v130
	ds_read_b128 v[112:115], v194 offset:11264
	ds_read_b128 v[116:119], v194 offset:11520
	ds_read_b128 v[120:123], v194 offset:11776
	ds_read_b128 v[124:127], v194 offset:12032
	ds_read_b32 v156, v140 offset:35148
	ds_read_b32 v157, v190 offset:16576
	ds_read_b32 v154, v140 offset:35084
	ds_read_b128 v[96:99], v194 offset:3072
	ds_read_b128 v[100:103], v194 offset:3328
	ds_read_b128 v[104:107], v194 offset:3584
	ds_read_b128 v[108:111], v194 offset:3840
	s_waitcnt lgkmcnt(15)
	v_mul_f32_e32 v133, v134, v135
	v_pk_mul_f32 v[80:81], v[80:81], v[132:133] op_sel:[0,1] op_sel_hi:[1,1]
	v_add_f32_dpp v213, v213, v213 row_ror:8 row_mask:0xf bank_mask:0xf bound_ctrl:1
	v_pk_mul_f32 v[82:83], v[82:83], v[132:133] op_sel:[0,1] op_sel_hi:[1,1]
	v_pk_mul_f32 v[84:85], v[84:85], v[132:133] op_sel:[0,1] op_sel_hi:[1,1]
	v_add_f32_dpp v213, v213, v213 row_ror:4 row_mask:0xf bank_mask:0xf bound_ctrl:1
	v_pk_mul_f32 v[86:87], v[86:87], v[132:133] op_sel:[0,1] op_sel_hi:[1,1]
	v_pk_mul_f32 v[88:89], v[88:89], v[132:133] op_sel:[0,1] op_sel_hi:[1,1]
	v_add_f32_dpp v213, v213, v213 row_ror:2 row_mask:0xf bank_mask:0xf bound_ctrl:1
	v_pk_mul_f32 v[90:91], v[90:91], v[132:133] op_sel:[0,1] op_sel_hi:[1,1]
	v_pk_mul_f32 v[92:93], v[92:93], v[132:133] op_sel:[0,1] op_sel_hi:[1,1]
	v_add_f32_dpp v213, v213, v213 row_ror:1 row_mask:0xf bank_mask:0xf bound_ctrl:1
	v_pk_mul_f32 v[94:95], v[94:95], v[132:133] op_sel:[0,1] op_sel_hi:[1,1]
	v_pk_fma_f32 v[196:197], v[132:133], v[196:197], v[80:81] op_sel_hi:[0,1,1]
	s_and_saveexec_b64 s[8:9], s[44:45]
	ds_write_b32 v190, v213 offset:34112
	s_mov_b64 exec, s[8:9]
	v_pk_fma_f32 v[198:199], v[132:133], v[198:199], v[82:83] op_sel_hi:[0,1,1]
	v_pk_fma_f32 v[200:201], v[132:133], v[200:201], v[84:85] op_sel_hi:[0,1,1]
	v_pk_fma_f32 v[202:203], v[132:133], v[202:203], v[86:87] op_sel_hi:[0,1,1]
	v_pk_fma_f32 v[204:205], v[132:133], v[204:205], v[88:89] op_sel_hi:[0,1,1]
	v_pk_fma_f32 v[206:207], v[132:133], v[206:207], v[90:91] op_sel_hi:[0,1,1]
	v_pk_fma_f32 v[208:209], v[132:133], v[208:209], v[92:93] op_sel_hi:[0,1,1]
	v_pk_fma_f32 v[210:211], v[132:133], v[210:211], v[94:95] op_sel_hi:[0,1,1]
	s_waitcnt lgkmcnt(15)
	v_pk_fma_f32 v[128:129], v[64:65], v[196:197], v[214:215]
	v_pk_fma_f32 v[130:131], v[66:67], v[198:199], v[214:215]
	v_pk_fma_f32 v[128:129], v[68:69], v[200:201], v[128:129]
	v_pk_fma_f32 v[130:131], v[70:71], v[202:203], v[130:131]
	s_waitcnt lgkmcnt(14)
	v_pk_fma_f32 v[128:129], v[72:73], v[204:205], v[128:129]
	v_pk_fma_f32 v[130:131], v[74:75], v[206:207], v[130:131]
	s_waitcnt lgkmcnt(13)
	v_pk_fma_f32 v[128:129], v[76:77], v[208:209], v[128:129]
	v_pk_fma_f32 v[130:131], v[78:79], v[210:211], v[130:131]
	v_add_f32_e32 v128, v128, v129
	v_add_f32_e32 v130, v130, v131
	v_add_f32_e32 v212, v128, v130
	ds_read_b128 v[80:83], v194 offset:12288
	ds_read_b128 v[84:87], v194 offset:12544
	ds_read_b128 v[88:91], v194 offset:12800
	ds_read_b128 v[92:95], v194 offset:13056
	ds_read_b32 v134, v140 offset:35152
	ds_read_b32 v135, v190 offset:16640
	ds_read_b32 v132, v140 offset:35088
	ds_read_b128 v[64:67], v194 offset:4096
	ds_read_b128 v[68:71], v194 offset:4352
	ds_read_b128 v[72:75], v194 offset:4608
	ds_read_b128 v[76:79], v194 offset:4864
	s_waitcnt lgkmcnt(15)
	v_mul_f32_e32 v155, v156, v157
	v_pk_mul_f32 v[112:113], v[112:113], v[154:155] op_sel:[0,1] op_sel_hi:[1,1]
	v_add_f32_dpp v212, v212, v212 row_ror:8 row_mask:0xf bank_mask:0xf bound_ctrl:1
	v_pk_mul_f32 v[114:115], v[114:115], v[154:155] op_sel:[0,1] op_sel_hi:[1,1]
	v_pk_mul_f32 v[116:117], v[116:117], v[154:155] op_sel:[0,1] op_sel_hi:[1,1]
	v_add_f32_dpp v212, v212, v212 row_ror:4 row_mask:0xf bank_mask:0xf bound_ctrl:1
	v_pk_mul_f32 v[118:119], v[118:119], v[154:155] op_sel:[0,1] op_sel_hi:[1,1]
	v_pk_mul_f32 v[120:121], v[120:121], v[154:155] op_sel:[0,1] op_sel_hi:[1,1]
	v_add_f32_dpp v212, v212, v212 row_ror:2 row_mask:0xf bank_mask:0xf bound_ctrl:1
	v_pk_mul_f32 v[122:123], v[122:123], v[154:155] op_sel:[0,1] op_sel_hi:[1,1]
	v_pk_mul_f32 v[124:125], v[124:125], v[154:155] op_sel:[0,1] op_sel_hi:[1,1]
	v_add_f32_dpp v212, v212, v212 row_ror:1 row_mask:0xf bank_mask:0xf bound_ctrl:1
	v_pk_mul_f32 v[126:127], v[126:127], v[154:155] op_sel:[0,1] op_sel_hi:[1,1]
	v_pk_fma_f32 v[196:197], v[154:155], v[196:197], v[112:113] op_sel_hi:[0,1,1]
	s_and_saveexec_b64 s[8:9], s[44:45]
	ds_write_b32 v190, v212 offset:34176
	s_mov_b64 exec, s[8:9]
	v_pk_fma_f32 v[198:199], v[154:155], v[198:199], v[114:115] op_sel_hi:[0,1,1]
	v_pk_fma_f32 v[200:201], v[154:155], v[200:201], v[116:117] op_sel_hi:[0,1,1]
	v_pk_fma_f32 v[202:203], v[154:155], v[202:203], v[118:119] op_sel_hi:[0,1,1]
	v_pk_fma_f32 v[204:205], v[154:155], v[204:205], v[120:121] op_sel_hi:[0,1,1]
	v_pk_fma_f32 v[206:207], v[154:155], v[206:207], v[122:123] op_sel_hi:[0,1,1]
	v_pk_fma_f32 v[208:209], v[154:155], v[208:209], v[124:125] op_sel_hi:[0,1,1]
	v_pk_fma_f32 v[210:211], v[154:155], v[210:211], v[126:127] op_sel_hi:[0,1,1]
	s_waitcnt lgkmcnt(15)
	v_pk_fma_f32 v[128:129], v[96:97], v[196:197], v[214:215]
	v_pk_fma_f32 v[130:131], v[98:99], v[198:199], v[214:215]
	v_pk_fma_f32 v[128:129], v[100:101], v[200:201], v[128:129]
	v_pk_fma_f32 v[130:131], v[102:103], v[202:203], v[130:131]
	s_waitcnt lgkmcnt(14)
	v_pk_fma_f32 v[128:129], v[104:105], v[204:205], v[128:129]
	v_pk_fma_f32 v[130:131], v[106:107], v[206:207], v[130:131]
	s_waitcnt lgkmcnt(13)
	v_pk_fma_f32 v[128:129], v[108:109], v[208:209], v[128:129]
	v_pk_fma_f32 v[130:131], v[110:111], v[210:211], v[130:131]
	v_add_f32_e32 v128, v128, v129
	v_add_f32_e32 v130, v130, v131
	v_add_f32_e32 v213, v128, v130
	ds_read_b128 v[112:115], v194 offset:13312
	ds_read_b128 v[116:119], v194 offset:13568
	ds_read_b128 v[120:123], v194 offset:13824
	ds_read_b128 v[124:127], v194 offset:14080
	ds_read_b32 v156, v140 offset:35156
	ds_read_b32 v157, v190 offset:16704
	ds_read_b32 v154, v140 offset:35092
	ds_read_b128 v[96:99], v194 offset:5120
	ds_read_b128 v[100:103], v194 offset:5376
	ds_read_b128 v[104:107], v194 offset:5632
	ds_read_b128 v[108:111], v194 offset:5888
	s_waitcnt lgkmcnt(15)
	v_mul_f32_e32 v133, v134, v135
	v_pk_mul_f32 v[80:81], v[80:81], v[132:133] op_sel:[0,1] op_sel_hi:[1,1]
	v_add_f32_dpp v213, v213, v213 row_ror:8 row_mask:0xf bank_mask:0xf bound_ctrl:1
	v_pk_mul_f32 v[82:83], v[82:83], v[132:133] op_sel:[0,1] op_sel_hi:[1,1]
	v_pk_mul_f32 v[84:85], v[84:85], v[132:133] op_sel:[0,1] op_sel_hi:[1,1]
	v_add_f32_dpp v213, v213, v213 row_ror:4 row_mask:0xf bank_mask:0xf bound_ctrl:1
	v_pk_mul_f32 v[86:87], v[86:87], v[132:133] op_sel:[0,1] op_sel_hi:[1,1]
	v_pk_mul_f32 v[88:89], v[88:89], v[132:133] op_sel:[0,1] op_sel_hi:[1,1]
	v_add_f32_dpp v213, v213, v213 row_ror:2 row_mask:0xf bank_mask:0xf bound_ctrl:1
	v_pk_mul_f32 v[90:91], v[90:91], v[132:133] op_sel:[0,1] op_sel_hi:[1,1]
	v_pk_mul_f32 v[92:93], v[92:93], v[132:133] op_sel:[0,1] op_sel_hi:[1,1]
	v_add_f32_dpp v213, v213, v213 row_ror:1 row_mask:0xf bank_mask:0xf bound_ctrl:1
	v_pk_mul_f32 v[94:95], v[94:95], v[132:133] op_sel:[0,1] op_sel_hi:[1,1]
	v_pk_fma_f32 v[196:197], v[132:133], v[196:197], v[80:81] op_sel_hi:[0,1,1]
	s_and_saveexec_b64 s[8:9], s[44:45]
	ds_write_b32 v190, v213 offset:34240
	s_mov_b64 exec, s[8:9]
	v_pk_fma_f32 v[198:199], v[132:133], v[198:199], v[82:83] op_sel_hi:[0,1,1]
	v_pk_fma_f32 v[200:201], v[132:133], v[200:201], v[84:85] op_sel_hi:[0,1,1]
	v_pk_fma_f32 v[202:203], v[132:133], v[202:203], v[86:87] op_sel_hi:[0,1,1]
	v_pk_fma_f32 v[204:205], v[132:133], v[204:205], v[88:89] op_sel_hi:[0,1,1]
	v_pk_fma_f32 v[206:207], v[132:133], v[206:207], v[90:91] op_sel_hi:[0,1,1]
	v_pk_fma_f32 v[208:209], v[132:133], v[208:209], v[92:93] op_sel_hi:[0,1,1]
	v_pk_fma_f32 v[210:211], v[132:133], v[210:211], v[94:95] op_sel_hi:[0,1,1]
	s_waitcnt lgkmcnt(15)
	v_pk_fma_f32 v[128:129], v[64:65], v[196:197], v[214:215]
	v_pk_fma_f32 v[130:131], v[66:67], v[198:199], v[214:215]
	v_pk_fma_f32 v[128:129], v[68:69], v[200:201], v[128:129]
	v_pk_fma_f32 v[130:131], v[70:71], v[202:203], v[130:131]
	s_waitcnt lgkmcnt(14)
	v_pk_fma_f32 v[128:129], v[72:73], v[204:205], v[128:129]
	v_pk_fma_f32 v[130:131], v[74:75], v[206:207], v[130:131]
	s_waitcnt lgkmcnt(13)
	v_pk_fma_f32 v[128:129], v[76:77], v[208:209], v[128:129]
	v_pk_fma_f32 v[130:131], v[78:79], v[210:211], v[130:131]
	v_add_f32_e32 v128, v128, v129
	v_add_f32_e32 v130, v130, v131
	v_add_f32_e32 v212, v128, v130
	ds_read_b128 v[80:83], v194 offset:14336
	ds_read_b128 v[84:87], v194 offset:14592
	ds_read_b128 v[88:91], v194 offset:14848
	ds_read_b128 v[92:95], v194 offset:15104
	ds_read_b32 v134, v140 offset:35160
	ds_read_b32 v135, v190 offset:16768
	ds_read_b32 v132, v140 offset:35096
	ds_read_b128 v[64:67], v194 offset:6144
	ds_read_b128 v[68:71], v194 offset:6400
	ds_read_b128 v[72:75], v194 offset:6656
	ds_read_b128 v[76:79], v194 offset:6912
	s_waitcnt lgkmcnt(15)
	v_mul_f32_e32 v155, v156, v157
	v_pk_mul_f32 v[112:113], v[112:113], v[154:155] op_sel:[0,1] op_sel_hi:[1,1]
	v_add_f32_dpp v212, v212, v212 row_ror:8 row_mask:0xf bank_mask:0xf bound_ctrl:1
	v_pk_mul_f32 v[114:115], v[114:115], v[154:155] op_sel:[0,1] op_sel_hi:[1,1]
	v_pk_mul_f32 v[116:117], v[116:117], v[154:155] op_sel:[0,1] op_sel_hi:[1,1]
	v_add_f32_dpp v212, v212, v212 row_ror:4 row_mask:0xf bank_mask:0xf bound_ctrl:1
	v_pk_mul_f32 v[118:119], v[118:119], v[154:155] op_sel:[0,1] op_sel_hi:[1,1]
	v_pk_mul_f32 v[120:121], v[120:121], v[154:155] op_sel:[0,1] op_sel_hi:[1,1]
	v_add_f32_dpp v212, v212, v212 row_ror:2 row_mask:0xf bank_mask:0xf bound_ctrl:1
	v_pk_mul_f32 v[122:123], v[122:123], v[154:155] op_sel:[0,1] op_sel_hi:[1,1]
	v_pk_mul_f32 v[124:125], v[124:125], v[154:155] op_sel:[0,1] op_sel_hi:[1,1]
	v_add_f32_dpp v212, v212, v212 row_ror:1 row_mask:0xf bank_mask:0xf bound_ctrl:1
	v_pk_mul_f32 v[126:127], v[126:127], v[154:155] op_sel:[0,1] op_sel_hi:[1,1]
	v_pk_fma_f32 v[196:197], v[154:155], v[196:197], v[112:113] op_sel_hi:[0,1,1]
	s_and_saveexec_b64 s[8:9], s[44:45]
	ds_write_b32 v190, v212 offset:34304
	s_mov_b64 exec, s[8:9]
	v_pk_fma_f32 v[198:199], v[154:155], v[198:199], v[114:115] op_sel_hi:[0,1,1]
	v_pk_fma_f32 v[200:201], v[154:155], v[200:201], v[116:117] op_sel_hi:[0,1,1]
	v_pk_fma_f32 v[202:203], v[154:155], v[202:203], v[118:119] op_sel_hi:[0,1,1]
	v_pk_fma_f32 v[204:205], v[154:155], v[204:205], v[120:121] op_sel_hi:[0,1,1]
	v_pk_fma_f32 v[206:207], v[154:155], v[206:207], v[122:123] op_sel_hi:[0,1,1]
	v_pk_fma_f32 v[208:209], v[154:155], v[208:209], v[124:125] op_sel_hi:[0,1,1]
	v_pk_fma_f32 v[210:211], v[154:155], v[210:211], v[126:127] op_sel_hi:[0,1,1]
	s_waitcnt lgkmcnt(15)
	v_pk_fma_f32 v[128:129], v[96:97], v[196:197], v[214:215]
	v_pk_fma_f32 v[130:131], v[98:99], v[198:199], v[214:215]
	v_pk_fma_f32 v[128:129], v[100:101], v[200:201], v[128:129]
	v_pk_fma_f32 v[130:131], v[102:103], v[202:203], v[130:131]
	s_waitcnt lgkmcnt(14)
	v_pk_fma_f32 v[128:129], v[104:105], v[204:205], v[128:129]
	v_pk_fma_f32 v[130:131], v[106:107], v[206:207], v[130:131]
	s_waitcnt lgkmcnt(13)
	v_pk_fma_f32 v[128:129], v[108:109], v[208:209], v[128:129]
	v_pk_fma_f32 v[130:131], v[110:111], v[210:211], v[130:131]
	v_add_f32_e32 v128, v128, v129
	v_add_f32_e32 v130, v130, v131
	v_add_f32_e32 v213, v128, v130
	ds_read_b128 v[112:115], v194 offset:15360
	ds_read_b128 v[116:119], v194 offset:15616
	ds_read_b128 v[120:123], v194 offset:15872
	ds_read_b128 v[124:127], v194 offset:16128
	ds_read_b32 v156, v140 offset:35164
	ds_read_b32 v157, v190 offset:16832
	ds_read_b32 v154, v140 offset:35100
	ds_read_b128 v[96:99], v194 offset:7168
	ds_read_b128 v[100:103], v194 offset:7424
	ds_read_b128 v[104:107], v194 offset:7680
	ds_read_b128 v[108:111], v194 offset:7936
	s_waitcnt lgkmcnt(15)
	v_mul_f32_e32 v133, v134, v135
	v_pk_mul_f32 v[80:81], v[80:81], v[132:133] op_sel:[0,1] op_sel_hi:[1,1]
	v_add_f32_dpp v213, v213, v213 row_ror:8 row_mask:0xf bank_mask:0xf bound_ctrl:1
	v_pk_mul_f32 v[82:83], v[82:83], v[132:133] op_sel:[0,1] op_sel_hi:[1,1]
	v_pk_mul_f32 v[84:85], v[84:85], v[132:133] op_sel:[0,1] op_sel_hi:[1,1]
	v_add_f32_dpp v213, v213, v213 row_ror:4 row_mask:0xf bank_mask:0xf bound_ctrl:1
	v_pk_mul_f32 v[86:87], v[86:87], v[132:133] op_sel:[0,1] op_sel_hi:[1,1]
	v_pk_mul_f32 v[88:89], v[88:89], v[132:133] op_sel:[0,1] op_sel_hi:[1,1]
	v_add_f32_dpp v213, v213, v213 row_ror:2 row_mask:0xf bank_mask:0xf bound_ctrl:1
	v_pk_mul_f32 v[90:91], v[90:91], v[132:133] op_sel:[0,1] op_sel_hi:[1,1]
	v_pk_mul_f32 v[92:93], v[92:93], v[132:133] op_sel:[0,1] op_sel_hi:[1,1]
	v_add_f32_dpp v213, v213, v213 row_ror:1 row_mask:0xf bank_mask:0xf bound_ctrl:1
	v_pk_mul_f32 v[94:95], v[94:95], v[132:133] op_sel:[0,1] op_sel_hi:[1,1]
	v_pk_fma_f32 v[196:197], v[132:133], v[196:197], v[80:81] op_sel_hi:[0,1,1]
	s_and_saveexec_b64 s[8:9], s[44:45]
	ds_write_b32 v190, v213 offset:34368
	s_mov_b64 exec, s[8:9]
	v_pk_fma_f32 v[198:199], v[132:133], v[198:199], v[82:83] op_sel_hi:[0,1,1]
	v_pk_fma_f32 v[200:201], v[132:133], v[200:201], v[84:85] op_sel_hi:[0,1,1]
	v_pk_fma_f32 v[202:203], v[132:133], v[202:203], v[86:87] op_sel_hi:[0,1,1]
	v_pk_fma_f32 v[204:205], v[132:133], v[204:205], v[88:89] op_sel_hi:[0,1,1]
	v_pk_fma_f32 v[206:207], v[132:133], v[206:207], v[90:91] op_sel_hi:[0,1,1]
	v_pk_fma_f32 v[208:209], v[132:133], v[208:209], v[92:93] op_sel_hi:[0,1,1]
	v_pk_fma_f32 v[210:211], v[132:133], v[210:211], v[94:95] op_sel_hi:[0,1,1]
	s_waitcnt lgkmcnt(15)
	v_pk_fma_f32 v[128:129], v[64:65], v[196:197], v[214:215]
	v_pk_fma_f32 v[130:131], v[66:67], v[198:199], v[214:215]
	v_pk_fma_f32 v[128:129], v[68:69], v[200:201], v[128:129]
	v_pk_fma_f32 v[130:131], v[70:71], v[202:203], v[130:131]
	s_waitcnt lgkmcnt(14)
	v_pk_fma_f32 v[128:129], v[72:73], v[204:205], v[128:129]
	v_pk_fma_f32 v[130:131], v[74:75], v[206:207], v[130:131]
	s_waitcnt lgkmcnt(13)
	v_pk_fma_f32 v[128:129], v[76:77], v[208:209], v[128:129]
	v_pk_fma_f32 v[130:131], v[78:79], v[210:211], v[130:131]
	v_add_f32_e32 v128, v128, v129
	v_add_f32_e32 v130, v130, v131
	v_add_f32_e32 v212, v128, v130
	s_waitcnt lgkmcnt(6)
	v_mul_f32_e32 v155, v156, v157
	v_pk_mul_f32 v[112:113], v[112:113], v[154:155] op_sel:[0,1] op_sel_hi:[1,1]
	v_add_f32_dpp v212, v212, v212 row_ror:8 row_mask:0xf bank_mask:0xf bound_ctrl:1
	v_pk_mul_f32 v[114:115], v[114:115], v[154:155] op_sel:[0,1] op_sel_hi:[1,1]
	v_pk_mul_f32 v[116:117], v[116:117], v[154:155] op_sel:[0,1] op_sel_hi:[1,1]
	v_add_f32_dpp v212, v212, v212 row_ror:4 row_mask:0xf bank_mask:0xf bound_ctrl:1
	v_pk_mul_f32 v[118:119], v[118:119], v[154:155] op_sel:[0,1] op_sel_hi:[1,1]
	v_pk_mul_f32 v[120:121], v[120:121], v[154:155] op_sel:[0,1] op_sel_hi:[1,1]
	v_add_f32_dpp v212, v212, v212 row_ror:2 row_mask:0xf bank_mask:0xf bound_ctrl:1
	v_pk_mul_f32 v[122:123], v[122:123], v[154:155] op_sel:[0,1] op_sel_hi:[1,1]
	v_pk_mul_f32 v[124:125], v[124:125], v[154:155] op_sel:[0,1] op_sel_hi:[1,1]
	v_add_f32_dpp v212, v212, v212 row_ror:1 row_mask:0xf bank_mask:0xf bound_ctrl:1
	v_pk_mul_f32 v[126:127], v[126:127], v[154:155] op_sel:[0,1] op_sel_hi:[1,1]
	s_waitcnt lgkmcnt(5)
	v_pk_fma_f32 v[196:197], v[154:155], v[196:197], v[112:113] op_sel_hi:[0,1,1]
	s_and_saveexec_b64 s[8:9], s[44:45]
	ds_write_b32 v190, v212 offset:34432
	s_mov_b64 exec, s[8:9]
	v_pk_fma_f32 v[198:199], v[154:155], v[198:199], v[114:115] op_sel_hi:[0,1,1]
	v_pk_fma_f32 v[200:201], v[154:155], v[200:201], v[116:117] op_sel_hi:[0,1,1]
	v_pk_fma_f32 v[202:203], v[154:155], v[202:203], v[118:119] op_sel_hi:[0,1,1]
	v_pk_fma_f32 v[204:205], v[154:155], v[204:205], v[120:121] op_sel_hi:[0,1,1]
	v_pk_fma_f32 v[206:207], v[154:155], v[206:207], v[122:123] op_sel_hi:[0,1,1]
	v_pk_fma_f32 v[208:209], v[154:155], v[208:209], v[124:125] op_sel_hi:[0,1,1]
	v_pk_fma_f32 v[210:211], v[154:155], v[210:211], v[126:127] op_sel_hi:[0,1,1]
	s_waitcnt lgkmcnt(5)
	v_pk_fma_f32 v[128:129], v[96:97], v[196:197], v[214:215]
	v_pk_fma_f32 v[130:131], v[98:99], v[198:199], v[214:215]
	s_waitcnt lgkmcnt(4)
	v_pk_fma_f32 v[128:129], v[100:101], v[200:201], v[128:129]
	v_pk_fma_f32 v[130:131], v[102:103], v[202:203], v[130:131]
	s_waitcnt lgkmcnt(3)
	v_pk_fma_f32 v[128:129], v[104:105], v[204:205], v[128:129]
	v_pk_fma_f32 v[130:131], v[106:107], v[206:207], v[130:131]
	s_waitcnt lgkmcnt(2)
	v_pk_fma_f32 v[128:129], v[108:109], v[208:209], v[128:129]
	v_pk_fma_f32 v[130:131], v[110:111], v[210:211], v[130:131]
	v_add_f32_e32 v128, v128, v129
	v_add_f32_e32 v130, v130, v131
	v_add_f32_e32 v213, v128, v130
	s_nop 1
	v_add_f32_dpp v213, v213, v213 row_ror:8 row_mask:0xf bank_mask:0xf bound_ctrl:1
	s_nop 1
	v_add_f32_dpp v213, v213, v213 row_ror:4 row_mask:0xf bank_mask:0xf bound_ctrl:1
	s_nop 1
	v_add_f32_dpp v213, v213, v213 row_ror:2 row_mask:0xf bank_mask:0xf bound_ctrl:1
	s_nop 1
	v_add_f32_dpp v213, v213, v213 row_ror:1 row_mask:0xf bank_mask:0xf bound_ctrl:1
	s_and_saveexec_b64 s[8:9], s[44:45]
	ds_write_b32 v190, v213 offset:34496
	s_mov_b64 exec, s[8:9]
	s_waitcnt vmcnt(11)
	ds_write_b128 v188, v[16:19] offset:17024
	s_waitcnt vmcnt(9)
	ds_write_b128 v191, v[24:27] offset:17024
	ds_write_b128 v188, v[20:23] offset:25216
	s_waitcnt vmcnt(8)
	ds_write_b128 v191, v[28:31] offset:25216
	s_and_saveexec_b64 s[8:9], s[40:41]
	ds_write_b32 v145, v183 offset:33408
	s_or_b64 exec, exec, s[8:9]
	s_and_saveexec_b64 s[8:9], s[42:43]
	s_cbranch_execz .LBB0_1176
	v_add_f32_e32 v64, v178, v185
	v_mul_f32_e64 v65, |v64|, s62
	v_exp_f32_e32 v65, v65
	v_min_f32_e32 v64, 0, v64
	v_add_f32_e32 v65, 1.0, v65
	v_cmp_gt_f32_e32 vcc, s5, v65
	s_nop 1
	v_cndmask_b32_e64 v66, 0, 32, vcc
	v_ldexp_f32 v65, v65, v66
	v_log_f32_e32 v65, v65
	v_cndmask_b32_e32 v67, 0, v171, vcc
	v_add_f32_e32 v66, v147, v184
	v_mul_f32_e32 v68, 0x3f317217, v65
	v_fma_f32 v68, v65, s76, -v68
	v_fmac_f32_e32 v68, 0x3377d1cf, v65
	v_fmac_f32_e32 v68, 0x3f317217, v65
	v_cmp_lt_f32_e64 vcc, |v65|, s77
	s_nop 1
	v_cndmask_b32_e32 v65, v65, v68, vcc
	v_sub_f32_e32 v65, v65, v67
	v_sub_f32_e32 v64, v64, v65
	v_add_u32_e32 v65, 0x8400, v145
	ds_write2_b32 v65, v66, v64 offset0:32 offset1:48

.LBB0_1189:
	s_or_b64 exec, exec, s[8:9]
	s_waitcnt lgkmcnt(0)
	s_barrier
	v_mov_b32_e32 v214, 0
	v_mov_b32_e32 v215, 0
	ds_read_b128 v[80:83], v194 offset:25216
	ds_read_b128 v[84:87], v194 offset:25472
	ds_read_b128 v[88:91], v194 offset:25728
	ds_read_b128 v[92:95], v194 offset:25984
	ds_read_b32 v134, v140 offset:35136
	ds_read_b32 v135, v190 offset:33408
	ds_read_b32 v132, v140 offset:35072
	ds_read_b128 v[64:67], v194 offset:17024
	ds_read_b128 v[68:71], v194 offset:17280
	ds_read_b128 v[72:75], v194 offset:17536
	ds_read_b128 v[76:79], v194 offset:17792
	ds_read_b128 v[112:115], v194 offset:26240
	ds_read_b128 v[116:119], v194 offset:26496
	ds_read_b128 v[120:123], v194 offset:26752
	ds_read_b128 v[124:127], v194 offset:27008
	ds_read_b32 v156, v140 offset:35140
	ds_read_b32 v157, v190 offset:33472
	ds_read_b32 v154, v140 offset:35076
	ds_read_b128 v[96:99], v194 offset:18048
	ds_read_b128 v[100:103], v194 offset:18304
	ds_read_b128 v[104:107], v194 offset:18560
	ds_read_b128 v[108:111], v194 offset:18816
	s_waitcnt lgkmcnt(15)
	v_mul_f32_e32 v133, v134, v135
	v_pk_mul_f32 v[80:81], v[80:81], v[132:133] op_sel:[0,1] op_sel_hi:[1,1]
	v_pk_mul_f32 v[82:83], v[82:83], v[132:133] op_sel:[0,1] op_sel_hi:[1,1]
	v_pk_mul_f32 v[84:85], v[84:85], v[132:133] op_sel:[0,1] op_sel_hi:[1,1]
	v_pk_mul_f32 v[86:87], v[86:87], v[132:133] op_sel:[0,1] op_sel_hi:[1,1]
	v_pk_mul_f32 v[88:89], v[88:89], v[132:133] op_sel:[0,1] op_sel_hi:[1,1]
	v_pk_mul_f32 v[90:91], v[90:91], v[132:133] op_sel:[0,1] op_sel_hi:[1,1]
	v_pk_mul_f32 v[92:93], v[92:93], v[132:133] op_sel:[0,1] op_sel_hi:[1,1]
	v_pk_mul_f32 v[94:95], v[94:95], v[132:133] op_sel:[0,1] op_sel_hi:[1,1]
	v_pk_fma_f32 v[196:197], v[132:133], v[196:197], v[80:81] op_sel_hi:[0,1,1]
	v_pk_fma_f32 v[198:199], v[132:133], v[198:199], v[82:83] op_sel_hi:[0,1,1]
	v_pk_fma_f32 v[200:201], v[132:133], v[200:201], v[84:85] op_sel_hi:[0,1,1]
	v_pk_fma_f32 v[202:203], v[132:133], v[202:203], v[86:87] op_sel_hi:[0,1,1]
	v_pk_fma_f32 v[204:205], v[132:133], v[204:205], v[88:89] op_sel_hi:[0,1,1]
	v_pk_fma_f32 v[206:207], v[132:133], v[206:207], v[90:91] op_sel_hi:[0,1,1]
	v_pk_fma_f32 v[208:209], v[132:133], v[208:209], v[92:93] op_sel_hi:[0,1,1]
	v_pk_fma_f32 v[210:211], v[132:133], v[210:211], v[94:95] op_sel_hi:[0,1,1]
	s_waitcnt lgkmcnt(14)
	v_pk_fma_f32 v[128:129], v[64:65], v[196:197], v[214:215]
	v_pk_fma_f32 v[130:131], v[66:67], v[198:199], v[214:215]
	s_waitcnt lgkmcnt(13)
	v_pk_fma_f32 v[128:129], v[68:69], v[200:201], v[128:129]
	v_pk_fma_f32 v[130:131], v[70:71], v[202:203], v[130:131]
	s_waitcnt lgkmcnt(12)
	v_pk_fma_f32 v[128:129], v[72:73], v[204:205], v[128:129]
	v_pk_fma_f32 v[130:131], v[74:75], v[206:207], v[130:131]
	s_waitcnt lgkmcnt(11)
	v_pk_fma_f32 v[128:129], v[76:77], v[208:209], v[128:129]
	v_pk_fma_f32 v[130:131], v[78:79], v[210:211], v[130:131]
	v_add_f32_e32 v128, v128, v129
	v_add_f32_e32 v130, v130, v131
	v_add_f32_e32 v212, v128, v130
	ds_read_b128 v[80:83], v194 offset:27264
	ds_read_b128 v[84:87], v194 offset:27520
	ds_read_b128 v[88:91], v194 offset:27776
	ds_read_b128 v[92:95], v194 offset:28032
	ds_read_b32 v134, v140 offset:35144
	ds_read_b32 v135, v190 offset:33536
	ds_read_b32 v132, v140 offset:35080
	ds_read_b128 v[64:67], v194 offset:19072
	ds_read_b128 v[68:71], v194 offset:19328
	ds_read_b128 v[72:75], v194 offset:19584
	ds_read_b128 v[76:79], v194 offset:19840
	s_waitcnt lgkmcnt(15)
	v_mul_f32_e32 v155, v156, v157
	v_pk_mul_f32 v[112:113], v[112:113], v[154:155] op_sel:[0,1] op_sel_hi:[1,1]
	v_add_f32_dpp v212, v212, v212 row_ror:8 row_mask:0xf bank_mask:0xf bound_ctrl:1
	v_pk_mul_f32 v[114:115], v[114:115], v[154:155] op_sel:[0,1] op_sel_hi:[1,1]
	v_pk_mul_f32 v[116:117], v[116:117], v[154:155] op_sel:[0,1] op_sel_hi:[1,1]
	v_add_f32_dpp v212, v212, v212 row_ror:4 row_mask:0xf bank_mask:0xf bound_ctrl:1
	v_pk_mul_f32 v[118:119], v[118:119], v[154:155] op_sel:[0,1] op_sel_hi:[1,1]
	v_pk_mul_f32 v[120:121], v[120:121], v[154:155] op_sel:[0,1] op_sel_hi:[1,1]
	v_add_f32_dpp v212, v212, v212 row_ror:2 row_mask:0xf bank_mask:0xf bound_ctrl:1
	v_pk_mul_f32 v[122:123], v[122:123], v[154:155] op_sel:[0,1] op_sel_hi:[1,1]
	v_pk_mul_f32 v[124:125], v[124:125], v[154:155] op_sel:[0,1] op_sel_hi:[1,1]
	v_add_f32_dpp v212, v212, v212 row_ror:1 row_mask:0xf bank_mask:0xf bound_ctrl:1
	v_pk_mul_f32 v[126:127], v[126:127], v[154:155] op_sel:[0,1] op_sel_hi:[1,1]
	v_pk_fma_f32 v[196:197], v[154:155], v[196:197], v[112:113] op_sel_hi:[0,1,1]
	s_and_saveexec_b64 s[8:9], s[44:45]
	ds_write_b32 v190, v212 offset:34560
	s_mov_b64 exec, s[8:9]
	v_pk_fma_f32 v[198:199], v[154:155], v[198:199], v[114:115] op_sel_hi:[0,1,1]
	v_pk_fma_f32 v[200:201], v[154:155], v[200:201], v[116:117] op_sel_hi:[0,1,1]
	v_pk_fma_f32 v[202:203], v[154:155], v[202:203], v[118:119] op_sel_hi:[0,1,1]
	v_pk_fma_f32 v[204:205], v[154:155], v[204:205], v[120:121] op_sel_hi:[0,1,1]
	v_pk_fma_f32 v[206:207], v[154:155], v[206:207], v[122:123] op_sel_hi:[0,1,1]
	v_pk_fma_f32 v[208:209], v[154:155], v[208:209], v[124:125] op_sel_hi:[0,1,1]
	v_pk_fma_f32 v[210:211], v[154:155], v[210:211], v[126:127] op_sel_hi:[0,1,1]
	s_waitcnt lgkmcnt(15)
	v_pk_fma_f32 v[128:129], v[96:97], v[196:197], v[214:215]
	v_pk_fma_f32 v[130:131], v[98:99], v[198:199], v[214:215]
	s_waitcnt lgkmcnt(14)
	v_pk_fma_f32 v[128:129], v[100:101], v[200:201], v[128:129]
	v_pk_fma_f32 v[130:131], v[102:103], v[202:203], v[130:131]
	s_waitcnt lgkmcnt(13)
	v_pk_fma_f32 v[128:129], v[104:105], v[204:205], v[128:129]
	v_pk_fma_f32 v[130:131], v[106:107], v[206:207], v[130:131]
	s_waitcnt lgkmcnt(12)
	v_pk_fma_f32 v[128:129], v[108:109], v[208:209], v[128:129]
	v_pk_fma_f32 v[130:131], v[110:111], v[210:211], v[130:131]
	v_add_f32_e32 v128, v128, v129
	v_add_f32_e32 v130, v130, v131
	v_add_f32_e32 v213, v128, v130
	ds_read_b128 v[112:115], v194 offset:28288
	ds_read_b128 v[116:119], v194 offset:28544
	ds_read_b128 v[120:123], v194 offset:28800
	ds_read_b128 v[124:127], v194 offset:29056
	ds_read_b32 v156, v140 offset:35148
	ds_read_b32 v157, v190 offset:33600
	ds_read_b32 v154, v140 offset:35084
	ds_read_b128 v[96:99], v194 offset:20096
	ds_read_b128 v[100:103], v194 offset:20352
	ds_read_b128 v[104:107], v194 offset:20608
	ds_read_b128 v[108:111], v194 offset:20864
	s_waitcnt lgkmcnt(15)
	v_mul_f32_e32 v133, v134, v135
	v_pk_mul_f32 v[80:81], v[80:81], v[132:133] op_sel:[0,1] op_sel_hi:[1,1]
	v_add_f32_dpp v213, v213, v213 row_ror:8 row_mask:0xf bank_mask:0xf bound_ctrl:1
	v_pk_mul_f32 v[82:83], v[82:83], v[132:133] op_sel:[0,1] op_sel_hi:[1,1]
	v_pk_mul_f32 v[84:85], v[84:85], v[132:133] op_sel:[0,1] op_sel_hi:[1,1]
	v_add_f32_dpp v213, v213, v213 row_ror:4 row_mask:0xf bank_mask:0xf bound_ctrl:1
	v_pk_mul_f32 v[86:87], v[86:87], v[132:133] op_sel:[0,1] op_sel_hi:[1,1]
	v_pk_mul_f32 v[88:89], v[88:89], v[132:133] op_sel:[0,1] op_sel_hi:[1,1]
	v_add_f32_dpp v213, v213, v213 row_ror:2 row_mask:0xf bank_mask:0xf bound_ctrl:1
	v_pk_mul_f32 v[90:91], v[90:91], v[132:133] op_sel:[0,1] op_sel_hi:[1,1]
	v_pk_mul_f32 v[92:93], v[92:93], v[132:133] op_sel:[0,1] op_sel_hi:[1,1]
	v_add_f32_dpp v213, v213, v213 row_ror:1 row_mask:0xf bank_mask:0xf bound_ctrl:1
	v_pk_mul_f32 v[94:95], v[94:95], v[132:133] op_sel:[0,1] op_sel_hi:[1,1]
	v_pk_fma_f32 v[196:197], v[132:133], v[196:197], v[80:81] op_sel_hi:[0,1,1]
	s_and_saveexec_b64 s[8:9], s[44:45]
	ds_write_b32 v190, v213 offset:34624
	s_mov_b64 exec, s[8:9]
	v_pk_fma_f32 v[198:199], v[132:133], v[198:199], v[82:83] op_sel_hi:[0,1,1]
	v_pk_fma_f32 v[200:201], v[132:133], v[200:201], v[84:85] op_sel_hi:[0,1,1]
	v_pk_fma_f32 v[202:203], v[132:133], v[202:203], v[86:87] op_sel_hi:[0,1,1]
	v_pk_fma_f32 v[204:205], v[132:133], v[204:205], v[88:89] op_sel_hi:[0,1,1]
	v_pk_fma_f32 v[206:207], v[132:133], v[206:207], v[90:91] op_sel_hi:[0,1,1]
	v_pk_fma_f32 v[208:209], v[132:133], v[208:209], v[92:93] op_sel_hi:[0,1,1]
	v_pk_fma_f32 v[210:211], v[132:133], v[210:211], v[94:95] op_sel_hi:[0,1,1]
	s_waitcnt lgkmcnt(15)
	v_pk_fma_f32 v[128:129], v[64:65], v[196:197], v[214:215]
	v_pk_fma_f32 v[130:131], v[66:67], v[198:199], v[214:215]
	v_pk_fma_f32 v[128:129], v[68:69], v[200:201], v[128:129]
	v_pk_fma_f32 v[130:131], v[70:71], v[202:203], v[130:131]
	s_waitcnt lgkmcnt(14)
	v_pk_fma_f32 v[128:129], v[72:73], v[204:205], v[128:129]
	v_pk_fma_f32 v[130:131], v[74:75], v[206:207], v[130:131]
	s_waitcnt lgkmcnt(13)
	v_pk_fma_f32 v[128:129], v[76:77], v[208:209], v[128:129]
	v_pk_fma_f32 v[130:131], v[78:79], v[210:211], v[130:131]
	v_add_f32_e32 v128, v128, v129
	v_add_f32_e32 v130, v130, v131
	v_add_f32_e32 v212, v128, v130
	ds_read_b128 v[80:83], v194 offset:29312
	ds_read_b128 v[84:87], v194 offset:29568
	ds_read_b128 v[88:91], v194 offset:29824
	ds_read_b128 v[92:95], v194 offset:30080
	ds_read_b32 v134, v140 offset:35152
	ds_read_b32 v135, v190 offset:33664
	ds_read_b32 v132, v140 offset:35088
	ds_read_b128 v[64:67], v194 offset:21120
	ds_read_b128 v[68:71], v194 offset:21376
	ds_read_b128 v[72:75], v194 offset:21632
	ds_read_b128 v[76:79], v194 offset:21888
	s_waitcnt lgkmcnt(15)
	v_mul_f32_e32 v155, v156, v157
	v_pk_mul_f32 v[112:113], v[112:113], v[154:155] op_sel:[0,1] op_sel_hi:[1,1]
	v_add_f32_dpp v212, v212, v212 row_ror:8 row_mask:0xf bank_mask:0xf bound_ctrl:1
	v_pk_mul_f32 v[114:115], v[114:115], v[154:155] op_sel:[0,1] op_sel_hi:[1,1]
	v_pk_mul_f32 v[116:117], v[116:117], v[154:155] op_sel:[0,1] op_sel_hi:[1,1]
	v_add_f32_dpp v212, v212, v212 row_ror:4 row_mask:0xf bank_mask:0xf bound_ctrl:1
	v_pk_mul_f32 v[118:119], v[118:119], v[154:155] op_sel:[0,1] op_sel_hi:[1,1]
	v_pk_mul_f32 v[120:121], v[120:121], v[154:155] op_sel:[0,1] op_sel_hi:[1,1]
	v_add_f32_dpp v212, v212, v212 row_ror:2 row_mask:0xf bank_mask:0xf bound_ctrl:1
	v_pk_mul_f32 v[122:123], v[122:123], v[154:155] op_sel:[0,1] op_sel_hi:[1,1]
	v_pk_mul_f32 v[124:125], v[124:125], v[154:155] op_sel:[0,1] op_sel_hi:[1,1]
	v_add_f32_dpp v212, v212, v212 row_ror:1 row_mask:0xf bank_mask:0xf bound_ctrl:1
	v_pk_mul_f32 v[126:127], v[126:127], v[154:155] op_sel:[0,1] op_sel_hi:[1,1]
	v_pk_fma_f32 v[196:197], v[154:155], v[196:197], v[112:113] op_sel_hi:[0,1,1]
	s_and_saveexec_b64 s[8:9], s[44:45]
	ds_write_b32 v190, v212 offset:34688
	s_mov_b64 exec, s[8:9]
	v_pk_fma_f32 v[198:199], v[154:155], v[198:199], v[114:115] op_sel_hi:[0,1,1]
	v_pk_fma_f32 v[200:201], v[154:155], v[200:201], v[116:117] op_sel_hi:[0,1,1]
	v_pk_fma_f32 v[202:203], v[154:155], v[202:203], v[118:119] op_sel_hi:[0,1,1]
	v_pk_fma_f32 v[204:205], v[154:155], v[204:205], v[120:121] op_sel_hi:[0,1,1]
	v_pk_fma_f32 v[206:207], v[154:155], v[206:207], v[122:123] op_sel_hi:[0,1,1]
	v_pk_fma_f32 v[208:209], v[154:155], v[208:209], v[124:125] op_sel_hi:[0,1,1]
	v_pk_fma_f32 v[210:211], v[154:155], v[210:211], v[126:127] op_sel_hi:[0,1,1]
	s_waitcnt lgkmcnt(15)
	v_pk_fma_f32 v[128:129], v[96:97], v[196:197], v[214:215]
	v_pk_fma_f32 v[130:131], v[98:99], v[198:199], v[214:215]
	v_pk_fma_f32 v[128:129], v[100:101], v[200:201], v[128:129]
	v_pk_fma_f32 v[130:131], v[102:103], v[202:203], v[130:131]
	s_waitcnt lgkmcnt(14)
	v_pk_fma_f32 v[128:129], v[104:105], v[204:205], v[128:129]
	v_pk_fma_f32 v[130:131], v[106:107], v[206:207], v[130:131]
	s_waitcnt lgkmcnt(13)
	v_pk_fma_f32 v[128:129], v[108:109], v[208:209], v[128:129]
	v_pk_fma_f32 v[130:131], v[110:111], v[210:211], v[130:131]
	v_add_f32_e32 v128, v128, v129
	v_add_f32_e32 v130, v130, v131
	v_add_f32_e32 v213, v128, v130
	ds_read_b128 v[112:115], v194 offset:30336
	ds_read_b128 v[116:119], v194 offset:30592
	ds_read_b128 v[120:123], v194 offset:30848
	ds_read_b128 v[124:127], v194 offset:31104
	ds_read_b32 v156, v140 offset:35156
	ds_read_b32 v157, v190 offset:33728
	ds_read_b32 v154, v140 offset:35092
	ds_read_b128 v[96:99], v194 offset:22144
	ds_read_b128 v[100:103], v194 offset:22400
	ds_read_b128 v[104:107], v194 offset:22656
	ds_read_b128 v[108:111], v194 offset:22912
	s_waitcnt lgkmcnt(15)
	v_mul_f32_e32 v133, v134, v135
	v_pk_mul_f32 v[80:81], v[80:81], v[132:133] op_sel:[0,1] op_sel_hi:[1,1]
	v_add_f32_dpp v213, v213, v213 row_ror:8 row_mask:0xf bank_mask:0xf bound_ctrl:1
	v_pk_mul_f32 v[82:83], v[82:83], v[132:133] op_sel:[0,1] op_sel_hi:[1,1]
	v_pk_mul_f32 v[84:85], v[84:85], v[132:133] op_sel:[0,1] op_sel_hi:[1,1]
	v_add_f32_dpp v213, v213, v213 row_ror:4 row_mask:0xf bank_mask:0xf bound_ctrl:1
	v_pk_mul_f32 v[86:87], v[86:87], v[132:133] op_sel:[0,1] op_sel_hi:[1,1]
	v_pk_mul_f32 v[88:89], v[88:89], v[132:133] op_sel:[0,1] op_sel_hi:[1,1]
	v_add_f32_dpp v213, v213, v213 row_ror:2 row_mask:0xf bank_mask:0xf bound_ctrl:1
	v_pk_mul_f32 v[90:91], v[90:91], v[132:133] op_sel:[0,1] op_sel_hi:[1,1]
	v_pk_mul_f32 v[92:93], v[92:93], v[132:133] op_sel:[0,1] op_sel_hi:[1,1]
	v_add_f32_dpp v213, v213, v213 row_ror:1 row_mask:0xf bank_mask:0xf bound_ctrl:1
	v_pk_mul_f32 v[94:95], v[94:95], v[132:133] op_sel:[0,1] op_sel_hi:[1,1]
	v_pk_fma_f32 v[196:197], v[132:133], v[196:197], v[80:81] op_sel_hi:[0,1,1]
	s_and_saveexec_b64 s[8:9], s[44:45]
	ds_write_b32 v190, v213 offset:34752
	s_mov_b64 exec, s[8:9]
	v_pk_fma_f32 v[198:199], v[132:133], v[198:199], v[82:83] op_sel_hi:[0,1,1]
	v_pk_fma_f32 v[200:201], v[132:133], v[200:201], v[84:85] op_sel_hi:[0,1,1]
	v_pk_fma_f32 v[202:203], v[132:133], v[202:203], v[86:87] op_sel_hi:[0,1,1]
	v_pk_fma_f32 v[204:205], v[132:133], v[204:205], v[88:89] op_sel_hi:[0,1,1]
	v_pk_fma_f32 v[206:207], v[132:133], v[206:207], v[90:91] op_sel_hi:[0,1,1]
	v_pk_fma_f32 v[208:209], v[132:133], v[208:209], v[92:93] op_sel_hi:[0,1,1]
	v_pk_fma_f32 v[210:211], v[132:133], v[210:211], v[94:95] op_sel_hi:[0,1,1]
	s_waitcnt lgkmcnt(15)
	v_pk_fma_f32 v[128:129], v[64:65], v[196:197], v[214:215]
	v_pk_fma_f32 v[130:131], v[66:67], v[198:199], v[214:215]
	v_pk_fma_f32 v[128:129], v[68:69], v[200:201], v[128:129]
	v_pk_fma_f32 v[130:131], v[70:71], v[202:203], v[130:131]
	s_waitcnt lgkmcnt(14)
	v_pk_fma_f32 v[128:129], v[72:73], v[204:205], v[128:129]
	v_pk_fma_f32 v[130:131], v[74:75], v[206:207], v[130:131]
	s_waitcnt lgkmcnt(13)
	v_pk_fma_f32 v[128:129], v[76:77], v[208:209], v[128:129]
	v_pk_fma_f32 v[130:131], v[78:79], v[210:211], v[130:131]
	v_add_f32_e32 v128, v128, v129
	v_add_f32_e32 v130, v130, v131
	v_add_f32_e32 v212, v128, v130
	ds_read_b128 v[80:83], v194 offset:31360
	ds_read_b128 v[84:87], v194 offset:31616
	ds_read_b128 v[88:91], v194 offset:31872
	ds_read_b128 v[92:95], v194 offset:32128
	ds_read_b32 v134, v140 offset:35160
	ds_read_b32 v135, v190 offset:33792
	ds_read_b32 v132, v140 offset:35096
	ds_read_b128 v[64:67], v194 offset:23168
	ds_read_b128 v[68:71], v194 offset:23424
	ds_read_b128 v[72:75], v194 offset:23680
	ds_read_b128 v[76:79], v194 offset:23936
	s_waitcnt lgkmcnt(15)
	v_mul_f32_e32 v155, v156, v157
	v_pk_mul_f32 v[112:113], v[112:113], v[154:155] op_sel:[0,1] op_sel_hi:[1,1]
	v_add_f32_dpp v212, v212, v212 row_ror:8 row_mask:0xf bank_mask:0xf bound_ctrl:1
	v_pk_mul_f32 v[114:115], v[114:115], v[154:155] op_sel:[0,1] op_sel_hi:[1,1]
	v_pk_mul_f32 v[116:117], v[116:117], v[154:155] op_sel:[0,1] op_sel_hi:[1,1]
	v_add_f32_dpp v212, v212, v212 row_ror:4 row_mask:0xf bank_mask:0xf bound_ctrl:1
	v_pk_mul_f32 v[118:119], v[118:119], v[154:155] op_sel:[0,1] op_sel_hi:[1,1]
	v_pk_mul_f32 v[120:121], v[120:121], v[154:155] op_sel:[0,1] op_sel_hi:[1,1]
	v_add_f32_dpp v212, v212, v212 row_ror:2 row_mask:0xf bank_mask:0xf bound_ctrl:1
	v_pk_mul_f32 v[122:123], v[122:123], v[154:155] op_sel:[0,1] op_sel_hi:[1,1]
	v_pk_mul_f32 v[124:125], v[124:125], v[154:155] op_sel:[0,1] op_sel_hi:[1,1]
	v_add_f32_dpp v212, v212, v212 row_ror:1 row_mask:0xf bank_mask:0xf bound_ctrl:1
	v_pk_mul_f32 v[126:127], v[126:127], v[154:155] op_sel:[0,1] op_sel_hi:[1,1]
	v_pk_fma_f32 v[196:197], v[154:155], v[196:197], v[112:113] op_sel_hi:[0,1,1]
	s_and_saveexec_b64 s[8:9], s[44:45]
	ds_write_b32 v190, v212 offset:34816
	s_mov_b64 exec, s[8:9]
	v_pk_fma_f32 v[198:199], v[154:155], v[198:199], v[114:115] op_sel_hi:[0,1,1]
	v_pk_fma_f32 v[200:201], v[154:155], v[200:201], v[116:117] op_sel_hi:[0,1,1]
	v_pk_fma_f32 v[202:203], v[154:155], v[202:203], v[118:119] op_sel_hi:[0,1,1]
	v_pk_fma_f32 v[204:205], v[154:155], v[204:205], v[120:121] op_sel_hi:[0,1,1]
	v_pk_fma_f32 v[206:207], v[154:155], v[206:207], v[122:123] op_sel_hi:[0,1,1]
	v_pk_fma_f32 v[208:209], v[154:155], v[208:209], v[124:125] op_sel_hi:[0,1,1]
	v_pk_fma_f32 v[210:211], v[154:155], v[210:211], v[126:127] op_sel_hi:[0,1,1]
	s_waitcnt lgkmcnt(15)
	v_pk_fma_f32 v[128:129], v[96:97], v[196:197], v[214:215]
	v_pk_fma_f32 v[130:131], v[98:99], v[198:199], v[214:215]
	v_pk_fma_f32 v[128:129], v[100:101], v[200:201], v[128:129]
	v_pk_fma_f32 v[130:131], v[102:103], v[202:203], v[130:131]
	s_waitcnt lgkmcnt(14)
	v_pk_fma_f32 v[128:129], v[104:105], v[204:205], v[128:129]
	v_pk_fma_f32 v[130:131], v[106:107], v[206:207], v[130:131]
	s_waitcnt lgkmcnt(13)
	v_pk_fma_f32 v[128:129], v[108:109], v[208:209], v[128:129]
	v_pk_fma_f32 v[130:131], v[110:111], v[210:211], v[130:131]
	v_add_f32_e32 v128, v128, v129
	v_add_f32_e32 v130, v130, v131
	v_add_f32_e32 v213, v128, v130
	ds_read_b128 v[112:115], v194 offset:32384
	ds_read_b128 v[116:119], v194 offset:32640
	ds_read_b128 v[120:123], v194 offset:32896
	ds_read_b128 v[124:127], v194 offset:33152
	ds_read_b32 v156, v140 offset:35164
	ds_read_b32 v157, v190 offset:33856
	ds_read_b32 v154, v140 offset:35100
	ds_read_b128 v[96:99], v194 offset:24192
	ds_read_b128 v[100:103], v194 offset:24448
	ds_read_b128 v[104:107], v194 offset:24704
	ds_read_b128 v[108:111], v194 offset:24960
	s_waitcnt lgkmcnt(15)
	v_mul_f32_e32 v133, v134, v135
	v_pk_mul_f32 v[80:81], v[80:81], v[132:133] op_sel:[0,1] op_sel_hi:[1,1]
	v_add_f32_dpp v213, v213, v213 row_ror:8 row_mask:0xf bank_mask:0xf bound_ctrl:1
	v_pk_mul_f32 v[82:83], v[82:83], v[132:133] op_sel:[0,1] op_sel_hi:[1,1]
	v_pk_mul_f32 v[84:85], v[84:85], v[132:133] op_sel:[0,1] op_sel_hi:[1,1]
	v_add_f32_dpp v213, v213, v213 row_ror:4 row_mask:0xf bank_mask:0xf bound_ctrl:1
	v_pk_mul_f32 v[86:87], v[86:87], v[132:133] op_sel:[0,1] op_sel_hi:[1,1]
	v_pk_mul_f32 v[88:89], v[88:89], v[132:133] op_sel:[0,1] op_sel_hi:[1,1]
	v_add_f32_dpp v213, v213, v213 row_ror:2 row_mask:0xf bank_mask:0xf bound_ctrl:1
	v_pk_mul_f32 v[90:91], v[90:91], v[132:133] op_sel:[0,1] op_sel_hi:[1,1]
	v_pk_mul_f32 v[92:93], v[92:93], v[132:133] op_sel:[0,1] op_sel_hi:[1,1]
	v_add_f32_dpp v213, v213, v213 row_ror:1 row_mask:0xf bank_mask:0xf bound_ctrl:1
	v_pk_mul_f32 v[94:95], v[94:95], v[132:133] op_sel:[0,1] op_sel_hi:[1,1]
	v_pk_fma_f32 v[196:197], v[132:133], v[196:197], v[80:81] op_sel_hi:[0,1,1]
	s_and_saveexec_b64 s[8:9], s[44:45]
	ds_write_b32 v190, v213 offset:34880
	s_mov_b64 exec, s[8:9]
	v_pk_fma_f32 v[198:199], v[132:133], v[198:199], v[82:83] op_sel_hi:[0,1,1]
	v_pk_fma_f32 v[200:201], v[132:133], v[200:201], v[84:85] op_sel_hi:[0,1,1]
	v_pk_fma_f32 v[202:203], v[132:133], v[202:203], v[86:87] op_sel_hi:[0,1,1]
	v_pk_fma_f32 v[204:205], v[132:133], v[204:205], v[88:89] op_sel_hi:[0,1,1]
	v_pk_fma_f32 v[206:207], v[132:133], v[206:207], v[90:91] op_sel_hi:[0,1,1]
	v_pk_fma_f32 v[208:209], v[132:133], v[208:209], v[92:93] op_sel_hi:[0,1,1]
	v_pk_fma_f32 v[210:211], v[132:133], v[210:211], v[94:95] op_sel_hi:[0,1,1]
	s_waitcnt lgkmcnt(15)
	v_pk_fma_f32 v[128:129], v[64:65], v[196:197], v[214:215]
	v_pk_fma_f32 v[130:131], v[66:67], v[198:199], v[214:215]
	v_pk_fma_f32 v[128:129], v[68:69], v[200:201], v[128:129]
	v_pk_fma_f32 v[130:131], v[70:71], v[202:203], v[130:131]
	s_waitcnt lgkmcnt(14)
	v_pk_fma_f32 v[128:129], v[72:73], v[204:205], v[128:129]
	v_pk_fma_f32 v[130:131], v[74:75], v[206:207], v[130:131]
	s_waitcnt lgkmcnt(13)
	v_pk_fma_f32 v[128:129], v[76:77], v[208:209], v[128:129]
	v_pk_fma_f32 v[130:131], v[78:79], v[210:211], v[130:131]
	v_add_f32_e32 v128, v128, v129
	v_add_f32_e32 v130, v130, v131
	v_add_f32_e32 v212, v128, v130
	s_waitcnt lgkmcnt(6)
	v_mul_f32_e32 v155, v156, v157
	v_pk_mul_f32 v[112:113], v[112:113], v[154:155] op_sel:[0,1] op_sel_hi:[1,1]
	v_add_f32_dpp v212, v212, v212 row_ror:8 row_mask:0xf bank_mask:0xf bound_ctrl:1
	v_pk_mul_f32 v[114:115], v[114:115], v[154:155] op_sel:[0,1] op_sel_hi:[1,1]
	v_pk_mul_f32 v[116:117], v[116:117], v[154:155] op_sel:[0,1] op_sel_hi:[1,1]
	v_add_f32_dpp v212, v212, v212 row_ror:4 row_mask:0xf bank_mask:0xf bound_ctrl:1
	v_pk_mul_f32 v[118:119], v[118:119], v[154:155] op_sel:[0,1] op_sel_hi:[1,1]
	v_pk_mul_f32 v[120:121], v[120:121], v[154:155] op_sel:[0,1] op_sel_hi:[1,1]
	v_add_f32_dpp v212, v212, v212 row_ror:2 row_mask:0xf bank_mask:0xf bound_ctrl:1
	v_pk_mul_f32 v[122:123], v[122:123], v[154:155] op_sel:[0,1] op_sel_hi:[1,1]
	v_pk_mul_f32 v[124:125], v[124:125], v[154:155] op_sel:[0,1] op_sel_hi:[1,1]
	v_add_f32_dpp v212, v212, v212 row_ror:1 row_mask:0xf bank_mask:0xf bound_ctrl:1
	v_pk_mul_f32 v[126:127], v[126:127], v[154:155] op_sel:[0,1] op_sel_hi:[1,1]
	s_waitcnt lgkmcnt(5)
	v_pk_fma_f32 v[196:197], v[154:155], v[196:197], v[112:113] op_sel_hi:[0,1,1]
	s_and_saveexec_b64 s[8:9], s[44:45]
	ds_write_b32 v190, v212 offset:34944
	s_mov_b64 exec, s[8:9]
	v_pk_fma_f32 v[198:199], v[154:155], v[198:199], v[114:115] op_sel_hi:[0,1,1]
	v_pk_fma_f32 v[200:201], v[154:155], v[200:201], v[116:117] op_sel_hi:[0,1,1]
	v_pk_fma_f32 v[202:203], v[154:155], v[202:203], v[118:119] op_sel_hi:[0,1,1]
	v_pk_fma_f32 v[204:205], v[154:155], v[204:205], v[120:121] op_sel_hi:[0,1,1]
	v_pk_fma_f32 v[206:207], v[154:155], v[206:207], v[122:123] op_sel_hi:[0,1,1]
	v_pk_fma_f32 v[208:209], v[154:155], v[208:209], v[124:125] op_sel_hi:[0,1,1]
	v_pk_fma_f32 v[210:211], v[154:155], v[210:211], v[126:127] op_sel_hi:[0,1,1]
	s_waitcnt lgkmcnt(5)
	v_pk_fma_f32 v[128:129], v[96:97], v[196:197], v[214:215]
	v_pk_fma_f32 v[130:131], v[98:99], v[198:199], v[214:215]
	s_waitcnt lgkmcnt(4)
	v_pk_fma_f32 v[128:129], v[100:101], v[200:201], v[128:129]
	v_pk_fma_f32 v[130:131], v[102:103], v[202:203], v[130:131]
	s_waitcnt lgkmcnt(3)
	v_pk_fma_f32 v[128:129], v[104:105], v[204:205], v[128:129]
	v_pk_fma_f32 v[130:131], v[106:107], v[206:207], v[130:131]
	s_waitcnt lgkmcnt(2)
	v_pk_fma_f32 v[128:129], v[108:109], v[208:209], v[128:129]
	v_pk_fma_f32 v[130:131], v[110:111], v[210:211], v[130:131]
	v_add_f32_e32 v128, v128, v129
	v_add_f32_e32 v130, v130, v131
	v_add_f32_e32 v213, v128, v130
	s_nop 1
	v_add_f32_dpp v213, v213, v213 row_ror:8 row_mask:0xf bank_mask:0xf bound_ctrl:1
	s_nop 1
	v_add_f32_dpp v213, v213, v213 row_ror:4 row_mask:0xf bank_mask:0xf bound_ctrl:1
	s_nop 1
	v_add_f32_dpp v213, v213, v213 row_ror:2 row_mask:0xf bank_mask:0xf bound_ctrl:1
	s_nop 1
	v_add_f32_dpp v213, v213, v213 row_ror:1 row_mask:0xf bank_mask:0xf bound_ctrl:1
	s_and_saveexec_b64 s[8:9], s[44:45]
	ds_write_b32 v190, v213 offset:35008
	s_mov_b64 exec, s[8:9]
	s_waitcnt vmcnt(7)
	ds_write_b128 v188, v[32:35]
	s_waitcnt vmcnt(5)
	ds_write_b128 v191, v[40:43]
	ds_write_b128 v188, v[36:39] offset:8192
	s_waitcnt vmcnt(4)
	ds_write_b128 v191, v[44:47] offset:8192
	s_and_saveexec_b64 s[8:9], s[40:41]
	ds_write_b32 v145, v186 offset:16384
	s_or_b64 exec, exec, s[8:9]
	s_and_saveexec_b64 s[8:9], s[42:43]
	s_cbranch_execz .LBB0_1209
	v_add_f32_e32 v64, v178, v189
	v_mul_f32_e64 v65, |v64|, s62
	v_exp_f32_e32 v65, v65
	v_min_f32_e32 v64, 0, v64
	v_add_f32_e32 v65, 1.0, v65
	v_cmp_gt_f32_e32 vcc, s5, v65
	s_nop 1
	v_cndmask_b32_e64 v66, 0, 32, vcc
	v_ldexp_f32 v65, v65, v66
	v_log_f32_e32 v65, v65
	v_cndmask_b32_e32 v67, 0, v171, vcc
	v_add_f32_e32 v66, v147, v187
	v_mul_f32_e32 v68, 0x3f317217, v65
	v_fma_f32 v68, v65, s76, -v68
	v_fmac_f32_e32 v68, 0x3377d1cf, v65
	v_fmac_f32_e32 v68, 0x3f317217, v65
	v_cmp_lt_f32_e64 vcc, |v65|, s77
	s_nop 1
	v_cndmask_b32_e32 v65, v65, v68, vcc
	v_sub_f32_e32 v65, v65, v67
	v_sub_f32_e32 v64, v64, v65
	v_add_u32_e32 v65, 0x4000, v145
	ds_write2_b32 v65, v66, v64 offset0:128 offset1:144

.LBB0_1222:
	s_or_b64 exec, exec, s[8:9]
	s_waitcnt lgkmcnt(0)
	s_barrier
	v_mov_b32_e32 v214, 0
	v_mov_b32_e32 v215, 0
	ds_read_b128 v[80:83], v194 offset:8192
	ds_read_b128 v[84:87], v194 offset:8448
	ds_read_b128 v[88:91], v194 offset:8704
	ds_read_b128 v[92:95], v194 offset:8960
	ds_read_b32 v134, v140 offset:35136
	ds_read_b32 v135, v190 offset:16384
	ds_read_b32 v132, v140 offset:35072
	ds_read_b128 v[64:67], v194
	ds_read_b128 v[68:71], v194 offset:256
	ds_read_b128 v[72:75], v194 offset:512
	ds_read_b128 v[76:79], v194 offset:768
	ds_read_b128 v[112:115], v194 offset:9216
	ds_read_b128 v[116:119], v194 offset:9472
	ds_read_b128 v[120:123], v194 offset:9728
	ds_read_b128 v[124:127], v194 offset:9984
	ds_read_b32 v156, v140 offset:35140
	ds_read_b32 v157, v190 offset:16448
	ds_read_b32 v154, v140 offset:35076
	ds_read_b128 v[96:99], v194 offset:1024
	ds_read_b128 v[100:103], v194 offset:1280
	ds_read_b128 v[104:107], v194 offset:1536
	ds_read_b128 v[108:111], v194 offset:1792
	s_waitcnt lgkmcnt(15)
	v_mul_f32_e32 v133, v134, v135
	v_pk_mul_f32 v[80:81], v[80:81], v[132:133] op_sel:[0,1] op_sel_hi:[1,1]
	v_pk_mul_f32 v[82:83], v[82:83], v[132:133] op_sel:[0,1] op_sel_hi:[1,1]
	v_pk_mul_f32 v[84:85], v[84:85], v[132:133] op_sel:[0,1] op_sel_hi:[1,1]
	v_pk_mul_f32 v[86:87], v[86:87], v[132:133] op_sel:[0,1] op_sel_hi:[1,1]
	v_pk_mul_f32 v[88:89], v[88:89], v[132:133] op_sel:[0,1] op_sel_hi:[1,1]
	v_pk_mul_f32 v[90:91], v[90:91], v[132:133] op_sel:[0,1] op_sel_hi:[1,1]
	v_pk_mul_f32 v[92:93], v[92:93], v[132:133] op_sel:[0,1] op_sel_hi:[1,1]
	v_pk_mul_f32 v[94:95], v[94:95], v[132:133] op_sel:[0,1] op_sel_hi:[1,1]
	v_pk_fma_f32 v[196:197], v[132:133], v[196:197], v[80:81] op_sel_hi:[0,1,1]
	v_pk_fma_f32 v[198:199], v[132:133], v[198:199], v[82:83] op_sel_hi:[0,1,1]
	v_pk_fma_f32 v[200:201], v[132:133], v[200:201], v[84:85] op_sel_hi:[0,1,1]
	v_pk_fma_f32 v[202:203], v[132:133], v[202:203], v[86:87] op_sel_hi:[0,1,1]
	v_pk_fma_f32 v[204:205], v[132:133], v[204:205], v[88:89] op_sel_hi:[0,1,1]
	v_pk_fma_f32 v[206:207], v[132:133], v[206:207], v[90:91] op_sel_hi:[0,1,1]
	v_pk_fma_f32 v[208:209], v[132:133], v[208:209], v[92:93] op_sel_hi:[0,1,1]
	v_pk_fma_f32 v[210:211], v[132:133], v[210:211], v[94:95] op_sel_hi:[0,1,1]
	s_waitcnt lgkmcnt(14)
	v_pk_fma_f32 v[128:129], v[64:65], v[196:197], v[214:215]
	v_pk_fma_f32 v[130:131], v[66:67], v[198:199], v[214:215]
	s_waitcnt lgkmcnt(13)
	v_pk_fma_f32 v[128:129], v[68:69], v[200:201], v[128:129]
	v_pk_fma_f32 v[130:131], v[70:71], v[202:203], v[130:131]
	s_waitcnt lgkmcnt(12)
	v_pk_fma_f32 v[128:129], v[72:73], v[204:205], v[128:129]
	v_pk_fma_f32 v[130:131], v[74:75], v[206:207], v[130:131]
	s_waitcnt lgkmcnt(11)
	v_pk_fma_f32 v[128:129], v[76:77], v[208:209], v[128:129]
	v_pk_fma_f32 v[130:131], v[78:79], v[210:211], v[130:131]
	v_add_f32_e32 v128, v128, v129
	v_add_f32_e32 v130, v130, v131
	v_add_f32_e32 v212, v128, v130
	ds_read_b128 v[80:83], v194 offset:10240
	ds_read_b128 v[84:87], v194 offset:10496
	ds_read_b128 v[88:91], v194 offset:10752
	ds_read_b128 v[92:95], v194 offset:11008
	ds_read_b32 v134, v140 offset:35144
	ds_read_b32 v135, v190 offset:16512
	ds_read_b32 v132, v140 offset:35080
	ds_read_b128 v[64:67], v194 offset:2048
	ds_read_b128 v[68:71], v194 offset:2304
	ds_read_b128 v[72:75], v194 offset:2560
	ds_read_b128 v[76:79], v194 offset:2816
	s_waitcnt lgkmcnt(15)
	v_mul_f32_e32 v155, v156, v157
	v_pk_mul_f32 v[112:113], v[112:113], v[154:155] op_sel:[0,1] op_sel_hi:[1,1]
	v_add_f32_dpp v212, v212, v212 row_ror:8 row_mask:0xf bank_mask:0xf bound_ctrl:1
	v_pk_mul_f32 v[114:115], v[114:115], v[154:155] op_sel:[0,1] op_sel_hi:[1,1]
	v_pk_mul_f32 v[116:117], v[116:117], v[154:155] op_sel:[0,1] op_sel_hi:[1,1]
	v_add_f32_dpp v212, v212, v212 row_ror:4 row_mask:0xf bank_mask:0xf bound_ctrl:1
	v_pk_mul_f32 v[118:119], v[118:119], v[154:155] op_sel:[0,1] op_sel_hi:[1,1]
	v_pk_mul_f32 v[120:121], v[120:121], v[154:155] op_sel:[0,1] op_sel_hi:[1,1]
	v_add_f32_dpp v212, v212, v212 row_ror:2 row_mask:0xf bank_mask:0xf bound_ctrl:1
	v_pk_mul_f32 v[122:123], v[122:123], v[154:155] op_sel:[0,1] op_sel_hi:[1,1]
	v_pk_mul_f32 v[124:125], v[124:125], v[154:155] op_sel:[0,1] op_sel_hi:[1,1]
	v_add_f32_dpp v212, v212, v212 row_ror:1 row_mask:0xf bank_mask:0xf bound_ctrl:1
	v_pk_mul_f32 v[126:127], v[126:127], v[154:155] op_sel:[0,1] op_sel_hi:[1,1]
	v_pk_fma_f32 v[196:197], v[154:155], v[196:197], v[112:113] op_sel_hi:[0,1,1]
	s_and_saveexec_b64 s[8:9], s[44:45]
	ds_write_b32 v190, v212 offset:34048
	s_mov_b64 exec, s[8:9]
	v_pk_fma_f32 v[198:199], v[154:155], v[198:199], v[114:115] op_sel_hi:[0,1,1]
	v_pk_fma_f32 v[200:201], v[154:155], v[200:201], v[116:117] op_sel_hi:[0,1,1]
	v_pk_fma_f32 v[202:203], v[154:155], v[202:203], v[118:119] op_sel_hi:[0,1,1]
	v_pk_fma_f32 v[204:205], v[154:155], v[204:205], v[120:121] op_sel_hi:[0,1,1]
	v_pk_fma_f32 v[206:207], v[154:155], v[206:207], v[122:123] op_sel_hi:[0,1,1]
	v_pk_fma_f32 v[208:209], v[154:155], v[208:209], v[124:125] op_sel_hi:[0,1,1]
	v_pk_fma_f32 v[210:211], v[154:155], v[210:211], v[126:127] op_sel_hi:[0,1,1]
	s_waitcnt lgkmcnt(15)
	v_pk_fma_f32 v[128:129], v[96:97], v[196:197], v[214:215]
	v_pk_fma_f32 v[130:131], v[98:99], v[198:199], v[214:215]
	s_waitcnt lgkmcnt(14)
	v_pk_fma_f32 v[128:129], v[100:101], v[200:201], v[128:129]
	v_pk_fma_f32 v[130:131], v[102:103], v[202:203], v[130:131]
	s_waitcnt lgkmcnt(13)
	v_pk_fma_f32 v[128:129], v[104:105], v[204:205], v[128:129]
	v_pk_fma_f32 v[130:131], v[106:107], v[206:207], v[130:131]
	s_waitcnt lgkmcnt(12)
	v_pk_fma_f32 v[128:129], v[108:109], v[208:209], v[128:129]
	v_pk_fma_f32 v[130:131], v[110:111], v[210:211], v[130:131]
	v_add_f32_e32 v128, v128, v129
	v_add_f32_e32 v130, v130, v131
	v_add_f32_e32 v213, v128, v130
	ds_read_b128 v[112:115], v194 offset:11264
	ds_read_b128 v[116:119], v194 offset:11520
	ds_read_b128 v[120:123], v194 offset:11776
	ds_read_b128 v[124:127], v194 offset:12032
	ds_read_b32 v156, v140 offset:35148
	ds_read_b32 v157, v190 offset:16576
	ds_read_b32 v154, v140 offset:35084
	ds_read_b128 v[96:99], v194 offset:3072
	ds_read_b128 v[100:103], v194 offset:3328
	ds_read_b128 v[104:107], v194 offset:3584
	ds_read_b128 v[108:111], v194 offset:3840
	s_waitcnt lgkmcnt(15)
	v_mul_f32_e32 v133, v134, v135
	v_pk_mul_f32 v[80:81], v[80:81], v[132:133] op_sel:[0,1] op_sel_hi:[1,1]
	v_add_f32_dpp v213, v213, v213 row_ror:8 row_mask:0xf bank_mask:0xf bound_ctrl:1
	v_pk_mul_f32 v[82:83], v[82:83], v[132:133] op_sel:[0,1] op_sel_hi:[1,1]
	v_pk_mul_f32 v[84:85], v[84:85], v[132:133] op_sel:[0,1] op_sel_hi:[1,1]
	v_add_f32_dpp v213, v213, v213 row_ror:4 row_mask:0xf bank_mask:0xf bound_ctrl:1
	v_pk_mul_f32 v[86:87], v[86:87], v[132:133] op_sel:[0,1] op_sel_hi:[1,1]
	v_pk_mul_f32 v[88:89], v[88:89], v[132:133] op_sel:[0,1] op_sel_hi:[1,1]
	v_add_f32_dpp v213, v213, v213 row_ror:2 row_mask:0xf bank_mask:0xf bound_ctrl:1
	v_pk_mul_f32 v[90:91], v[90:91], v[132:133] op_sel:[0,1] op_sel_hi:[1,1]
	v_pk_mul_f32 v[92:93], v[92:93], v[132:133] op_sel:[0,1] op_sel_hi:[1,1]
	v_add_f32_dpp v213, v213, v213 row_ror:1 row_mask:0xf bank_mask:0xf bound_ctrl:1
	v_pk_mul_f32 v[94:95], v[94:95], v[132:133] op_sel:[0,1] op_sel_hi:[1,1]
	v_pk_fma_f32 v[196:197], v[132:133], v[196:197], v[80:81] op_sel_hi:[0,1,1]
	s_and_saveexec_b64 s[8:9], s[44:45]
	ds_write_b32 v190, v213 offset:34112
	s_mov_b64 exec, s[8:9]
	v_pk_fma_f32 v[198:199], v[132:133], v[198:199], v[82:83] op_sel_hi:[0,1,1]
	v_pk_fma_f32 v[200:201], v[132:133], v[200:201], v[84:85] op_sel_hi:[0,1,1]
	v_pk_fma_f32 v[202:203], v[132:133], v[202:203], v[86:87] op_sel_hi:[0,1,1]
	v_pk_fma_f32 v[204:205], v[132:133], v[204:205], v[88:89] op_sel_hi:[0,1,1]
	v_pk_fma_f32 v[206:207], v[132:133], v[206:207], v[90:91] op_sel_hi:[0,1,1]
	v_pk_fma_f32 v[208:209], v[132:133], v[208:209], v[92:93] op_sel_hi:[0,1,1]
	v_pk_fma_f32 v[210:211], v[132:133], v[210:211], v[94:95] op_sel_hi:[0,1,1]
	s_waitcnt lgkmcnt(15)
	v_pk_fma_f32 v[128:129], v[64:65], v[196:197], v[214:215]
	v_pk_fma_f32 v[130:131], v[66:67], v[198:199], v[214:215]
	v_pk_fma_f32 v[128:129], v[68:69], v[200:201], v[128:129]
	v_pk_fma_f32 v[130:131], v[70:71], v[202:203], v[130:131]
	s_waitcnt lgkmcnt(14)
	v_pk_fma_f32 v[128:129], v[72:73], v[204:205], v[128:129]
	v_pk_fma_f32 v[130:131], v[74:75], v[206:207], v[130:131]
	s_waitcnt lgkmcnt(13)
	v_pk_fma_f32 v[128:129], v[76:77], v[208:209], v[128:129]
	v_pk_fma_f32 v[130:131], v[78:79], v[210:211], v[130:131]
	v_add_f32_e32 v128, v128, v129
	v_add_f32_e32 v130, v130, v131
	v_add_f32_e32 v212, v128, v130
	ds_read_b128 v[80:83], v194 offset:12288
	ds_read_b128 v[84:87], v194 offset:12544
	ds_read_b128 v[88:91], v194 offset:12800
	ds_read_b128 v[92:95], v194 offset:13056
	ds_read_b32 v134, v140 offset:35152
	ds_read_b32 v135, v190 offset:16640
	ds_read_b32 v132, v140 offset:35088
	ds_read_b128 v[64:67], v194 offset:4096
	ds_read_b128 v[68:71], v194 offset:4352
	ds_read_b128 v[72:75], v194 offset:4608
	ds_read_b128 v[76:79], v194 offset:4864
	s_waitcnt lgkmcnt(15)
	v_mul_f32_e32 v155, v156, v157
	v_pk_mul_f32 v[112:113], v[112:113], v[154:155] op_sel:[0,1] op_sel_hi:[1,1]
	v_add_f32_dpp v212, v212, v212 row_ror:8 row_mask:0xf bank_mask:0xf bound_ctrl:1
	v_pk_mul_f32 v[114:115], v[114:115], v[154:155] op_sel:[0,1] op_sel_hi:[1,1]
	v_pk_mul_f32 v[116:117], v[116:117], v[154:155] op_sel:[0,1] op_sel_hi:[1,1]
	v_add_f32_dpp v212, v212, v212 row_ror:4 row_mask:0xf bank_mask:0xf bound_ctrl:1
	v_pk_mul_f32 v[118:119], v[118:119], v[154:155] op_sel:[0,1] op_sel_hi:[1,1]
	v_pk_mul_f32 v[120:121], v[120:121], v[154:155] op_sel:[0,1] op_sel_hi:[1,1]
	v_add_f32_dpp v212, v212, v212 row_ror:2 row_mask:0xf bank_mask:0xf bound_ctrl:1
	v_pk_mul_f32 v[122:123], v[122:123], v[154:155] op_sel:[0,1] op_sel_hi:[1,1]
	v_pk_mul_f32 v[124:125], v[124:125], v[154:155] op_sel:[0,1] op_sel_hi:[1,1]
	v_add_f32_dpp v212, v212, v212 row_ror:1 row_mask:0xf bank_mask:0xf bound_ctrl:1
	v_pk_mul_f32 v[126:127], v[126:127], v[154:155] op_sel:[0,1] op_sel_hi:[1,1]
	v_pk_fma_f32 v[196:197], v[154:155], v[196:197], v[112:113] op_sel_hi:[0,1,1]
	s_and_saveexec_b64 s[8:9], s[44:45]
	ds_write_b32 v190, v212 offset:34176
	s_mov_b64 exec, s[8:9]
	v_pk_fma_f32 v[198:199], v[154:155], v[198:199], v[114:115] op_sel_hi:[0,1,1]
	v_pk_fma_f32 v[200:201], v[154:155], v[200:201], v[116:117] op_sel_hi:[0,1,1]
	v_pk_fma_f32 v[202:203], v[154:155], v[202:203], v[118:119] op_sel_hi:[0,1,1]
	v_pk_fma_f32 v[204:205], v[154:155], v[204:205], v[120:121] op_sel_hi:[0,1,1]
	v_pk_fma_f32 v[206:207], v[154:155], v[206:207], v[122:123] op_sel_hi:[0,1,1]
	v_pk_fma_f32 v[208:209], v[154:155], v[208:209], v[124:125] op_sel_hi:[0,1,1]
	v_pk_fma_f32 v[210:211], v[154:155], v[210:211], v[126:127] op_sel_hi:[0,1,1]
	s_waitcnt lgkmcnt(15)
	v_pk_fma_f32 v[128:129], v[96:97], v[196:197], v[214:215]
	v_pk_fma_f32 v[130:131], v[98:99], v[198:199], v[214:215]
	v_pk_fma_f32 v[128:129], v[100:101], v[200:201], v[128:129]
	v_pk_fma_f32 v[130:131], v[102:103], v[202:203], v[130:131]
	s_waitcnt lgkmcnt(14)
	v_pk_fma_f32 v[128:129], v[104:105], v[204:205], v[128:129]
	v_pk_fma_f32 v[130:131], v[106:107], v[206:207], v[130:131]
	s_waitcnt lgkmcnt(13)
	v_pk_fma_f32 v[128:129], v[108:109], v[208:209], v[128:129]
	v_pk_fma_f32 v[130:131], v[110:111], v[210:211], v[130:131]
	v_add_f32_e32 v128, v128, v129
	v_add_f32_e32 v130, v130, v131
	v_add_f32_e32 v213, v128, v130
	ds_read_b128 v[112:115], v194 offset:13312
	ds_read_b128 v[116:119], v194 offset:13568
	ds_read_b128 v[120:123], v194 offset:13824
	ds_read_b128 v[124:127], v194 offset:14080
	ds_read_b32 v156, v140 offset:35156
	ds_read_b32 v157, v190 offset:16704
	ds_read_b32 v154, v140 offset:35092
	ds_read_b128 v[96:99], v194 offset:5120
	ds_read_b128 v[100:103], v194 offset:5376
	ds_read_b128 v[104:107], v194 offset:5632
	ds_read_b128 v[108:111], v194 offset:5888
	s_waitcnt lgkmcnt(15)
	v_mul_f32_e32 v133, v134, v135
	v_pk_mul_f32 v[80:81], v[80:81], v[132:133] op_sel:[0,1] op_sel_hi:[1,1]
	v_add_f32_dpp v213, v213, v213 row_ror:8 row_mask:0xf bank_mask:0xf bound_ctrl:1
	v_pk_mul_f32 v[82:83], v[82:83], v[132:133] op_sel:[0,1] op_sel_hi:[1,1]
	v_pk_mul_f32 v[84:85], v[84:85], v[132:133] op_sel:[0,1] op_sel_hi:[1,1]
	v_add_f32_dpp v213, v213, v213 row_ror:4 row_mask:0xf bank_mask:0xf bound_ctrl:1
	v_pk_mul_f32 v[86:87], v[86:87], v[132:133] op_sel:[0,1] op_sel_hi:[1,1]
	v_pk_mul_f32 v[88:89], v[88:89], v[132:133] op_sel:[0,1] op_sel_hi:[1,1]
	v_add_f32_dpp v213, v213, v213 row_ror:2 row_mask:0xf bank_mask:0xf bound_ctrl:1
	v_pk_mul_f32 v[90:91], v[90:91], v[132:133] op_sel:[0,1] op_sel_hi:[1,1]
	v_pk_mul_f32 v[92:93], v[92:93], v[132:133] op_sel:[0,1] op_sel_hi:[1,1]
	v_add_f32_dpp v213, v213, v213 row_ror:1 row_mask:0xf bank_mask:0xf bound_ctrl:1
	v_pk_mul_f32 v[94:95], v[94:95], v[132:133] op_sel:[0,1] op_sel_hi:[1,1]
	v_pk_fma_f32 v[196:197], v[132:133], v[196:197], v[80:81] op_sel_hi:[0,1,1]
	s_and_saveexec_b64 s[8:9], s[44:45]
	ds_write_b32 v190, v213 offset:34240
	s_mov_b64 exec, s[8:9]
	v_pk_fma_f32 v[198:199], v[132:133], v[198:199], v[82:83] op_sel_hi:[0,1,1]
	v_pk_fma_f32 v[200:201], v[132:133], v[200:201], v[84:85] op_sel_hi:[0,1,1]
	v_pk_fma_f32 v[202:203], v[132:133], v[202:203], v[86:87] op_sel_hi:[0,1,1]
	v_pk_fma_f32 v[204:205], v[132:133], v[204:205], v[88:89] op_sel_hi:[0,1,1]
	v_pk_fma_f32 v[206:207], v[132:133], v[206:207], v[90:91] op_sel_hi:[0,1,1]
	v_pk_fma_f32 v[208:209], v[132:133], v[208:209], v[92:93] op_sel_hi:[0,1,1]
	v_pk_fma_f32 v[210:211], v[132:133], v[210:211], v[94:95] op_sel_hi:[0,1,1]
	s_waitcnt lgkmcnt(15)
	v_pk_fma_f32 v[128:129], v[64:65], v[196:197], v[214:215]
	v_pk_fma_f32 v[130:131], v[66:67], v[198:199], v[214:215]
	v_pk_fma_f32 v[128:129], v[68:69], v[200:201], v[128:129]
	v_pk_fma_f32 v[130:131], v[70:71], v[202:203], v[130:131]
	s_waitcnt lgkmcnt(14)
	v_pk_fma_f32 v[128:129], v[72:73], v[204:205], v[128:129]
	v_pk_fma_f32 v[130:131], v[74:75], v[206:207], v[130:131]
	s_waitcnt lgkmcnt(13)
	v_pk_fma_f32 v[128:129], v[76:77], v[208:209], v[128:129]
	v_pk_fma_f32 v[130:131], v[78:79], v[210:211], v[130:131]
	v_add_f32_e32 v128, v128, v129
	v_add_f32_e32 v130, v130, v131
	v_add_f32_e32 v212, v128, v130
	ds_read_b128 v[80:83], v194 offset:14336
	ds_read_b128 v[84:87], v194 offset:14592
	ds_read_b128 v[88:91], v194 offset:14848
	ds_read_b128 v[92:95], v194 offset:15104
	ds_read_b32 v134, v140 offset:35160
	ds_read_b32 v135, v190 offset:16768
	ds_read_b32 v132, v140 offset:35096
	ds_read_b128 v[64:67], v194 offset:6144
	ds_read_b128 v[68:71], v194 offset:6400
	ds_read_b128 v[72:75], v194 offset:6656
	ds_read_b128 v[76:79], v194 offset:6912
	s_waitcnt lgkmcnt(15)
	v_mul_f32_e32 v155, v156, v157
	v_pk_mul_f32 v[112:113], v[112:113], v[154:155] op_sel:[0,1] op_sel_hi:[1,1]
	v_add_f32_dpp v212, v212, v212 row_ror:8 row_mask:0xf bank_mask:0xf bound_ctrl:1
	v_pk_mul_f32 v[114:115], v[114:115], v[154:155] op_sel:[0,1] op_sel_hi:[1,1]
	v_pk_mul_f32 v[116:117], v[116:117], v[154:155] op_sel:[0,1] op_sel_hi:[1,1]
	v_add_f32_dpp v212, v212, v212 row_ror:4 row_mask:0xf bank_mask:0xf bound_ctrl:1
	v_pk_mul_f32 v[118:119], v[118:119], v[154:155] op_sel:[0,1] op_sel_hi:[1,1]
	v_pk_mul_f32 v[120:121], v[120:121], v[154:155] op_sel:[0,1] op_sel_hi:[1,1]
	v_add_f32_dpp v212, v212, v212 row_ror:2 row_mask:0xf bank_mask:0xf bound_ctrl:1
	v_pk_mul_f32 v[122:123], v[122:123], v[154:155] op_sel:[0,1] op_sel_hi:[1,1]
	v_pk_mul_f32 v[124:125], v[124:125], v[154:155] op_sel:[0,1] op_sel_hi:[1,1]
	v_add_f32_dpp v212, v212, v212 row_ror:1 row_mask:0xf bank_mask:0xf bound_ctrl:1
	v_pk_mul_f32 v[126:127], v[126:127], v[154:155] op_sel:[0,1] op_sel_hi:[1,1]
	v_pk_fma_f32 v[196:197], v[154:155], v[196:197], v[112:113] op_sel_hi:[0,1,1]
	s_and_saveexec_b64 s[8:9], s[44:45]
	ds_write_b32 v190, v212 offset:34304
	s_mov_b64 exec, s[8:9]
	v_pk_fma_f32 v[198:199], v[154:155], v[198:199], v[114:115] op_sel_hi:[0,1,1]
	v_pk_fma_f32 v[200:201], v[154:155], v[200:201], v[116:117] op_sel_hi:[0,1,1]
	v_pk_fma_f32 v[202:203], v[154:155], v[202:203], v[118:119] op_sel_hi:[0,1,1]
	v_pk_fma_f32 v[204:205], v[154:155], v[204:205], v[120:121] op_sel_hi:[0,1,1]
	v_pk_fma_f32 v[206:207], v[154:155], v[206:207], v[122:123] op_sel_hi:[0,1,1]
	v_pk_fma_f32 v[208:209], v[154:155], v[208:209], v[124:125] op_sel_hi:[0,1,1]
	v_pk_fma_f32 v[210:211], v[154:155], v[210:211], v[126:127] op_sel_hi:[0,1,1]
	s_waitcnt lgkmcnt(15)
	v_pk_fma_f32 v[128:129], v[96:97], v[196:197], v[214:215]
	v_pk_fma_f32 v[130:131], v[98:99], v[198:199], v[214:215]
	v_pk_fma_f32 v[128:129], v[100:101], v[200:201], v[128:129]
	v_pk_fma_f32 v[130:131], v[102:103], v[202:203], v[130:131]
	s_waitcnt lgkmcnt(14)
	v_pk_fma_f32 v[128:129], v[104:105], v[204:205], v[128:129]
	v_pk_fma_f32 v[130:131], v[106:107], v[206:207], v[130:131]
	s_waitcnt lgkmcnt(13)
	v_pk_fma_f32 v[128:129], v[108:109], v[208:209], v[128:129]
	v_pk_fma_f32 v[130:131], v[110:111], v[210:211], v[130:131]
	v_add_f32_e32 v128, v128, v129
	v_add_f32_e32 v130, v130, v131
	v_add_f32_e32 v213, v128, v130
	ds_read_b128 v[112:115], v194 offset:15360
	ds_read_b128 v[116:119], v194 offset:15616
	ds_read_b128 v[120:123], v194 offset:15872
	ds_read_b128 v[124:127], v194 offset:16128
	ds_read_b32 v156, v140 offset:35164
	ds_read_b32 v157, v190 offset:16832
	ds_read_b32 v154, v140 offset:35100
	ds_read_b128 v[96:99], v194 offset:7168
	ds_read_b128 v[100:103], v194 offset:7424
	ds_read_b128 v[104:107], v194 offset:7680
	ds_read_b128 v[108:111], v194 offset:7936
	s_waitcnt lgkmcnt(15)
	v_mul_f32_e32 v133, v134, v135
	v_pk_mul_f32 v[80:81], v[80:81], v[132:133] op_sel:[0,1] op_sel_hi:[1,1]
	v_add_f32_dpp v213, v213, v213 row_ror:8 row_mask:0xf bank_mask:0xf bound_ctrl:1
	v_pk_mul_f32 v[82:83], v[82:83], v[132:133] op_sel:[0,1] op_sel_hi:[1,1]
	v_pk_mul_f32 v[84:85], v[84:85], v[132:133] op_sel:[0,1] op_sel_hi:[1,1]
	v_add_f32_dpp v213, v213, v213 row_ror:4 row_mask:0xf bank_mask:0xf bound_ctrl:1
	v_pk_mul_f32 v[86:87], v[86:87], v[132:133] op_sel:[0,1] op_sel_hi:[1,1]
	v_pk_mul_f32 v[88:89], v[88:89], v[132:133] op_sel:[0,1] op_sel_hi:[1,1]
	v_add_f32_dpp v213, v213, v213 row_ror:2 row_mask:0xf bank_mask:0xf bound_ctrl:1
	v_pk_mul_f32 v[90:91], v[90:91], v[132:133] op_sel:[0,1] op_sel_hi:[1,1]
	v_pk_mul_f32 v[92:93], v[92:93], v[132:133] op_sel:[0,1] op_sel_hi:[1,1]
	v_add_f32_dpp v213, v213, v213 row_ror:1 row_mask:0xf bank_mask:0xf bound_ctrl:1
	v_pk_mul_f32 v[94:95], v[94:95], v[132:133] op_sel:[0,1] op_sel_hi:[1,1]
	v_pk_fma_f32 v[196:197], v[132:133], v[196:197], v[80:81] op_sel_hi:[0,1,1]
	s_and_saveexec_b64 s[8:9], s[44:45]
	ds_write_b32 v190, v213 offset:34368
	s_mov_b64 exec, s[8:9]
	v_pk_fma_f32 v[198:199], v[132:133], v[198:199], v[82:83] op_sel_hi:[0,1,1]
	v_pk_fma_f32 v[200:201], v[132:133], v[200:201], v[84:85] op_sel_hi:[0,1,1]
	v_pk_fma_f32 v[202:203], v[132:133], v[202:203], v[86:87] op_sel_hi:[0,1,1]
	v_pk_fma_f32 v[204:205], v[132:133], v[204:205], v[88:89] op_sel_hi:[0,1,1]
	v_pk_fma_f32 v[206:207], v[132:133], v[206:207], v[90:91] op_sel_hi:[0,1,1]
	v_pk_fma_f32 v[208:209], v[132:133], v[208:209], v[92:93] op_sel_hi:[0,1,1]
	v_pk_fma_f32 v[210:211], v[132:133], v[210:211], v[94:95] op_sel_hi:[0,1,1]
	s_waitcnt lgkmcnt(15)
	v_pk_fma_f32 v[128:129], v[64:65], v[196:197], v[214:215]
	v_pk_fma_f32 v[130:131], v[66:67], v[198:199], v[214:215]
	v_pk_fma_f32 v[128:129], v[68:69], v[200:201], v[128:129]
	v_pk_fma_f32 v[130:131], v[70:71], v[202:203], v[130:131]
	s_waitcnt lgkmcnt(14)
	v_pk_fma_f32 v[128:129], v[72:73], v[204:205], v[128:129]
	v_pk_fma_f32 v[130:131], v[74:75], v[206:207], v[130:131]
	s_waitcnt lgkmcnt(13)
	v_pk_fma_f32 v[128:129], v[76:77], v[208:209], v[128:129]
	v_pk_fma_f32 v[130:131], v[78:79], v[210:211], v[130:131]
	v_add_f32_e32 v128, v128, v129
	v_add_f32_e32 v130, v130, v131
	v_add_f32_e32 v212, v128, v130
	s_waitcnt lgkmcnt(6)
	v_mul_f32_e32 v155, v156, v157
	v_pk_mul_f32 v[112:113], v[112:113], v[154:155] op_sel:[0,1] op_sel_hi:[1,1]
	v_add_f32_dpp v212, v212, v212 row_ror:8 row_mask:0xf bank_mask:0xf bound_ctrl:1
	v_pk_mul_f32 v[114:115], v[114:115], v[154:155] op_sel:[0,1] op_sel_hi:[1,1]
	v_pk_mul_f32 v[116:117], v[116:117], v[154:155] op_sel:[0,1] op_sel_hi:[1,1]
	v_add_f32_dpp v212, v212, v212 row_ror:4 row_mask:0xf bank_mask:0xf bound_ctrl:1
	v_pk_mul_f32 v[118:119], v[118:119], v[154:155] op_sel:[0,1] op_sel_hi:[1,1]
	v_pk_mul_f32 v[120:121], v[120:121], v[154:155] op_sel:[0,1] op_sel_hi:[1,1]
	v_add_f32_dpp v212, v212, v212 row_ror:2 row_mask:0xf bank_mask:0xf bound_ctrl:1
	v_pk_mul_f32 v[122:123], v[122:123], v[154:155] op_sel:[0,1] op_sel_hi:[1,1]
	v_pk_mul_f32 v[124:125], v[124:125], v[154:155] op_sel:[0,1] op_sel_hi:[1,1]
	v_add_f32_dpp v212, v212, v212 row_ror:1 row_mask:0xf bank_mask:0xf bound_ctrl:1
	v_pk_mul_f32 v[126:127], v[126:127], v[154:155] op_sel:[0,1] op_sel_hi:[1,1]
	s_waitcnt lgkmcnt(5)
	v_pk_fma_f32 v[196:197], v[154:155], v[196:197], v[112:113] op_sel_hi:[0,1,1]
	s_and_saveexec_b64 s[8:9], s[44:45]
	ds_write_b32 v190, v212 offset:34432
	s_mov_b64 exec, s[8:9]
	v_pk_fma_f32 v[198:199], v[154:155], v[198:199], v[114:115] op_sel_hi:[0,1,1]
	v_pk_fma_f32 v[200:201], v[154:155], v[200:201], v[116:117] op_sel_hi:[0,1,1]
	v_pk_fma_f32 v[202:203], v[154:155], v[202:203], v[118:119] op_sel_hi:[0,1,1]
	v_pk_fma_f32 v[204:205], v[154:155], v[204:205], v[120:121] op_sel_hi:[0,1,1]
	v_pk_fma_f32 v[206:207], v[154:155], v[206:207], v[122:123] op_sel_hi:[0,1,1]
	v_pk_fma_f32 v[208:209], v[154:155], v[208:209], v[124:125] op_sel_hi:[0,1,1]
	v_pk_fma_f32 v[210:211], v[154:155], v[210:211], v[126:127] op_sel_hi:[0,1,1]
	s_waitcnt lgkmcnt(5)
	v_pk_fma_f32 v[128:129], v[96:97], v[196:197], v[214:215]
	v_pk_fma_f32 v[130:131], v[98:99], v[198:199], v[214:215]
	s_waitcnt lgkmcnt(4)
	v_pk_fma_f32 v[128:129], v[100:101], v[200:201], v[128:129]
	v_pk_fma_f32 v[130:131], v[102:103], v[202:203], v[130:131]
	s_waitcnt lgkmcnt(3)
	v_pk_fma_f32 v[128:129], v[104:105], v[204:205], v[128:129]
	v_pk_fma_f32 v[130:131], v[106:107], v[206:207], v[130:131]
	s_waitcnt lgkmcnt(2)
	v_pk_fma_f32 v[128:129], v[108:109], v[208:209], v[128:129]
	v_pk_fma_f32 v[130:131], v[110:111], v[210:211], v[130:131]
	v_add_f32_e32 v128, v128, v129
	v_add_f32_e32 v130, v130, v131
	v_add_f32_e32 v213, v128, v130
	s_nop 1
	v_add_f32_dpp v213, v213, v213 row_ror:8 row_mask:0xf bank_mask:0xf bound_ctrl:1
	s_nop 1
	v_add_f32_dpp v213, v213, v213 row_ror:4 row_mask:0xf bank_mask:0xf bound_ctrl:1
	s_nop 1
	v_add_f32_dpp v213, v213, v213 row_ror:2 row_mask:0xf bank_mask:0xf bound_ctrl:1
	s_nop 1
	v_add_f32_dpp v213, v213, v213 row_ror:1 row_mask:0xf bank_mask:0xf bound_ctrl:1
	s_and_saveexec_b64 s[8:9], s[44:45]
	ds_write_b32 v190, v213 offset:34496
	s_mov_b64 exec, s[8:9]
	s_waitcnt vmcnt(3)
	ds_write_b128 v188, v[48:51] offset:17024
	s_waitcnt vmcnt(1)
	ds_write_b128 v191, v[56:59] offset:17024
	ds_write_b128 v188, v[52:55] offset:25216
	s_waitcnt vmcnt(0)
	ds_write_b128 v191, v[60:63] offset:25216
	s_and_saveexec_b64 s[8:9], s[40:41]
	ds_write_b32 v145, v192 offset:33408
	s_or_b64 exec, exec, s[8:9]
	s_and_saveexec_b64 s[8:9], s[42:43]
	s_cbranch_execz .LBB0_1242
	v_add_f32_e32 v64, v178, v195
	v_mul_f32_e64 v65, |v64|, s62
	v_exp_f32_e32 v65, v65
	v_min_f32_e32 v64, 0, v64
	v_add_f32_e32 v65, 1.0, v65
	v_cmp_gt_f32_e32 vcc, s5, v65
	s_nop 1
	v_cndmask_b32_e64 v66, 0, 32, vcc
	v_ldexp_f32 v65, v65, v66
	v_log_f32_e32 v65, v65
	v_cndmask_b32_e32 v67, 0, v171, vcc
	v_add_f32_e32 v66, v147, v193
	v_mul_f32_e32 v68, 0x3f317217, v65
	v_fma_f32 v68, v65, s76, -v68
	v_fmac_f32_e32 v68, 0x3377d1cf, v65
	v_fmac_f32_e32 v68, 0x3f317217, v65
	v_cmp_lt_f32_e64 vcc, |v65|, s77
	s_nop 1
	v_cndmask_b32_e32 v65, v65, v68, vcc
	v_sub_f32_e32 v65, v65, v67
	v_sub_f32_e32 v64, v64, v65
	v_add_u32_e32 v65, 0x8400, v145
	ds_write2_b32 v65, v66, v64 offset0:32 offset1:48

.LBB0_1255:
	s_or_b64 exec, exec, s[8:9]
	s_waitcnt lgkmcnt(0)
	s_barrier
	v_mov_b32_e32 v214, 0
	v_mov_b32_e32 v215, 0
	ds_read_b128 v[80:83], v194 offset:25216
	ds_read_b128 v[84:87], v194 offset:25472
	ds_read_b128 v[88:91], v194 offset:25728
	ds_read_b128 v[92:95], v194 offset:25984
	ds_read_b32 v134, v140 offset:35136
	ds_read_b32 v135, v190 offset:33408
	ds_read_b32 v132, v140 offset:35072
	ds_read_b128 v[64:67], v194 offset:17024
	ds_read_b128 v[68:71], v194 offset:17280
	ds_read_b128 v[72:75], v194 offset:17536
	ds_read_b128 v[76:79], v194 offset:17792
	ds_read_b128 v[112:115], v194 offset:26240
	ds_read_b128 v[116:119], v194 offset:26496
	ds_read_b128 v[120:123], v194 offset:26752
	ds_read_b128 v[124:127], v194 offset:27008
	ds_read_b32 v156, v140 offset:35140
	ds_read_b32 v157, v190 offset:33472
	ds_read_b32 v154, v140 offset:35076
	ds_read_b128 v[96:99], v194 offset:18048
	ds_read_b128 v[100:103], v194 offset:18304
	ds_read_b128 v[104:107], v194 offset:18560
	ds_read_b128 v[108:111], v194 offset:18816
	s_waitcnt lgkmcnt(15)
	v_mul_f32_e32 v133, v134, v135
	v_pk_mul_f32 v[80:81], v[80:81], v[132:133] op_sel:[0,1] op_sel_hi:[1,1]
	v_pk_mul_f32 v[82:83], v[82:83], v[132:133] op_sel:[0,1] op_sel_hi:[1,1]
	v_pk_mul_f32 v[84:85], v[84:85], v[132:133] op_sel:[0,1] op_sel_hi:[1,1]
	v_pk_mul_f32 v[86:87], v[86:87], v[132:133] op_sel:[0,1] op_sel_hi:[1,1]
	v_pk_mul_f32 v[88:89], v[88:89], v[132:133] op_sel:[0,1] op_sel_hi:[1,1]
	v_pk_mul_f32 v[90:91], v[90:91], v[132:133] op_sel:[0,1] op_sel_hi:[1,1]
	v_pk_mul_f32 v[92:93], v[92:93], v[132:133] op_sel:[0,1] op_sel_hi:[1,1]
	v_pk_mul_f32 v[94:95], v[94:95], v[132:133] op_sel:[0,1] op_sel_hi:[1,1]
	v_pk_fma_f32 v[196:197], v[132:133], v[196:197], v[80:81] op_sel_hi:[0,1,1]
	v_pk_fma_f32 v[198:199], v[132:133], v[198:199], v[82:83] op_sel_hi:[0,1,1]
	v_pk_fma_f32 v[200:201], v[132:133], v[200:201], v[84:85] op_sel_hi:[0,1,1]
	v_pk_fma_f32 v[202:203], v[132:133], v[202:203], v[86:87] op_sel_hi:[0,1,1]
	v_pk_fma_f32 v[204:205], v[132:133], v[204:205], v[88:89] op_sel_hi:[0,1,1]
	v_pk_fma_f32 v[206:207], v[132:133], v[206:207], v[90:91] op_sel_hi:[0,1,1]
	v_pk_fma_f32 v[208:209], v[132:133], v[208:209], v[92:93] op_sel_hi:[0,1,1]
	v_pk_fma_f32 v[210:211], v[132:133], v[210:211], v[94:95] op_sel_hi:[0,1,1]
	s_waitcnt lgkmcnt(14)
	v_pk_fma_f32 v[128:129], v[64:65], v[196:197], v[214:215]
	v_pk_fma_f32 v[130:131], v[66:67], v[198:199], v[214:215]
	s_waitcnt lgkmcnt(13)
	v_pk_fma_f32 v[128:129], v[68:69], v[200:201], v[128:129]
	v_pk_fma_f32 v[130:131], v[70:71], v[202:203], v[130:131]
	s_waitcnt lgkmcnt(12)
	v_pk_fma_f32 v[128:129], v[72:73], v[204:205], v[128:129]
	v_pk_fma_f32 v[130:131], v[74:75], v[206:207], v[130:131]
	s_waitcnt lgkmcnt(11)
	v_pk_fma_f32 v[128:129], v[76:77], v[208:209], v[128:129]
	v_pk_fma_f32 v[130:131], v[78:79], v[210:211], v[130:131]
	v_add_f32_e32 v128, v128, v129
	v_add_f32_e32 v130, v130, v131
	v_add_f32_e32 v212, v128, v130
	ds_read_b128 v[80:83], v194 offset:27264
	ds_read_b128 v[84:87], v194 offset:27520
	ds_read_b128 v[88:91], v194 offset:27776
	ds_read_b128 v[92:95], v194 offset:28032
	ds_read_b32 v134, v140 offset:35144
	ds_read_b32 v135, v190 offset:33536
	ds_read_b32 v132, v140 offset:35080
	ds_read_b128 v[64:67], v194 offset:19072
	ds_read_b128 v[68:71], v194 offset:19328
	ds_read_b128 v[72:75], v194 offset:19584
	ds_read_b128 v[76:79], v194 offset:19840
	s_waitcnt lgkmcnt(15)
	v_mul_f32_e32 v155, v156, v157
	v_pk_mul_f32 v[112:113], v[112:113], v[154:155] op_sel:[0,1] op_sel_hi:[1,1]
	v_add_f32_dpp v212, v212, v212 row_ror:8 row_mask:0xf bank_mask:0xf bound_ctrl:1
	v_pk_mul_f32 v[114:115], v[114:115], v[154:155] op_sel:[0,1] op_sel_hi:[1,1]
	v_pk_mul_f32 v[116:117], v[116:117], v[154:155] op_sel:[0,1] op_sel_hi:[1,1]
	v_add_f32_dpp v212, v212, v212 row_ror:4 row_mask:0xf bank_mask:0xf bound_ctrl:1
	v_pk_mul_f32 v[118:119], v[118:119], v[154:155] op_sel:[0,1] op_sel_hi:[1,1]
	v_pk_mul_f32 v[120:121], v[120:121], v[154:155] op_sel:[0,1] op_sel_hi:[1,1]
	v_add_f32_dpp v212, v212, v212 row_ror:2 row_mask:0xf bank_mask:0xf bound_ctrl:1
	v_pk_mul_f32 v[122:123], v[122:123], v[154:155] op_sel:[0,1] op_sel_hi:[1,1]
	v_pk_mul_f32 v[124:125], v[124:125], v[154:155] op_sel:[0,1] op_sel_hi:[1,1]
	v_add_f32_dpp v212, v212, v212 row_ror:1 row_mask:0xf bank_mask:0xf bound_ctrl:1
	v_pk_mul_f32 v[126:127], v[126:127], v[154:155] op_sel:[0,1] op_sel_hi:[1,1]
	v_pk_fma_f32 v[196:197], v[154:155], v[196:197], v[112:113] op_sel_hi:[0,1,1]
	s_and_saveexec_b64 s[8:9], s[44:45]
	ds_write_b32 v190, v212 offset:34560
	s_mov_b64 exec, s[8:9]
	v_pk_fma_f32 v[198:199], v[154:155], v[198:199], v[114:115] op_sel_hi:[0,1,1]
	v_pk_fma_f32 v[200:201], v[154:155], v[200:201], v[116:117] op_sel_hi:[0,1,1]
	v_pk_fma_f32 v[202:203], v[154:155], v[202:203], v[118:119] op_sel_hi:[0,1,1]
	v_pk_fma_f32 v[204:205], v[154:155], v[204:205], v[120:121] op_sel_hi:[0,1,1]
	v_pk_fma_f32 v[206:207], v[154:155], v[206:207], v[122:123] op_sel_hi:[0,1,1]
	v_pk_fma_f32 v[208:209], v[154:155], v[208:209], v[124:125] op_sel_hi:[0,1,1]
	v_pk_fma_f32 v[210:211], v[154:155], v[210:211], v[126:127] op_sel_hi:[0,1,1]
	s_waitcnt lgkmcnt(15)
	v_pk_fma_f32 v[128:129], v[96:97], v[196:197], v[214:215]
	v_pk_fma_f32 v[130:131], v[98:99], v[198:199], v[214:215]
	s_waitcnt lgkmcnt(14)
	v_pk_fma_f32 v[128:129], v[100:101], v[200:201], v[128:129]
	v_pk_fma_f32 v[130:131], v[102:103], v[202:203], v[130:131]
	s_waitcnt lgkmcnt(13)
	v_pk_fma_f32 v[128:129], v[104:105], v[204:205], v[128:129]
	v_pk_fma_f32 v[130:131], v[106:107], v[206:207], v[130:131]
	s_waitcnt lgkmcnt(12)
	v_pk_fma_f32 v[128:129], v[108:109], v[208:209], v[128:129]
	v_pk_fma_f32 v[130:131], v[110:111], v[210:211], v[130:131]
	v_add_f32_e32 v128, v128, v129
	v_add_f32_e32 v130, v130, v131
	v_add_f32_e32 v213, v128, v130
	ds_read_b128 v[112:115], v194 offset:28288
	ds_read_b128 v[116:119], v194 offset:28544
	ds_read_b128 v[120:123], v194 offset:28800
	ds_read_b128 v[124:127], v194 offset:29056
	ds_read_b32 v156, v140 offset:35148
	ds_read_b32 v157, v190 offset:33600
	ds_read_b32 v154, v140 offset:35084
	ds_read_b128 v[96:99], v194 offset:20096
	ds_read_b128 v[100:103], v194 offset:20352
	ds_read_b128 v[104:107], v194 offset:20608
	ds_read_b128 v[108:111], v194 offset:20864
	s_waitcnt lgkmcnt(15)
	v_mul_f32_e32 v133, v134, v135
	v_pk_mul_f32 v[80:81], v[80:81], v[132:133] op_sel:[0,1] op_sel_hi:[1,1]
	v_add_f32_dpp v213, v213, v213 row_ror:8 row_mask:0xf bank_mask:0xf bound_ctrl:1
	v_pk_mul_f32 v[82:83], v[82:83], v[132:133] op_sel:[0,1] op_sel_hi:[1,1]
	v_pk_mul_f32 v[84:85], v[84:85], v[132:133] op_sel:[0,1] op_sel_hi:[1,1]
	v_add_f32_dpp v213, v213, v213 row_ror:4 row_mask:0xf bank_mask:0xf bound_ctrl:1
	v_pk_mul_f32 v[86:87], v[86:87], v[132:133] op_sel:[0,1] op_sel_hi:[1,1]
	v_pk_mul_f32 v[88:89], v[88:89], v[132:133] op_sel:[0,1] op_sel_hi:[1,1]
	v_add_f32_dpp v213, v213, v213 row_ror:2 row_mask:0xf bank_mask:0xf bound_ctrl:1
	v_pk_mul_f32 v[90:91], v[90:91], v[132:133] op_sel:[0,1] op_sel_hi:[1,1]
	v_pk_mul_f32 v[92:93], v[92:93], v[132:133] op_sel:[0,1] op_sel_hi:[1,1]
	v_add_f32_dpp v213, v213, v213 row_ror:1 row_mask:0xf bank_mask:0xf bound_ctrl:1
	v_pk_mul_f32 v[94:95], v[94:95], v[132:133] op_sel:[0,1] op_sel_hi:[1,1]
	v_pk_fma_f32 v[196:197], v[132:133], v[196:197], v[80:81] op_sel_hi:[0,1,1]
	s_and_saveexec_b64 s[8:9], s[44:45]
	ds_write_b32 v190, v213 offset:34624
	s_mov_b64 exec, s[8:9]
	v_pk_fma_f32 v[198:199], v[132:133], v[198:199], v[82:83] op_sel_hi:[0,1,1]
	v_pk_fma_f32 v[200:201], v[132:133], v[200:201], v[84:85] op_sel_hi:[0,1,1]
	v_pk_fma_f32 v[202:203], v[132:133], v[202:203], v[86:87] op_sel_hi:[0,1,1]
	v_pk_fma_f32 v[204:205], v[132:133], v[204:205], v[88:89] op_sel_hi:[0,1,1]
	v_pk_fma_f32 v[206:207], v[132:133], v[206:207], v[90:91] op_sel_hi:[0,1,1]
	v_pk_fma_f32 v[208:209], v[132:133], v[208:209], v[92:93] op_sel_hi:[0,1,1]
	v_pk_fma_f32 v[210:211], v[132:133], v[210:211], v[94:95] op_sel_hi:[0,1,1]
	s_waitcnt lgkmcnt(15)
	v_pk_fma_f32 v[128:129], v[64:65], v[196:197], v[214:215]
	v_pk_fma_f32 v[130:131], v[66:67], v[198:199], v[214:215]
	v_pk_fma_f32 v[128:129], v[68:69], v[200:201], v[128:129]
	v_pk_fma_f32 v[130:131], v[70:71], v[202:203], v[130:131]
	s_waitcnt lgkmcnt(14)
	v_pk_fma_f32 v[128:129], v[72:73], v[204:205], v[128:129]
	v_pk_fma_f32 v[130:131], v[74:75], v[206:207], v[130:131]
	s_waitcnt lgkmcnt(13)
	v_pk_fma_f32 v[128:129], v[76:77], v[208:209], v[128:129]
	v_pk_fma_f32 v[130:131], v[78:79], v[210:211], v[130:131]
	v_add_f32_e32 v128, v128, v129
	v_add_f32_e32 v130, v130, v131
	v_add_f32_e32 v212, v128, v130
	ds_read_b128 v[80:83], v194 offset:29312
	ds_read_b128 v[84:87], v194 offset:29568
	ds_read_b128 v[88:91], v194 offset:29824
	ds_read_b128 v[92:95], v194 offset:30080
	ds_read_b32 v134, v140 offset:35152
	ds_read_b32 v135, v190 offset:33664
	ds_read_b32 v132, v140 offset:35088
	ds_read_b128 v[64:67], v194 offset:21120
	ds_read_b128 v[68:71], v194 offset:21376
	ds_read_b128 v[72:75], v194 offset:21632
	ds_read_b128 v[76:79], v194 offset:21888
	s_waitcnt lgkmcnt(15)
	v_mul_f32_e32 v155, v156, v157
	v_pk_mul_f32 v[112:113], v[112:113], v[154:155] op_sel:[0,1] op_sel_hi:[1,1]
	v_add_f32_dpp v212, v212, v212 row_ror:8 row_mask:0xf bank_mask:0xf bound_ctrl:1
	v_pk_mul_f32 v[114:115], v[114:115], v[154:155] op_sel:[0,1] op_sel_hi:[1,1]
	v_pk_mul_f32 v[116:117], v[116:117], v[154:155] op_sel:[0,1] op_sel_hi:[1,1]
	v_add_f32_dpp v212, v212, v212 row_ror:4 row_mask:0xf bank_mask:0xf bound_ctrl:1
	v_pk_mul_f32 v[118:119], v[118:119], v[154:155] op_sel:[0,1] op_sel_hi:[1,1]
	v_pk_mul_f32 v[120:121], v[120:121], v[154:155] op_sel:[0,1] op_sel_hi:[1,1]
	v_add_f32_dpp v212, v212, v212 row_ror:2 row_mask:0xf bank_mask:0xf bound_ctrl:1
	v_pk_mul_f32 v[122:123], v[122:123], v[154:155] op_sel:[0,1] op_sel_hi:[1,1]
	v_pk_mul_f32 v[124:125], v[124:125], v[154:155] op_sel:[0,1] op_sel_hi:[1,1]
	v_add_f32_dpp v212, v212, v212 row_ror:1 row_mask:0xf bank_mask:0xf bound_ctrl:1
	v_pk_mul_f32 v[126:127], v[126:127], v[154:155] op_sel:[0,1] op_sel_hi:[1,1]
	v_pk_fma_f32 v[196:197], v[154:155], v[196:197], v[112:113] op_sel_hi:[0,1,1]
	s_and_saveexec_b64 s[8:9], s[44:45]
	ds_write_b32 v190, v212 offset:34688
	s_mov_b64 exec, s[8:9]
	v_pk_fma_f32 v[198:199], v[154:155], v[198:199], v[114:115] op_sel_hi:[0,1,1]
	v_pk_fma_f32 v[200:201], v[154:155], v[200:201], v[116:117] op_sel_hi:[0,1,1]
	v_pk_fma_f32 v[202:203], v[154:155], v[202:203], v[118:119] op_sel_hi:[0,1,1]
	v_pk_fma_f32 v[204:205], v[154:155], v[204:205], v[120:121] op_sel_hi:[0,1,1]
	v_pk_fma_f32 v[206:207], v[154:155], v[206:207], v[122:123] op_sel_hi:[0,1,1]
	v_pk_fma_f32 v[208:209], v[154:155], v[208:209], v[124:125] op_sel_hi:[0,1,1]
	v_pk_fma_f32 v[210:211], v[154:155], v[210:211], v[126:127] op_sel_hi:[0,1,1]
	s_waitcnt lgkmcnt(15)
	v_pk_fma_f32 v[128:129], v[96:97], v[196:197], v[214:215]
	v_pk_fma_f32 v[130:131], v[98:99], v[198:199], v[214:215]
	v_pk_fma_f32 v[128:129], v[100:101], v[200:201], v[128:129]
	v_pk_fma_f32 v[130:131], v[102:103], v[202:203], v[130:131]
	s_waitcnt lgkmcnt(14)
	v_pk_fma_f32 v[128:129], v[104:105], v[204:205], v[128:129]
	v_pk_fma_f32 v[130:131], v[106:107], v[206:207], v[130:131]
	s_waitcnt lgkmcnt(13)
	v_pk_fma_f32 v[128:129], v[108:109], v[208:209], v[128:129]
	v_pk_fma_f32 v[130:131], v[110:111], v[210:211], v[130:131]
	v_add_f32_e32 v128, v128, v129
	v_add_f32_e32 v130, v130, v131
	v_add_f32_e32 v213, v128, v130
	ds_read_b128 v[112:115], v194 offset:30336
	ds_read_b128 v[116:119], v194 offset:30592
	ds_read_b128 v[120:123], v194 offset:30848
	ds_read_b128 v[124:127], v194 offset:31104
	ds_read_b32 v156, v140 offset:35156
	ds_read_b32 v157, v190 offset:33728
	ds_read_b32 v154, v140 offset:35092
	ds_read_b128 v[96:99], v194 offset:22144
	ds_read_b128 v[100:103], v194 offset:22400
	ds_read_b128 v[104:107], v194 offset:22656
	ds_read_b128 v[108:111], v194 offset:22912
	s_waitcnt lgkmcnt(15)
	v_mul_f32_e32 v133, v134, v135
	v_pk_mul_f32 v[80:81], v[80:81], v[132:133] op_sel:[0,1] op_sel_hi:[1,1]
	v_add_f32_dpp v213, v213, v213 row_ror:8 row_mask:0xf bank_mask:0xf bound_ctrl:1
	v_pk_mul_f32 v[82:83], v[82:83], v[132:133] op_sel:[0,1] op_sel_hi:[1,1]
	v_pk_mul_f32 v[84:85], v[84:85], v[132:133] op_sel:[0,1] op_sel_hi:[1,1]
	v_add_f32_dpp v213, v213, v213 row_ror:4 row_mask:0xf bank_mask:0xf bound_ctrl:1
	v_pk_mul_f32 v[86:87], v[86:87], v[132:133] op_sel:[0,1] op_sel_hi:[1,1]
	v_pk_mul_f32 v[88:89], v[88:89], v[132:133] op_sel:[0,1] op_sel_hi:[1,1]
	v_add_f32_dpp v213, v213, v213 row_ror:2 row_mask:0xf bank_mask:0xf bound_ctrl:1
	v_pk_mul_f32 v[90:91], v[90:91], v[132:133] op_sel:[0,1] op_sel_hi:[1,1]
	v_pk_mul_f32 v[92:93], v[92:93], v[132:133] op_sel:[0,1] op_sel_hi:[1,1]
	v_add_f32_dpp v213, v213, v213 row_ror:1 row_mask:0xf bank_mask:0xf bound_ctrl:1
	v_pk_mul_f32 v[94:95], v[94:95], v[132:133] op_sel:[0,1] op_sel_hi:[1,1]
	v_pk_fma_f32 v[196:197], v[132:133], v[196:197], v[80:81] op_sel_hi:[0,1,1]
	s_and_saveexec_b64 s[8:9], s[44:45]
	ds_write_b32 v190, v213 offset:34752
	s_mov_b64 exec, s[8:9]
	v_pk_fma_f32 v[198:199], v[132:133], v[198:199], v[82:83] op_sel_hi:[0,1,1]
	v_pk_fma_f32 v[200:201], v[132:133], v[200:201], v[84:85] op_sel_hi:[0,1,1]
	v_pk_fma_f32 v[202:203], v[132:133], v[202:203], v[86:87] op_sel_hi:[0,1,1]
	v_pk_fma_f32 v[204:205], v[132:133], v[204:205], v[88:89] op_sel_hi:[0,1,1]
	v_pk_fma_f32 v[206:207], v[132:133], v[206:207], v[90:91] op_sel_hi:[0,1,1]
	v_pk_fma_f32 v[208:209], v[132:133], v[208:209], v[92:93] op_sel_hi:[0,1,1]
	v_pk_fma_f32 v[210:211], v[132:133], v[210:211], v[94:95] op_sel_hi:[0,1,1]
	s_waitcnt lgkmcnt(15)
	v_pk_fma_f32 v[128:129], v[64:65], v[196:197], v[214:215]
	v_pk_fma_f32 v[130:131], v[66:67], v[198:199], v[214:215]
	v_pk_fma_f32 v[128:129], v[68:69], v[200:201], v[128:129]
	v_pk_fma_f32 v[130:131], v[70:71], v[202:203], v[130:131]
	s_waitcnt lgkmcnt(14)
	v_pk_fma_f32 v[128:129], v[72:73], v[204:205], v[128:129]
	v_pk_fma_f32 v[130:131], v[74:75], v[206:207], v[130:131]
	s_waitcnt lgkmcnt(13)
	v_pk_fma_f32 v[128:129], v[76:77], v[208:209], v[128:129]
	v_pk_fma_f32 v[130:131], v[78:79], v[210:211], v[130:131]
	v_add_f32_e32 v128, v128, v129
	v_add_f32_e32 v130, v130, v131
	v_add_f32_e32 v212, v128, v130
	ds_read_b128 v[80:83], v194 offset:31360
	ds_read_b128 v[84:87], v194 offset:31616
	ds_read_b128 v[88:91], v194 offset:31872
	ds_read_b128 v[92:95], v194 offset:32128
	ds_read_b32 v134, v140 offset:35160
	ds_read_b32 v135, v190 offset:33792
	ds_read_b32 v132, v140 offset:35096
	ds_read_b128 v[64:67], v194 offset:23168
	ds_read_b128 v[68:71], v194 offset:23424
	ds_read_b128 v[72:75], v194 offset:23680
	ds_read_b128 v[76:79], v194 offset:23936
	s_waitcnt lgkmcnt(15)
	v_mul_f32_e32 v155, v156, v157
	v_pk_mul_f32 v[112:113], v[112:113], v[154:155] op_sel:[0,1] op_sel_hi:[1,1]
	v_add_f32_dpp v212, v212, v212 row_ror:8 row_mask:0xf bank_mask:0xf bound_ctrl:1
	v_pk_mul_f32 v[114:115], v[114:115], v[154:155] op_sel:[0,1] op_sel_hi:[1,1]
	v_pk_mul_f32 v[116:117], v[116:117], v[154:155] op_sel:[0,1] op_sel_hi:[1,1]
	v_add_f32_dpp v212, v212, v212 row_ror:4 row_mask:0xf bank_mask:0xf bound_ctrl:1
	v_pk_mul_f32 v[118:119], v[118:119], v[154:155] op_sel:[0,1] op_sel_hi:[1,1]
	v_pk_mul_f32 v[120:121], v[120:121], v[154:155] op_sel:[0,1] op_sel_hi:[1,1]
	v_add_f32_dpp v212, v212, v212 row_ror:2 row_mask:0xf bank_mask:0xf bound_ctrl:1
	v_pk_mul_f32 v[122:123], v[122:123], v[154:155] op_sel:[0,1] op_sel_hi:[1,1]
	v_pk_mul_f32 v[124:125], v[124:125], v[154:155] op_sel:[0,1] op_sel_hi:[1,1]
	v_add_f32_dpp v212, v212, v212 row_ror:1 row_mask:0xf bank_mask:0xf bound_ctrl:1
	v_pk_mul_f32 v[126:127], v[126:127], v[154:155] op_sel:[0,1] op_sel_hi:[1,1]
	v_pk_fma_f32 v[196:197], v[154:155], v[196:197], v[112:113] op_sel_hi:[0,1,1]
	s_and_saveexec_b64 s[8:9], s[44:45]
	ds_write_b32 v190, v212 offset:34816
	s_mov_b64 exec, s[8:9]
	v_pk_fma_f32 v[198:199], v[154:155], v[198:199], v[114:115] op_sel_hi:[0,1,1]
	v_pk_fma_f32 v[200:201], v[154:155], v[200:201], v[116:117] op_sel_hi:[0,1,1]
	v_pk_fma_f32 v[202:203], v[154:155], v[202:203], v[118:119] op_sel_hi:[0,1,1]
	v_pk_fma_f32 v[204:205], v[154:155], v[204:205], v[120:121] op_sel_hi:[0,1,1]
	v_pk_fma_f32 v[206:207], v[154:155], v[206:207], v[122:123] op_sel_hi:[0,1,1]
	v_pk_fma_f32 v[208:209], v[154:155], v[208:209], v[124:125] op_sel_hi:[0,1,1]
	v_pk_fma_f32 v[210:211], v[154:155], v[210:211], v[126:127] op_sel_hi:[0,1,1]
	s_waitcnt lgkmcnt(15)
	v_pk_fma_f32 v[128:129], v[96:97], v[196:197], v[214:215]
	v_pk_fma_f32 v[130:131], v[98:99], v[198:199], v[214:215]
	v_pk_fma_f32 v[128:129], v[100:101], v[200:201], v[128:129]
	v_pk_fma_f32 v[130:131], v[102:103], v[202:203], v[130:131]
	s_waitcnt lgkmcnt(14)
	v_pk_fma_f32 v[128:129], v[104:105], v[204:205], v[128:129]
	v_pk_fma_f32 v[130:131], v[106:107], v[206:207], v[130:131]
	s_waitcnt lgkmcnt(13)
	v_pk_fma_f32 v[128:129], v[108:109], v[208:209], v[128:129]
	v_pk_fma_f32 v[130:131], v[110:111], v[210:211], v[130:131]
	v_add_f32_e32 v128, v128, v129
	v_add_f32_e32 v130, v130, v131
	v_add_f32_e32 v213, v128, v130
	ds_read_b128 v[112:115], v194 offset:32384
	ds_read_b128 v[116:119], v194 offset:32640
	ds_read_b128 v[120:123], v194 offset:32896
	ds_read_b128 v[124:127], v194 offset:33152
	ds_read_b32 v156, v140 offset:35164
	ds_read_b32 v157, v190 offset:33856
	ds_read_b32 v154, v140 offset:35100
	ds_read_b128 v[96:99], v194 offset:24192
	ds_read_b128 v[100:103], v194 offset:24448
	ds_read_b128 v[104:107], v194 offset:24704
	ds_read_b128 v[108:111], v194 offset:24960
	s_waitcnt lgkmcnt(15)
	v_mul_f32_e32 v133, v134, v135
	v_pk_mul_f32 v[80:81], v[80:81], v[132:133] op_sel:[0,1] op_sel_hi:[1,1]
	v_add_f32_dpp v213, v213, v213 row_ror:8 row_mask:0xf bank_mask:0xf bound_ctrl:1
	v_pk_mul_f32 v[82:83], v[82:83], v[132:133] op_sel:[0,1] op_sel_hi:[1,1]
	v_pk_mul_f32 v[84:85], v[84:85], v[132:133] op_sel:[0,1] op_sel_hi:[1,1]
	v_add_f32_dpp v213, v213, v213 row_ror:4 row_mask:0xf bank_mask:0xf bound_ctrl:1
	v_pk_mul_f32 v[86:87], v[86:87], v[132:133] op_sel:[0,1] op_sel_hi:[1,1]
	v_pk_mul_f32 v[88:89], v[88:89], v[132:133] op_sel:[0,1] op_sel_hi:[1,1]
	v_add_f32_dpp v213, v213, v213 row_ror:2 row_mask:0xf bank_mask:0xf bound_ctrl:1
	v_pk_mul_f32 v[90:91], v[90:91], v[132:133] op_sel:[0,1] op_sel_hi:[1,1]
	v_pk_mul_f32 v[92:93], v[92:93], v[132:133] op_sel:[0,1] op_sel_hi:[1,1]
	v_add_f32_dpp v213, v213, v213 row_ror:1 row_mask:0xf bank_mask:0xf bound_ctrl:1
	v_pk_mul_f32 v[94:95], v[94:95], v[132:133] op_sel:[0,1] op_sel_hi:[1,1]
	v_pk_fma_f32 v[196:197], v[132:133], v[196:197], v[80:81] op_sel_hi:[0,1,1]
	s_and_saveexec_b64 s[8:9], s[44:45]
	ds_write_b32 v190, v213 offset:34880
	s_mov_b64 exec, s[8:9]
	v_pk_fma_f32 v[198:199], v[132:133], v[198:199], v[82:83] op_sel_hi:[0,1,1]
	v_pk_fma_f32 v[200:201], v[132:133], v[200:201], v[84:85] op_sel_hi:[0,1,1]
	v_pk_fma_f32 v[202:203], v[132:133], v[202:203], v[86:87] op_sel_hi:[0,1,1]
	v_pk_fma_f32 v[204:205], v[132:133], v[204:205], v[88:89] op_sel_hi:[0,1,1]
	v_pk_fma_f32 v[206:207], v[132:133], v[206:207], v[90:91] op_sel_hi:[0,1,1]
	v_pk_fma_f32 v[208:209], v[132:133], v[208:209], v[92:93] op_sel_hi:[0,1,1]
	v_pk_fma_f32 v[210:211], v[132:133], v[210:211], v[94:95] op_sel_hi:[0,1,1]
	s_waitcnt lgkmcnt(15)
	v_pk_fma_f32 v[128:129], v[64:65], v[196:197], v[214:215]
	v_pk_fma_f32 v[130:131], v[66:67], v[198:199], v[214:215]
	v_pk_fma_f32 v[128:129], v[68:69], v[200:201], v[128:129]
	v_pk_fma_f32 v[130:131], v[70:71], v[202:203], v[130:131]
	s_waitcnt lgkmcnt(14)
	v_pk_fma_f32 v[128:129], v[72:73], v[204:205], v[128:129]
	v_pk_fma_f32 v[130:131], v[74:75], v[206:207], v[130:131]
	s_waitcnt lgkmcnt(13)
	v_pk_fma_f32 v[128:129], v[76:77], v[208:209], v[128:129]
	v_pk_fma_f32 v[130:131], v[78:79], v[210:211], v[130:131]
	v_add_f32_e32 v128, v128, v129
	v_add_f32_e32 v130, v130, v131
	v_add_f32_e32 v212, v128, v130
	s_waitcnt lgkmcnt(6)
	v_mul_f32_e32 v155, v156, v157
	v_pk_mul_f32 v[112:113], v[112:113], v[154:155] op_sel:[0,1] op_sel_hi:[1,1]
	v_add_f32_dpp v212, v212, v212 row_ror:8 row_mask:0xf bank_mask:0xf bound_ctrl:1
	v_pk_mul_f32 v[114:115], v[114:115], v[154:155] op_sel:[0,1] op_sel_hi:[1,1]
	v_pk_mul_f32 v[116:117], v[116:117], v[154:155] op_sel:[0,1] op_sel_hi:[1,1]
	v_add_f32_dpp v212, v212, v212 row_ror:4 row_mask:0xf bank_mask:0xf bound_ctrl:1
	v_pk_mul_f32 v[118:119], v[118:119], v[154:155] op_sel:[0,1] op_sel_hi:[1,1]
	v_pk_mul_f32 v[120:121], v[120:121], v[154:155] op_sel:[0,1] op_sel_hi:[1,1]
	v_add_f32_dpp v212, v212, v212 row_ror:2 row_mask:0xf bank_mask:0xf bound_ctrl:1
	v_pk_mul_f32 v[122:123], v[122:123], v[154:155] op_sel:[0,1] op_sel_hi:[1,1]
	v_pk_mul_f32 v[124:125], v[124:125], v[154:155] op_sel:[0,1] op_sel_hi:[1,1]
	v_add_f32_dpp v212, v212, v212 row_ror:1 row_mask:0xf bank_mask:0xf bound_ctrl:1
	v_pk_mul_f32 v[126:127], v[126:127], v[154:155] op_sel:[0,1] op_sel_hi:[1,1]
	s_waitcnt lgkmcnt(5)
	v_pk_fma_f32 v[196:197], v[154:155], v[196:197], v[112:113] op_sel_hi:[0,1,1]
	s_and_saveexec_b64 s[8:9], s[44:45]
	ds_write_b32 v190, v212 offset:34944
	s_mov_b64 exec, s[8:9]
	v_pk_fma_f32 v[198:199], v[154:155], v[198:199], v[114:115] op_sel_hi:[0,1,1]
	v_pk_fma_f32 v[200:201], v[154:155], v[200:201], v[116:117] op_sel_hi:[0,1,1]
	v_pk_fma_f32 v[202:203], v[154:155], v[202:203], v[118:119] op_sel_hi:[0,1,1]
	v_pk_fma_f32 v[204:205], v[154:155], v[204:205], v[120:121] op_sel_hi:[0,1,1]
	v_pk_fma_f32 v[206:207], v[154:155], v[206:207], v[122:123] op_sel_hi:[0,1,1]
	v_pk_fma_f32 v[208:209], v[154:155], v[208:209], v[124:125] op_sel_hi:[0,1,1]
	v_pk_fma_f32 v[210:211], v[154:155], v[210:211], v[126:127] op_sel_hi:[0,1,1]
	s_waitcnt lgkmcnt(5)
	v_pk_fma_f32 v[128:129], v[96:97], v[196:197], v[214:215]
	v_pk_fma_f32 v[130:131], v[98:99], v[198:199], v[214:215]
	s_waitcnt lgkmcnt(4)
	v_pk_fma_f32 v[128:129], v[100:101], v[200:201], v[128:129]
	v_pk_fma_f32 v[130:131], v[102:103], v[202:203], v[130:131]
	s_waitcnt lgkmcnt(3)
	v_pk_fma_f32 v[128:129], v[104:105], v[204:205], v[128:129]
	v_pk_fma_f32 v[130:131], v[106:107], v[206:207], v[130:131]
	s_waitcnt lgkmcnt(2)
	v_pk_fma_f32 v[128:129], v[108:109], v[208:209], v[128:129]
	v_pk_fma_f32 v[130:131], v[110:111], v[210:211], v[130:131]
	v_add_f32_e32 v128, v128, v129
	v_add_f32_e32 v130, v130, v131
	v_add_f32_e32 v213, v128, v130
	s_nop 1
	v_add_f32_dpp v213, v213, v213 row_ror:8 row_mask:0xf bank_mask:0xf bound_ctrl:1
	s_nop 1
	v_add_f32_dpp v213, v213, v213 row_ror:4 row_mask:0xf bank_mask:0xf bound_ctrl:1
	s_nop 1
	v_add_f32_dpp v213, v213, v213 row_ror:2 row_mask:0xf bank_mask:0xf bound_ctrl:1
	s_nop 1
	v_add_f32_dpp v213, v213, v213 row_ror:1 row_mask:0xf bank_mask:0xf bound_ctrl:1
	s_and_saveexec_b64 s[8:9], s[44:45]
	ds_write_b32 v190, v213 offset:35008
	s_mov_b64 exec, s[8:9]
	s_waitcnt lgkmcnt(0)
	v_mov_b32_e32 v88, v196
	v_mov_b32_e32 v89, v197
	v_mov_b32_e32 v90, v198
	v_mov_b32_e32 v100, v199
	v_mov_b32_e32 v91, v200
	v_mov_b32_e32 v101, v201
	v_mov_b32_e32 v102, v202
	v_mov_b32_e32 v104, v203
	v_mov_b32_e32 v103, v204
	v_mov_b32_e32 v105, v205
	v_mov_b32_e32 v106, v206
	v_mov_b32_e32 v109, v207
	v_mov_b32_e32 v107, v208
	v_mov_b32_e32 v110, v209
	v_mov_b32_e32 v108, v210
	v_mov_b32_e32 v111, v211
	s_branch .LBB0_1138

.LBB0_1289:
	v_mov_b32_e32 v178, v118
	v_mov_b32_e32 v179, v119
	v_mov_b32_e32 v180, v88
	v_mov_b32_e32 v181, v89
	v_mov_b32_e32 v182, v90
	v_mov_b32_e32 v183, v80
	v_mov_b32_e32 v184, v81
	v_mov_b32_e32 v185, v82
	v_mov_b32_e32 v186, v146
	v_mov_b32_e32 v187, v120
	v_mov_b32_e32 v188, v121
	v_mov_b32_e32 v189, v91
	v_mov_b32_e32 v190, v147
	v_mov_b32_e32 v191, v148
	v_mov_b32_e32 v192, v149
	v_mov_b32_e32 v193, v83
	v_mov_b32_e32 v196, 0
	v_mov_b32_e32 v197, 0
	v_add_u32_e32 v194, 0x4000, v103
	v_add_u32_e32 v195, 0x4400, v103
	ds_read2_b32 v[118:119], v194 offset0:0 offset1:16
	ds_read_b128 v[72:75], v145 offset:8192
	ds_read_b128 v[76:79], v145 offset:8448
	ds_read_b128 v[64:67], v145
	ds_read_b128 v[68:71], v145 offset:256
	ds_read2_b32 v[120:121], v194 offset0:32 offset1:48
	ds_read_b128 v[88:91], v145 offset:8704
	ds_read_b128 v[92:95], v145 offset:8960
	ds_read_b128 v[80:83], v145 offset:512
	ds_read_b128 v[84:87], v145 offset:768
	s_waitcnt lgkmcnt(9)
	v_pk_add_f32 v[178:179], v[178:179], v[118:119] op_sel_hi:[1,0] neg_lo:[0,1] neg_hi:[0,1]
	v_pk_add_f32 v[186:187], v[186:187], v[118:119] op_sel:[0,1] op_sel_hi:[1,1] neg_lo:[0,1] neg_hi:[0,1]
	v_pk_add_f32 v[180:181], v[180:181], v[118:119] op_sel_hi:[1,0] neg_lo:[0,1] neg_hi:[0,1]
	v_pk_add_f32 v[188:189], v[188:189], v[118:119] op_sel:[0,1] op_sel_hi:[1,1] neg_lo:[0,1] neg_hi:[0,1]
	v_pk_add_f32 v[182:183], v[182:183], v[118:119] op_sel_hi:[1,0] neg_lo:[0,1] neg_hi:[0,1]
	v_pk_add_f32 v[190:191], v[190:191], v[118:119] op_sel:[0,1] op_sel_hi:[1,1] neg_lo:[0,1] neg_hi:[0,1]
	v_pk_add_f32 v[184:185], v[184:185], v[118:119] op_sel_hi:[1,0] neg_lo:[0,1] neg_hi:[0,1]
	v_pk_add_f32 v[192:193], v[192:193], v[118:119] op_sel:[0,1] op_sel_hi:[1,1] neg_lo:[0,1] neg_hi:[0,1]
	s_waitcnt lgkmcnt(8)
	v_pk_fma_f32 v[178:179], v[72:73], v[178:179], v[118:119] op_sel_hi:[1,1,0]
	v_pk_fma_f32 v[186:187], v[72:73], v[186:187], v[118:119] op_sel:[0,0,1] op_sel_hi:[1,1,1]
	v_pk_fma_f32 v[180:181], v[74:75], v[180:181], v[118:119] op_sel_hi:[1,1,0]
	v_pk_fma_f32 v[188:189], v[74:75], v[188:189], v[118:119] op_sel:[0,0,1] op_sel_hi:[1,1,1]
	s_waitcnt lgkmcnt(7)
	v_pk_fma_f32 v[182:183], v[76:77], v[182:183], v[118:119] op_sel_hi:[1,1,0]
	v_pk_fma_f32 v[190:191], v[76:77], v[190:191], v[118:119] op_sel:[0,0,1] op_sel_hi:[1,1,1]
	v_pk_fma_f32 v[184:185], v[78:79], v[184:185], v[118:119] op_sel_hi:[1,1,0]
	v_pk_fma_f32 v[192:193], v[78:79], v[192:193], v[118:119] op_sel:[0,0,1] op_sel_hi:[1,1,1]
	s_waitcnt lgkmcnt(6)
	v_pk_fma_f32 v[146:147], v[64:65], v[178:179], v[196:197]
	v_pk_fma_f32 v[150:151], v[64:65], v[186:187], v[196:197]
	v_pk_fma_f32 v[148:149], v[66:67], v[180:181], v[196:197]
	v_pk_fma_f32 v[152:153], v[66:67], v[188:189], v[196:197]
	s_waitcnt lgkmcnt(5)
	v_pk_fma_f32 v[146:147], v[68:69], v[182:183], v[146:147]
	v_pk_fma_f32 v[150:151], v[68:69], v[190:191], v[150:151]
	v_pk_fma_f32 v[148:149], v[70:71], v[184:185], v[148:149]
	v_pk_fma_f32 v[152:153], v[70:71], v[192:193], v[152:153]
	v_add_f32_e32 v146, v146, v147
	v_add_f32_e32 v148, v148, v149
	v_add_f32_e32 v150, v150, v151
	v_add_f32_e32 v152, v152, v153
	v_add_f32_e32 v154, v146, v148
	v_add_f32_e32 v155, v150, v152
	ds_read2_b32 v[118:119], v194 offset0:64 offset1:80
	ds_read_b128 v[72:75], v145 offset:9216
	ds_read_b128 v[76:79], v145 offset:9472
	ds_read_b128 v[64:67], v145 offset:1024
	ds_read_b128 v[68:71], v145 offset:1280
	s_waitcnt lgkmcnt(9)
	v_pk_add_f32 v[178:179], v[178:179], v[120:121] op_sel_hi:[1,0] neg_lo:[0,1] neg_hi:[0,1]
	v_add_f32_dpp v154, v154, v154 row_ror:8 row_mask:0xf bank_mask:0xf bound_ctrl:1
	v_pk_add_f32 v[186:187], v[186:187], v[120:121] op_sel:[0,1] op_sel_hi:[1,1] neg_lo:[0,1] neg_hi:[0,1]
	v_add_f32_dpp v155, v155, v155 row_ror:8 row_mask:0xf bank_mask:0xf bound_ctrl:1
	v_pk_add_f32 v[180:181], v[180:181], v[120:121] op_sel_hi:[1,0] neg_lo:[0,1] neg_hi:[0,1]
	v_add_f32_dpp v154, v154, v154 row_ror:4 row_mask:0xf bank_mask:0xf bound_ctrl:1
	v_pk_add_f32 v[188:189], v[188:189], v[120:121] op_sel:[0,1] op_sel_hi:[1,1] neg_lo:[0,1] neg_hi:[0,1]
	v_add_f32_dpp v155, v155, v155 row_ror:4 row_mask:0xf bank_mask:0xf bound_ctrl:1
	v_pk_add_f32 v[182:183], v[182:183], v[120:121] op_sel_hi:[1,0] neg_lo:[0,1] neg_hi:[0,1]
	v_add_f32_dpp v154, v154, v154 row_ror:2 row_mask:0xf bank_mask:0xf bound_ctrl:1
	v_pk_add_f32 v[190:191], v[190:191], v[120:121] op_sel:[0,1] op_sel_hi:[1,1] neg_lo:[0,1] neg_hi:[0,1]
	v_add_f32_dpp v155, v155, v155 row_ror:2 row_mask:0xf bank_mask:0xf bound_ctrl:1
	v_pk_add_f32 v[184:185], v[184:185], v[120:121] op_sel_hi:[1,0] neg_lo:[0,1] neg_hi:[0,1]
	v_add_f32_dpp v154, v154, v154 row_ror:1 row_mask:0xf bank_mask:0xf bound_ctrl:1
	v_pk_add_f32 v[192:193], v[192:193], v[120:121] op_sel:[0,1] op_sel_hi:[1,1] neg_lo:[0,1] neg_hi:[0,1]
	v_add_f32_dpp v155, v155, v155 row_ror:1 row_mask:0xf bank_mask:0xf bound_ctrl:1
	s_waitcnt lgkmcnt(8)
	v_pk_fma_f32 v[178:179], v[88:89], v[178:179], v[120:121] op_sel_hi:[1,1,0]
	s_and_saveexec_b64 s[8:9], s[38:39]
	ds_write_b32 v103, v154 offset:36864
	ds_write_b32 v103, v155 offset:36928
	s_mov_b64 exec, s[8:9]
	v_pk_fma_f32 v[186:187], v[88:89], v[186:187], v[120:121] op_sel:[0,0,1] op_sel_hi:[1,1,1]
	v_pk_fma_f32 v[180:181], v[90:91], v[180:181], v[120:121] op_sel_hi:[1,1,0]
	v_pk_fma_f32 v[188:189], v[90:91], v[188:189], v[120:121] op_sel:[0,0,1] op_sel_hi:[1,1,1]
	s_waitcnt lgkmcnt(9)
	v_pk_fma_f32 v[182:183], v[92:93], v[182:183], v[120:121] op_sel_hi:[1,1,0]
	v_pk_fma_f32 v[190:191], v[92:93], v[190:191], v[120:121] op_sel:[0,0,1] op_sel_hi:[1,1,1]
	v_pk_fma_f32 v[184:185], v[94:95], v[184:185], v[120:121] op_sel_hi:[1,1,0]
	v_pk_fma_f32 v[192:193], v[94:95], v[192:193], v[120:121] op_sel:[0,0,1] op_sel_hi:[1,1,1]
	s_waitcnt lgkmcnt(8)
	v_pk_fma_f32 v[146:147], v[80:81], v[178:179], v[196:197]
	v_pk_fma_f32 v[150:151], v[80:81], v[186:187], v[196:197]
	v_pk_fma_f32 v[148:149], v[82:83], v[180:181], v[196:197]
	v_pk_fma_f32 v[152:153], v[82:83], v[188:189], v[196:197]
	s_waitcnt lgkmcnt(7)
	v_pk_fma_f32 v[146:147], v[84:85], v[182:183], v[146:147]
	v_pk_fma_f32 v[150:151], v[84:85], v[190:191], v[150:151]
	v_pk_fma_f32 v[148:149], v[86:87], v[184:185], v[148:149]
	v_pk_fma_f32 v[152:153], v[86:87], v[192:193], v[152:153]
	v_add_f32_e32 v146, v146, v147
	v_add_f32_e32 v148, v148, v149
	v_add_f32_e32 v150, v150, v151
	v_add_f32_e32 v152, v152, v153
	v_add_f32_e32 v156, v146, v148
	v_add_f32_e32 v157, v150, v152
	ds_read2_b32 v[120:121], v194 offset0:96 offset1:112
	ds_read_b128 v[88:91], v145 offset:9728
	ds_read_b128 v[92:95], v145 offset:9984
	ds_read_b128 v[80:83], v145 offset:1536
	ds_read_b128 v[84:87], v145 offset:1792
	s_waitcnt lgkmcnt(11)
	v_pk_add_f32 v[178:179], v[178:179], v[118:119] op_sel_hi:[1,0] neg_lo:[0,1] neg_hi:[0,1]
	v_add_f32_dpp v156, v156, v156 row_ror:8 row_mask:0xf bank_mask:0xf bound_ctrl:1
	v_pk_add_f32 v[186:187], v[186:187], v[118:119] op_sel:[0,1] op_sel_hi:[1,1] neg_lo:[0,1] neg_hi:[0,1]
	v_add_f32_dpp v157, v157, v157 row_ror:8 row_mask:0xf bank_mask:0xf bound_ctrl:1
	v_pk_add_f32 v[180:181], v[180:181], v[118:119] op_sel_hi:[1,0] neg_lo:[0,1] neg_hi:[0,1]
	v_add_f32_dpp v156, v156, v156 row_ror:4 row_mask:0xf bank_mask:0xf bound_ctrl:1
	v_pk_add_f32 v[188:189], v[188:189], v[118:119] op_sel:[0,1] op_sel_hi:[1,1] neg_lo:[0,1] neg_hi:[0,1]
	v_add_f32_dpp v157, v157, v157 row_ror:4 row_mask:0xf bank_mask:0xf bound_ctrl:1
	v_pk_add_f32 v[182:183], v[182:183], v[118:119] op_sel_hi:[1,0] neg_lo:[0,1] neg_hi:[0,1]
	v_add_f32_dpp v156, v156, v156 row_ror:2 row_mask:0xf bank_mask:0xf bound_ctrl:1
	v_pk_add_f32 v[190:191], v[190:191], v[118:119] op_sel:[0,1] op_sel_hi:[1,1] neg_lo:[0,1] neg_hi:[0,1]
	v_add_f32_dpp v157, v157, v157 row_ror:2 row_mask:0xf bank_mask:0xf bound_ctrl:1
	v_pk_add_f32 v[184:185], v[184:185], v[118:119] op_sel_hi:[1,0] neg_lo:[0,1] neg_hi:[0,1]
	v_add_f32_dpp v156, v156, v156 row_ror:1 row_mask:0xf bank_mask:0xf bound_ctrl:1
	v_pk_add_f32 v[192:193], v[192:193], v[118:119] op_sel:[0,1] op_sel_hi:[1,1] neg_lo:[0,1] neg_hi:[0,1]
	v_add_f32_dpp v157, v157, v157 row_ror:1 row_mask:0xf bank_mask:0xf bound_ctrl:1
	s_waitcnt lgkmcnt(10)
	v_pk_fma_f32 v[178:179], v[72:73], v[178:179], v[118:119] op_sel_hi:[1,1,0]
	s_and_saveexec_b64 s[8:9], s[38:39]
	ds_write_b32 v103, v156 offset:36992
	ds_write_b32 v103, v157 offset:37056
	s_mov_b64 exec, s[8:9]
	v_pk_fma_f32 v[186:187], v[72:73], v[186:187], v[118:119] op_sel:[0,0,1] op_sel_hi:[1,1,1]
	v_pk_fma_f32 v[180:181], v[74:75], v[180:181], v[118:119] op_sel_hi:[1,1,0]
	v_pk_fma_f32 v[188:189], v[74:75], v[188:189], v[118:119] op_sel:[0,0,1] op_sel_hi:[1,1,1]
	s_waitcnt lgkmcnt(11)
	v_pk_fma_f32 v[182:183], v[76:77], v[182:183], v[118:119] op_sel_hi:[1,1,0]
	v_pk_fma_f32 v[190:191], v[76:77], v[190:191], v[118:119] op_sel:[0,0,1] op_sel_hi:[1,1,1]
	v_pk_fma_f32 v[184:185], v[78:79], v[184:185], v[118:119] op_sel_hi:[1,1,0]
	v_pk_fma_f32 v[192:193], v[78:79], v[192:193], v[118:119] op_sel:[0,0,1] op_sel_hi:[1,1,1]
	s_waitcnt lgkmcnt(10)
	v_pk_fma_f32 v[146:147], v[64:65], v[178:179], v[196:197]
	v_pk_fma_f32 v[150:151], v[64:65], v[186:187], v[196:197]
	v_pk_fma_f32 v[148:149], v[66:67], v[180:181], v[196:197]
	v_pk_fma_f32 v[152:153], v[66:67], v[188:189], v[196:197]
	s_waitcnt lgkmcnt(9)
	v_pk_fma_f32 v[146:147], v[68:69], v[182:183], v[146:147]
	v_pk_fma_f32 v[150:151], v[68:69], v[190:191], v[150:151]
	v_pk_fma_f32 v[148:149], v[70:71], v[184:185], v[148:149]
	v_pk_fma_f32 v[152:153], v[70:71], v[192:193], v[152:153]
	v_add_f32_e32 v146, v146, v147
	v_add_f32_e32 v148, v148, v149
	v_add_f32_e32 v150, v150, v151
	v_add_f32_e32 v152, v152, v153
	v_add_f32_e32 v154, v146, v148
	v_add_f32_e32 v155, v150, v152
	ds_read2_b32 v[118:119], v194 offset0:128 offset1:144
	ds_read_b128 v[72:75], v145 offset:10240
	ds_read_b128 v[76:79], v145 offset:10496
	ds_read_b128 v[64:67], v145 offset:2048
	ds_read_b128 v[68:71], v145 offset:2304
	s_waitcnt lgkmcnt(11)
	v_pk_add_f32 v[178:179], v[178:179], v[120:121] op_sel_hi:[1,0] neg_lo:[0,1] neg_hi:[0,1]
	v_add_f32_dpp v154, v154, v154 row_ror:8 row_mask:0xf bank_mask:0xf bound_ctrl:1
	v_pk_add_f32 v[186:187], v[186:187], v[120:121] op_sel:[0,1] op_sel_hi:[1,1] neg_lo:[0,1] neg_hi:[0,1]
	v_add_f32_dpp v155, v155, v155 row_ror:8 row_mask:0xf bank_mask:0xf bound_ctrl:1
	v_pk_add_f32 v[180:181], v[180:181], v[120:121] op_sel_hi:[1,0] neg_lo:[0,1] neg_hi:[0,1]
	v_add_f32_dpp v154, v154, v154 row_ror:4 row_mask:0xf bank_mask:0xf bound_ctrl:1
	v_pk_add_f32 v[188:189], v[188:189], v[120:121] op_sel:[0,1] op_sel_hi:[1,1] neg_lo:[0,1] neg_hi:[0,1]
	v_add_f32_dpp v155, v155, v155 row_ror:4 row_mask:0xf bank_mask:0xf bound_ctrl:1
	v_pk_add_f32 v[182:183], v[182:183], v[120:121] op_sel_hi:[1,0] neg_lo:[0,1] neg_hi:[0,1]
	v_add_f32_dpp v154, v154, v154 row_ror:2 row_mask:0xf bank_mask:0xf bound_ctrl:1
	v_pk_add_f32 v[190:191], v[190:191], v[120:121] op_sel:[0,1] op_sel_hi:[1,1] neg_lo:[0,1] neg_hi:[0,1]
	v_add_f32_dpp v155, v155, v155 row_ror:2 row_mask:0xf bank_mask:0xf bound_ctrl:1
	v_pk_add_f32 v[184:185], v[184:185], v[120:121] op_sel_hi:[1,0] neg_lo:[0,1] neg_hi:[0,1]
	v_add_f32_dpp v154, v154, v154 row_ror:1 row_mask:0xf bank_mask:0xf bound_ctrl:1
	v_pk_add_f32 v[192:193], v[192:193], v[120:121] op_sel:[0,1] op_sel_hi:[1,1] neg_lo:[0,1] neg_hi:[0,1]
	v_add_f32_dpp v155, v155, v155 row_ror:1 row_mask:0xf bank_mask:0xf bound_ctrl:1
	s_waitcnt lgkmcnt(10)
	v_pk_fma_f32 v[178:179], v[88:89], v[178:179], v[120:121] op_sel_hi:[1,1,0]
	s_and_saveexec_b64 s[8:9], s[38:39]
	ds_write_b32 v103, v154 offset:37120
	ds_write_b32 v103, v155 offset:37184
	s_mov_b64 exec, s[8:9]
	v_pk_fma_f32 v[186:187], v[88:89], v[186:187], v[120:121] op_sel:[0,0,1] op_sel_hi:[1,1,1]
	v_pk_fma_f32 v[180:181], v[90:91], v[180:181], v[120:121] op_sel_hi:[1,1,0]
	v_pk_fma_f32 v[188:189], v[90:91], v[188:189], v[120:121] op_sel:[0,0,1] op_sel_hi:[1,1,1]
	s_waitcnt lgkmcnt(11)
	v_pk_fma_f32 v[182:183], v[92:93], v[182:183], v[120:121] op_sel_hi:[1,1,0]
	v_pk_fma_f32 v[190:191], v[92:93], v[190:191], v[120:121] op_sel:[0,0,1] op_sel_hi:[1,1,1]
	v_pk_fma_f32 v[184:185], v[94:95], v[184:185], v[120:121] op_sel_hi:[1,1,0]
	v_pk_fma_f32 v[192:193], v[94:95], v[192:193], v[120:121] op_sel:[0,0,1] op_sel_hi:[1,1,1]
	s_waitcnt lgkmcnt(10)
	v_pk_fma_f32 v[146:147], v[80:81], v[178:179], v[196:197]
	v_pk_fma_f32 v[150:151], v[80:81], v[186:187], v[196:197]
	v_pk_fma_f32 v[148:149], v[82:83], v[180:181], v[196:197]
	v_pk_fma_f32 v[152:153], v[82:83], v[188:189], v[196:197]
	s_waitcnt lgkmcnt(9)
	v_pk_fma_f32 v[146:147], v[84:85], v[182:183], v[146:147]
	v_pk_fma_f32 v[150:151], v[84:85], v[190:191], v[150:151]
	v_pk_fma_f32 v[148:149], v[86:87], v[184:185], v[148:149]
	v_pk_fma_f32 v[152:153], v[86:87], v[192:193], v[152:153]
	v_add_f32_e32 v146, v146, v147
	v_add_f32_e32 v148, v148, v149
	v_add_f32_e32 v150, v150, v151
	v_add_f32_e32 v152, v152, v153
	v_add_f32_e32 v156, v146, v148
	v_add_f32_e32 v157, v150, v152
	ds_read2_b32 v[120:121], v194 offset0:160 offset1:176
	ds_read_b128 v[88:91], v145 offset:10752
	ds_read_b128 v[92:95], v145 offset:11008
	ds_read_b128 v[80:83], v145 offset:2560
	ds_read_b128 v[84:87], v145 offset:2816
	s_waitcnt lgkmcnt(11)
	v_pk_add_f32 v[178:179], v[178:179], v[118:119] op_sel_hi:[1,0] neg_lo:[0,1] neg_hi:[0,1]
	v_add_f32_dpp v156, v156, v156 row_ror:8 row_mask:0xf bank_mask:0xf bound_ctrl:1
	v_pk_add_f32 v[186:187], v[186:187], v[118:119] op_sel:[0,1] op_sel_hi:[1,1] neg_lo:[0,1] neg_hi:[0,1]
	v_add_f32_dpp v157, v157, v157 row_ror:8 row_mask:0xf bank_mask:0xf bound_ctrl:1
	v_pk_add_f32 v[180:181], v[180:181], v[118:119] op_sel_hi:[1,0] neg_lo:[0,1] neg_hi:[0,1]
	v_add_f32_dpp v156, v156, v156 row_ror:4 row_mask:0xf bank_mask:0xf bound_ctrl:1
	v_pk_add_f32 v[188:189], v[188:189], v[118:119] op_sel:[0,1] op_sel_hi:[1,1] neg_lo:[0,1] neg_hi:[0,1]
	v_add_f32_dpp v157, v157, v157 row_ror:4 row_mask:0xf bank_mask:0xf bound_ctrl:1
	v_pk_add_f32 v[182:183], v[182:183], v[118:119] op_sel_hi:[1,0] neg_lo:[0,1] neg_hi:[0,1]
	v_add_f32_dpp v156, v156, v156 row_ror:2 row_mask:0xf bank_mask:0xf bound_ctrl:1
	v_pk_add_f32 v[190:191], v[190:191], v[118:119] op_sel:[0,1] op_sel_hi:[1,1] neg_lo:[0,1] neg_hi:[0,1]
	v_add_f32_dpp v157, v157, v157 row_ror:2 row_mask:0xf bank_mask:0xf bound_ctrl:1
	v_pk_add_f32 v[184:185], v[184:185], v[118:119] op_sel_hi:[1,0] neg_lo:[0,1] neg_hi:[0,1]
	v_add_f32_dpp v156, v156, v156 row_ror:1 row_mask:0xf bank_mask:0xf bound_ctrl:1
	v_pk_add_f32 v[192:193], v[192:193], v[118:119] op_sel:[0,1] op_sel_hi:[1,1] neg_lo:[0,1] neg_hi:[0,1]
	v_add_f32_dpp v157, v157, v157 row_ror:1 row_mask:0xf bank_mask:0xf bound_ctrl:1
	s_waitcnt lgkmcnt(10)
	v_pk_fma_f32 v[178:179], v[72:73], v[178:179], v[118:119] op_sel_hi:[1,1,0]
	s_and_saveexec_b64 s[8:9], s[38:39]
	ds_write_b32 v103, v156 offset:37248
	ds_write_b32 v103, v157 offset:37312
	s_mov_b64 exec, s[8:9]
	v_pk_fma_f32 v[186:187], v[72:73], v[186:187], v[118:119] op_sel:[0,0,1] op_sel_hi:[1,1,1]
	v_pk_fma_f32 v[180:181], v[74:75], v[180:181], v[118:119] op_sel_hi:[1,1,0]
	v_pk_fma_f32 v[188:189], v[74:75], v[188:189], v[118:119] op_sel:[0,0,1] op_sel_hi:[1,1,1]
	s_waitcnt lgkmcnt(11)
	v_pk_fma_f32 v[182:183], v[76:77], v[182:183], v[118:119] op_sel_hi:[1,1,0]
	v_pk_fma_f32 v[190:191], v[76:77], v[190:191], v[118:119] op_sel:[0,0,1] op_sel_hi:[1,1,1]
	v_pk_fma_f32 v[184:185], v[78:79], v[184:185], v[118:119] op_sel_hi:[1,1,0]
	v_pk_fma_f32 v[192:193], v[78:79], v[192:193], v[118:119] op_sel:[0,0,1] op_sel_hi:[1,1,1]
	s_waitcnt lgkmcnt(10)
	v_pk_fma_f32 v[146:147], v[64:65], v[178:179], v[196:197]
	v_pk_fma_f32 v[150:151], v[64:65], v[186:187], v[196:197]
	v_pk_fma_f32 v[148:149], v[66:67], v[180:181], v[196:197]
	v_pk_fma_f32 v[152:153], v[66:67], v[188:189], v[196:197]
	s_waitcnt lgkmcnt(9)
	v_pk_fma_f32 v[146:147], v[68:69], v[182:183], v[146:147]
	v_pk_fma_f32 v[150:151], v[68:69], v[190:191], v[150:151]
	v_pk_fma_f32 v[148:149], v[70:71], v[184:185], v[148:149]
	v_pk_fma_f32 v[152:153], v[70:71], v[192:193], v[152:153]
	v_add_f32_e32 v146, v146, v147
	v_add_f32_e32 v148, v148, v149
	v_add_f32_e32 v150, v150, v151
	v_add_f32_e32 v152, v152, v153
	v_add_f32_e32 v154, v146, v148
	v_add_f32_e32 v155, v150, v152
	ds_read2_b32 v[118:119], v194 offset0:192 offset1:208
	ds_read_b128 v[72:75], v145 offset:11264
	ds_read_b128 v[76:79], v145 offset:11520
	ds_read_b128 v[64:67], v145 offset:3072
	ds_read_b128 v[68:71], v145 offset:3328
	s_waitcnt lgkmcnt(11)
	v_pk_add_f32 v[178:179], v[178:179], v[120:121] op_sel_hi:[1,0] neg_lo:[0,1] neg_hi:[0,1]
	v_add_f32_dpp v154, v154, v154 row_ror:8 row_mask:0xf bank_mask:0xf bound_ctrl:1
	v_pk_add_f32 v[186:187], v[186:187], v[120:121] op_sel:[0,1] op_sel_hi:[1,1] neg_lo:[0,1] neg_hi:[0,1]
	v_add_f32_dpp v155, v155, v155 row_ror:8 row_mask:0xf bank_mask:0xf bound_ctrl:1
	v_pk_add_f32 v[180:181], v[180:181], v[120:121] op_sel_hi:[1,0] neg_lo:[0,1] neg_hi:[0,1]
	v_add_f32_dpp v154, v154, v154 row_ror:4 row_mask:0xf bank_mask:0xf bound_ctrl:1
	v_pk_add_f32 v[188:189], v[188:189], v[120:121] op_sel:[0,1] op_sel_hi:[1,1] neg_lo:[0,1] neg_hi:[0,1]
	v_add_f32_dpp v155, v155, v155 row_ror:4 row_mask:0xf bank_mask:0xf bound_ctrl:1
	v_pk_add_f32 v[182:183], v[182:183], v[120:121] op_sel_hi:[1,0] neg_lo:[0,1] neg_hi:[0,1]
	v_add_f32_dpp v154, v154, v154 row_ror:2 row_mask:0xf bank_mask:0xf bound_ctrl:1
	v_pk_add_f32 v[190:191], v[190:191], v[120:121] op_sel:[0,1] op_sel_hi:[1,1] neg_lo:[0,1] neg_hi:[0,1]
	v_add_f32_dpp v155, v155, v155 row_ror:2 row_mask:0xf bank_mask:0xf bound_ctrl:1
	v_pk_add_f32 v[184:185], v[184:185], v[120:121] op_sel_hi:[1,0] neg_lo:[0,1] neg_hi:[0,1]
	v_add_f32_dpp v154, v154, v154 row_ror:1 row_mask:0xf bank_mask:0xf bound_ctrl:1
	v_pk_add_f32 v[192:193], v[192:193], v[120:121] op_sel:[0,1] op_sel_hi:[1,1] neg_lo:[0,1] neg_hi:[0,1]
	v_add_f32_dpp v155, v155, v155 row_ror:1 row_mask:0xf bank_mask:0xf bound_ctrl:1
	s_waitcnt lgkmcnt(10)
	v_pk_fma_f32 v[178:179], v[88:89], v[178:179], v[120:121] op_sel_hi:[1,1,0]
	s_and_saveexec_b64 s[8:9], s[38:39]
	ds_write_b32 v103, v154 offset:37376
	ds_write_b32 v103, v155 offset:37440
	s_mov_b64 exec, s[8:9]
	v_pk_fma_f32 v[186:187], v[88:89], v[186:187], v[120:121] op_sel:[0,0,1] op_sel_hi:[1,1,1]
	v_pk_fma_f32 v[180:181], v[90:91], v[180:181], v[120:121] op_sel_hi:[1,1,0]
	v_pk_fma_f32 v[188:189], v[90:91], v[188:189], v[120:121] op_sel:[0,0,1] op_sel_hi:[1,1,1]
	s_waitcnt lgkmcnt(11)
	v_pk_fma_f32 v[182:183], v[92:93], v[182:183], v[120:121] op_sel_hi:[1,1,0]
	v_pk_fma_f32 v[190:191], v[92:93], v[190:191], v[120:121] op_sel:[0,0,1] op_sel_hi:[1,1,1]
	v_pk_fma_f32 v[184:185], v[94:95], v[184:185], v[120:121] op_sel_hi:[1,1,0]
	v_pk_fma_f32 v[192:193], v[94:95], v[192:193], v[120:121] op_sel:[0,0,1] op_sel_hi:[1,1,1]
	s_waitcnt lgkmcnt(10)
	v_pk_fma_f32 v[146:147], v[80:81], v[178:179], v[196:197]
	v_pk_fma_f32 v[150:151], v[80:81], v[186:187], v[196:197]
	v_pk_fma_f32 v[148:149], v[82:83], v[180:181], v[196:197]
	v_pk_fma_f32 v[152:153], v[82:83], v[188:189], v[196:197]
	s_waitcnt lgkmcnt(9)
	v_pk_fma_f32 v[146:147], v[84:85], v[182:183], v[146:147]
	v_pk_fma_f32 v[150:151], v[84:85], v[190:191], v[150:151]
	v_pk_fma_f32 v[148:149], v[86:87], v[184:185], v[148:149]
	v_pk_fma_f32 v[152:153], v[86:87], v[192:193], v[152:153]
	v_add_f32_e32 v146, v146, v147
	v_add_f32_e32 v148, v148, v149
	v_add_f32_e32 v150, v150, v151
	v_add_f32_e32 v152, v152, v153
	v_add_f32_e32 v156, v146, v148
	v_add_f32_e32 v157, v150, v152
	ds_read2_b32 v[120:121], v194 offset0:224 offset1:240
	ds_read_b128 v[88:91], v145 offset:11776
	ds_read_b128 v[92:95], v145 offset:12032
	ds_read_b128 v[80:83], v145 offset:3584
	ds_read_b128 v[84:87], v145 offset:3840
	s_waitcnt lgkmcnt(11)
	v_pk_add_f32 v[178:179], v[178:179], v[118:119] op_sel_hi:[1,0] neg_lo:[0,1] neg_hi:[0,1]
	v_add_f32_dpp v156, v156, v156 row_ror:8 row_mask:0xf bank_mask:0xf bound_ctrl:1
	v_pk_add_f32 v[186:187], v[186:187], v[118:119] op_sel:[0,1] op_sel_hi:[1,1] neg_lo:[0,1] neg_hi:[0,1]
	v_add_f32_dpp v157, v157, v157 row_ror:8 row_mask:0xf bank_mask:0xf bound_ctrl:1
	v_pk_add_f32 v[180:181], v[180:181], v[118:119] op_sel_hi:[1,0] neg_lo:[0,1] neg_hi:[0,1]
	v_add_f32_dpp v156, v156, v156 row_ror:4 row_mask:0xf bank_mask:0xf bound_ctrl:1
	v_pk_add_f32 v[188:189], v[188:189], v[118:119] op_sel:[0,1] op_sel_hi:[1,1] neg_lo:[0,1] neg_hi:[0,1]
	v_add_f32_dpp v157, v157, v157 row_ror:4 row_mask:0xf bank_mask:0xf bound_ctrl:1
	v_pk_add_f32 v[182:183], v[182:183], v[118:119] op_sel_hi:[1,0] neg_lo:[0,1] neg_hi:[0,1]
	v_add_f32_dpp v156, v156, v156 row_ror:2 row_mask:0xf bank_mask:0xf bound_ctrl:1
	v_pk_add_f32 v[190:191], v[190:191], v[118:119] op_sel:[0,1] op_sel_hi:[1,1] neg_lo:[0,1] neg_hi:[0,1]
	v_add_f32_dpp v157, v157, v157 row_ror:2 row_mask:0xf bank_mask:0xf bound_ctrl:1
	v_pk_add_f32 v[184:185], v[184:185], v[118:119] op_sel_hi:[1,0] neg_lo:[0,1] neg_hi:[0,1]
	v_add_f32_dpp v156, v156, v156 row_ror:1 row_mask:0xf bank_mask:0xf bound_ctrl:1
	v_pk_add_f32 v[192:193], v[192:193], v[118:119] op_sel:[0,1] op_sel_hi:[1,1] neg_lo:[0,1] neg_hi:[0,1]
	v_add_f32_dpp v157, v157, v157 row_ror:1 row_mask:0xf bank_mask:0xf bound_ctrl:1
	s_waitcnt lgkmcnt(10)
	v_pk_fma_f32 v[178:179], v[72:73], v[178:179], v[118:119] op_sel_hi:[1,1,0]
	s_and_saveexec_b64 s[8:9], s[38:39]
	ds_write_b32 v103, v156 offset:37504
	ds_write_b32 v103, v157 offset:37568
	s_mov_b64 exec, s[8:9]
	v_pk_fma_f32 v[186:187], v[72:73], v[186:187], v[118:119] op_sel:[0,0,1] op_sel_hi:[1,1,1]
	v_pk_fma_f32 v[180:181], v[74:75], v[180:181], v[118:119] op_sel_hi:[1,1,0]
	v_pk_fma_f32 v[188:189], v[74:75], v[188:189], v[118:119] op_sel:[0,0,1] op_sel_hi:[1,1,1]
	s_waitcnt lgkmcnt(11)
	v_pk_fma_f32 v[182:183], v[76:77], v[182:183], v[118:119] op_sel_hi:[1,1,0]
	v_pk_fma_f32 v[190:191], v[76:77], v[190:191], v[118:119] op_sel:[0,0,1] op_sel_hi:[1,1,1]
	v_pk_fma_f32 v[184:185], v[78:79], v[184:185], v[118:119] op_sel_hi:[1,1,0]
	v_pk_fma_f32 v[192:193], v[78:79], v[192:193], v[118:119] op_sel:[0,0,1] op_sel_hi:[1,1,1]
	s_waitcnt lgkmcnt(10)
	v_pk_fma_f32 v[146:147], v[64:65], v[178:179], v[196:197]
	v_pk_fma_f32 v[150:151], v[64:65], v[186:187], v[196:197]
	v_pk_fma_f32 v[148:149], v[66:67], v[180:181], v[196:197]
	v_pk_fma_f32 v[152:153], v[66:67], v[188:189], v[196:197]
	s_waitcnt lgkmcnt(9)
	v_pk_fma_f32 v[146:147], v[68:69], v[182:183], v[146:147]
	v_pk_fma_f32 v[150:151], v[68:69], v[190:191], v[150:151]
	v_pk_fma_f32 v[148:149], v[70:71], v[184:185], v[148:149]
	v_pk_fma_f32 v[152:153], v[70:71], v[192:193], v[152:153]
	v_add_f32_e32 v146, v146, v147
	v_add_f32_e32 v148, v148, v149
	v_add_f32_e32 v150, v150, v151
	v_add_f32_e32 v152, v152, v153
	v_add_f32_e32 v154, v146, v148
	v_add_f32_e32 v155, v150, v152
	ds_read2_b32 v[118:119], v195 offset0:0 offset1:16
	ds_read_b128 v[72:75], v145 offset:12288
	ds_read_b128 v[76:79], v145 offset:12544
	ds_read_b128 v[64:67], v145 offset:4096
	ds_read_b128 v[68:71], v145 offset:4352
	s_waitcnt lgkmcnt(11)
	v_pk_add_f32 v[178:179], v[178:179], v[120:121] op_sel_hi:[1,0] neg_lo:[0,1] neg_hi:[0,1]
	v_add_f32_dpp v154, v154, v154 row_ror:8 row_mask:0xf bank_mask:0xf bound_ctrl:1
	v_pk_add_f32 v[186:187], v[186:187], v[120:121] op_sel:[0,1] op_sel_hi:[1,1] neg_lo:[0,1] neg_hi:[0,1]
	v_add_f32_dpp v155, v155, v155 row_ror:8 row_mask:0xf bank_mask:0xf bound_ctrl:1
	v_pk_add_f32 v[180:181], v[180:181], v[120:121] op_sel_hi:[1,0] neg_lo:[0,1] neg_hi:[0,1]
	v_add_f32_dpp v154, v154, v154 row_ror:4 row_mask:0xf bank_mask:0xf bound_ctrl:1
	v_pk_add_f32 v[188:189], v[188:189], v[120:121] op_sel:[0,1] op_sel_hi:[1,1] neg_lo:[0,1] neg_hi:[0,1]
	v_add_f32_dpp v155, v155, v155 row_ror:4 row_mask:0xf bank_mask:0xf bound_ctrl:1
	v_pk_add_f32 v[182:183], v[182:183], v[120:121] op_sel_hi:[1,0] neg_lo:[0,1] neg_hi:[0,1]
	v_add_f32_dpp v154, v154, v154 row_ror:2 row_mask:0xf bank_mask:0xf bound_ctrl:1
	v_pk_add_f32 v[190:191], v[190:191], v[120:121] op_sel:[0,1] op_sel_hi:[1,1] neg_lo:[0,1] neg_hi:[0,1]
	v_add_f32_dpp v155, v155, v155 row_ror:2 row_mask:0xf bank_mask:0xf bound_ctrl:1
	v_pk_add_f32 v[184:185], v[184:185], v[120:121] op_sel_hi:[1,0] neg_lo:[0,1] neg_hi:[0,1]
	v_add_f32_dpp v154, v154, v154 row_ror:1 row_mask:0xf bank_mask:0xf bound_ctrl:1
	v_pk_add_f32 v[192:193], v[192:193], v[120:121] op_sel:[0,1] op_sel_hi:[1,1] neg_lo:[0,1] neg_hi:[0,1]
	v_add_f32_dpp v155, v155, v155 row_ror:1 row_mask:0xf bank_mask:0xf bound_ctrl:1
	s_waitcnt lgkmcnt(10)
	v_pk_fma_f32 v[178:179], v[88:89], v[178:179], v[120:121] op_sel_hi:[1,1,0]
	s_and_saveexec_b64 s[8:9], s[38:39]
	ds_write_b32 v103, v154 offset:37632
	ds_write_b32 v103, v155 offset:37696
	s_mov_b64 exec, s[8:9]
	v_pk_fma_f32 v[186:187], v[88:89], v[186:187], v[120:121] op_sel:[0,0,1] op_sel_hi:[1,1,1]
	v_pk_fma_f32 v[180:181], v[90:91], v[180:181], v[120:121] op_sel_hi:[1,1,0]
	v_pk_fma_f32 v[188:189], v[90:91], v[188:189], v[120:121] op_sel:[0,0,1] op_sel_hi:[1,1,1]
	s_waitcnt lgkmcnt(11)
	v_pk_fma_f32 v[182:183], v[92:93], v[182:183], v[120:121] op_sel_hi:[1,1,0]
	v_pk_fma_f32 v[190:191], v[92:93], v[190:191], v[120:121] op_sel:[0,0,1] op_sel_hi:[1,1,1]
	v_pk_fma_f32 v[184:185], v[94:95], v[184:185], v[120:121] op_sel_hi:[1,1,0]
	v_pk_fma_f32 v[192:193], v[94:95], v[192:193], v[120:121] op_sel:[0,0,1] op_sel_hi:[1,1,1]
	s_waitcnt lgkmcnt(10)
	v_pk_fma_f32 v[146:147], v[80:81], v[178:179], v[196:197]
	v_pk_fma_f32 v[150:151], v[80:81], v[186:187], v[196:197]
	v_pk_fma_f32 v[148:149], v[82:83], v[180:181], v[196:197]
	v_pk_fma_f32 v[152:153], v[82:83], v[188:189], v[196:197]
	s_waitcnt lgkmcnt(9)
	v_pk_fma_f32 v[146:147], v[84:85], v[182:183], v[146:147]
	v_pk_fma_f32 v[150:151], v[84:85], v[190:191], v[150:151]
	v_pk_fma_f32 v[148:149], v[86:87], v[184:185], v[148:149]
	v_pk_fma_f32 v[152:153], v[86:87], v[192:193], v[152:153]
	v_add_f32_e32 v146, v146, v147
	v_add_f32_e32 v148, v148, v149
	v_add_f32_e32 v150, v150, v151
	v_add_f32_e32 v152, v152, v153
	v_add_f32_e32 v156, v146, v148
	v_add_f32_e32 v157, v150, v152
	ds_read2_b32 v[120:121], v195 offset0:32 offset1:48
	ds_read_b128 v[88:91], v145 offset:12800
	ds_read_b128 v[92:95], v145 offset:13056
	ds_read_b128 v[80:83], v145 offset:4608
	ds_read_b128 v[84:87], v145 offset:4864
	s_waitcnt lgkmcnt(11)
	v_pk_add_f32 v[178:179], v[178:179], v[118:119] op_sel_hi:[1,0] neg_lo:[0,1] neg_hi:[0,1]
	v_add_f32_dpp v156, v156, v156 row_ror:8 row_mask:0xf bank_mask:0xf bound_ctrl:1
	v_pk_add_f32 v[186:187], v[186:187], v[118:119] op_sel:[0,1] op_sel_hi:[1,1] neg_lo:[0,1] neg_hi:[0,1]
	v_add_f32_dpp v157, v157, v157 row_ror:8 row_mask:0xf bank_mask:0xf bound_ctrl:1
	v_pk_add_f32 v[180:181], v[180:181], v[118:119] op_sel_hi:[1,0] neg_lo:[0,1] neg_hi:[0,1]
	v_add_f32_dpp v156, v156, v156 row_ror:4 row_mask:0xf bank_mask:0xf bound_ctrl:1
	v_pk_add_f32 v[188:189], v[188:189], v[118:119] op_sel:[0,1] op_sel_hi:[1,1] neg_lo:[0,1] neg_hi:[0,1]
	v_add_f32_dpp v157, v157, v157 row_ror:4 row_mask:0xf bank_mask:0xf bound_ctrl:1
	v_pk_add_f32 v[182:183], v[182:183], v[118:119] op_sel_hi:[1,0] neg_lo:[0,1] neg_hi:[0,1]
	v_add_f32_dpp v156, v156, v156 row_ror:2 row_mask:0xf bank_mask:0xf bound_ctrl:1
	v_pk_add_f32 v[190:191], v[190:191], v[118:119] op_sel:[0,1] op_sel_hi:[1,1] neg_lo:[0,1] neg_hi:[0,1]
	v_add_f32_dpp v157, v157, v157 row_ror:2 row_mask:0xf bank_mask:0xf bound_ctrl:1
	v_pk_add_f32 v[184:185], v[184:185], v[118:119] op_sel_hi:[1,0] neg_lo:[0,1] neg_hi:[0,1]
	v_add_f32_dpp v156, v156, v156 row_ror:1 row_mask:0xf bank_mask:0xf bound_ctrl:1
	v_pk_add_f32 v[192:193], v[192:193], v[118:119] op_sel:[0,1] op_sel_hi:[1,1] neg_lo:[0,1] neg_hi:[0,1]
	v_add_f32_dpp v157, v157, v157 row_ror:1 row_mask:0xf bank_mask:0xf bound_ctrl:1
	s_waitcnt lgkmcnt(10)
	v_pk_fma_f32 v[178:179], v[72:73], v[178:179], v[118:119] op_sel_hi:[1,1,0]
	s_and_saveexec_b64 s[8:9], s[38:39]
	ds_write_b32 v103, v156 offset:37760
	ds_write_b32 v103, v157 offset:37824
	s_mov_b64 exec, s[8:9]
	v_pk_fma_f32 v[186:187], v[72:73], v[186:187], v[118:119] op_sel:[0,0,1] op_sel_hi:[1,1,1]
	v_pk_fma_f32 v[180:181], v[74:75], v[180:181], v[118:119] op_sel_hi:[1,1,0]
	v_pk_fma_f32 v[188:189], v[74:75], v[188:189], v[118:119] op_sel:[0,0,1] op_sel_hi:[1,1,1]
	s_waitcnt lgkmcnt(11)
	v_pk_fma_f32 v[182:183], v[76:77], v[182:183], v[118:119] op_sel_hi:[1,1,0]
	v_pk_fma_f32 v[190:191], v[76:77], v[190:191], v[118:119] op_sel:[0,0,1] op_sel_hi:[1,1,1]
	v_pk_fma_f32 v[184:185], v[78:79], v[184:185], v[118:119] op_sel_hi:[1,1,0]
	v_pk_fma_f32 v[192:193], v[78:79], v[192:193], v[118:119] op_sel:[0,0,1] op_sel_hi:[1,1,1]
	s_waitcnt lgkmcnt(10)
	v_pk_fma_f32 v[146:147], v[64:65], v[178:179], v[196:197]
	v_pk_fma_f32 v[150:151], v[64:65], v[186:187], v[196:197]
	v_pk_fma_f32 v[148:149], v[66:67], v[180:181], v[196:197]
	v_pk_fma_f32 v[152:153], v[66:67], v[188:189], v[196:197]
	s_waitcnt lgkmcnt(9)
	v_pk_fma_f32 v[146:147], v[68:69], v[182:183], v[146:147]
	v_pk_fma_f32 v[150:151], v[68:69], v[190:191], v[150:151]
	v_pk_fma_f32 v[148:149], v[70:71], v[184:185], v[148:149]
	v_pk_fma_f32 v[152:153], v[70:71], v[192:193], v[152:153]
	v_add_f32_e32 v146, v146, v147
	v_add_f32_e32 v148, v148, v149
	v_add_f32_e32 v150, v150, v151
	v_add_f32_e32 v152, v152, v153
	v_add_f32_e32 v154, v146, v148
	v_add_f32_e32 v155, v150, v152
	ds_read2_b32 v[118:119], v195 offset0:64 offset1:80
	ds_read_b128 v[72:75], v145 offset:13312
	ds_read_b128 v[76:79], v145 offset:13568
	ds_read_b128 v[64:67], v145 offset:5120
	ds_read_b128 v[68:71], v145 offset:5376
	s_waitcnt lgkmcnt(11)
	v_pk_add_f32 v[178:179], v[178:179], v[120:121] op_sel_hi:[1,0] neg_lo:[0,1] neg_hi:[0,1]
	v_add_f32_dpp v154, v154, v154 row_ror:8 row_mask:0xf bank_mask:0xf bound_ctrl:1
	v_pk_add_f32 v[186:187], v[186:187], v[120:121] op_sel:[0,1] op_sel_hi:[1,1] neg_lo:[0,1] neg_hi:[0,1]
	v_add_f32_dpp v155, v155, v155 row_ror:8 row_mask:0xf bank_mask:0xf bound_ctrl:1
	v_pk_add_f32 v[180:181], v[180:181], v[120:121] op_sel_hi:[1,0] neg_lo:[0,1] neg_hi:[0,1]
	v_add_f32_dpp v154, v154, v154 row_ror:4 row_mask:0xf bank_mask:0xf bound_ctrl:1
	v_pk_add_f32 v[188:189], v[188:189], v[120:121] op_sel:[0,1] op_sel_hi:[1,1] neg_lo:[0,1] neg_hi:[0,1]
	v_add_f32_dpp v155, v155, v155 row_ror:4 row_mask:0xf bank_mask:0xf bound_ctrl:1
	v_pk_add_f32 v[182:183], v[182:183], v[120:121] op_sel_hi:[1,0] neg_lo:[0,1] neg_hi:[0,1]
	v_add_f32_dpp v154, v154, v154 row_ror:2 row_mask:0xf bank_mask:0xf bound_ctrl:1
	v_pk_add_f32 v[190:191], v[190:191], v[120:121] op_sel:[0,1] op_sel_hi:[1,1] neg_lo:[0,1] neg_hi:[0,1]
	v_add_f32_dpp v155, v155, v155 row_ror:2 row_mask:0xf bank_mask:0xf bound_ctrl:1
	v_pk_add_f32 v[184:185], v[184:185], v[120:121] op_sel_hi:[1,0] neg_lo:[0,1] neg_hi:[0,1]
	v_add_f32_dpp v154, v154, v154 row_ror:1 row_mask:0xf bank_mask:0xf bound_ctrl:1
	v_pk_add_f32 v[192:193], v[192:193], v[120:121] op_sel:[0,1] op_sel_hi:[1,1] neg_lo:[0,1] neg_hi:[0,1]
	v_add_f32_dpp v155, v155, v155 row_ror:1 row_mask:0xf bank_mask:0xf bound_ctrl:1
	s_waitcnt lgkmcnt(10)
	v_pk_fma_f32 v[178:179], v[88:89], v[178:179], v[120:121] op_sel_hi:[1,1,0]
	s_and_saveexec_b64 s[8:9], s[38:39]
	ds_write_b32 v103, v154 offset:37888
	ds_write_b32 v103, v155 offset:37952
	s_mov_b64 exec, s[8:9]
	v_pk_fma_f32 v[186:187], v[88:89], v[186:187], v[120:121] op_sel:[0,0,1] op_sel_hi:[1,1,1]
	v_pk_fma_f32 v[180:181], v[90:91], v[180:181], v[120:121] op_sel_hi:[1,1,0]
	v_pk_fma_f32 v[188:189], v[90:91], v[188:189], v[120:121] op_sel:[0,0,1] op_sel_hi:[1,1,1]
	s_waitcnt lgkmcnt(11)
	v_pk_fma_f32 v[182:183], v[92:93], v[182:183], v[120:121] op_sel_hi:[1,1,0]
	v_pk_fma_f32 v[190:191], v[92:93], v[190:191], v[120:121] op_sel:[0,0,1] op_sel_hi:[1,1,1]
	v_pk_fma_f32 v[184:185], v[94:95], v[184:185], v[120:121] op_sel_hi:[1,1,0]
	v_pk_fma_f32 v[192:193], v[94:95], v[192:193], v[120:121] op_sel:[0,0,1] op_sel_hi:[1,1,1]
	s_waitcnt lgkmcnt(10)
	v_pk_fma_f32 v[146:147], v[80:81], v[178:179], v[196:197]
	v_pk_fma_f32 v[150:151], v[80:81], v[186:187], v[196:197]
	v_pk_fma_f32 v[148:149], v[82:83], v[180:181], v[196:197]
	v_pk_fma_f32 v[152:153], v[82:83], v[188:189], v[196:197]
	s_waitcnt lgkmcnt(9)
	v_pk_fma_f32 v[146:147], v[84:85], v[182:183], v[146:147]
	v_pk_fma_f32 v[150:151], v[84:85], v[190:191], v[150:151]
	v_pk_fma_f32 v[148:149], v[86:87], v[184:185], v[148:149]
	v_pk_fma_f32 v[152:153], v[86:87], v[192:193], v[152:153]
	v_add_f32_e32 v146, v146, v147
	v_add_f32_e32 v148, v148, v149
	v_add_f32_e32 v150, v150, v151
	v_add_f32_e32 v152, v152, v153
	v_add_f32_e32 v156, v146, v148
	v_add_f32_e32 v157, v150, v152
	ds_read2_b32 v[120:121], v195 offset0:96 offset1:112
	ds_read_b128 v[88:91], v145 offset:13824
	ds_read_b128 v[92:95], v145 offset:14080
	ds_read_b128 v[80:83], v145 offset:5632
	ds_read_b128 v[84:87], v145 offset:5888
	s_waitcnt lgkmcnt(11)
	v_pk_add_f32 v[178:179], v[178:179], v[118:119] op_sel_hi:[1,0] neg_lo:[0,1] neg_hi:[0,1]
	v_add_f32_dpp v156, v156, v156 row_ror:8 row_mask:0xf bank_mask:0xf bound_ctrl:1
	v_pk_add_f32 v[186:187], v[186:187], v[118:119] op_sel:[0,1] op_sel_hi:[1,1] neg_lo:[0,1] neg_hi:[0,1]
	v_add_f32_dpp v157, v157, v157 row_ror:8 row_mask:0xf bank_mask:0xf bound_ctrl:1
	v_pk_add_f32 v[180:181], v[180:181], v[118:119] op_sel_hi:[1,0] neg_lo:[0,1] neg_hi:[0,1]
	v_add_f32_dpp v156, v156, v156 row_ror:4 row_mask:0xf bank_mask:0xf bound_ctrl:1
	v_pk_add_f32 v[188:189], v[188:189], v[118:119] op_sel:[0,1] op_sel_hi:[1,1] neg_lo:[0,1] neg_hi:[0,1]
	v_add_f32_dpp v157, v157, v157 row_ror:4 row_mask:0xf bank_mask:0xf bound_ctrl:1
	v_pk_add_f32 v[182:183], v[182:183], v[118:119] op_sel_hi:[1,0] neg_lo:[0,1] neg_hi:[0,1]
	v_add_f32_dpp v156, v156, v156 row_ror:2 row_mask:0xf bank_mask:0xf bound_ctrl:1
	v_pk_add_f32 v[190:191], v[190:191], v[118:119] op_sel:[0,1] op_sel_hi:[1,1] neg_lo:[0,1] neg_hi:[0,1]
	v_add_f32_dpp v157, v157, v157 row_ror:2 row_mask:0xf bank_mask:0xf bound_ctrl:1
	v_pk_add_f32 v[184:185], v[184:185], v[118:119] op_sel_hi:[1,0] neg_lo:[0,1] neg_hi:[0,1]
	v_add_f32_dpp v156, v156, v156 row_ror:1 row_mask:0xf bank_mask:0xf bound_ctrl:1
	v_pk_add_f32 v[192:193], v[192:193], v[118:119] op_sel:[0,1] op_sel_hi:[1,1] neg_lo:[0,1] neg_hi:[0,1]
	v_add_f32_dpp v157, v157, v157 row_ror:1 row_mask:0xf bank_mask:0xf bound_ctrl:1
	s_waitcnt lgkmcnt(10)
	v_pk_fma_f32 v[178:179], v[72:73], v[178:179], v[118:119] op_sel_hi:[1,1,0]
	s_and_saveexec_b64 s[8:9], s[38:39]
	ds_write_b32 v103, v156 offset:38016
	ds_write_b32 v103, v157 offset:38080
	s_mov_b64 exec, s[8:9]
	v_pk_fma_f32 v[186:187], v[72:73], v[186:187], v[118:119] op_sel:[0,0,1] op_sel_hi:[1,1,1]
	v_pk_fma_f32 v[180:181], v[74:75], v[180:181], v[118:119] op_sel_hi:[1,1,0]
	v_pk_fma_f32 v[188:189], v[74:75], v[188:189], v[118:119] op_sel:[0,0,1] op_sel_hi:[1,1,1]
	s_waitcnt lgkmcnt(11)
	v_pk_fma_f32 v[182:183], v[76:77], v[182:183], v[118:119] op_sel_hi:[1,1,0]
	v_pk_fma_f32 v[190:191], v[76:77], v[190:191], v[118:119] op_sel:[0,0,1] op_sel_hi:[1,1,1]
	v_pk_fma_f32 v[184:185], v[78:79], v[184:185], v[118:119] op_sel_hi:[1,1,0]
	v_pk_fma_f32 v[192:193], v[78:79], v[192:193], v[118:119] op_sel:[0,0,1] op_sel_hi:[1,1,1]
	s_waitcnt lgkmcnt(10)
	v_pk_fma_f32 v[146:147], v[64:65], v[178:179], v[196:197]
	v_pk_fma_f32 v[150:151], v[64:65], v[186:187], v[196:197]
	v_pk_fma_f32 v[148:149], v[66:67], v[180:181], v[196:197]
	v_pk_fma_f32 v[152:153], v[66:67], v[188:189], v[196:197]
	s_waitcnt lgkmcnt(9)
	v_pk_fma_f32 v[146:147], v[68:69], v[182:183], v[146:147]
	v_pk_fma_f32 v[150:151], v[68:69], v[190:191], v[150:151]
	v_pk_fma_f32 v[148:149], v[70:71], v[184:185], v[148:149]
	v_pk_fma_f32 v[152:153], v[70:71], v[192:193], v[152:153]
	v_add_f32_e32 v146, v146, v147
	v_add_f32_e32 v148, v148, v149
	v_add_f32_e32 v150, v150, v151
	v_add_f32_e32 v152, v152, v153
	v_add_f32_e32 v154, v146, v148
	v_add_f32_e32 v155, v150, v152
	ds_read2_b32 v[118:119], v195 offset0:128 offset1:144
	ds_read_b128 v[72:75], v145 offset:14336
	ds_read_b128 v[76:79], v145 offset:14592
	ds_read_b128 v[64:67], v145 offset:6144
	ds_read_b128 v[68:71], v145 offset:6400
	s_waitcnt lgkmcnt(11)
	v_pk_add_f32 v[178:179], v[178:179], v[120:121] op_sel_hi:[1,0] neg_lo:[0,1] neg_hi:[0,1]
	v_add_f32_dpp v154, v154, v154 row_ror:8 row_mask:0xf bank_mask:0xf bound_ctrl:1
	v_pk_add_f32 v[186:187], v[186:187], v[120:121] op_sel:[0,1] op_sel_hi:[1,1] neg_lo:[0,1] neg_hi:[0,1]
	v_add_f32_dpp v155, v155, v155 row_ror:8 row_mask:0xf bank_mask:0xf bound_ctrl:1
	v_pk_add_f32 v[180:181], v[180:181], v[120:121] op_sel_hi:[1,0] neg_lo:[0,1] neg_hi:[0,1]
	v_add_f32_dpp v154, v154, v154 row_ror:4 row_mask:0xf bank_mask:0xf bound_ctrl:1
	v_pk_add_f32 v[188:189], v[188:189], v[120:121] op_sel:[0,1] op_sel_hi:[1,1] neg_lo:[0,1] neg_hi:[0,1]
	v_add_f32_dpp v155, v155, v155 row_ror:4 row_mask:0xf bank_mask:0xf bound_ctrl:1
	v_pk_add_f32 v[182:183], v[182:183], v[120:121] op_sel_hi:[1,0] neg_lo:[0,1] neg_hi:[0,1]
	v_add_f32_dpp v154, v154, v154 row_ror:2 row_mask:0xf bank_mask:0xf bound_ctrl:1
	v_pk_add_f32 v[190:191], v[190:191], v[120:121] op_sel:[0,1] op_sel_hi:[1,1] neg_lo:[0,1] neg_hi:[0,1]
	v_add_f32_dpp v155, v155, v155 row_ror:2 row_mask:0xf bank_mask:0xf bound_ctrl:1
	v_pk_add_f32 v[184:185], v[184:185], v[120:121] op_sel_hi:[1,0] neg_lo:[0,1] neg_hi:[0,1]
	v_add_f32_dpp v154, v154, v154 row_ror:1 row_mask:0xf bank_mask:0xf bound_ctrl:1
	v_pk_add_f32 v[192:193], v[192:193], v[120:121] op_sel:[0,1] op_sel_hi:[1,1] neg_lo:[0,1] neg_hi:[0,1]
	v_add_f32_dpp v155, v155, v155 row_ror:1 row_mask:0xf bank_mask:0xf bound_ctrl:1
	s_waitcnt lgkmcnt(10)
	v_pk_fma_f32 v[178:179], v[88:89], v[178:179], v[120:121] op_sel_hi:[1,1,0]
	s_and_saveexec_b64 s[8:9], s[38:39]
	ds_write_b32 v103, v154 offset:38144
	ds_write_b32 v103, v155 offset:38208
	s_mov_b64 exec, s[8:9]
	v_pk_fma_f32 v[186:187], v[88:89], v[186:187], v[120:121] op_sel:[0,0,1] op_sel_hi:[1,1,1]
	v_pk_fma_f32 v[180:181], v[90:91], v[180:181], v[120:121] op_sel_hi:[1,1,0]
	v_pk_fma_f32 v[188:189], v[90:91], v[188:189], v[120:121] op_sel:[0,0,1] op_sel_hi:[1,1,1]
	s_waitcnt lgkmcnt(11)
	v_pk_fma_f32 v[182:183], v[92:93], v[182:183], v[120:121] op_sel_hi:[1,1,0]
	v_pk_fma_f32 v[190:191], v[92:93], v[190:191], v[120:121] op_sel:[0,0,1] op_sel_hi:[1,1,1]
	v_pk_fma_f32 v[184:185], v[94:95], v[184:185], v[120:121] op_sel_hi:[1,1,0]
	v_pk_fma_f32 v[192:193], v[94:95], v[192:193], v[120:121] op_sel:[0,0,1] op_sel_hi:[1,1,1]
	s_waitcnt lgkmcnt(10)
	v_pk_fma_f32 v[146:147], v[80:81], v[178:179], v[196:197]
	v_pk_fma_f32 v[150:151], v[80:81], v[186:187], v[196:197]
	v_pk_fma_f32 v[148:149], v[82:83], v[180:181], v[196:197]
	v_pk_fma_f32 v[152:153], v[82:83], v[188:189], v[196:197]
	s_waitcnt lgkmcnt(9)
	v_pk_fma_f32 v[146:147], v[84:85], v[182:183], v[146:147]
	v_pk_fma_f32 v[150:151], v[84:85], v[190:191], v[150:151]
	v_pk_fma_f32 v[148:149], v[86:87], v[184:185], v[148:149]
	v_pk_fma_f32 v[152:153], v[86:87], v[192:193], v[152:153]
	v_add_f32_e32 v146, v146, v147
	v_add_f32_e32 v148, v148, v149
	v_add_f32_e32 v150, v150, v151
	v_add_f32_e32 v152, v152, v153
	v_add_f32_e32 v156, v146, v148
	v_add_f32_e32 v157, v150, v152
	ds_read2_b32 v[120:121], v195 offset0:160 offset1:176
	ds_read_b128 v[88:91], v145 offset:14848
	ds_read_b128 v[92:95], v145 offset:15104
	ds_read_b128 v[80:83], v145 offset:6656
	ds_read_b128 v[84:87], v145 offset:6912
	s_waitcnt lgkmcnt(11)
	v_pk_add_f32 v[178:179], v[178:179], v[118:119] op_sel_hi:[1,0] neg_lo:[0,1] neg_hi:[0,1]
	v_add_f32_dpp v156, v156, v156 row_ror:8 row_mask:0xf bank_mask:0xf bound_ctrl:1
	v_pk_add_f32 v[186:187], v[186:187], v[118:119] op_sel:[0,1] op_sel_hi:[1,1] neg_lo:[0,1] neg_hi:[0,1]
	v_add_f32_dpp v157, v157, v157 row_ror:8 row_mask:0xf bank_mask:0xf bound_ctrl:1
	v_pk_add_f32 v[180:181], v[180:181], v[118:119] op_sel_hi:[1,0] neg_lo:[0,1] neg_hi:[0,1]
	v_add_f32_dpp v156, v156, v156 row_ror:4 row_mask:0xf bank_mask:0xf bound_ctrl:1
	v_pk_add_f32 v[188:189], v[188:189], v[118:119] op_sel:[0,1] op_sel_hi:[1,1] neg_lo:[0,1] neg_hi:[0,1]
	v_add_f32_dpp v157, v157, v157 row_ror:4 row_mask:0xf bank_mask:0xf bound_ctrl:1
	v_pk_add_f32 v[182:183], v[182:183], v[118:119] op_sel_hi:[1,0] neg_lo:[0,1] neg_hi:[0,1]
	v_add_f32_dpp v156, v156, v156 row_ror:2 row_mask:0xf bank_mask:0xf bound_ctrl:1
	v_pk_add_f32 v[190:191], v[190:191], v[118:119] op_sel:[0,1] op_sel_hi:[1,1] neg_lo:[0,1] neg_hi:[0,1]
	v_add_f32_dpp v157, v157, v157 row_ror:2 row_mask:0xf bank_mask:0xf bound_ctrl:1
	v_pk_add_f32 v[184:185], v[184:185], v[118:119] op_sel_hi:[1,0] neg_lo:[0,1] neg_hi:[0,1]
	v_add_f32_dpp v156, v156, v156 row_ror:1 row_mask:0xf bank_mask:0xf bound_ctrl:1
	v_pk_add_f32 v[192:193], v[192:193], v[118:119] op_sel:[0,1] op_sel_hi:[1,1] neg_lo:[0,1] neg_hi:[0,1]
	v_add_f32_dpp v157, v157, v157 row_ror:1 row_mask:0xf bank_mask:0xf bound_ctrl:1
	s_waitcnt lgkmcnt(10)
	v_pk_fma_f32 v[178:179], v[72:73], v[178:179], v[118:119] op_sel_hi:[1,1,0]
	s_and_saveexec_b64 s[8:9], s[38:39]
	ds_write_b32 v103, v156 offset:38272
	ds_write_b32 v103, v157 offset:38336
	s_mov_b64 exec, s[8:9]
	v_pk_fma_f32 v[186:187], v[72:73], v[186:187], v[118:119] op_sel:[0,0,1] op_sel_hi:[1,1,1]
	v_pk_fma_f32 v[180:181], v[74:75], v[180:181], v[118:119] op_sel_hi:[1,1,0]
	v_pk_fma_f32 v[188:189], v[74:75], v[188:189], v[118:119] op_sel:[0,0,1] op_sel_hi:[1,1,1]
	s_waitcnt lgkmcnt(11)
	v_pk_fma_f32 v[182:183], v[76:77], v[182:183], v[118:119] op_sel_hi:[1,1,0]
	v_pk_fma_f32 v[190:191], v[76:77], v[190:191], v[118:119] op_sel:[0,0,1] op_sel_hi:[1,1,1]
	v_pk_fma_f32 v[184:185], v[78:79], v[184:185], v[118:119] op_sel_hi:[1,1,0]
	v_pk_fma_f32 v[192:193], v[78:79], v[192:193], v[118:119] op_sel:[0,0,1] op_sel_hi:[1,1,1]
	s_waitcnt lgkmcnt(10)
	v_pk_fma_f32 v[146:147], v[64:65], v[178:179], v[196:197]
	v_pk_fma_f32 v[150:151], v[64:65], v[186:187], v[196:197]
	v_pk_fma_f32 v[148:149], v[66:67], v[180:181], v[196:197]
	v_pk_fma_f32 v[152:153], v[66:67], v[188:189], v[196:197]
	s_waitcnt lgkmcnt(9)
	v_pk_fma_f32 v[146:147], v[68:69], v[182:183], v[146:147]
	v_pk_fma_f32 v[150:151], v[68:69], v[190:191], v[150:151]
	v_pk_fma_f32 v[148:149], v[70:71], v[184:185], v[148:149]
	v_pk_fma_f32 v[152:153], v[70:71], v[192:193], v[152:153]
	v_add_f32_e32 v146, v146, v147
	v_add_f32_e32 v148, v148, v149
	v_add_f32_e32 v150, v150, v151
	v_add_f32_e32 v152, v152, v153
	v_add_f32_e32 v154, v146, v148
	v_add_f32_e32 v155, v150, v152
	ds_read2_b32 v[118:119], v195 offset0:192 offset1:208
	ds_read_b128 v[72:75], v145 offset:15360
	ds_read_b128 v[76:79], v145 offset:15616
	ds_read_b128 v[64:67], v145 offset:7168
	ds_read_b128 v[68:71], v145 offset:7424
	s_waitcnt lgkmcnt(11)
	v_pk_add_f32 v[178:179], v[178:179], v[120:121] op_sel_hi:[1,0] neg_lo:[0,1] neg_hi:[0,1]
	v_add_f32_dpp v154, v154, v154 row_ror:8 row_mask:0xf bank_mask:0xf bound_ctrl:1
	v_pk_add_f32 v[186:187], v[186:187], v[120:121] op_sel:[0,1] op_sel_hi:[1,1] neg_lo:[0,1] neg_hi:[0,1]
	v_add_f32_dpp v155, v155, v155 row_ror:8 row_mask:0xf bank_mask:0xf bound_ctrl:1
	v_pk_add_f32 v[180:181], v[180:181], v[120:121] op_sel_hi:[1,0] neg_lo:[0,1] neg_hi:[0,1]
	v_add_f32_dpp v154, v154, v154 row_ror:4 row_mask:0xf bank_mask:0xf bound_ctrl:1
	v_pk_add_f32 v[188:189], v[188:189], v[120:121] op_sel:[0,1] op_sel_hi:[1,1] neg_lo:[0,1] neg_hi:[0,1]
	v_add_f32_dpp v155, v155, v155 row_ror:4 row_mask:0xf bank_mask:0xf bound_ctrl:1
	v_pk_add_f32 v[182:183], v[182:183], v[120:121] op_sel_hi:[1,0] neg_lo:[0,1] neg_hi:[0,1]
	v_add_f32_dpp v154, v154, v154 row_ror:2 row_mask:0xf bank_mask:0xf bound_ctrl:1
	v_pk_add_f32 v[190:191], v[190:191], v[120:121] op_sel:[0,1] op_sel_hi:[1,1] neg_lo:[0,1] neg_hi:[0,1]
	v_add_f32_dpp v155, v155, v155 row_ror:2 row_mask:0xf bank_mask:0xf bound_ctrl:1
	v_pk_add_f32 v[184:185], v[184:185], v[120:121] op_sel_hi:[1,0] neg_lo:[0,1] neg_hi:[0,1]
	v_add_f32_dpp v154, v154, v154 row_ror:1 row_mask:0xf bank_mask:0xf bound_ctrl:1
	v_pk_add_f32 v[192:193], v[192:193], v[120:121] op_sel:[0,1] op_sel_hi:[1,1] neg_lo:[0,1] neg_hi:[0,1]
	v_add_f32_dpp v155, v155, v155 row_ror:1 row_mask:0xf bank_mask:0xf bound_ctrl:1
	s_waitcnt lgkmcnt(10)
	v_pk_fma_f32 v[178:179], v[88:89], v[178:179], v[120:121] op_sel_hi:[1,1,0]
	s_and_saveexec_b64 s[8:9], s[38:39]
	ds_write_b32 v103, v154 offset:38400
	ds_write_b32 v103, v155 offset:38464
	s_mov_b64 exec, s[8:9]
	v_pk_fma_f32 v[186:187], v[88:89], v[186:187], v[120:121] op_sel:[0,0,1] op_sel_hi:[1,1,1]
	v_pk_fma_f32 v[180:181], v[90:91], v[180:181], v[120:121] op_sel_hi:[1,1,0]
	v_pk_fma_f32 v[188:189], v[90:91], v[188:189], v[120:121] op_sel:[0,0,1] op_sel_hi:[1,1,1]
	s_waitcnt lgkmcnt(11)
	v_pk_fma_f32 v[182:183], v[92:93], v[182:183], v[120:121] op_sel_hi:[1,1,0]
	v_pk_fma_f32 v[190:191], v[92:93], v[190:191], v[120:121] op_sel:[0,0,1] op_sel_hi:[1,1,1]
	v_pk_fma_f32 v[184:185], v[94:95], v[184:185], v[120:121] op_sel_hi:[1,1,0]
	v_pk_fma_f32 v[192:193], v[94:95], v[192:193], v[120:121] op_sel:[0,0,1] op_sel_hi:[1,1,1]
	s_waitcnt lgkmcnt(10)
	v_pk_fma_f32 v[146:147], v[80:81], v[178:179], v[196:197]
	v_pk_fma_f32 v[150:151], v[80:81], v[186:187], v[196:197]
	v_pk_fma_f32 v[148:149], v[82:83], v[180:181], v[196:197]
	v_pk_fma_f32 v[152:153], v[82:83], v[188:189], v[196:197]
	s_waitcnt lgkmcnt(9)
	v_pk_fma_f32 v[146:147], v[84:85], v[182:183], v[146:147]
	v_pk_fma_f32 v[150:151], v[84:85], v[190:191], v[150:151]
	v_pk_fma_f32 v[148:149], v[86:87], v[184:185], v[148:149]
	v_pk_fma_f32 v[152:153], v[86:87], v[192:193], v[152:153]
	v_add_f32_e32 v146, v146, v147
	v_add_f32_e32 v148, v148, v149
	v_add_f32_e32 v150, v150, v151
	v_add_f32_e32 v152, v152, v153
	v_add_f32_e32 v156, v146, v148
	v_add_f32_e32 v157, v150, v152
	ds_read2_b32 v[120:121], v195 offset0:224 offset1:240
	ds_read_b128 v[88:91], v145 offset:15872
	ds_read_b128 v[92:95], v145 offset:16128
	ds_read_b128 v[80:83], v145 offset:7680
	ds_read_b128 v[84:87], v145 offset:7936
	s_waitcnt lgkmcnt(11)
	v_pk_add_f32 v[178:179], v[178:179], v[118:119] op_sel_hi:[1,0] neg_lo:[0,1] neg_hi:[0,1]
	v_add_f32_dpp v156, v156, v156 row_ror:8 row_mask:0xf bank_mask:0xf bound_ctrl:1
	v_pk_add_f32 v[186:187], v[186:187], v[118:119] op_sel:[0,1] op_sel_hi:[1,1] neg_lo:[0,1] neg_hi:[0,1]
	v_add_f32_dpp v157, v157, v157 row_ror:8 row_mask:0xf bank_mask:0xf bound_ctrl:1
	v_pk_add_f32 v[180:181], v[180:181], v[118:119] op_sel_hi:[1,0] neg_lo:[0,1] neg_hi:[0,1]
	v_add_f32_dpp v156, v156, v156 row_ror:4 row_mask:0xf bank_mask:0xf bound_ctrl:1
	v_pk_add_f32 v[188:189], v[188:189], v[118:119] op_sel:[0,1] op_sel_hi:[1,1] neg_lo:[0,1] neg_hi:[0,1]
	v_add_f32_dpp v157, v157, v157 row_ror:4 row_mask:0xf bank_mask:0xf bound_ctrl:1
	v_pk_add_f32 v[182:183], v[182:183], v[118:119] op_sel_hi:[1,0] neg_lo:[0,1] neg_hi:[0,1]
	v_add_f32_dpp v156, v156, v156 row_ror:2 row_mask:0xf bank_mask:0xf bound_ctrl:1
	v_pk_add_f32 v[190:191], v[190:191], v[118:119] op_sel:[0,1] op_sel_hi:[1,1] neg_lo:[0,1] neg_hi:[0,1]
	v_add_f32_dpp v157, v157, v157 row_ror:2 row_mask:0xf bank_mask:0xf bound_ctrl:1
	v_pk_add_f32 v[184:185], v[184:185], v[118:119] op_sel_hi:[1,0] neg_lo:[0,1] neg_hi:[0,1]
	v_add_f32_dpp v156, v156, v156 row_ror:1 row_mask:0xf bank_mask:0xf bound_ctrl:1
	v_pk_add_f32 v[192:193], v[192:193], v[118:119] op_sel:[0,1] op_sel_hi:[1,1] neg_lo:[0,1] neg_hi:[0,1]
	v_add_f32_dpp v157, v157, v157 row_ror:1 row_mask:0xf bank_mask:0xf bound_ctrl:1
	s_waitcnt lgkmcnt(10)
	v_pk_fma_f32 v[178:179], v[72:73], v[178:179], v[118:119] op_sel_hi:[1,1,0]
	s_and_saveexec_b64 s[8:9], s[38:39]
	ds_write_b32 v103, v156 offset:38528
	ds_write_b32 v103, v157 offset:38592
	s_mov_b64 exec, s[8:9]
	v_pk_fma_f32 v[186:187], v[72:73], v[186:187], v[118:119] op_sel:[0,0,1] op_sel_hi:[1,1,1]
	v_pk_fma_f32 v[180:181], v[74:75], v[180:181], v[118:119] op_sel_hi:[1,1,0]
	v_pk_fma_f32 v[188:189], v[74:75], v[188:189], v[118:119] op_sel:[0,0,1] op_sel_hi:[1,1,1]
	s_waitcnt lgkmcnt(11)
	v_pk_fma_f32 v[182:183], v[76:77], v[182:183], v[118:119] op_sel_hi:[1,1,0]
	v_pk_fma_f32 v[190:191], v[76:77], v[190:191], v[118:119] op_sel:[0,0,1] op_sel_hi:[1,1,1]
	v_pk_fma_f32 v[184:185], v[78:79], v[184:185], v[118:119] op_sel_hi:[1,1,0]
	v_pk_fma_f32 v[192:193], v[78:79], v[192:193], v[118:119] op_sel:[0,0,1] op_sel_hi:[1,1,1]
	s_waitcnt lgkmcnt(10)
	v_pk_fma_f32 v[146:147], v[64:65], v[178:179], v[196:197]
	v_pk_fma_f32 v[150:151], v[64:65], v[186:187], v[196:197]
	v_pk_fma_f32 v[148:149], v[66:67], v[180:181], v[196:197]
	v_pk_fma_f32 v[152:153], v[66:67], v[188:189], v[196:197]
	s_waitcnt lgkmcnt(9)
	v_pk_fma_f32 v[146:147], v[68:69], v[182:183], v[146:147]
	v_pk_fma_f32 v[150:151], v[68:69], v[190:191], v[150:151]
	v_pk_fma_f32 v[148:149], v[70:71], v[184:185], v[148:149]
	v_pk_fma_f32 v[152:153], v[70:71], v[192:193], v[152:153]
	v_add_f32_e32 v146, v146, v147
	v_add_f32_e32 v148, v148, v149
	v_add_f32_e32 v150, v150, v151
	v_add_f32_e32 v152, v152, v153
	v_add_f32_e32 v154, v146, v148
	v_add_f32_e32 v155, v150, v152
	s_waitcnt lgkmcnt(6)
	v_pk_add_f32 v[178:179], v[178:179], v[120:121] op_sel_hi:[1,0] neg_lo:[0,1] neg_hi:[0,1]
	v_add_f32_dpp v154, v154, v154 row_ror:8 row_mask:0xf bank_mask:0xf bound_ctrl:1
	v_pk_add_f32 v[186:187], v[186:187], v[120:121] op_sel:[0,1] op_sel_hi:[1,1] neg_lo:[0,1] neg_hi:[0,1]
	v_add_f32_dpp v155, v155, v155 row_ror:8 row_mask:0xf bank_mask:0xf bound_ctrl:1
	v_pk_add_f32 v[180:181], v[180:181], v[120:121] op_sel_hi:[1,0] neg_lo:[0,1] neg_hi:[0,1]
	v_add_f32_dpp v154, v154, v154 row_ror:4 row_mask:0xf bank_mask:0xf bound_ctrl:1
	v_pk_add_f32 v[188:189], v[188:189], v[120:121] op_sel:[0,1] op_sel_hi:[1,1] neg_lo:[0,1] neg_hi:[0,1]
	v_add_f32_dpp v155, v155, v155 row_ror:4 row_mask:0xf bank_mask:0xf bound_ctrl:1
	v_pk_add_f32 v[182:183], v[182:183], v[120:121] op_sel_hi:[1,0] neg_lo:[0,1] neg_hi:[0,1]
	v_add_f32_dpp v154, v154, v154 row_ror:2 row_mask:0xf bank_mask:0xf bound_ctrl:1
	v_pk_add_f32 v[190:191], v[190:191], v[120:121] op_sel:[0,1] op_sel_hi:[1,1] neg_lo:[0,1] neg_hi:[0,1]
	v_add_f32_dpp v155, v155, v155 row_ror:2 row_mask:0xf bank_mask:0xf bound_ctrl:1
	v_pk_add_f32 v[184:185], v[184:185], v[120:121] op_sel_hi:[1,0] neg_lo:[0,1] neg_hi:[0,1]
	v_add_f32_dpp v154, v154, v154 row_ror:1 row_mask:0xf bank_mask:0xf bound_ctrl:1
	v_pk_add_f32 v[192:193], v[192:193], v[120:121] op_sel:[0,1] op_sel_hi:[1,1] neg_lo:[0,1] neg_hi:[0,1]
	v_add_f32_dpp v155, v155, v155 row_ror:1 row_mask:0xf bank_mask:0xf bound_ctrl:1
	s_waitcnt lgkmcnt(5)
	v_pk_fma_f32 v[178:179], v[88:89], v[178:179], v[120:121] op_sel_hi:[1,1,0]
	s_and_saveexec_b64 s[8:9], s[38:39]
	ds_write_b32 v103, v154 offset:38656
	ds_write_b32 v103, v155 offset:38720
	s_mov_b64 exec, s[8:9]
	v_pk_fma_f32 v[186:187], v[88:89], v[186:187], v[120:121] op_sel:[0,0,1] op_sel_hi:[1,1,1]
	v_pk_fma_f32 v[180:181], v[90:91], v[180:181], v[120:121] op_sel_hi:[1,1,0]
	v_pk_fma_f32 v[188:189], v[90:91], v[188:189], v[120:121] op_sel:[0,0,1] op_sel_hi:[1,1,1]
	s_waitcnt lgkmcnt(6)
	v_pk_fma_f32 v[182:183], v[92:93], v[182:183], v[120:121] op_sel_hi:[1,1,0]
	v_pk_fma_f32 v[190:191], v[92:93], v[190:191], v[120:121] op_sel:[0,0,1] op_sel_hi:[1,1,1]
	v_pk_fma_f32 v[184:185], v[94:95], v[184:185], v[120:121] op_sel_hi:[1,1,0]
	v_pk_fma_f32 v[192:193], v[94:95], v[192:193], v[120:121] op_sel:[0,0,1] op_sel_hi:[1,1,1]
	s_waitcnt lgkmcnt(5)
	v_pk_fma_f32 v[146:147], v[80:81], v[178:179], v[196:197]
	v_pk_fma_f32 v[150:151], v[80:81], v[186:187], v[196:197]
	v_pk_fma_f32 v[148:149], v[82:83], v[180:181], v[196:197]
	v_pk_fma_f32 v[152:153], v[82:83], v[188:189], v[196:197]
	s_waitcnt lgkmcnt(4)
	v_pk_fma_f32 v[146:147], v[84:85], v[182:183], v[146:147]
	v_pk_fma_f32 v[150:151], v[84:85], v[190:191], v[150:151]
	v_pk_fma_f32 v[148:149], v[86:87], v[184:185], v[148:149]
	v_pk_fma_f32 v[152:153], v[86:87], v[192:193], v[152:153]
	v_add_f32_e32 v146, v146, v147
	v_add_f32_e32 v148, v148, v149
	v_add_f32_e32 v150, v150, v151
	v_add_f32_e32 v152, v152, v153
	v_add_f32_e32 v156, v146, v148
	v_add_f32_e32 v157, v150, v152
	s_nop 0
	v_add_f32_dpp v156, v156, v156 row_ror:8 row_mask:0xf bank_mask:0xf bound_ctrl:1
	v_add_f32_dpp v157, v157, v157 row_ror:8 row_mask:0xf bank_mask:0xf bound_ctrl:1
	s_nop 0
	v_add_f32_dpp v156, v156, v156 row_ror:4 row_mask:0xf bank_mask:0xf bound_ctrl:1
	v_add_f32_dpp v157, v157, v157 row_ror:4 row_mask:0xf bank_mask:0xf bound_ctrl:1
	s_nop 0
	v_add_f32_dpp v156, v156, v156 row_ror:2 row_mask:0xf bank_mask:0xf bound_ctrl:1
	v_add_f32_dpp v157, v157, v157 row_ror:2 row_mask:0xf bank_mask:0xf bound_ctrl:1
	s_nop 0
	v_add_f32_dpp v156, v156, v156 row_ror:1 row_mask:0xf bank_mask:0xf bound_ctrl:1
	v_add_f32_dpp v157, v157, v157 row_ror:1 row_mask:0xf bank_mask:0xf bound_ctrl:1
	s_and_saveexec_b64 s[8:9], s[38:39]
	ds_write_b32 v103, v156 offset:38784
	ds_write_b32 v103, v157 offset:38848
	s_mov_b64 exec, s[8:9]
	s_waitcnt vmcnt(9)
	v_mul_f32_e32 v64, 0xbfb8aa3b, v16
	v_mul_f32_e32 v65, 0xbfb8aa3b, v17
	v_exp_f32_e32 v64, v64
	v_exp_f32_e32 v65, v65
	v_mul_f32_e32 v66, 0xbfb8aa3b, v18
	v_mul_f32_e32 v67, 0xbfb8aa3b, v19
	v_exp_f32_e32 v66, v66
	v_pk_add_f32 v[64:65], v[64:65], 1.0 op_sel_hi:[1,0]
	v_exp_f32_e32 v67, v67
	v_div_scale_f32 v76, s[8:9], v65, v65, v17
	v_rcp_f32_e32 v77, v76
	v_pk_add_f32 v[66:67], v[66:67], 1.0 op_sel_hi:[1,0]
	s_waitcnt vmcnt(8)
	v_mul_f32_e32 v72, 0xbfb8aa3b, v20
	v_mul_f32_e32 v73, 0xbfb8aa3b, v21
	v_fma_f32 v78, -v76, v77, 1.0
	v_fmac_f32_e32 v77, v78, v77
	v_div_scale_f32 v78, vcc, v17, v65, v17
	v_mul_f32_e32 v79, v78, v77
	v_fma_f32 v80, -v76, v79, v78
	v_fmac_f32_e32 v79, v80, v77
	v_fma_f32 v76, -v76, v79, v78
	v_div_fmas_f32 v76, v76, v77, v79
	v_div_fixup_f32 v65, v76, v65, v17
	v_div_scale_f32 v76, s[8:9], v64, v64, v16
	v_rcp_f32_e32 v77, v76
	v_exp_f32_e32 v72, v72
	v_exp_f32_e32 v73, v73
	v_mul_f32_e32 v74, 0xbfb8aa3b, v22
	v_fma_f32 v78, -v76, v77, 1.0
	v_fmac_f32_e32 v77, v78, v77
	v_div_scale_f32 v78, vcc, v16, v64, v16
	v_mul_f32_e32 v79, v78, v77
	v_fma_f32 v80, -v76, v79, v78
	v_fmac_f32_e32 v79, v80, v77
	v_fma_f32 v76, -v76, v79, v78
	v_div_fmas_f32 v76, v76, v77, v79
	v_div_fixup_f32 v64, v76, v64, v16
	v_div_scale_f32 v76, s[8:9], v67, v67, v19
	v_rcp_f32_e32 v77, v76
	v_pk_mul_f32 v[64:65], v[64:65], s[18:19] op_sel_hi:[1,0]
	v_mul_f32_e32 v75, 0xbfb8aa3b, v23
	v_exp_f32_e32 v74, v74
	v_fma_f32 v78, -v76, v77, 1.0
	v_fmac_f32_e32 v77, v78, v77
	v_div_scale_f32 v78, vcc, v19, v67, v19
	v_mul_f32_e32 v79, v78, v77
	v_fma_f32 v80, -v76, v79, v78
	v_fmac_f32_e32 v79, v80, v77
	v_fma_f32 v76, -v76, v79, v78
	v_div_fmas_f32 v76, v76, v77, v79
	v_div_fixup_f32 v67, v76, v67, v19
	v_div_scale_f32 v76, s[8:9], v66, v66, v18
	v_rcp_f32_e32 v77, v76
	v_exp_f32_e32 v75, v75
	s_cmpk_lt_u32 s48, 0x7b
	v_fma_f32 v78, -v76, v77, 1.0
	v_fmac_f32_e32 v77, v78, v77
	v_div_scale_f32 v78, vcc, v18, v66, v18
	v_mul_f32_e32 v79, v78, v77
	v_fma_f32 v80, -v76, v79, v78
	v_fmac_f32_e32 v79, v80, v77
	v_fma_f32 v76, -v76, v79, v78
	v_div_fmas_f32 v76, v76, v77, v79
	v_div_fixup_f32 v66, v76, v66, v18
	v_pk_mul_f32 v[66:67], v[66:67], s[18:19] op_sel_hi:[1,0]
	ds_write_b128 v141, v[64:67] offset:18432
	v_pk_add_f32 v[64:65], v[72:73], 1.0 op_sel_hi:[1,0]
	v_div_scale_f32 v66, s[8:9], v65, v65, 1.0
	v_rcp_f32_e32 v67, v66
	s_nop 0
	v_fma_f32 v72, -v66, v67, 1.0
	v_fmac_f32_e32 v67, v72, v67
	v_div_scale_f32 v72, vcc, 1.0, v65, 1.0
	v_mul_f32_e32 v73, v72, v67
	v_fma_f32 v76, -v66, v73, v72
	v_fmac_f32_e32 v73, v76, v67
	v_fma_f32 v66, -v66, v73, v72
	v_div_fmas_f32 v66, v66, v67, v73
	v_div_fixup_f32 v65, v66, v65, 1.0
	v_div_scale_f32 v66, s[8:9], v64, v64, 1.0
	v_rcp_f32_e32 v67, v66
	s_nop 0
	v_fma_f32 v72, -v66, v67, 1.0
	v_fmac_f32_e32 v67, v72, v67
	v_div_scale_f32 v72, vcc, 1.0, v64, 1.0
	v_mul_f32_e32 v73, v72, v67
	v_fma_f32 v76, -v66, v73, v72
	v_fmac_f32_e32 v73, v76, v67
	v_fma_f32 v66, -v66, v73, v72
	v_div_fmas_f32 v66, v66, v67, v73
	v_div_fixup_f32 v64, v66, v64, 1.0
	v_pk_add_f32 v[66:67], v[74:75], 1.0 op_sel_hi:[1,0]
	v_pk_fma_f32 v[64:65], v[110:111], v[64:65], v[104:105]
	v_div_scale_f32 v72, s[8:9], v67, v67, 1.0
	v_rcp_f32_e32 v73, v72
	s_nop 0
	v_fma_f32 v74, -v72, v73, 1.0
	v_fmac_f32_e32 v73, v74, v73
	v_div_scale_f32 v74, vcc, 1.0, v67, 1.0
	v_mul_f32_e32 v75, v74, v73
	v_fma_f32 v76, -v72, v75, v74
	v_fmac_f32_e32 v75, v76, v73
	v_fma_f32 v72, -v72, v75, v74
	v_div_fmas_f32 v72, v72, v73, v75
	v_div_fixup_f32 v67, v72, v67, 1.0
	v_div_scale_f32 v72, s[8:9], v66, v66, 1.0
	v_rcp_f32_e32 v73, v72
	s_nop 0
	v_fma_f32 v74, -v72, v73, 1.0
	v_fmac_f32_e32 v73, v74, v73
	v_div_scale_f32 v74, vcc, 1.0, v66, 1.0
	v_mul_f32_e32 v75, v74, v73
	v_fma_f32 v76, -v72, v75, v74
	v_fmac_f32_e32 v75, v76, v73
	v_fma_f32 v72, -v72, v75, v74
	v_div_fmas_f32 v72, v72, v73, v75
	v_div_fixup_f32 v66, v72, v66, 1.0
	v_pk_fma_f32 v[66:67], v[112:113], v[66:67], v[106:107]
	ds_write_b128 v141, v[64:67] offset:26624
	ds_write_b32 v134, v129 offset:34816
	v_mul_f32_e32 v64, 0xbfb8aa3b, v24
	v_mul_f32_e32 v65, 0xbfb8aa3b, v25
	v_exp_f32_e32 v64, v64
	v_exp_f32_e32 v65, v65
	v_mul_f32_e32 v66, 0xbfb8aa3b, v26
	v_mul_f32_e32 v67, 0xbfb8aa3b, v27
	v_exp_f32_e32 v66, v66
	v_pk_add_f32 v[64:65], v[64:65], 1.0 op_sel_hi:[1,0]
	v_exp_f32_e32 v67, v67
	v_div_scale_f32 v76, s[8:9], v65, v65, v25
	v_rcp_f32_e32 v77, v76
	v_pk_add_f32 v[66:67], v[66:67], 1.0 op_sel_hi:[1,0]
	v_mul_f32_e32 v72, 0xbfb8aa3b, v36
	v_mul_f32_e32 v73, 0xbfb8aa3b, v37
	v_fma_f32 v78, -v76, v77, 1.0
	v_fmac_f32_e32 v77, v78, v77
	v_div_scale_f32 v78, vcc, v25, v65, v25
	v_mul_f32_e32 v79, v78, v77
	v_fma_f32 v80, -v76, v79, v78
	v_fmac_f32_e32 v79, v80, v77
	v_fma_f32 v76, -v76, v79, v78
	v_div_fmas_f32 v76, v76, v77, v79
	v_div_fixup_f32 v65, v76, v65, v25
	v_div_scale_f32 v76, s[8:9], v64, v64, v24
	v_rcp_f32_e32 v77, v76
	v_exp_f32_e32 v72, v72
	v_exp_f32_e32 v73, v73
	v_mul_f32_e32 v74, 0xbfb8aa3b, v38
	v_fma_f32 v78, -v76, v77, 1.0
	v_fmac_f32_e32 v77, v78, v77
	v_div_scale_f32 v78, vcc, v24, v64, v24
	v_mul_f32_e32 v79, v78, v77
	v_fma_f32 v80, -v76, v79, v78
	v_fmac_f32_e32 v79, v80, v77
	v_fma_f32 v76, -v76, v79, v78
	v_div_fmas_f32 v76, v76, v77, v79
	v_div_fixup_f32 v64, v76, v64, v24
	v_div_scale_f32 v76, s[8:9], v67, v67, v27
	v_rcp_f32_e32 v77, v76
	v_pk_mul_f32 v[64:65], v[64:65], s[18:19] op_sel_hi:[1,0]
	v_mul_f32_e32 v75, 0xbfb8aa3b, v39
	v_exp_f32_e32 v74, v74
	v_fma_f32 v78, -v76, v77, 1.0
	v_fmac_f32_e32 v77, v78, v77
	v_div_scale_f32 v78, vcc, v27, v67, v27
	v_mul_f32_e32 v79, v78, v77
	v_fma_f32 v80, -v76, v79, v78
	v_fmac_f32_e32 v79, v80, v77
	v_fma_f32 v76, -v76, v79, v78
	v_div_fmas_f32 v76, v76, v77, v79
	v_div_fixup_f32 v67, v76, v67, v27
	v_div_scale_f32 v76, s[8:9], v66, v66, v26
	v_rcp_f32_e32 v77, v76
	v_exp_f32_e32 v75, v75
	v_fma_f32 v78, -v76, v77, 1.0
	v_fmac_f32_e32 v77, v78, v77
	v_div_scale_f32 v78, vcc, v26, v66, v26
	v_mul_f32_e32 v79, v78, v77
	v_fma_f32 v80, -v76, v79, v78
	v_fmac_f32_e32 v79, v80, v77
	v_fma_f32 v76, -v76, v79, v78
	v_div_fmas_f32 v76, v76, v77, v79
	v_div_fixup_f32 v66, v76, v66, v26
	v_pk_mul_f32 v[66:67], v[66:67], s[18:19] op_sel_hi:[1,0]
	ds_write_b128 v144, v[64:67] offset:18432
	v_pk_add_f32 v[64:65], v[72:73], 1.0 op_sel_hi:[1,0]
	v_div_scale_f32 v66, s[8:9], v65, v65, 1.0
	v_rcp_f32_e32 v67, v66
	s_nop 0
	v_fma_f32 v72, -v66, v67, 1.0
	v_fmac_f32_e32 v67, v72, v67
	v_div_scale_f32 v72, vcc, 1.0, v65, 1.0
	v_mul_f32_e32 v73, v72, v67
	v_fma_f32 v76, -v66, v73, v72
	v_fmac_f32_e32 v73, v76, v67
	v_fma_f32 v66, -v66, v73, v72
	v_div_fmas_f32 v66, v66, v67, v73
	v_div_fixup_f32 v65, v66, v65, 1.0
	v_div_scale_f32 v66, s[8:9], v64, v64, 1.0
	v_rcp_f32_e32 v67, v66
	s_nop 0
	v_fma_f32 v72, -v66, v67, 1.0
	v_fmac_f32_e32 v67, v72, v67
	v_div_scale_f32 v72, vcc, 1.0, v64, 1.0
	v_mul_f32_e32 v73, v72, v67
	v_fma_f32 v76, -v66, v73, v72
	v_fmac_f32_e32 v73, v76, v67
	v_fma_f32 v66, -v66, v73, v72
	v_div_fmas_f32 v66, v66, v67, v73
	v_div_fixup_f32 v64, v66, v64, 1.0
	v_pk_add_f32 v[66:67], v[74:75], 1.0 op_sel_hi:[1,0]
	v_pk_fma_f32 v[64:65], v[110:111], v[64:65], v[104:105]
	v_div_scale_f32 v72, s[8:9], v67, v67, 1.0
	v_rcp_f32_e32 v73, v72
	s_nop 0
	v_fma_f32 v74, -v72, v73, 1.0
	v_fmac_f32_e32 v73, v74, v73
	v_div_scale_f32 v74, vcc, 1.0, v67, 1.0
	v_mul_f32_e32 v75, v74, v73
	v_fma_f32 v76, -v72, v75, v74
	v_fmac_f32_e32 v75, v76, v73
	v_fma_f32 v72, -v72, v75, v74
	v_div_fmas_f32 v72, v72, v73, v75
	v_div_fixup_f32 v67, v72, v67, 1.0
	v_div_scale_f32 v72, s[8:9], v66, v66, 1.0
	v_rcp_f32_e32 v73, v72
	s_mov_b64 s[8:9], -1
	v_fma_f32 v74, -v72, v73, 1.0
	v_fmac_f32_e32 v73, v74, v73
	v_div_scale_f32 v74, vcc, 1.0, v66, 1.0
	v_mul_f32_e32 v75, v74, v73
	v_fma_f32 v76, -v72, v75, v74
	v_fmac_f32_e32 v75, v76, v73
	v_fma_f32 v72, -v72, v75, v74
	v_div_fmas_f32 v72, v72, v73, v75
	v_div_fixup_f32 v66, v72, v66, 1.0
	v_pk_fma_f32 v[66:67], v[112:113], v[66:67], v[106:107]
	ds_write_b128 v144, v[64:67] offset:26624
	ds_write_b32 v134, v130 offset:35840
	s_waitcnt lgkmcnt(0)
	s_barrier
	v_add_u32_e32 v64, s47, v124
	v_add_u32_e32 v65, s47, v126
	s_cbranch_scc1 .LBB0_1323
	v_add_u32_e32 v98, s47, v124
	v_add_u32_e32 v96, s47, v126
	s_mov_b64 s[8:9], 0

.LBB0_1325:
	ds_read2st64_b32 v[64:65], v134 offset0:144 offset1:148
	v_ashrrev_i32_e32 v99, 31, v98
	v_lshlrev_b64 v[66:67], 12, v[98:99]
	v_ashrrev_i32_e32 v97, 31, v96
	v_lshl_add_u64 v[66:67], v[108:109], 0, v[66:67]
	s_waitcnt lgkmcnt(0)
	global_store_dword v[66:67], v64, off
	v_lshlrev_b64 v[66:67], 12, v[96:97]
	v_lshl_add_u64 v[66:67], v[108:109], 0, v[66:67]
	global_store_dword v[66:67], v65, off
	v_mov_b32_e32 v196, 0
	v_mov_b32_e32 v197, 0
	v_add_u32_e32 v194, 0x8800, v103
	v_add_u32_e32 v195, 0x8c00, v103
	ds_read2_b32 v[118:119], v194 offset0:0 offset1:16
	ds_read_b128 v[72:75], v145 offset:26624
	ds_read_b128 v[76:79], v145 offset:26880
	ds_read_b128 v[64:67], v145 offset:18432
	ds_read_b128 v[68:71], v145 offset:18688
	ds_read2_b32 v[120:121], v194 offset0:32 offset1:48
	ds_read_b128 v[88:91], v145 offset:27136
	ds_read_b128 v[92:95], v145 offset:27392
	ds_read_b128 v[80:83], v145 offset:18944
	ds_read_b128 v[84:87], v145 offset:19200
	s_waitcnt lgkmcnt(9)
	v_pk_add_f32 v[178:179], v[178:179], v[118:119] op_sel_hi:[1,0] neg_lo:[0,1] neg_hi:[0,1]
	v_pk_add_f32 v[186:187], v[186:187], v[118:119] op_sel:[0,1] op_sel_hi:[1,1] neg_lo:[0,1] neg_hi:[0,1]
	v_pk_add_f32 v[180:181], v[180:181], v[118:119] op_sel_hi:[1,0] neg_lo:[0,1] neg_hi:[0,1]
	v_pk_add_f32 v[188:189], v[188:189], v[118:119] op_sel:[0,1] op_sel_hi:[1,1] neg_lo:[0,1] neg_hi:[0,1]
	v_pk_add_f32 v[182:183], v[182:183], v[118:119] op_sel_hi:[1,0] neg_lo:[0,1] neg_hi:[0,1]
	v_pk_add_f32 v[190:191], v[190:191], v[118:119] op_sel:[0,1] op_sel_hi:[1,1] neg_lo:[0,1] neg_hi:[0,1]
	v_pk_add_f32 v[184:185], v[184:185], v[118:119] op_sel_hi:[1,0] neg_lo:[0,1] neg_hi:[0,1]
	v_pk_add_f32 v[192:193], v[192:193], v[118:119] op_sel:[0,1] op_sel_hi:[1,1] neg_lo:[0,1] neg_hi:[0,1]
	s_waitcnt lgkmcnt(8)
	v_pk_fma_f32 v[178:179], v[72:73], v[178:179], v[118:119] op_sel_hi:[1,1,0]
	v_pk_fma_f32 v[186:187], v[72:73], v[186:187], v[118:119] op_sel:[0,0,1] op_sel_hi:[1,1,1]
	v_pk_fma_f32 v[180:181], v[74:75], v[180:181], v[118:119] op_sel_hi:[1,1,0]
	v_pk_fma_f32 v[188:189], v[74:75], v[188:189], v[118:119] op_sel:[0,0,1] op_sel_hi:[1,1,1]
	s_waitcnt lgkmcnt(7)
	v_pk_fma_f32 v[182:183], v[76:77], v[182:183], v[118:119] op_sel_hi:[1,1,0]
	v_pk_fma_f32 v[190:191], v[76:77], v[190:191], v[118:119] op_sel:[0,0,1] op_sel_hi:[1,1,1]
	v_pk_fma_f32 v[184:185], v[78:79], v[184:185], v[118:119] op_sel_hi:[1,1,0]
	v_pk_fma_f32 v[192:193], v[78:79], v[192:193], v[118:119] op_sel:[0,0,1] op_sel_hi:[1,1,1]
	s_waitcnt lgkmcnt(6)
	v_pk_fma_f32 v[146:147], v[64:65], v[178:179], v[196:197]
	v_pk_fma_f32 v[150:151], v[64:65], v[186:187], v[196:197]
	v_pk_fma_f32 v[148:149], v[66:67], v[180:181], v[196:197]
	v_pk_fma_f32 v[152:153], v[66:67], v[188:189], v[196:197]
	s_waitcnt lgkmcnt(5)
	v_pk_fma_f32 v[146:147], v[68:69], v[182:183], v[146:147]
	v_pk_fma_f32 v[150:151], v[68:69], v[190:191], v[150:151]
	v_pk_fma_f32 v[148:149], v[70:71], v[184:185], v[148:149]
	v_pk_fma_f32 v[152:153], v[70:71], v[192:193], v[152:153]
	v_add_f32_e32 v146, v146, v147
	v_add_f32_e32 v148, v148, v149
	v_add_f32_e32 v150, v150, v151
	v_add_f32_e32 v152, v152, v153
	v_add_f32_e32 v154, v146, v148
	v_add_f32_e32 v155, v150, v152
	ds_read2_b32 v[118:119], v194 offset0:64 offset1:80
	ds_read_b128 v[72:75], v145 offset:27648
	ds_read_b128 v[76:79], v145 offset:27904
	ds_read_b128 v[64:67], v145 offset:19456
	ds_read_b128 v[68:71], v145 offset:19712
	s_waitcnt lgkmcnt(9)
	v_pk_add_f32 v[178:179], v[178:179], v[120:121] op_sel_hi:[1,0] neg_lo:[0,1] neg_hi:[0,1]
	v_add_f32_dpp v154, v154, v154 row_ror:8 row_mask:0xf bank_mask:0xf bound_ctrl:1
	v_pk_add_f32 v[186:187], v[186:187], v[120:121] op_sel:[0,1] op_sel_hi:[1,1] neg_lo:[0,1] neg_hi:[0,1]
	v_add_f32_dpp v155, v155, v155 row_ror:8 row_mask:0xf bank_mask:0xf bound_ctrl:1
	v_pk_add_f32 v[180:181], v[180:181], v[120:121] op_sel_hi:[1,0] neg_lo:[0,1] neg_hi:[0,1]
	v_add_f32_dpp v154, v154, v154 row_ror:4 row_mask:0xf bank_mask:0xf bound_ctrl:1
	v_pk_add_f32 v[188:189], v[188:189], v[120:121] op_sel:[0,1] op_sel_hi:[1,1] neg_lo:[0,1] neg_hi:[0,1]
	v_add_f32_dpp v155, v155, v155 row_ror:4 row_mask:0xf bank_mask:0xf bound_ctrl:1
	v_pk_add_f32 v[182:183], v[182:183], v[120:121] op_sel_hi:[1,0] neg_lo:[0,1] neg_hi:[0,1]
	v_add_f32_dpp v154, v154, v154 row_ror:2 row_mask:0xf bank_mask:0xf bound_ctrl:1
	v_pk_add_f32 v[190:191], v[190:191], v[120:121] op_sel:[0,1] op_sel_hi:[1,1] neg_lo:[0,1] neg_hi:[0,1]
	v_add_f32_dpp v155, v155, v155 row_ror:2 row_mask:0xf bank_mask:0xf bound_ctrl:1
	v_pk_add_f32 v[184:185], v[184:185], v[120:121] op_sel_hi:[1,0] neg_lo:[0,1] neg_hi:[0,1]
	v_add_f32_dpp v154, v154, v154 row_ror:1 row_mask:0xf bank_mask:0xf bound_ctrl:1
	v_pk_add_f32 v[192:193], v[192:193], v[120:121] op_sel:[0,1] op_sel_hi:[1,1] neg_lo:[0,1] neg_hi:[0,1]
	v_add_f32_dpp v155, v155, v155 row_ror:1 row_mask:0xf bank_mask:0xf bound_ctrl:1
	s_waitcnt lgkmcnt(8)
	v_pk_fma_f32 v[178:179], v[88:89], v[178:179], v[120:121] op_sel_hi:[1,1,0]
	s_and_saveexec_b64 s[8:9], s[38:39]
	ds_write_b32 v103, v154 offset:38912
	ds_write_b32 v103, v155 offset:38976
	s_mov_b64 exec, s[8:9]
	v_pk_fma_f32 v[186:187], v[88:89], v[186:187], v[120:121] op_sel:[0,0,1] op_sel_hi:[1,1,1]
	v_pk_fma_f32 v[180:181], v[90:91], v[180:181], v[120:121] op_sel_hi:[1,1,0]
	v_pk_fma_f32 v[188:189], v[90:91], v[188:189], v[120:121] op_sel:[0,0,1] op_sel_hi:[1,1,1]
	s_waitcnt lgkmcnt(9)
	v_pk_fma_f32 v[182:183], v[92:93], v[182:183], v[120:121] op_sel_hi:[1,1,0]
	v_pk_fma_f32 v[190:191], v[92:93], v[190:191], v[120:121] op_sel:[0,0,1] op_sel_hi:[1,1,1]
	v_pk_fma_f32 v[184:185], v[94:95], v[184:185], v[120:121] op_sel_hi:[1,1,0]
	v_pk_fma_f32 v[192:193], v[94:95], v[192:193], v[120:121] op_sel:[0,0,1] op_sel_hi:[1,1,1]
	s_waitcnt lgkmcnt(8)
	v_pk_fma_f32 v[146:147], v[80:81], v[178:179], v[196:197]
	v_pk_fma_f32 v[150:151], v[80:81], v[186:187], v[196:197]
	v_pk_fma_f32 v[148:149], v[82:83], v[180:181], v[196:197]
	v_pk_fma_f32 v[152:153], v[82:83], v[188:189], v[196:197]
	s_waitcnt lgkmcnt(7)
	v_pk_fma_f32 v[146:147], v[84:85], v[182:183], v[146:147]
	v_pk_fma_f32 v[150:151], v[84:85], v[190:191], v[150:151]
	v_pk_fma_f32 v[148:149], v[86:87], v[184:185], v[148:149]
	v_pk_fma_f32 v[152:153], v[86:87], v[192:193], v[152:153]
	v_add_f32_e32 v146, v146, v147
	v_add_f32_e32 v148, v148, v149
	v_add_f32_e32 v150, v150, v151
	v_add_f32_e32 v152, v152, v153
	v_add_f32_e32 v156, v146, v148
	v_add_f32_e32 v157, v150, v152
	ds_read2_b32 v[120:121], v194 offset0:96 offset1:112
	ds_read_b128 v[88:91], v145 offset:28160
	ds_read_b128 v[92:95], v145 offset:28416
	ds_read_b128 v[80:83], v145 offset:19968
	ds_read_b128 v[84:87], v145 offset:20224
	s_waitcnt lgkmcnt(11)
	v_pk_add_f32 v[178:179], v[178:179], v[118:119] op_sel_hi:[1,0] neg_lo:[0,1] neg_hi:[0,1]
	v_add_f32_dpp v156, v156, v156 row_ror:8 row_mask:0xf bank_mask:0xf bound_ctrl:1
	v_pk_add_f32 v[186:187], v[186:187], v[118:119] op_sel:[0,1] op_sel_hi:[1,1] neg_lo:[0,1] neg_hi:[0,1]
	v_add_f32_dpp v157, v157, v157 row_ror:8 row_mask:0xf bank_mask:0xf bound_ctrl:1
	v_pk_add_f32 v[180:181], v[180:181], v[118:119] op_sel_hi:[1,0] neg_lo:[0,1] neg_hi:[0,1]
	v_add_f32_dpp v156, v156, v156 row_ror:4 row_mask:0xf bank_mask:0xf bound_ctrl:1
	v_pk_add_f32 v[188:189], v[188:189], v[118:119] op_sel:[0,1] op_sel_hi:[1,1] neg_lo:[0,1] neg_hi:[0,1]
	v_add_f32_dpp v157, v157, v157 row_ror:4 row_mask:0xf bank_mask:0xf bound_ctrl:1
	v_pk_add_f32 v[182:183], v[182:183], v[118:119] op_sel_hi:[1,0] neg_lo:[0,1] neg_hi:[0,1]
	v_add_f32_dpp v156, v156, v156 row_ror:2 row_mask:0xf bank_mask:0xf bound_ctrl:1
	v_pk_add_f32 v[190:191], v[190:191], v[118:119] op_sel:[0,1] op_sel_hi:[1,1] neg_lo:[0,1] neg_hi:[0,1]
	v_add_f32_dpp v157, v157, v157 row_ror:2 row_mask:0xf bank_mask:0xf bound_ctrl:1
	v_pk_add_f32 v[184:185], v[184:185], v[118:119] op_sel_hi:[1,0] neg_lo:[0,1] neg_hi:[0,1]
	v_add_f32_dpp v156, v156, v156 row_ror:1 row_mask:0xf bank_mask:0xf bound_ctrl:1
	v_pk_add_f32 v[192:193], v[192:193], v[118:119] op_sel:[0,1] op_sel_hi:[1,1] neg_lo:[0,1] neg_hi:[0,1]
	v_add_f32_dpp v157, v157, v157 row_ror:1 row_mask:0xf bank_mask:0xf bound_ctrl:1
	s_waitcnt lgkmcnt(10)
	v_pk_fma_f32 v[178:179], v[72:73], v[178:179], v[118:119] op_sel_hi:[1,1,0]
	s_and_saveexec_b64 s[8:9], s[38:39]
	ds_write_b32 v103, v156 offset:39040
	ds_write_b32 v103, v157 offset:39104
	s_mov_b64 exec, s[8:9]
	v_pk_fma_f32 v[186:187], v[72:73], v[186:187], v[118:119] op_sel:[0,0,1] op_sel_hi:[1,1,1]
	v_pk_fma_f32 v[180:181], v[74:75], v[180:181], v[118:119] op_sel_hi:[1,1,0]
	v_pk_fma_f32 v[188:189], v[74:75], v[188:189], v[118:119] op_sel:[0,0,1] op_sel_hi:[1,1,1]
	s_waitcnt lgkmcnt(11)
	v_pk_fma_f32 v[182:183], v[76:77], v[182:183], v[118:119] op_sel_hi:[1,1,0]
	v_pk_fma_f32 v[190:191], v[76:77], v[190:191], v[118:119] op_sel:[0,0,1] op_sel_hi:[1,1,1]
	v_pk_fma_f32 v[184:185], v[78:79], v[184:185], v[118:119] op_sel_hi:[1,1,0]
	v_pk_fma_f32 v[192:193], v[78:79], v[192:193], v[118:119] op_sel:[0,0,1] op_sel_hi:[1,1,1]
	s_waitcnt lgkmcnt(10)
	v_pk_fma_f32 v[146:147], v[64:65], v[178:179], v[196:197]
	v_pk_fma_f32 v[150:151], v[64:65], v[186:187], v[196:197]
	v_pk_fma_f32 v[148:149], v[66:67], v[180:181], v[196:197]
	v_pk_fma_f32 v[152:153], v[66:67], v[188:189], v[196:197]
	s_waitcnt lgkmcnt(9)
	v_pk_fma_f32 v[146:147], v[68:69], v[182:183], v[146:147]
	v_pk_fma_f32 v[150:151], v[68:69], v[190:191], v[150:151]
	v_pk_fma_f32 v[148:149], v[70:71], v[184:185], v[148:149]
	v_pk_fma_f32 v[152:153], v[70:71], v[192:193], v[152:153]
	v_add_f32_e32 v146, v146, v147
	v_add_f32_e32 v148, v148, v149
	v_add_f32_e32 v150, v150, v151
	v_add_f32_e32 v152, v152, v153
	v_add_f32_e32 v154, v146, v148
	v_add_f32_e32 v155, v150, v152
	ds_read2_b32 v[118:119], v194 offset0:128 offset1:144
	ds_read_b128 v[72:75], v145 offset:28672
	ds_read_b128 v[76:79], v145 offset:28928
	ds_read_b128 v[64:67], v145 offset:20480
	ds_read_b128 v[68:71], v145 offset:20736
	s_waitcnt lgkmcnt(11)
	v_pk_add_f32 v[178:179], v[178:179], v[120:121] op_sel_hi:[1,0] neg_lo:[0,1] neg_hi:[0,1]
	v_add_f32_dpp v154, v154, v154 row_ror:8 row_mask:0xf bank_mask:0xf bound_ctrl:1
	v_pk_add_f32 v[186:187], v[186:187], v[120:121] op_sel:[0,1] op_sel_hi:[1,1] neg_lo:[0,1] neg_hi:[0,1]
	v_add_f32_dpp v155, v155, v155 row_ror:8 row_mask:0xf bank_mask:0xf bound_ctrl:1
	v_pk_add_f32 v[180:181], v[180:181], v[120:121] op_sel_hi:[1,0] neg_lo:[0,1] neg_hi:[0,1]
	v_add_f32_dpp v154, v154, v154 row_ror:4 row_mask:0xf bank_mask:0xf bound_ctrl:1
	v_pk_add_f32 v[188:189], v[188:189], v[120:121] op_sel:[0,1] op_sel_hi:[1,1] neg_lo:[0,1] neg_hi:[0,1]
	v_add_f32_dpp v155, v155, v155 row_ror:4 row_mask:0xf bank_mask:0xf bound_ctrl:1
	v_pk_add_f32 v[182:183], v[182:183], v[120:121] op_sel_hi:[1,0] neg_lo:[0,1] neg_hi:[0,1]
	v_add_f32_dpp v154, v154, v154 row_ror:2 row_mask:0xf bank_mask:0xf bound_ctrl:1
	v_pk_add_f32 v[190:191], v[190:191], v[120:121] op_sel:[0,1] op_sel_hi:[1,1] neg_lo:[0,1] neg_hi:[0,1]
	v_add_f32_dpp v155, v155, v155 row_ror:2 row_mask:0xf bank_mask:0xf bound_ctrl:1
	v_pk_add_f32 v[184:185], v[184:185], v[120:121] op_sel_hi:[1,0] neg_lo:[0,1] neg_hi:[0,1]
	v_add_f32_dpp v154, v154, v154 row_ror:1 row_mask:0xf bank_mask:0xf bound_ctrl:1
	v_pk_add_f32 v[192:193], v[192:193], v[120:121] op_sel:[0,1] op_sel_hi:[1,1] neg_lo:[0,1] neg_hi:[0,1]
	v_add_f32_dpp v155, v155, v155 row_ror:1 row_mask:0xf bank_mask:0xf bound_ctrl:1
	s_waitcnt lgkmcnt(10)
	v_pk_fma_f32 v[178:179], v[88:89], v[178:179], v[120:121] op_sel_hi:[1,1,0]
	s_and_saveexec_b64 s[8:9], s[38:39]
	ds_write_b32 v103, v154 offset:39168
	ds_write_b32 v103, v155 offset:39232
	s_mov_b64 exec, s[8:9]
	v_pk_fma_f32 v[186:187], v[88:89], v[186:187], v[120:121] op_sel:[0,0,1] op_sel_hi:[1,1,1]
	v_pk_fma_f32 v[180:181], v[90:91], v[180:181], v[120:121] op_sel_hi:[1,1,0]
	v_pk_fma_f32 v[188:189], v[90:91], v[188:189], v[120:121] op_sel:[0,0,1] op_sel_hi:[1,1,1]
	s_waitcnt lgkmcnt(11)
	v_pk_fma_f32 v[182:183], v[92:93], v[182:183], v[120:121] op_sel_hi:[1,1,0]
	v_pk_fma_f32 v[190:191], v[92:93], v[190:191], v[120:121] op_sel:[0,0,1] op_sel_hi:[1,1,1]
	v_pk_fma_f32 v[184:185], v[94:95], v[184:185], v[120:121] op_sel_hi:[1,1,0]
	v_pk_fma_f32 v[192:193], v[94:95], v[192:193], v[120:121] op_sel:[0,0,1] op_sel_hi:[1,1,1]
	s_waitcnt lgkmcnt(10)
	v_pk_fma_f32 v[146:147], v[80:81], v[178:179], v[196:197]
	v_pk_fma_f32 v[150:151], v[80:81], v[186:187], v[196:197]
	v_pk_fma_f32 v[148:149], v[82:83], v[180:181], v[196:197]
	v_pk_fma_f32 v[152:153], v[82:83], v[188:189], v[196:197]
	s_waitcnt lgkmcnt(9)
	v_pk_fma_f32 v[146:147], v[84:85], v[182:183], v[146:147]
	v_pk_fma_f32 v[150:151], v[84:85], v[190:191], v[150:151]
	v_pk_fma_f32 v[148:149], v[86:87], v[184:185], v[148:149]
	v_pk_fma_f32 v[152:153], v[86:87], v[192:193], v[152:153]
	v_add_f32_e32 v146, v146, v147
	v_add_f32_e32 v148, v148, v149
	v_add_f32_e32 v150, v150, v151
	v_add_f32_e32 v152, v152, v153
	v_add_f32_e32 v156, v146, v148
	v_add_f32_e32 v157, v150, v152
	ds_read2_b32 v[120:121], v194 offset0:160 offset1:176
	ds_read_b128 v[88:91], v145 offset:29184
	ds_read_b128 v[92:95], v145 offset:29440
	ds_read_b128 v[80:83], v145 offset:20992
	ds_read_b128 v[84:87], v145 offset:21248
	s_waitcnt lgkmcnt(11)
	v_pk_add_f32 v[178:179], v[178:179], v[118:119] op_sel_hi:[1,0] neg_lo:[0,1] neg_hi:[0,1]
	v_add_f32_dpp v156, v156, v156 row_ror:8 row_mask:0xf bank_mask:0xf bound_ctrl:1
	v_pk_add_f32 v[186:187], v[186:187], v[118:119] op_sel:[0,1] op_sel_hi:[1,1] neg_lo:[0,1] neg_hi:[0,1]
	v_add_f32_dpp v157, v157, v157 row_ror:8 row_mask:0xf bank_mask:0xf bound_ctrl:1
	v_pk_add_f32 v[180:181], v[180:181], v[118:119] op_sel_hi:[1,0] neg_lo:[0,1] neg_hi:[0,1]
	v_add_f32_dpp v156, v156, v156 row_ror:4 row_mask:0xf bank_mask:0xf bound_ctrl:1
	v_pk_add_f32 v[188:189], v[188:189], v[118:119] op_sel:[0,1] op_sel_hi:[1,1] neg_lo:[0,1] neg_hi:[0,1]
	v_add_f32_dpp v157, v157, v157 row_ror:4 row_mask:0xf bank_mask:0xf bound_ctrl:1
	v_pk_add_f32 v[182:183], v[182:183], v[118:119] op_sel_hi:[1,0] neg_lo:[0,1] neg_hi:[0,1]
	v_add_f32_dpp v156, v156, v156 row_ror:2 row_mask:0xf bank_mask:0xf bound_ctrl:1
	v_pk_add_f32 v[190:191], v[190:191], v[118:119] op_sel:[0,1] op_sel_hi:[1,1] neg_lo:[0,1] neg_hi:[0,1]
	v_add_f32_dpp v157, v157, v157 row_ror:2 row_mask:0xf bank_mask:0xf bound_ctrl:1
	v_pk_add_f32 v[184:185], v[184:185], v[118:119] op_sel_hi:[1,0] neg_lo:[0,1] neg_hi:[0,1]
	v_add_f32_dpp v156, v156, v156 row_ror:1 row_mask:0xf bank_mask:0xf bound_ctrl:1
	v_pk_add_f32 v[192:193], v[192:193], v[118:119] op_sel:[0,1] op_sel_hi:[1,1] neg_lo:[0,1] neg_hi:[0,1]
	v_add_f32_dpp v157, v157, v157 row_ror:1 row_mask:0xf bank_mask:0xf bound_ctrl:1
	s_waitcnt lgkmcnt(10)
	v_pk_fma_f32 v[178:179], v[72:73], v[178:179], v[118:119] op_sel_hi:[1,1,0]
	s_and_saveexec_b64 s[8:9], s[38:39]
	ds_write_b32 v103, v156 offset:39296
	ds_write_b32 v103, v157 offset:39360
	s_mov_b64 exec, s[8:9]
	v_pk_fma_f32 v[186:187], v[72:73], v[186:187], v[118:119] op_sel:[0,0,1] op_sel_hi:[1,1,1]
	v_pk_fma_f32 v[180:181], v[74:75], v[180:181], v[118:119] op_sel_hi:[1,1,0]
	v_pk_fma_f32 v[188:189], v[74:75], v[188:189], v[118:119] op_sel:[0,0,1] op_sel_hi:[1,1,1]
	s_waitcnt lgkmcnt(11)
	v_pk_fma_f32 v[182:183], v[76:77], v[182:183], v[118:119] op_sel_hi:[1,1,0]
	v_pk_fma_f32 v[190:191], v[76:77], v[190:191], v[118:119] op_sel:[0,0,1] op_sel_hi:[1,1,1]
	v_pk_fma_f32 v[184:185], v[78:79], v[184:185], v[118:119] op_sel_hi:[1,1,0]
	v_pk_fma_f32 v[192:193], v[78:79], v[192:193], v[118:119] op_sel:[0,0,1] op_sel_hi:[1,1,1]
	s_waitcnt lgkmcnt(10)
	v_pk_fma_f32 v[146:147], v[64:65], v[178:179], v[196:197]
	v_pk_fma_f32 v[150:151], v[64:65], v[186:187], v[196:197]
	v_pk_fma_f32 v[148:149], v[66:67], v[180:181], v[196:197]
	v_pk_fma_f32 v[152:153], v[66:67], v[188:189], v[196:197]
	s_waitcnt lgkmcnt(9)
	v_pk_fma_f32 v[146:147], v[68:69], v[182:183], v[146:147]
	v_pk_fma_f32 v[150:151], v[68:69], v[190:191], v[150:151]
	v_pk_fma_f32 v[148:149], v[70:71], v[184:185], v[148:149]
	v_pk_fma_f32 v[152:153], v[70:71], v[192:193], v[152:153]
	v_add_f32_e32 v146, v146, v147
	v_add_f32_e32 v148, v148, v149
	v_add_f32_e32 v150, v150, v151
	v_add_f32_e32 v152, v152, v153
	v_add_f32_e32 v154, v146, v148
	v_add_f32_e32 v155, v150, v152
	ds_read2_b32 v[118:119], v194 offset0:192 offset1:208
	ds_read_b128 v[72:75], v145 offset:29696
	ds_read_b128 v[76:79], v145 offset:29952
	ds_read_b128 v[64:67], v145 offset:21504
	ds_read_b128 v[68:71], v145 offset:21760
	s_waitcnt lgkmcnt(11)
	v_pk_add_f32 v[178:179], v[178:179], v[120:121] op_sel_hi:[1,0] neg_lo:[0,1] neg_hi:[0,1]
	v_add_f32_dpp v154, v154, v154 row_ror:8 row_mask:0xf bank_mask:0xf bound_ctrl:1
	v_pk_add_f32 v[186:187], v[186:187], v[120:121] op_sel:[0,1] op_sel_hi:[1,1] neg_lo:[0,1] neg_hi:[0,1]
	v_add_f32_dpp v155, v155, v155 row_ror:8 row_mask:0xf bank_mask:0xf bound_ctrl:1
	v_pk_add_f32 v[180:181], v[180:181], v[120:121] op_sel_hi:[1,0] neg_lo:[0,1] neg_hi:[0,1]
	v_add_f32_dpp v154, v154, v154 row_ror:4 row_mask:0xf bank_mask:0xf bound_ctrl:1
	v_pk_add_f32 v[188:189], v[188:189], v[120:121] op_sel:[0,1] op_sel_hi:[1,1] neg_lo:[0,1] neg_hi:[0,1]
	v_add_f32_dpp v155, v155, v155 row_ror:4 row_mask:0xf bank_mask:0xf bound_ctrl:1
	v_pk_add_f32 v[182:183], v[182:183], v[120:121] op_sel_hi:[1,0] neg_lo:[0,1] neg_hi:[0,1]
	v_add_f32_dpp v154, v154, v154 row_ror:2 row_mask:0xf bank_mask:0xf bound_ctrl:1
	v_pk_add_f32 v[190:191], v[190:191], v[120:121] op_sel:[0,1] op_sel_hi:[1,1] neg_lo:[0,1] neg_hi:[0,1]
	v_add_f32_dpp v155, v155, v155 row_ror:2 row_mask:0xf bank_mask:0xf bound_ctrl:1
	v_pk_add_f32 v[184:185], v[184:185], v[120:121] op_sel_hi:[1,0] neg_lo:[0,1] neg_hi:[0,1]
	v_add_f32_dpp v154, v154, v154 row_ror:1 row_mask:0xf bank_mask:0xf bound_ctrl:1
	v_pk_add_f32 v[192:193], v[192:193], v[120:121] op_sel:[0,1] op_sel_hi:[1,1] neg_lo:[0,1] neg_hi:[0,1]
	v_add_f32_dpp v155, v155, v155 row_ror:1 row_mask:0xf bank_mask:0xf bound_ctrl:1
	s_waitcnt lgkmcnt(10)
	v_pk_fma_f32 v[178:179], v[88:89], v[178:179], v[120:121] op_sel_hi:[1,1,0]
	s_and_saveexec_b64 s[8:9], s[38:39]
	ds_write_b32 v103, v154 offset:39424
	ds_write_b32 v103, v155 offset:39488
	s_mov_b64 exec, s[8:9]
	v_pk_fma_f32 v[186:187], v[88:89], v[186:187], v[120:121] op_sel:[0,0,1] op_sel_hi:[1,1,1]
	v_pk_fma_f32 v[180:181], v[90:91], v[180:181], v[120:121] op_sel_hi:[1,1,0]
	v_pk_fma_f32 v[188:189], v[90:91], v[188:189], v[120:121] op_sel:[0,0,1] op_sel_hi:[1,1,1]
	s_waitcnt lgkmcnt(11)
	v_pk_fma_f32 v[182:183], v[92:93], v[182:183], v[120:121] op_sel_hi:[1,1,0]
	v_pk_fma_f32 v[190:191], v[92:93], v[190:191], v[120:121] op_sel:[0,0,1] op_sel_hi:[1,1,1]
	v_pk_fma_f32 v[184:185], v[94:95], v[184:185], v[120:121] op_sel_hi:[1,1,0]
	v_pk_fma_f32 v[192:193], v[94:95], v[192:193], v[120:121] op_sel:[0,0,1] op_sel_hi:[1,1,1]
	s_waitcnt lgkmcnt(10)
	v_pk_fma_f32 v[146:147], v[80:81], v[178:179], v[196:197]
	v_pk_fma_f32 v[150:151], v[80:81], v[186:187], v[196:197]
	v_pk_fma_f32 v[148:149], v[82:83], v[180:181], v[196:197]
	v_pk_fma_f32 v[152:153], v[82:83], v[188:189], v[196:197]
	s_waitcnt lgkmcnt(9)
	v_pk_fma_f32 v[146:147], v[84:85], v[182:183], v[146:147]
	v_pk_fma_f32 v[150:151], v[84:85], v[190:191], v[150:151]
	v_pk_fma_f32 v[148:149], v[86:87], v[184:185], v[148:149]
	v_pk_fma_f32 v[152:153], v[86:87], v[192:193], v[152:153]
	v_add_f32_e32 v146, v146, v147
	v_add_f32_e32 v148, v148, v149
	v_add_f32_e32 v150, v150, v151
	v_add_f32_e32 v152, v152, v153
	v_add_f32_e32 v156, v146, v148
	v_add_f32_e32 v157, v150, v152
	ds_read2_b32 v[120:121], v194 offset0:224 offset1:240
	ds_read_b128 v[88:91], v145 offset:30208
	ds_read_b128 v[92:95], v145 offset:30464
	ds_read_b128 v[80:83], v145 offset:22016
	ds_read_b128 v[84:87], v145 offset:22272
	s_waitcnt lgkmcnt(11)
	v_pk_add_f32 v[178:179], v[178:179], v[118:119] op_sel_hi:[1,0] neg_lo:[0,1] neg_hi:[0,1]
	v_add_f32_dpp v156, v156, v156 row_ror:8 row_mask:0xf bank_mask:0xf bound_ctrl:1
	v_pk_add_f32 v[186:187], v[186:187], v[118:119] op_sel:[0,1] op_sel_hi:[1,1] neg_lo:[0,1] neg_hi:[0,1]
	v_add_f32_dpp v157, v157, v157 row_ror:8 row_mask:0xf bank_mask:0xf bound_ctrl:1
	v_pk_add_f32 v[180:181], v[180:181], v[118:119] op_sel_hi:[1,0] neg_lo:[0,1] neg_hi:[0,1]
	v_add_f32_dpp v156, v156, v156 row_ror:4 row_mask:0xf bank_mask:0xf bound_ctrl:1
	v_pk_add_f32 v[188:189], v[188:189], v[118:119] op_sel:[0,1] op_sel_hi:[1,1] neg_lo:[0,1] neg_hi:[0,1]
	v_add_f32_dpp v157, v157, v157 row_ror:4 row_mask:0xf bank_mask:0xf bound_ctrl:1
	v_pk_add_f32 v[182:183], v[182:183], v[118:119] op_sel_hi:[1,0] neg_lo:[0,1] neg_hi:[0,1]
	v_add_f32_dpp v156, v156, v156 row_ror:2 row_mask:0xf bank_mask:0xf bound_ctrl:1
	v_pk_add_f32 v[190:191], v[190:191], v[118:119] op_sel:[0,1] op_sel_hi:[1,1] neg_lo:[0,1] neg_hi:[0,1]
	v_add_f32_dpp v157, v157, v157 row_ror:2 row_mask:0xf bank_mask:0xf bound_ctrl:1
	v_pk_add_f32 v[184:185], v[184:185], v[118:119] op_sel_hi:[1,0] neg_lo:[0,1] neg_hi:[0,1]
	v_add_f32_dpp v156, v156, v156 row_ror:1 row_mask:0xf bank_mask:0xf bound_ctrl:1
	v_pk_add_f32 v[192:193], v[192:193], v[118:119] op_sel:[0,1] op_sel_hi:[1,1] neg_lo:[0,1] neg_hi:[0,1]
	v_add_f32_dpp v157, v157, v157 row_ror:1 row_mask:0xf bank_mask:0xf bound_ctrl:1
	s_waitcnt lgkmcnt(10)
	v_pk_fma_f32 v[178:179], v[72:73], v[178:179], v[118:119] op_sel_hi:[1,1,0]
	s_and_saveexec_b64 s[8:9], s[38:39]
	ds_write_b32 v103, v156 offset:39552
	ds_write_b32 v103, v157 offset:39616
	s_mov_b64 exec, s[8:9]
	v_pk_fma_f32 v[186:187], v[72:73], v[186:187], v[118:119] op_sel:[0,0,1] op_sel_hi:[1,1,1]
	v_pk_fma_f32 v[180:181], v[74:75], v[180:181], v[118:119] op_sel_hi:[1,1,0]
	v_pk_fma_f32 v[188:189], v[74:75], v[188:189], v[118:119] op_sel:[0,0,1] op_sel_hi:[1,1,1]
	s_waitcnt lgkmcnt(11)
	v_pk_fma_f32 v[182:183], v[76:77], v[182:183], v[118:119] op_sel_hi:[1,1,0]
	v_pk_fma_f32 v[190:191], v[76:77], v[190:191], v[118:119] op_sel:[0,0,1] op_sel_hi:[1,1,1]
	v_pk_fma_f32 v[184:185], v[78:79], v[184:185], v[118:119] op_sel_hi:[1,1,0]
	v_pk_fma_f32 v[192:193], v[78:79], v[192:193], v[118:119] op_sel:[0,0,1] op_sel_hi:[1,1,1]
	s_waitcnt lgkmcnt(10)
	v_pk_fma_f32 v[146:147], v[64:65], v[178:179], v[196:197]
	v_pk_fma_f32 v[150:151], v[64:65], v[186:187], v[196:197]
	v_pk_fma_f32 v[148:149], v[66:67], v[180:181], v[196:197]
	v_pk_fma_f32 v[152:153], v[66:67], v[188:189], v[196:197]
	s_waitcnt lgkmcnt(9)
	v_pk_fma_f32 v[146:147], v[68:69], v[182:183], v[146:147]
	v_pk_fma_f32 v[150:151], v[68:69], v[190:191], v[150:151]
	v_pk_fma_f32 v[148:149], v[70:71], v[184:185], v[148:149]
	v_pk_fma_f32 v[152:153], v[70:71], v[192:193], v[152:153]
	v_add_f32_e32 v146, v146, v147
	v_add_f32_e32 v148, v148, v149
	v_add_f32_e32 v150, v150, v151
	v_add_f32_e32 v152, v152, v153
	v_add_f32_e32 v154, v146, v148
	v_add_f32_e32 v155, v150, v152
	ds_read2_b32 v[118:119], v195 offset0:0 offset1:16
	ds_read_b128 v[72:75], v145 offset:30720
	ds_read_b128 v[76:79], v145 offset:30976
	ds_read_b128 v[64:67], v145 offset:22528
	ds_read_b128 v[68:71], v145 offset:22784
	s_waitcnt lgkmcnt(11)
	v_pk_add_f32 v[178:179], v[178:179], v[120:121] op_sel_hi:[1,0] neg_lo:[0,1] neg_hi:[0,1]
	v_add_f32_dpp v154, v154, v154 row_ror:8 row_mask:0xf bank_mask:0xf bound_ctrl:1
	v_pk_add_f32 v[186:187], v[186:187], v[120:121] op_sel:[0,1] op_sel_hi:[1,1] neg_lo:[0,1] neg_hi:[0,1]
	v_add_f32_dpp v155, v155, v155 row_ror:8 row_mask:0xf bank_mask:0xf bound_ctrl:1
	v_pk_add_f32 v[180:181], v[180:181], v[120:121] op_sel_hi:[1,0] neg_lo:[0,1] neg_hi:[0,1]
	v_add_f32_dpp v154, v154, v154 row_ror:4 row_mask:0xf bank_mask:0xf bound_ctrl:1
	v_pk_add_f32 v[188:189], v[188:189], v[120:121] op_sel:[0,1] op_sel_hi:[1,1] neg_lo:[0,1] neg_hi:[0,1]
	v_add_f32_dpp v155, v155, v155 row_ror:4 row_mask:0xf bank_mask:0xf bound_ctrl:1
	v_pk_add_f32 v[182:183], v[182:183], v[120:121] op_sel_hi:[1,0] neg_lo:[0,1] neg_hi:[0,1]
	v_add_f32_dpp v154, v154, v154 row_ror:2 row_mask:0xf bank_mask:0xf bound_ctrl:1
	v_pk_add_f32 v[190:191], v[190:191], v[120:121] op_sel:[0,1] op_sel_hi:[1,1] neg_lo:[0,1] neg_hi:[0,1]
	v_add_f32_dpp v155, v155, v155 row_ror:2 row_mask:0xf bank_mask:0xf bound_ctrl:1
	v_pk_add_f32 v[184:185], v[184:185], v[120:121] op_sel_hi:[1,0] neg_lo:[0,1] neg_hi:[0,1]
	v_add_f32_dpp v154, v154, v154 row_ror:1 row_mask:0xf bank_mask:0xf bound_ctrl:1
	v_pk_add_f32 v[192:193], v[192:193], v[120:121] op_sel:[0,1] op_sel_hi:[1,1] neg_lo:[0,1] neg_hi:[0,1]
	v_add_f32_dpp v155, v155, v155 row_ror:1 row_mask:0xf bank_mask:0xf bound_ctrl:1
	s_waitcnt lgkmcnt(10)
	v_pk_fma_f32 v[178:179], v[88:89], v[178:179], v[120:121] op_sel_hi:[1,1,0]
	s_and_saveexec_b64 s[8:9], s[38:39]
	ds_write_b32 v103, v154 offset:39680
	ds_write_b32 v103, v155 offset:39744
	s_mov_b64 exec, s[8:9]
	v_pk_fma_f32 v[186:187], v[88:89], v[186:187], v[120:121] op_sel:[0,0,1] op_sel_hi:[1,1,1]
	v_pk_fma_f32 v[180:181], v[90:91], v[180:181], v[120:121] op_sel_hi:[1,1,0]
	v_pk_fma_f32 v[188:189], v[90:91], v[188:189], v[120:121] op_sel:[0,0,1] op_sel_hi:[1,1,1]
	s_waitcnt lgkmcnt(11)
	v_pk_fma_f32 v[182:183], v[92:93], v[182:183], v[120:121] op_sel_hi:[1,1,0]
	v_pk_fma_f32 v[190:191], v[92:93], v[190:191], v[120:121] op_sel:[0,0,1] op_sel_hi:[1,1,1]
	v_pk_fma_f32 v[184:185], v[94:95], v[184:185], v[120:121] op_sel_hi:[1,1,0]
	v_pk_fma_f32 v[192:193], v[94:95], v[192:193], v[120:121] op_sel:[0,0,1] op_sel_hi:[1,1,1]
	s_waitcnt lgkmcnt(10)
	v_pk_fma_f32 v[146:147], v[80:81], v[178:179], v[196:197]
	v_pk_fma_f32 v[150:151], v[80:81], v[186:187], v[196:197]
	v_pk_fma_f32 v[148:149], v[82:83], v[180:181], v[196:197]
	v_pk_fma_f32 v[152:153], v[82:83], v[188:189], v[196:197]
	s_waitcnt lgkmcnt(9)
	v_pk_fma_f32 v[146:147], v[84:85], v[182:183], v[146:147]
	v_pk_fma_f32 v[150:151], v[84:85], v[190:191], v[150:151]
	v_pk_fma_f32 v[148:149], v[86:87], v[184:185], v[148:149]
	v_pk_fma_f32 v[152:153], v[86:87], v[192:193], v[152:153]
	v_add_f32_e32 v146, v146, v147
	v_add_f32_e32 v148, v148, v149
	v_add_f32_e32 v150, v150, v151
	v_add_f32_e32 v152, v152, v153
	v_add_f32_e32 v156, v146, v148
	v_add_f32_e32 v157, v150, v152
	ds_read2_b32 v[120:121], v195 offset0:32 offset1:48
	ds_read_b128 v[88:91], v145 offset:31232
	ds_read_b128 v[92:95], v145 offset:31488
	ds_read_b128 v[80:83], v145 offset:23040
	ds_read_b128 v[84:87], v145 offset:23296
	s_waitcnt lgkmcnt(11)
	v_pk_add_f32 v[178:179], v[178:179], v[118:119] op_sel_hi:[1,0] neg_lo:[0,1] neg_hi:[0,1]
	v_add_f32_dpp v156, v156, v156 row_ror:8 row_mask:0xf bank_mask:0xf bound_ctrl:1
	v_pk_add_f32 v[186:187], v[186:187], v[118:119] op_sel:[0,1] op_sel_hi:[1,1] neg_lo:[0,1] neg_hi:[0,1]
	v_add_f32_dpp v157, v157, v157 row_ror:8 row_mask:0xf bank_mask:0xf bound_ctrl:1
	v_pk_add_f32 v[180:181], v[180:181], v[118:119] op_sel_hi:[1,0] neg_lo:[0,1] neg_hi:[0,1]
	v_add_f32_dpp v156, v156, v156 row_ror:4 row_mask:0xf bank_mask:0xf bound_ctrl:1
	v_pk_add_f32 v[188:189], v[188:189], v[118:119] op_sel:[0,1] op_sel_hi:[1,1] neg_lo:[0,1] neg_hi:[0,1]
	v_add_f32_dpp v157, v157, v157 row_ror:4 row_mask:0xf bank_mask:0xf bound_ctrl:1
	v_pk_add_f32 v[182:183], v[182:183], v[118:119] op_sel_hi:[1,0] neg_lo:[0,1] neg_hi:[0,1]
	v_add_f32_dpp v156, v156, v156 row_ror:2 row_mask:0xf bank_mask:0xf bound_ctrl:1
	v_pk_add_f32 v[190:191], v[190:191], v[118:119] op_sel:[0,1] op_sel_hi:[1,1] neg_lo:[0,1] neg_hi:[0,1]
	v_add_f32_dpp v157, v157, v157 row_ror:2 row_mask:0xf bank_mask:0xf bound_ctrl:1
	v_pk_add_f32 v[184:185], v[184:185], v[118:119] op_sel_hi:[1,0] neg_lo:[0,1] neg_hi:[0,1]
	v_add_f32_dpp v156, v156, v156 row_ror:1 row_mask:0xf bank_mask:0xf bound_ctrl:1
	v_pk_add_f32 v[192:193], v[192:193], v[118:119] op_sel:[0,1] op_sel_hi:[1,1] neg_lo:[0,1] neg_hi:[0,1]
	v_add_f32_dpp v157, v157, v157 row_ror:1 row_mask:0xf bank_mask:0xf bound_ctrl:1
	s_waitcnt lgkmcnt(10)
	v_pk_fma_f32 v[178:179], v[72:73], v[178:179], v[118:119] op_sel_hi:[1,1,0]
	s_and_saveexec_b64 s[8:9], s[38:39]
	ds_write_b32 v103, v156 offset:39808
	ds_write_b32 v103, v157 offset:39872
	s_mov_b64 exec, s[8:9]
	v_pk_fma_f32 v[186:187], v[72:73], v[186:187], v[118:119] op_sel:[0,0,1] op_sel_hi:[1,1,1]
	v_pk_fma_f32 v[180:181], v[74:75], v[180:181], v[118:119] op_sel_hi:[1,1,0]
	v_pk_fma_f32 v[188:189], v[74:75], v[188:189], v[118:119] op_sel:[0,0,1] op_sel_hi:[1,1,1]
	s_waitcnt lgkmcnt(11)
	v_pk_fma_f32 v[182:183], v[76:77], v[182:183], v[118:119] op_sel_hi:[1,1,0]
	v_pk_fma_f32 v[190:191], v[76:77], v[190:191], v[118:119] op_sel:[0,0,1] op_sel_hi:[1,1,1]
	v_pk_fma_f32 v[184:185], v[78:79], v[184:185], v[118:119] op_sel_hi:[1,1,0]
	v_pk_fma_f32 v[192:193], v[78:79], v[192:193], v[118:119] op_sel:[0,0,1] op_sel_hi:[1,1,1]
	s_waitcnt lgkmcnt(10)
	v_pk_fma_f32 v[146:147], v[64:65], v[178:179], v[196:197]
	v_pk_fma_f32 v[150:151], v[64:65], v[186:187], v[196:197]
	v_pk_fma_f32 v[148:149], v[66:67], v[180:181], v[196:197]
	v_pk_fma_f32 v[152:153], v[66:67], v[188:189], v[196:197]
	s_waitcnt lgkmcnt(9)
	v_pk_fma_f32 v[146:147], v[68:69], v[182:183], v[146:147]
	v_pk_fma_f32 v[150:151], v[68:69], v[190:191], v[150:151]
	v_pk_fma_f32 v[148:149], v[70:71], v[184:185], v[148:149]
	v_pk_fma_f32 v[152:153], v[70:71], v[192:193], v[152:153]
	v_add_f32_e32 v146, v146, v147
	v_add_f32_e32 v148, v148, v149
	v_add_f32_e32 v150, v150, v151
	v_add_f32_e32 v152, v152, v153
	v_add_f32_e32 v154, v146, v148
	v_add_f32_e32 v155, v150, v152
	ds_read2_b32 v[118:119], v195 offset0:64 offset1:80
	ds_read_b128 v[72:75], v145 offset:31744
	ds_read_b128 v[76:79], v145 offset:32000
	ds_read_b128 v[64:67], v145 offset:23552
	ds_read_b128 v[68:71], v145 offset:23808
	s_waitcnt lgkmcnt(11)
	v_pk_add_f32 v[178:179], v[178:179], v[120:121] op_sel_hi:[1,0] neg_lo:[0,1] neg_hi:[0,1]
	v_add_f32_dpp v154, v154, v154 row_ror:8 row_mask:0xf bank_mask:0xf bound_ctrl:1
	v_pk_add_f32 v[186:187], v[186:187], v[120:121] op_sel:[0,1] op_sel_hi:[1,1] neg_lo:[0,1] neg_hi:[0,1]
	v_add_f32_dpp v155, v155, v155 row_ror:8 row_mask:0xf bank_mask:0xf bound_ctrl:1
	v_pk_add_f32 v[180:181], v[180:181], v[120:121] op_sel_hi:[1,0] neg_lo:[0,1] neg_hi:[0,1]
	v_add_f32_dpp v154, v154, v154 row_ror:4 row_mask:0xf bank_mask:0xf bound_ctrl:1
	v_pk_add_f32 v[188:189], v[188:189], v[120:121] op_sel:[0,1] op_sel_hi:[1,1] neg_lo:[0,1] neg_hi:[0,1]
	v_add_f32_dpp v155, v155, v155 row_ror:4 row_mask:0xf bank_mask:0xf bound_ctrl:1
	v_pk_add_f32 v[182:183], v[182:183], v[120:121] op_sel_hi:[1,0] neg_lo:[0,1] neg_hi:[0,1]
	v_add_f32_dpp v154, v154, v154 row_ror:2 row_mask:0xf bank_mask:0xf bound_ctrl:1
	v_pk_add_f32 v[190:191], v[190:191], v[120:121] op_sel:[0,1] op_sel_hi:[1,1] neg_lo:[0,1] neg_hi:[0,1]
	v_add_f32_dpp v155, v155, v155 row_ror:2 row_mask:0xf bank_mask:0xf bound_ctrl:1
	v_pk_add_f32 v[184:185], v[184:185], v[120:121] op_sel_hi:[1,0] neg_lo:[0,1] neg_hi:[0,1]
	v_add_f32_dpp v154, v154, v154 row_ror:1 row_mask:0xf bank_mask:0xf bound_ctrl:1
	v_pk_add_f32 v[192:193], v[192:193], v[120:121] op_sel:[0,1] op_sel_hi:[1,1] neg_lo:[0,1] neg_hi:[0,1]
	v_add_f32_dpp v155, v155, v155 row_ror:1 row_mask:0xf bank_mask:0xf bound_ctrl:1
	s_waitcnt lgkmcnt(10)
	v_pk_fma_f32 v[178:179], v[88:89], v[178:179], v[120:121] op_sel_hi:[1,1,0]
	s_and_saveexec_b64 s[8:9], s[38:39]
	ds_write_b32 v103, v154 offset:39936
	ds_write_b32 v103, v155 offset:40000
	s_mov_b64 exec, s[8:9]
	v_pk_fma_f32 v[186:187], v[88:89], v[186:187], v[120:121] op_sel:[0,0,1] op_sel_hi:[1,1,1]
	v_pk_fma_f32 v[180:181], v[90:91], v[180:181], v[120:121] op_sel_hi:[1,1,0]
	v_pk_fma_f32 v[188:189], v[90:91], v[188:189], v[120:121] op_sel:[0,0,1] op_sel_hi:[1,1,1]
	s_waitcnt lgkmcnt(11)
	v_pk_fma_f32 v[182:183], v[92:93], v[182:183], v[120:121] op_sel_hi:[1,1,0]
	v_pk_fma_f32 v[190:191], v[92:93], v[190:191], v[120:121] op_sel:[0,0,1] op_sel_hi:[1,1,1]
	v_pk_fma_f32 v[184:185], v[94:95], v[184:185], v[120:121] op_sel_hi:[1,1,0]
	v_pk_fma_f32 v[192:193], v[94:95], v[192:193], v[120:121] op_sel:[0,0,1] op_sel_hi:[1,1,1]
	s_waitcnt lgkmcnt(10)
	v_pk_fma_f32 v[146:147], v[80:81], v[178:179], v[196:197]
	v_pk_fma_f32 v[150:151], v[80:81], v[186:187], v[196:197]
	v_pk_fma_f32 v[148:149], v[82:83], v[180:181], v[196:197]
	v_pk_fma_f32 v[152:153], v[82:83], v[188:189], v[196:197]
	s_waitcnt lgkmcnt(9)
	v_pk_fma_f32 v[146:147], v[84:85], v[182:183], v[146:147]
	v_pk_fma_f32 v[150:151], v[84:85], v[190:191], v[150:151]
	v_pk_fma_f32 v[148:149], v[86:87], v[184:185], v[148:149]
	v_pk_fma_f32 v[152:153], v[86:87], v[192:193], v[152:153]
	v_add_f32_e32 v146, v146, v147
	v_add_f32_e32 v148, v148, v149
	v_add_f32_e32 v150, v150, v151
	v_add_f32_e32 v152, v152, v153
	v_add_f32_e32 v156, v146, v148
	v_add_f32_e32 v157, v150, v152
	ds_read2_b32 v[120:121], v195 offset0:96 offset1:112
	ds_read_b128 v[88:91], v145 offset:32256
	ds_read_b128 v[92:95], v145 offset:32512
	ds_read_b128 v[80:83], v145 offset:24064
	ds_read_b128 v[84:87], v145 offset:24320
	s_waitcnt lgkmcnt(11)
	v_pk_add_f32 v[178:179], v[178:179], v[118:119] op_sel_hi:[1,0] neg_lo:[0,1] neg_hi:[0,1]
	v_add_f32_dpp v156, v156, v156 row_ror:8 row_mask:0xf bank_mask:0xf bound_ctrl:1
	v_pk_add_f32 v[186:187], v[186:187], v[118:119] op_sel:[0,1] op_sel_hi:[1,1] neg_lo:[0,1] neg_hi:[0,1]
	v_add_f32_dpp v157, v157, v157 row_ror:8 row_mask:0xf bank_mask:0xf bound_ctrl:1
	v_pk_add_f32 v[180:181], v[180:181], v[118:119] op_sel_hi:[1,0] neg_lo:[0,1] neg_hi:[0,1]
	v_add_f32_dpp v156, v156, v156 row_ror:4 row_mask:0xf bank_mask:0xf bound_ctrl:1
	v_pk_add_f32 v[188:189], v[188:189], v[118:119] op_sel:[0,1] op_sel_hi:[1,1] neg_lo:[0,1] neg_hi:[0,1]
	v_add_f32_dpp v157, v157, v157 row_ror:4 row_mask:0xf bank_mask:0xf bound_ctrl:1
	v_pk_add_f32 v[182:183], v[182:183], v[118:119] op_sel_hi:[1,0] neg_lo:[0,1] neg_hi:[0,1]
	v_add_f32_dpp v156, v156, v156 row_ror:2 row_mask:0xf bank_mask:0xf bound_ctrl:1
	v_pk_add_f32 v[190:191], v[190:191], v[118:119] op_sel:[0,1] op_sel_hi:[1,1] neg_lo:[0,1] neg_hi:[0,1]
	v_add_f32_dpp v157, v157, v157 row_ror:2 row_mask:0xf bank_mask:0xf bound_ctrl:1
	v_pk_add_f32 v[184:185], v[184:185], v[118:119] op_sel_hi:[1,0] neg_lo:[0,1] neg_hi:[0,1]
	v_add_f32_dpp v156, v156, v156 row_ror:1 row_mask:0xf bank_mask:0xf bound_ctrl:1
	v_pk_add_f32 v[192:193], v[192:193], v[118:119] op_sel:[0,1] op_sel_hi:[1,1] neg_lo:[0,1] neg_hi:[0,1]
	v_add_f32_dpp v157, v157, v157 row_ror:1 row_mask:0xf bank_mask:0xf bound_ctrl:1
	s_waitcnt lgkmcnt(10)
	v_pk_fma_f32 v[178:179], v[72:73], v[178:179], v[118:119] op_sel_hi:[1,1,0]
	s_and_saveexec_b64 s[8:9], s[38:39]
	ds_write_b32 v103, v156 offset:40064
	ds_write_b32 v103, v157 offset:40128
	s_mov_b64 exec, s[8:9]
	v_pk_fma_f32 v[186:187], v[72:73], v[186:187], v[118:119] op_sel:[0,0,1] op_sel_hi:[1,1,1]
	v_pk_fma_f32 v[180:181], v[74:75], v[180:181], v[118:119] op_sel_hi:[1,1,0]
	v_pk_fma_f32 v[188:189], v[74:75], v[188:189], v[118:119] op_sel:[0,0,1] op_sel_hi:[1,1,1]
	s_waitcnt lgkmcnt(11)
	v_pk_fma_f32 v[182:183], v[76:77], v[182:183], v[118:119] op_sel_hi:[1,1,0]
	v_pk_fma_f32 v[190:191], v[76:77], v[190:191], v[118:119] op_sel:[0,0,1] op_sel_hi:[1,1,1]
	v_pk_fma_f32 v[184:185], v[78:79], v[184:185], v[118:119] op_sel_hi:[1,1,0]
	v_pk_fma_f32 v[192:193], v[78:79], v[192:193], v[118:119] op_sel:[0,0,1] op_sel_hi:[1,1,1]
	s_waitcnt lgkmcnt(10)
	v_pk_fma_f32 v[146:147], v[64:65], v[178:179], v[196:197]
	v_pk_fma_f32 v[150:151], v[64:65], v[186:187], v[196:197]
	v_pk_fma_f32 v[148:149], v[66:67], v[180:181], v[196:197]
	v_pk_fma_f32 v[152:153], v[66:67], v[188:189], v[196:197]
	s_waitcnt lgkmcnt(9)
	v_pk_fma_f32 v[146:147], v[68:69], v[182:183], v[146:147]
	v_pk_fma_f32 v[150:151], v[68:69], v[190:191], v[150:151]
	v_pk_fma_f32 v[148:149], v[70:71], v[184:185], v[148:149]
	v_pk_fma_f32 v[152:153], v[70:71], v[192:193], v[152:153]
	v_add_f32_e32 v146, v146, v147
	v_add_f32_e32 v148, v148, v149
	v_add_f32_e32 v150, v150, v151
	v_add_f32_e32 v152, v152, v153
	v_add_f32_e32 v154, v146, v148
	v_add_f32_e32 v155, v150, v152
	ds_read2_b32 v[118:119], v195 offset0:128 offset1:144
	ds_read_b128 v[72:75], v145 offset:32768
	ds_read_b128 v[76:79], v145 offset:33024
	ds_read_b128 v[64:67], v145 offset:24576
	ds_read_b128 v[68:71], v145 offset:24832
	s_waitcnt lgkmcnt(11)
	v_pk_add_f32 v[178:179], v[178:179], v[120:121] op_sel_hi:[1,0] neg_lo:[0,1] neg_hi:[0,1]
	v_add_f32_dpp v154, v154, v154 row_ror:8 row_mask:0xf bank_mask:0xf bound_ctrl:1
	v_pk_add_f32 v[186:187], v[186:187], v[120:121] op_sel:[0,1] op_sel_hi:[1,1] neg_lo:[0,1] neg_hi:[0,1]
	v_add_f32_dpp v155, v155, v155 row_ror:8 row_mask:0xf bank_mask:0xf bound_ctrl:1
	v_pk_add_f32 v[180:181], v[180:181], v[120:121] op_sel_hi:[1,0] neg_lo:[0,1] neg_hi:[0,1]
	v_add_f32_dpp v154, v154, v154 row_ror:4 row_mask:0xf bank_mask:0xf bound_ctrl:1
	v_pk_add_f32 v[188:189], v[188:189], v[120:121] op_sel:[0,1] op_sel_hi:[1,1] neg_lo:[0,1] neg_hi:[0,1]
	v_add_f32_dpp v155, v155, v155 row_ror:4 row_mask:0xf bank_mask:0xf bound_ctrl:1
	v_pk_add_f32 v[182:183], v[182:183], v[120:121] op_sel_hi:[1,0] neg_lo:[0,1] neg_hi:[0,1]
	v_add_f32_dpp v154, v154, v154 row_ror:2 row_mask:0xf bank_mask:0xf bound_ctrl:1
	v_pk_add_f32 v[190:191], v[190:191], v[120:121] op_sel:[0,1] op_sel_hi:[1,1] neg_lo:[0,1] neg_hi:[0,1]
	v_add_f32_dpp v155, v155, v155 row_ror:2 row_mask:0xf bank_mask:0xf bound_ctrl:1
	v_pk_add_f32 v[184:185], v[184:185], v[120:121] op_sel_hi:[1,0] neg_lo:[0,1] neg_hi:[0,1]
	v_add_f32_dpp v154, v154, v154 row_ror:1 row_mask:0xf bank_mask:0xf bound_ctrl:1
	v_pk_add_f32 v[192:193], v[192:193], v[120:121] op_sel:[0,1] op_sel_hi:[1,1] neg_lo:[0,1] neg_hi:[0,1]
	v_add_f32_dpp v155, v155, v155 row_ror:1 row_mask:0xf bank_mask:0xf bound_ctrl:1
	s_waitcnt lgkmcnt(10)
	v_pk_fma_f32 v[178:179], v[88:89], v[178:179], v[120:121] op_sel_hi:[1,1,0]
	s_and_saveexec_b64 s[8:9], s[38:39]
	ds_write_b32 v103, v154 offset:40192
	ds_write_b32 v103, v155 offset:40256
	s_mov_b64 exec, s[8:9]
	v_pk_fma_f32 v[186:187], v[88:89], v[186:187], v[120:121] op_sel:[0,0,1] op_sel_hi:[1,1,1]
	v_pk_fma_f32 v[180:181], v[90:91], v[180:181], v[120:121] op_sel_hi:[1,1,0]
	v_pk_fma_f32 v[188:189], v[90:91], v[188:189], v[120:121] op_sel:[0,0,1] op_sel_hi:[1,1,1]
	s_waitcnt lgkmcnt(11)
	v_pk_fma_f32 v[182:183], v[92:93], v[182:183], v[120:121] op_sel_hi:[1,1,0]
	v_pk_fma_f32 v[190:191], v[92:93], v[190:191], v[120:121] op_sel:[0,0,1] op_sel_hi:[1,1,1]
	v_pk_fma_f32 v[184:185], v[94:95], v[184:185], v[120:121] op_sel_hi:[1,1,0]
	v_pk_fma_f32 v[192:193], v[94:95], v[192:193], v[120:121] op_sel:[0,0,1] op_sel_hi:[1,1,1]
	s_waitcnt lgkmcnt(10)
	v_pk_fma_f32 v[146:147], v[80:81], v[178:179], v[196:197]
	v_pk_fma_f32 v[150:151], v[80:81], v[186:187], v[196:197]
	v_pk_fma_f32 v[148:149], v[82:83], v[180:181], v[196:197]
	v_pk_fma_f32 v[152:153], v[82:83], v[188:189], v[196:197]
	s_waitcnt lgkmcnt(9)
	v_pk_fma_f32 v[146:147], v[84:85], v[182:183], v[146:147]
	v_pk_fma_f32 v[150:151], v[84:85], v[190:191], v[150:151]
	v_pk_fma_f32 v[148:149], v[86:87], v[184:185], v[148:149]
	v_pk_fma_f32 v[152:153], v[86:87], v[192:193], v[152:153]
	v_add_f32_e32 v146, v146, v147
	v_add_f32_e32 v148, v148, v149
	v_add_f32_e32 v150, v150, v151
	v_add_f32_e32 v152, v152, v153
	v_add_f32_e32 v156, v146, v148
	v_add_f32_e32 v157, v150, v152
	ds_read2_b32 v[120:121], v195 offset0:160 offset1:176
	ds_read_b128 v[88:91], v145 offset:33280
	ds_read_b128 v[92:95], v145 offset:33536
	ds_read_b128 v[80:83], v145 offset:25088
	ds_read_b128 v[84:87], v145 offset:25344
	s_waitcnt lgkmcnt(11)
	v_pk_add_f32 v[178:179], v[178:179], v[118:119] op_sel_hi:[1,0] neg_lo:[0,1] neg_hi:[0,1]
	v_add_f32_dpp v156, v156, v156 row_ror:8 row_mask:0xf bank_mask:0xf bound_ctrl:1
	v_pk_add_f32 v[186:187], v[186:187], v[118:119] op_sel:[0,1] op_sel_hi:[1,1] neg_lo:[0,1] neg_hi:[0,1]
	v_add_f32_dpp v157, v157, v157 row_ror:8 row_mask:0xf bank_mask:0xf bound_ctrl:1
	v_pk_add_f32 v[180:181], v[180:181], v[118:119] op_sel_hi:[1,0] neg_lo:[0,1] neg_hi:[0,1]
	v_add_f32_dpp v156, v156, v156 row_ror:4 row_mask:0xf bank_mask:0xf bound_ctrl:1
	v_pk_add_f32 v[188:189], v[188:189], v[118:119] op_sel:[0,1] op_sel_hi:[1,1] neg_lo:[0,1] neg_hi:[0,1]
	v_add_f32_dpp v157, v157, v157 row_ror:4 row_mask:0xf bank_mask:0xf bound_ctrl:1
	v_pk_add_f32 v[182:183], v[182:183], v[118:119] op_sel_hi:[1,0] neg_lo:[0,1] neg_hi:[0,1]
	v_add_f32_dpp v156, v156, v156 row_ror:2 row_mask:0xf bank_mask:0xf bound_ctrl:1
	v_pk_add_f32 v[190:191], v[190:191], v[118:119] op_sel:[0,1] op_sel_hi:[1,1] neg_lo:[0,1] neg_hi:[0,1]
	v_add_f32_dpp v157, v157, v157 row_ror:2 row_mask:0xf bank_mask:0xf bound_ctrl:1
	v_pk_add_f32 v[184:185], v[184:185], v[118:119] op_sel_hi:[1,0] neg_lo:[0,1] neg_hi:[0,1]
	v_add_f32_dpp v156, v156, v156 row_ror:1 row_mask:0xf bank_mask:0xf bound_ctrl:1
	v_pk_add_f32 v[192:193], v[192:193], v[118:119] op_sel:[0,1] op_sel_hi:[1,1] neg_lo:[0,1] neg_hi:[0,1]
	v_add_f32_dpp v157, v157, v157 row_ror:1 row_mask:0xf bank_mask:0xf bound_ctrl:1
	s_waitcnt lgkmcnt(10)
	v_pk_fma_f32 v[178:179], v[72:73], v[178:179], v[118:119] op_sel_hi:[1,1,0]
	s_and_saveexec_b64 s[8:9], s[38:39]
	ds_write_b32 v103, v156 offset:40320
	ds_write_b32 v103, v157 offset:40384
	s_mov_b64 exec, s[8:9]
	v_pk_fma_f32 v[186:187], v[72:73], v[186:187], v[118:119] op_sel:[0,0,1] op_sel_hi:[1,1,1]
	v_pk_fma_f32 v[180:181], v[74:75], v[180:181], v[118:119] op_sel_hi:[1,1,0]
	v_pk_fma_f32 v[188:189], v[74:75], v[188:189], v[118:119] op_sel:[0,0,1] op_sel_hi:[1,1,1]
	s_waitcnt lgkmcnt(11)
	v_pk_fma_f32 v[182:183], v[76:77], v[182:183], v[118:119] op_sel_hi:[1,1,0]
	v_pk_fma_f32 v[190:191], v[76:77], v[190:191], v[118:119] op_sel:[0,0,1] op_sel_hi:[1,1,1]
	v_pk_fma_f32 v[184:185], v[78:79], v[184:185], v[118:119] op_sel_hi:[1,1,0]
	v_pk_fma_f32 v[192:193], v[78:79], v[192:193], v[118:119] op_sel:[0,0,1] op_sel_hi:[1,1,1]
	s_waitcnt lgkmcnt(10)
	v_pk_fma_f32 v[146:147], v[64:65], v[178:179], v[196:197]
	v_pk_fma_f32 v[150:151], v[64:65], v[186:187], v[196:197]
	v_pk_fma_f32 v[148:149], v[66:67], v[180:181], v[196:197]
	v_pk_fma_f32 v[152:153], v[66:67], v[188:189], v[196:197]
	s_waitcnt lgkmcnt(9)
	v_pk_fma_f32 v[146:147], v[68:69], v[182:183], v[146:147]
	v_pk_fma_f32 v[150:151], v[68:69], v[190:191], v[150:151]
	v_pk_fma_f32 v[148:149], v[70:71], v[184:185], v[148:149]
	v_pk_fma_f32 v[152:153], v[70:71], v[192:193], v[152:153]
	v_add_f32_e32 v146, v146, v147
	v_add_f32_e32 v148, v148, v149
	v_add_f32_e32 v150, v150, v151
	v_add_f32_e32 v152, v152, v153
	v_add_f32_e32 v154, v146, v148
	v_add_f32_e32 v155, v150, v152
	ds_read2_b32 v[118:119], v195 offset0:192 offset1:208
	ds_read_b128 v[72:75], v145 offset:33792
	ds_read_b128 v[76:79], v145 offset:34048
	ds_read_b128 v[64:67], v145 offset:25600
	ds_read_b128 v[68:71], v145 offset:25856
	s_waitcnt lgkmcnt(11)
	v_pk_add_f32 v[178:179], v[178:179], v[120:121] op_sel_hi:[1,0] neg_lo:[0,1] neg_hi:[0,1]
	v_add_f32_dpp v154, v154, v154 row_ror:8 row_mask:0xf bank_mask:0xf bound_ctrl:1
	v_pk_add_f32 v[186:187], v[186:187], v[120:121] op_sel:[0,1] op_sel_hi:[1,1] neg_lo:[0,1] neg_hi:[0,1]
	v_add_f32_dpp v155, v155, v155 row_ror:8 row_mask:0xf bank_mask:0xf bound_ctrl:1
	v_pk_add_f32 v[180:181], v[180:181], v[120:121] op_sel_hi:[1,0] neg_lo:[0,1] neg_hi:[0,1]
	v_add_f32_dpp v154, v154, v154 row_ror:4 row_mask:0xf bank_mask:0xf bound_ctrl:1
	v_pk_add_f32 v[188:189], v[188:189], v[120:121] op_sel:[0,1] op_sel_hi:[1,1] neg_lo:[0,1] neg_hi:[0,1]
	v_add_f32_dpp v155, v155, v155 row_ror:4 row_mask:0xf bank_mask:0xf bound_ctrl:1
	v_pk_add_f32 v[182:183], v[182:183], v[120:121] op_sel_hi:[1,0] neg_lo:[0,1] neg_hi:[0,1]
	v_add_f32_dpp v154, v154, v154 row_ror:2 row_mask:0xf bank_mask:0xf bound_ctrl:1
	v_pk_add_f32 v[190:191], v[190:191], v[120:121] op_sel:[0,1] op_sel_hi:[1,1] neg_lo:[0,1] neg_hi:[0,1]
	v_add_f32_dpp v155, v155, v155 row_ror:2 row_mask:0xf bank_mask:0xf bound_ctrl:1
	v_pk_add_f32 v[184:185], v[184:185], v[120:121] op_sel_hi:[1,0] neg_lo:[0,1] neg_hi:[0,1]
	v_add_f32_dpp v154, v154, v154 row_ror:1 row_mask:0xf bank_mask:0xf bound_ctrl:1
	v_pk_add_f32 v[192:193], v[192:193], v[120:121] op_sel:[0,1] op_sel_hi:[1,1] neg_lo:[0,1] neg_hi:[0,1]
	v_add_f32_dpp v155, v155, v155 row_ror:1 row_mask:0xf bank_mask:0xf bound_ctrl:1
	s_waitcnt lgkmcnt(10)
	v_pk_fma_f32 v[178:179], v[88:89], v[178:179], v[120:121] op_sel_hi:[1,1,0]
	s_and_saveexec_b64 s[8:9], s[38:39]
	ds_write_b32 v103, v154 offset:40448
	ds_write_b32 v103, v155 offset:40512
	s_mov_b64 exec, s[8:9]
	v_pk_fma_f32 v[186:187], v[88:89], v[186:187], v[120:121] op_sel:[0,0,1] op_sel_hi:[1,1,1]
	v_pk_fma_f32 v[180:181], v[90:91], v[180:181], v[120:121] op_sel_hi:[1,1,0]
	v_pk_fma_f32 v[188:189], v[90:91], v[188:189], v[120:121] op_sel:[0,0,1] op_sel_hi:[1,1,1]
	s_waitcnt lgkmcnt(11)
	v_pk_fma_f32 v[182:183], v[92:93], v[182:183], v[120:121] op_sel_hi:[1,1,0]
	v_pk_fma_f32 v[190:191], v[92:93], v[190:191], v[120:121] op_sel:[0,0,1] op_sel_hi:[1,1,1]
	v_pk_fma_f32 v[184:185], v[94:95], v[184:185], v[120:121] op_sel_hi:[1,1,0]
	v_pk_fma_f32 v[192:193], v[94:95], v[192:193], v[120:121] op_sel:[0,0,1] op_sel_hi:[1,1,1]
	s_waitcnt lgkmcnt(10)
	v_pk_fma_f32 v[146:147], v[80:81], v[178:179], v[196:197]
	v_pk_fma_f32 v[150:151], v[80:81], v[186:187], v[196:197]
	v_pk_fma_f32 v[148:149], v[82:83], v[180:181], v[196:197]
	v_pk_fma_f32 v[152:153], v[82:83], v[188:189], v[196:197]
	s_waitcnt lgkmcnt(9)
	v_pk_fma_f32 v[146:147], v[84:85], v[182:183], v[146:147]
	v_pk_fma_f32 v[150:151], v[84:85], v[190:191], v[150:151]
	v_pk_fma_f32 v[148:149], v[86:87], v[184:185], v[148:149]
	v_pk_fma_f32 v[152:153], v[86:87], v[192:193], v[152:153]
	v_add_f32_e32 v146, v146, v147
	v_add_f32_e32 v148, v148, v149
	v_add_f32_e32 v150, v150, v151
	v_add_f32_e32 v152, v152, v153
	v_add_f32_e32 v156, v146, v148
	v_add_f32_e32 v157, v150, v152
	ds_read2_b32 v[120:121], v195 offset0:224 offset1:240
	ds_read_b128 v[88:91], v145 offset:34304
	ds_read_b128 v[92:95], v145 offset:34560
	ds_read_b128 v[80:83], v145 offset:26112
	ds_read_b128 v[84:87], v145 offset:26368
	s_waitcnt lgkmcnt(11)
	v_pk_add_f32 v[178:179], v[178:179], v[118:119] op_sel_hi:[1,0] neg_lo:[0,1] neg_hi:[0,1]
	v_add_f32_dpp v156, v156, v156 row_ror:8 row_mask:0xf bank_mask:0xf bound_ctrl:1
	v_pk_add_f32 v[186:187], v[186:187], v[118:119] op_sel:[0,1] op_sel_hi:[1,1] neg_lo:[0,1] neg_hi:[0,1]
	v_add_f32_dpp v157, v157, v157 row_ror:8 row_mask:0xf bank_mask:0xf bound_ctrl:1
	v_pk_add_f32 v[180:181], v[180:181], v[118:119] op_sel_hi:[1,0] neg_lo:[0,1] neg_hi:[0,1]
	v_add_f32_dpp v156, v156, v156 row_ror:4 row_mask:0xf bank_mask:0xf bound_ctrl:1
	v_pk_add_f32 v[188:189], v[188:189], v[118:119] op_sel:[0,1] op_sel_hi:[1,1] neg_lo:[0,1] neg_hi:[0,1]
	v_add_f32_dpp v157, v157, v157 row_ror:4 row_mask:0xf bank_mask:0xf bound_ctrl:1
	v_pk_add_f32 v[182:183], v[182:183], v[118:119] op_sel_hi:[1,0] neg_lo:[0,1] neg_hi:[0,1]
	v_add_f32_dpp v156, v156, v156 row_ror:2 row_mask:0xf bank_mask:0xf bound_ctrl:1
	v_pk_add_f32 v[190:191], v[190:191], v[118:119] op_sel:[0,1] op_sel_hi:[1,1] neg_lo:[0,1] neg_hi:[0,1]
	v_add_f32_dpp v157, v157, v157 row_ror:2 row_mask:0xf bank_mask:0xf bound_ctrl:1
	v_pk_add_f32 v[184:185], v[184:185], v[118:119] op_sel_hi:[1,0] neg_lo:[0,1] neg_hi:[0,1]
	v_add_f32_dpp v156, v156, v156 row_ror:1 row_mask:0xf bank_mask:0xf bound_ctrl:1
	v_pk_add_f32 v[192:193], v[192:193], v[118:119] op_sel:[0,1] op_sel_hi:[1,1] neg_lo:[0,1] neg_hi:[0,1]
	v_add_f32_dpp v157, v157, v157 row_ror:1 row_mask:0xf bank_mask:0xf bound_ctrl:1
	s_waitcnt lgkmcnt(10)
	v_pk_fma_f32 v[178:179], v[72:73], v[178:179], v[118:119] op_sel_hi:[1,1,0]
	s_and_saveexec_b64 s[8:9], s[38:39]
	ds_write_b32 v103, v156 offset:40576
	ds_write_b32 v103, v157 offset:40640
	s_mov_b64 exec, s[8:9]
	v_pk_fma_f32 v[186:187], v[72:73], v[186:187], v[118:119] op_sel:[0,0,1] op_sel_hi:[1,1,1]
	v_pk_fma_f32 v[180:181], v[74:75], v[180:181], v[118:119] op_sel_hi:[1,1,0]
	v_pk_fma_f32 v[188:189], v[74:75], v[188:189], v[118:119] op_sel:[0,0,1] op_sel_hi:[1,1,1]
	s_waitcnt lgkmcnt(11)
	v_pk_fma_f32 v[182:183], v[76:77], v[182:183], v[118:119] op_sel_hi:[1,1,0]
	v_pk_fma_f32 v[190:191], v[76:77], v[190:191], v[118:119] op_sel:[0,0,1] op_sel_hi:[1,1,1]
	v_pk_fma_f32 v[184:185], v[78:79], v[184:185], v[118:119] op_sel_hi:[1,1,0]
	v_pk_fma_f32 v[192:193], v[78:79], v[192:193], v[118:119] op_sel:[0,0,1] op_sel_hi:[1,1,1]
	s_waitcnt lgkmcnt(10)
	v_pk_fma_f32 v[146:147], v[64:65], v[178:179], v[196:197]
	v_pk_fma_f32 v[150:151], v[64:65], v[186:187], v[196:197]
	v_pk_fma_f32 v[148:149], v[66:67], v[180:181], v[196:197]
	v_pk_fma_f32 v[152:153], v[66:67], v[188:189], v[196:197]
	s_waitcnt lgkmcnt(9)
	v_pk_fma_f32 v[146:147], v[68:69], v[182:183], v[146:147]
	v_pk_fma_f32 v[150:151], v[68:69], v[190:191], v[150:151]
	v_pk_fma_f32 v[148:149], v[70:71], v[184:185], v[148:149]
	v_pk_fma_f32 v[152:153], v[70:71], v[192:193], v[152:153]
	v_add_f32_e32 v146, v146, v147
	v_add_f32_e32 v148, v148, v149
	v_add_f32_e32 v150, v150, v151
	v_add_f32_e32 v152, v152, v153
	v_add_f32_e32 v154, v146, v148
	v_add_f32_e32 v155, v150, v152
	s_waitcnt lgkmcnt(6)
	v_pk_add_f32 v[178:179], v[178:179], v[120:121] op_sel_hi:[1,0] neg_lo:[0,1] neg_hi:[0,1]
	v_add_f32_dpp v154, v154, v154 row_ror:8 row_mask:0xf bank_mask:0xf bound_ctrl:1
	v_pk_add_f32 v[186:187], v[186:187], v[120:121] op_sel:[0,1] op_sel_hi:[1,1] neg_lo:[0,1] neg_hi:[0,1]
	v_add_f32_dpp v155, v155, v155 row_ror:8 row_mask:0xf bank_mask:0xf bound_ctrl:1
	v_pk_add_f32 v[180:181], v[180:181], v[120:121] op_sel_hi:[1,0] neg_lo:[0,1] neg_hi:[0,1]
	v_add_f32_dpp v154, v154, v154 row_ror:4 row_mask:0xf bank_mask:0xf bound_ctrl:1
	v_pk_add_f32 v[188:189], v[188:189], v[120:121] op_sel:[0,1] op_sel_hi:[1,1] neg_lo:[0,1] neg_hi:[0,1]
	v_add_f32_dpp v155, v155, v155 row_ror:4 row_mask:0xf bank_mask:0xf bound_ctrl:1
	v_pk_add_f32 v[182:183], v[182:183], v[120:121] op_sel_hi:[1,0] neg_lo:[0,1] neg_hi:[0,1]
	v_add_f32_dpp v154, v154, v154 row_ror:2 row_mask:0xf bank_mask:0xf bound_ctrl:1
	v_pk_add_f32 v[190:191], v[190:191], v[120:121] op_sel:[0,1] op_sel_hi:[1,1] neg_lo:[0,1] neg_hi:[0,1]
	v_add_f32_dpp v155, v155, v155 row_ror:2 row_mask:0xf bank_mask:0xf bound_ctrl:1
	v_pk_add_f32 v[184:185], v[184:185], v[120:121] op_sel_hi:[1,0] neg_lo:[0,1] neg_hi:[0,1]
	v_add_f32_dpp v154, v154, v154 row_ror:1 row_mask:0xf bank_mask:0xf bound_ctrl:1
	v_pk_add_f32 v[192:193], v[192:193], v[120:121] op_sel:[0,1] op_sel_hi:[1,1] neg_lo:[0,1] neg_hi:[0,1]
	v_add_f32_dpp v155, v155, v155 row_ror:1 row_mask:0xf bank_mask:0xf bound_ctrl:1
	s_waitcnt lgkmcnt(5)
	v_pk_fma_f32 v[178:179], v[88:89], v[178:179], v[120:121] op_sel_hi:[1,1,0]
	s_and_saveexec_b64 s[8:9], s[38:39]
	ds_write_b32 v103, v154 offset:40704
	ds_write_b32 v103, v155 offset:40768
	s_mov_b64 exec, s[8:9]
	v_pk_fma_f32 v[186:187], v[88:89], v[186:187], v[120:121] op_sel:[0,0,1] op_sel_hi:[1,1,1]
	v_pk_fma_f32 v[180:181], v[90:91], v[180:181], v[120:121] op_sel_hi:[1,1,0]
	v_pk_fma_f32 v[188:189], v[90:91], v[188:189], v[120:121] op_sel:[0,0,1] op_sel_hi:[1,1,1]
	s_waitcnt lgkmcnt(6)
	v_pk_fma_f32 v[182:183], v[92:93], v[182:183], v[120:121] op_sel_hi:[1,1,0]
	v_pk_fma_f32 v[190:191], v[92:93], v[190:191], v[120:121] op_sel:[0,0,1] op_sel_hi:[1,1,1]
	v_pk_fma_f32 v[184:185], v[94:95], v[184:185], v[120:121] op_sel_hi:[1,1,0]
	v_pk_fma_f32 v[192:193], v[94:95], v[192:193], v[120:121] op_sel:[0,0,1] op_sel_hi:[1,1,1]
	s_waitcnt lgkmcnt(5)
	v_pk_fma_f32 v[146:147], v[80:81], v[178:179], v[196:197]
	v_pk_fma_f32 v[150:151], v[80:81], v[186:187], v[196:197]
	v_pk_fma_f32 v[148:149], v[82:83], v[180:181], v[196:197]
	v_pk_fma_f32 v[152:153], v[82:83], v[188:189], v[196:197]
	s_waitcnt lgkmcnt(4)
	v_pk_fma_f32 v[146:147], v[84:85], v[182:183], v[146:147]
	v_pk_fma_f32 v[150:151], v[84:85], v[190:191], v[150:151]
	v_pk_fma_f32 v[148:149], v[86:87], v[184:185], v[148:149]
	v_pk_fma_f32 v[152:153], v[86:87], v[192:193], v[152:153]
	v_add_f32_e32 v146, v146, v147
	v_add_f32_e32 v148, v148, v149
	v_add_f32_e32 v150, v150, v151
	v_add_f32_e32 v152, v152, v153
	v_add_f32_e32 v156, v146, v148
	v_add_f32_e32 v157, v150, v152
	s_nop 0
	v_add_f32_dpp v156, v156, v156 row_ror:8 row_mask:0xf bank_mask:0xf bound_ctrl:1
	v_add_f32_dpp v157, v157, v157 row_ror:8 row_mask:0xf bank_mask:0xf bound_ctrl:1
	s_nop 0
	v_add_f32_dpp v156, v156, v156 row_ror:4 row_mask:0xf bank_mask:0xf bound_ctrl:1
	v_add_f32_dpp v157, v157, v157 row_ror:4 row_mask:0xf bank_mask:0xf bound_ctrl:1
	s_nop 0
	v_add_f32_dpp v156, v156, v156 row_ror:2 row_mask:0xf bank_mask:0xf bound_ctrl:1
	v_add_f32_dpp v157, v157, v157 row_ror:2 row_mask:0xf bank_mask:0xf bound_ctrl:1
	s_nop 0
	v_add_f32_dpp v156, v156, v156 row_ror:1 row_mask:0xf bank_mask:0xf bound_ctrl:1
	v_add_f32_dpp v157, v157, v157 row_ror:1 row_mask:0xf bank_mask:0xf bound_ctrl:1
	s_and_saveexec_b64 s[8:9], s[38:39]
	ds_write_b32 v103, v156 offset:40832
	ds_write_b32 v103, v157 offset:40896
	s_mov_b64 exec, s[8:9]
	s_waitcnt vmcnt(9)
	v_mul_f32_e32 v64, 0xbfb8aa3b, v28
	v_mul_f32_e32 v65, 0xbfb8aa3b, v29
	v_exp_f32_e32 v64, v64
	v_exp_f32_e32 v65, v65
	v_mul_f32_e32 v66, 0xbfb8aa3b, v30
	v_mul_f32_e32 v67, 0xbfb8aa3b, v31
	v_exp_f32_e32 v66, v66
	v_pk_add_f32 v[64:65], v[64:65], 1.0 op_sel_hi:[1,0]
	v_exp_f32_e32 v67, v67
	v_div_scale_f32 v80, s[8:9], v65, v65, v29
	v_rcp_f32_e32 v81, v80
	v_pk_add_f32 v[66:67], v[66:67], 1.0 op_sel_hi:[1,0]
	s_waitcnt vmcnt(8)
	v_mul_f32_e32 v72, 0xbfb8aa3b, v32
	v_mul_f32_e32 v73, 0xbfb8aa3b, v33
	v_fma_f32 v82, -v80, v81, 1.0
	v_fmac_f32_e32 v81, v82, v81
	v_div_scale_f32 v82, vcc, v29, v65, v29
	v_mul_f32_e32 v83, v82, v81
	v_fma_f32 v88, -v80, v83, v82
	v_fmac_f32_e32 v83, v88, v81
	v_fma_f32 v80, -v80, v83, v82
	v_div_fmas_f32 v80, v80, v81, v83
	v_div_fixup_f32 v65, v80, v65, v29
	v_div_scale_f32 v80, s[8:9], v64, v64, v28
	v_rcp_f32_e32 v81, v80
	v_exp_f32_e32 v72, v72
	v_exp_f32_e32 v73, v73
	v_mul_f32_e32 v74, 0xbfb8aa3b, v34
	v_fma_f32 v82, -v80, v81, 1.0
	v_fmac_f32_e32 v81, v82, v81
	v_div_scale_f32 v82, vcc, v28, v64, v28
	v_mul_f32_e32 v83, v82, v81
	v_fma_f32 v88, -v80, v83, v82
	v_fmac_f32_e32 v83, v88, v81
	v_fma_f32 v80, -v80, v83, v82
	v_div_fmas_f32 v80, v80, v81, v83
	v_div_fixup_f32 v64, v80, v64, v28
	v_div_scale_f32 v80, s[8:9], v67, v67, v31
	v_rcp_f32_e32 v81, v80
	v_pk_mul_f32 v[64:65], v[64:65], s[18:19] op_sel_hi:[1,0]
	v_mul_f32_e32 v75, 0xbfb8aa3b, v35
	v_exp_f32_e32 v74, v74
	v_fma_f32 v82, -v80, v81, 1.0
	v_fmac_f32_e32 v81, v82, v81
	v_div_scale_f32 v82, vcc, v31, v67, v31
	v_mul_f32_e32 v83, v82, v81
	v_fma_f32 v88, -v80, v83, v82
	v_fmac_f32_e32 v83, v88, v81
	v_fma_f32 v80, -v80, v83, v82
	v_div_fmas_f32 v80, v80, v81, v83
	v_div_fixup_f32 v67, v80, v67, v31
	v_div_scale_f32 v80, s[8:9], v66, v66, v30
	v_rcp_f32_e32 v81, v80
	v_exp_f32_e32 v75, v75
	s_cmpk_gt_u32 s48, 0x79
	v_fma_f32 v82, -v80, v81, 1.0
	v_fmac_f32_e32 v81, v82, v81
	v_div_scale_f32 v82, vcc, v30, v66, v30
	v_mul_f32_e32 v83, v82, v81
	v_fma_f32 v88, -v80, v83, v82
	v_fmac_f32_e32 v83, v88, v81
	v_fma_f32 v80, -v80, v83, v82
	v_div_fmas_f32 v80, v80, v81, v83
	v_div_fixup_f32 v66, v80, v66, v30
	v_pk_mul_f32 v[66:67], v[66:67], s[18:19] op_sel_hi:[1,0]
	ds_write_b128 v141, v[64:67]
	v_pk_add_f32 v[64:65], v[72:73], 1.0 op_sel_hi:[1,0]
	v_div_scale_f32 v66, s[8:9], v65, v65, 1.0
	v_rcp_f32_e32 v67, v66
	s_nop 0
	v_fma_f32 v72, -v66, v67, 1.0
	v_fmac_f32_e32 v67, v72, v67
	v_div_scale_f32 v72, vcc, 1.0, v65, 1.0
	v_mul_f32_e32 v73, v72, v67
	v_fma_f32 v80, -v66, v73, v72
	v_fmac_f32_e32 v73, v80, v67
	v_fma_f32 v66, -v66, v73, v72
	v_div_fmas_f32 v66, v66, v67, v73
	v_div_fixup_f32 v65, v66, v65, 1.0
	v_div_scale_f32 v66, s[8:9], v64, v64, 1.0
	v_rcp_f32_e32 v67, v66
	s_nop 0
	v_fma_f32 v72, -v66, v67, 1.0
	v_fmac_f32_e32 v67, v72, v67
	v_div_scale_f32 v72, vcc, 1.0, v64, 1.0
	v_mul_f32_e32 v73, v72, v67
	v_fma_f32 v80, -v66, v73, v72
	v_fmac_f32_e32 v73, v80, v67
	v_fma_f32 v66, -v66, v73, v72
	v_div_fmas_f32 v66, v66, v67, v73
	v_div_fixup_f32 v64, v66, v64, 1.0
	v_pk_add_f32 v[66:67], v[74:75], 1.0 op_sel_hi:[1,0]
	v_pk_fma_f32 v[64:65], v[110:111], v[64:65], v[104:105]
	v_div_scale_f32 v72, s[8:9], v67, v67, 1.0
	v_rcp_f32_e32 v73, v72
	s_nop 0
	v_fma_f32 v74, -v72, v73, 1.0
	v_fmac_f32_e32 v73, v74, v73
	v_div_scale_f32 v74, vcc, 1.0, v67, 1.0
	v_mul_f32_e32 v75, v74, v73
	v_fma_f32 v80, -v72, v75, v74
	v_fmac_f32_e32 v75, v80, v73
	v_fma_f32 v72, -v72, v75, v74
	v_div_fmas_f32 v72, v72, v73, v75
	v_div_fixup_f32 v67, v72, v67, 1.0
	v_div_scale_f32 v72, s[8:9], v66, v66, 1.0
	v_rcp_f32_e32 v73, v72
	s_nop 0
	v_fma_f32 v74, -v72, v73, 1.0
	v_fmac_f32_e32 v73, v74, v73
	v_div_scale_f32 v74, vcc, 1.0, v66, 1.0
	v_mul_f32_e32 v75, v74, v73
	v_fma_f32 v80, -v72, v75, v74
	v_fmac_f32_e32 v75, v80, v73
	v_fma_f32 v72, -v72, v75, v74
	v_div_fmas_f32 v72, v72, v73, v75
	v_div_fixup_f32 v66, v72, v66, 1.0
	v_pk_fma_f32 v[66:67], v[112:113], v[66:67], v[106:107]
	ds_write_b128 v141, v[64:67] offset:8192
	ds_write_b32 v134, v131 offset:16384
	v_mul_f32_e32 v64, 0xbfb8aa3b, v40
	v_mul_f32_e32 v65, 0xbfb8aa3b, v41
	v_exp_f32_e32 v64, v64
	v_exp_f32_e32 v65, v65
	v_mul_f32_e32 v66, 0xbfb8aa3b, v42
	v_mul_f32_e32 v67, 0xbfb8aa3b, v43
	v_exp_f32_e32 v66, v66
	v_pk_add_f32 v[64:65], v[64:65], 1.0 op_sel_hi:[1,0]
	v_exp_f32_e32 v67, v67
	v_div_scale_f32 v80, s[8:9], v65, v65, v41
	v_rcp_f32_e32 v81, v80
	v_pk_add_f32 v[66:67], v[66:67], 1.0 op_sel_hi:[1,0]
	s_waitcnt vmcnt(7)
	v_mul_f32_e32 v72, 0xbfb8aa3b, v52
	v_mul_f32_e32 v73, 0xbfb8aa3b, v53
	v_fma_f32 v82, -v80, v81, 1.0
	v_fmac_f32_e32 v81, v82, v81
	v_div_scale_f32 v82, vcc, v41, v65, v41
	v_mul_f32_e32 v83, v82, v81
	v_fma_f32 v88, -v80, v83, v82
	v_fmac_f32_e32 v83, v88, v81
	v_fma_f32 v80, -v80, v83, v82
	v_div_fmas_f32 v80, v80, v81, v83
	v_div_fixup_f32 v65, v80, v65, v41
	v_div_scale_f32 v80, s[8:9], v64, v64, v40
	v_rcp_f32_e32 v81, v80
	v_exp_f32_e32 v72, v72
	v_exp_f32_e32 v73, v73
	v_mul_f32_e32 v74, 0xbfb8aa3b, v54
	v_fma_f32 v82, -v80, v81, 1.0
	v_fmac_f32_e32 v81, v82, v81
	v_div_scale_f32 v82, vcc, v40, v64, v40
	v_mul_f32_e32 v83, v82, v81
	v_fma_f32 v88, -v80, v83, v82
	v_fmac_f32_e32 v83, v88, v81
	v_fma_f32 v80, -v80, v83, v82
	v_div_fmas_f32 v80, v80, v81, v83
	v_div_fixup_f32 v64, v80, v64, v40
	v_div_scale_f32 v80, s[8:9], v67, v67, v43
	v_rcp_f32_e32 v81, v80
	v_pk_mul_f32 v[64:65], v[64:65], s[18:19] op_sel_hi:[1,0]
	v_mul_f32_e32 v75, 0xbfb8aa3b, v55
	v_exp_f32_e32 v74, v74
	v_fma_f32 v82, -v80, v81, 1.0
	v_fmac_f32_e32 v81, v82, v81
	v_div_scale_f32 v82, vcc, v43, v67, v43
	v_mul_f32_e32 v83, v82, v81
	v_fma_f32 v88, -v80, v83, v82
	v_fmac_f32_e32 v83, v88, v81
	v_fma_f32 v80, -v80, v83, v82
	v_div_fmas_f32 v80, v80, v81, v83
	v_div_fixup_f32 v67, v80, v67, v43
	v_div_scale_f32 v80, s[8:9], v66, v66, v42
	v_rcp_f32_e32 v81, v80
	v_exp_f32_e32 v75, v75
	v_fma_f32 v82, -v80, v81, 1.0
	v_fmac_f32_e32 v81, v82, v81
	v_div_scale_f32 v82, vcc, v42, v66, v42
	v_mul_f32_e32 v83, v82, v81
	v_fma_f32 v88, -v80, v83, v82
	v_fmac_f32_e32 v83, v88, v81
	v_fma_f32 v80, -v80, v83, v82
	v_div_fmas_f32 v80, v80, v81, v83
	v_div_fixup_f32 v66, v80, v66, v42
	v_pk_mul_f32 v[66:67], v[66:67], s[18:19] op_sel_hi:[1,0]
	ds_write_b128 v144, v[64:67]
	v_pk_add_f32 v[64:65], v[72:73], 1.0 op_sel_hi:[1,0]
	v_div_scale_f32 v66, s[8:9], v65, v65, 1.0
	v_rcp_f32_e32 v67, v66
	s_nop 0
	v_fma_f32 v72, -v66, v67, 1.0
	v_fmac_f32_e32 v67, v72, v67
	v_div_scale_f32 v72, vcc, 1.0, v65, 1.0
	v_mul_f32_e32 v73, v72, v67
	v_fma_f32 v80, -v66, v73, v72
	v_fmac_f32_e32 v73, v80, v67
	v_fma_f32 v66, -v66, v73, v72
	v_div_fmas_f32 v66, v66, v67, v73
	v_div_fixup_f32 v65, v66, v65, 1.0
	v_div_scale_f32 v66, s[8:9], v64, v64, 1.0
	v_rcp_f32_e32 v67, v66
	s_nop 0
	v_fma_f32 v72, -v66, v67, 1.0
	v_fmac_f32_e32 v67, v72, v67
	v_div_scale_f32 v72, vcc, 1.0, v64, 1.0
	v_mul_f32_e32 v73, v72, v67
	v_fma_f32 v80, -v66, v73, v72
	v_fmac_f32_e32 v73, v80, v67
	v_fma_f32 v66, -v66, v73, v72
	v_div_fmas_f32 v66, v66, v67, v73
	v_div_fixup_f32 v64, v66, v64, 1.0
	v_pk_add_f32 v[66:67], v[74:75], 1.0 op_sel_hi:[1,0]
	v_pk_fma_f32 v[64:65], v[110:111], v[64:65], v[104:105]
	v_div_scale_f32 v72, s[8:9], v67, v67, 1.0
	v_rcp_f32_e32 v73, v72
	s_nop 0
	v_fma_f32 v74, -v72, v73, 1.0
	v_fmac_f32_e32 v73, v74, v73
	v_div_scale_f32 v74, vcc, 1.0, v67, 1.0
	v_mul_f32_e32 v75, v74, v73
	v_fma_f32 v80, -v72, v75, v74
	v_fmac_f32_e32 v75, v80, v73
	v_fma_f32 v72, -v72, v75, v74
	v_div_fmas_f32 v72, v72, v73, v75
	v_div_fixup_f32 v67, v72, v67, 1.0
	v_div_scale_f32 v72, s[8:9], v66, v66, 1.0
	v_rcp_f32_e32 v73, v72
	s_nop 0
	v_fma_f32 v74, -v72, v73, 1.0
	v_fmac_f32_e32 v73, v74, v73
	v_div_scale_f32 v74, vcc, 1.0, v66, 1.0
	v_mul_f32_e32 v75, v74, v73
	v_fma_f32 v80, -v72, v75, v74
	v_fmac_f32_e32 v75, v80, v73
	v_fma_f32 v72, -v72, v75, v74
	v_div_fmas_f32 v72, v72, v73, v75
	v_div_fixup_f32 v66, v72, v66, 1.0
	v_pk_fma_f32 v[66:67], v[112:113], v[66:67], v[106:107]
	ds_write_b128 v144, v[64:67] offset:8192
	s_waitcnt vmcnt(6)
	ds_write_b32 v134, v132 offset:17408
	s_waitcnt lgkmcnt(0)
	s_barrier
	s_cbranch_scc1 .LBB0_1359
	v_add_u32_e32 v28, 0x60, v98
	v_mov_b64_e32 v[40:41], s[30:31]
	v_mad_i64_i32 v[28:29], s[8:9], v28, s25, v[40:41]
	s_lshl_b32 s94, s46, 2
	v_lshl_add_u64 v[42:43], v[28:29], 0, s[94:95]
	v_mov_b32_e32 v117, v140
	v_lshl_add_u64 v[28:29], v[42:43], 0, v[116:117]
	v_add_co_u32_e32 v30, vcc, 0x4000, v28
	s_lshl_b32 s8, s42, 2
	s_nop 0
	v_addc_co_u32_e32 v31, vcc, 0, v29, vcc
	s_mov_b32 s9, s95
	v_add_co_u32_e32 v32, vcc, 0x5000, v28
	v_lshl_add_u64 v[42:43], v[42:43], 0, s[8:9]
	v_mov_b32_e32 v115, v140
	v_add_u32_e32 v52, 0x60, v96
	v_addc_co_u32_e32 v33, vcc, 0, v29, vcc
	v_lshl_add_u64 v[42:43], v[42:43], 0, v[114:115]
	v_mad_i64_i32 v[40:41], s[22:23], v52, s25, v[40:41]
	v_add_co_u32_e32 v42, vcc, s81, v42
	v_lshl_add_u64 v[52:53], v[40:41], 0, s[94:95]
	s_nop 0
	v_addc_co_u32_e32 v43, vcc, 0, v43, vcc
	v_lshl_add_u64 v[54:55], v[52:53], 0, v[116:117]
	v_add_co_u32_e32 v40, vcc, s80, v54
	v_lshl_add_u64 v[52:53], v[52:53], 0, s[8:9]
	s_nop 0
	v_addc_co_u32_e32 v41, vcc, 0, v55, vcc
	v_add_co_u32_e32 v54, vcc, 0x5000, v54
	v_lshl_add_u64 v[52:53], v[52:53], 0, v[114:115]
	s_nop 0
	v_addc_co_u32_e32 v55, vcc, 0, v55, vcc
	v_add_co_u32_e32 v64, vcc, 0x6000, v52
	global_load_dwordx4 v[28:31], v[30:31], off offset:32
	s_nop 0
	global_load_dwordx4 v[32:35], v[32:33], off offset:32
	s_nop 0
	global_load_dword v131, v[42:43], off offset:32
	s_nop 0
	global_load_dwordx4 v[40:43], v[40:41], off offset:32
	v_addc_co_u32_e32 v65, vcc, 0, v53, vcc
	global_load_dwordx4 v[52:55], v[54:55], off offset:32
	s_nop 0
	global_load_dword v132, v[64:65], off offset:32
.LBB0_1359:
	ds_read2st64_b32 v[64:65], v134 offset0:152 offset1:156
	v_add_u32_e32 v66, 16, v98
	v_ashrrev_i32_e32 v67, 31, v66
	v_lshlrev_b64 v[66:67], 12, v[66:67]
	v_lshl_add_u64 v[66:67], v[108:109], 0, v[66:67]
	s_waitcnt lgkmcnt(0)
	global_store_dword v[66:67], v64, off
	v_add_u32_e32 v66, 16, v96
	v_ashrrev_i32_e32 v67, 31, v66
	v_lshlrev_b64 v[66:67], 12, v[66:67]
	v_lshl_add_u64 v[66:67], v[108:109], 0, v[66:67]
	global_store_dword v[66:67], v65, off
	v_mov_b32_e32 v196, 0
	v_mov_b32_e32 v197, 0
	v_add_u32_e32 v194, 0x4000, v103
	v_add_u32_e32 v195, 0x4400, v103
	ds_read2_b32 v[118:119], v194 offset0:0 offset1:16
	ds_read_b128 v[72:75], v145 offset:8192
	ds_read_b128 v[76:79], v145 offset:8448
	ds_read_b128 v[64:67], v145
	ds_read_b128 v[68:71], v145 offset:256
	ds_read2_b32 v[120:121], v194 offset0:32 offset1:48
	ds_read_b128 v[88:91], v145 offset:8704
	ds_read_b128 v[92:95], v145 offset:8960
	ds_read_b128 v[80:83], v145 offset:512
	ds_read_b128 v[84:87], v145 offset:768
	s_waitcnt lgkmcnt(9)
	v_pk_add_f32 v[178:179], v[178:179], v[118:119] op_sel_hi:[1,0] neg_lo:[0,1] neg_hi:[0,1]
	v_pk_add_f32 v[186:187], v[186:187], v[118:119] op_sel:[0,1] op_sel_hi:[1,1] neg_lo:[0,1] neg_hi:[0,1]
	v_pk_add_f32 v[180:181], v[180:181], v[118:119] op_sel_hi:[1,0] neg_lo:[0,1] neg_hi:[0,1]
	v_pk_add_f32 v[188:189], v[188:189], v[118:119] op_sel:[0,1] op_sel_hi:[1,1] neg_lo:[0,1] neg_hi:[0,1]
	v_pk_add_f32 v[182:183], v[182:183], v[118:119] op_sel_hi:[1,0] neg_lo:[0,1] neg_hi:[0,1]
	v_pk_add_f32 v[190:191], v[190:191], v[118:119] op_sel:[0,1] op_sel_hi:[1,1] neg_lo:[0,1] neg_hi:[0,1]
	v_pk_add_f32 v[184:185], v[184:185], v[118:119] op_sel_hi:[1,0] neg_lo:[0,1] neg_hi:[0,1]
	v_pk_add_f32 v[192:193], v[192:193], v[118:119] op_sel:[0,1] op_sel_hi:[1,1] neg_lo:[0,1] neg_hi:[0,1]
	s_waitcnt lgkmcnt(8)
	v_pk_fma_f32 v[178:179], v[72:73], v[178:179], v[118:119] op_sel_hi:[1,1,0]
	v_pk_fma_f32 v[186:187], v[72:73], v[186:187], v[118:119] op_sel:[0,0,1] op_sel_hi:[1,1,1]
	v_pk_fma_f32 v[180:181], v[74:75], v[180:181], v[118:119] op_sel_hi:[1,1,0]
	v_pk_fma_f32 v[188:189], v[74:75], v[188:189], v[118:119] op_sel:[0,0,1] op_sel_hi:[1,1,1]
	s_waitcnt lgkmcnt(7)
	v_pk_fma_f32 v[182:183], v[76:77], v[182:183], v[118:119] op_sel_hi:[1,1,0]
	v_pk_fma_f32 v[190:191], v[76:77], v[190:191], v[118:119] op_sel:[0,0,1] op_sel_hi:[1,1,1]
	v_pk_fma_f32 v[184:185], v[78:79], v[184:185], v[118:119] op_sel_hi:[1,1,0]
	v_pk_fma_f32 v[192:193], v[78:79], v[192:193], v[118:119] op_sel:[0,0,1] op_sel_hi:[1,1,1]
	s_waitcnt lgkmcnt(6)
	v_pk_fma_f32 v[146:147], v[64:65], v[178:179], v[196:197]
	v_pk_fma_f32 v[150:151], v[64:65], v[186:187], v[196:197]
	v_pk_fma_f32 v[148:149], v[66:67], v[180:181], v[196:197]
	v_pk_fma_f32 v[152:153], v[66:67], v[188:189], v[196:197]
	s_waitcnt lgkmcnt(5)
	v_pk_fma_f32 v[146:147], v[68:69], v[182:183], v[146:147]
	v_pk_fma_f32 v[150:151], v[68:69], v[190:191], v[150:151]
	v_pk_fma_f32 v[148:149], v[70:71], v[184:185], v[148:149]
	v_pk_fma_f32 v[152:153], v[70:71], v[192:193], v[152:153]
	v_add_f32_e32 v146, v146, v147
	v_add_f32_e32 v148, v148, v149
	v_add_f32_e32 v150, v150, v151
	v_add_f32_e32 v152, v152, v153
	v_add_f32_e32 v154, v146, v148
	v_add_f32_e32 v155, v150, v152
	ds_read2_b32 v[118:119], v194 offset0:64 offset1:80
	ds_read_b128 v[72:75], v145 offset:9216
	ds_read_b128 v[76:79], v145 offset:9472
	ds_read_b128 v[64:67], v145 offset:1024
	ds_read_b128 v[68:71], v145 offset:1280
	s_waitcnt lgkmcnt(9)
	v_pk_add_f32 v[178:179], v[178:179], v[120:121] op_sel_hi:[1,0] neg_lo:[0,1] neg_hi:[0,1]
	v_add_f32_dpp v154, v154, v154 row_ror:8 row_mask:0xf bank_mask:0xf bound_ctrl:1
	v_pk_add_f32 v[186:187], v[186:187], v[120:121] op_sel:[0,1] op_sel_hi:[1,1] neg_lo:[0,1] neg_hi:[0,1]
	v_add_f32_dpp v155, v155, v155 row_ror:8 row_mask:0xf bank_mask:0xf bound_ctrl:1
	v_pk_add_f32 v[180:181], v[180:181], v[120:121] op_sel_hi:[1,0] neg_lo:[0,1] neg_hi:[0,1]
	v_add_f32_dpp v154, v154, v154 row_ror:4 row_mask:0xf bank_mask:0xf bound_ctrl:1
	v_pk_add_f32 v[188:189], v[188:189], v[120:121] op_sel:[0,1] op_sel_hi:[1,1] neg_lo:[0,1] neg_hi:[0,1]
	v_add_f32_dpp v155, v155, v155 row_ror:4 row_mask:0xf bank_mask:0xf bound_ctrl:1
	v_pk_add_f32 v[182:183], v[182:183], v[120:121] op_sel_hi:[1,0] neg_lo:[0,1] neg_hi:[0,1]
	v_add_f32_dpp v154, v154, v154 row_ror:2 row_mask:0xf bank_mask:0xf bound_ctrl:1
	v_pk_add_f32 v[190:191], v[190:191], v[120:121] op_sel:[0,1] op_sel_hi:[1,1] neg_lo:[0,1] neg_hi:[0,1]
	v_add_f32_dpp v155, v155, v155 row_ror:2 row_mask:0xf bank_mask:0xf bound_ctrl:1
	v_pk_add_f32 v[184:185], v[184:185], v[120:121] op_sel_hi:[1,0] neg_lo:[0,1] neg_hi:[0,1]
	v_add_f32_dpp v154, v154, v154 row_ror:1 row_mask:0xf bank_mask:0xf bound_ctrl:1
	v_pk_add_f32 v[192:193], v[192:193], v[120:121] op_sel:[0,1] op_sel_hi:[1,1] neg_lo:[0,1] neg_hi:[0,1]
	v_add_f32_dpp v155, v155, v155 row_ror:1 row_mask:0xf bank_mask:0xf bound_ctrl:1
	s_waitcnt lgkmcnt(8)
	v_pk_fma_f32 v[178:179], v[88:89], v[178:179], v[120:121] op_sel_hi:[1,1,0]
	s_and_saveexec_b64 s[8:9], s[38:39]
	ds_write_b32 v103, v154 offset:36864
	ds_write_b32 v103, v155 offset:36928
	s_mov_b64 exec, s[8:9]
	v_pk_fma_f32 v[186:187], v[88:89], v[186:187], v[120:121] op_sel:[0,0,1] op_sel_hi:[1,1,1]
	v_pk_fma_f32 v[180:181], v[90:91], v[180:181], v[120:121] op_sel_hi:[1,1,0]
	v_pk_fma_f32 v[188:189], v[90:91], v[188:189], v[120:121] op_sel:[0,0,1] op_sel_hi:[1,1,1]
	s_waitcnt lgkmcnt(9)
	v_pk_fma_f32 v[182:183], v[92:93], v[182:183], v[120:121] op_sel_hi:[1,1,0]
	v_pk_fma_f32 v[190:191], v[92:93], v[190:191], v[120:121] op_sel:[0,0,1] op_sel_hi:[1,1,1]
	v_pk_fma_f32 v[184:185], v[94:95], v[184:185], v[120:121] op_sel_hi:[1,1,0]
	v_pk_fma_f32 v[192:193], v[94:95], v[192:193], v[120:121] op_sel:[0,0,1] op_sel_hi:[1,1,1]
	s_waitcnt lgkmcnt(8)
	v_pk_fma_f32 v[146:147], v[80:81], v[178:179], v[196:197]
	v_pk_fma_f32 v[150:151], v[80:81], v[186:187], v[196:197]
	v_pk_fma_f32 v[148:149], v[82:83], v[180:181], v[196:197]
	v_pk_fma_f32 v[152:153], v[82:83], v[188:189], v[196:197]
	s_waitcnt lgkmcnt(7)
	v_pk_fma_f32 v[146:147], v[84:85], v[182:183], v[146:147]
	v_pk_fma_f32 v[150:151], v[84:85], v[190:191], v[150:151]
	v_pk_fma_f32 v[148:149], v[86:87], v[184:185], v[148:149]
	v_pk_fma_f32 v[152:153], v[86:87], v[192:193], v[152:153]
	v_add_f32_e32 v146, v146, v147
	v_add_f32_e32 v148, v148, v149
	v_add_f32_e32 v150, v150, v151
	v_add_f32_e32 v152, v152, v153
	v_add_f32_e32 v156, v146, v148
	v_add_f32_e32 v157, v150, v152
	ds_read2_b32 v[120:121], v194 offset0:96 offset1:112
	ds_read_b128 v[88:91], v145 offset:9728
	ds_read_b128 v[92:95], v145 offset:9984
	ds_read_b128 v[80:83], v145 offset:1536
	ds_read_b128 v[84:87], v145 offset:1792
	s_waitcnt lgkmcnt(11)
	v_pk_add_f32 v[178:179], v[178:179], v[118:119] op_sel_hi:[1,0] neg_lo:[0,1] neg_hi:[0,1]
	v_add_f32_dpp v156, v156, v156 row_ror:8 row_mask:0xf bank_mask:0xf bound_ctrl:1
	v_pk_add_f32 v[186:187], v[186:187], v[118:119] op_sel:[0,1] op_sel_hi:[1,1] neg_lo:[0,1] neg_hi:[0,1]
	v_add_f32_dpp v157, v157, v157 row_ror:8 row_mask:0xf bank_mask:0xf bound_ctrl:1
	v_pk_add_f32 v[180:181], v[180:181], v[118:119] op_sel_hi:[1,0] neg_lo:[0,1] neg_hi:[0,1]
	v_add_f32_dpp v156, v156, v156 row_ror:4 row_mask:0xf bank_mask:0xf bound_ctrl:1
	v_pk_add_f32 v[188:189], v[188:189], v[118:119] op_sel:[0,1] op_sel_hi:[1,1] neg_lo:[0,1] neg_hi:[0,1]
	v_add_f32_dpp v157, v157, v157 row_ror:4 row_mask:0xf bank_mask:0xf bound_ctrl:1
	v_pk_add_f32 v[182:183], v[182:183], v[118:119] op_sel_hi:[1,0] neg_lo:[0,1] neg_hi:[0,1]
	v_add_f32_dpp v156, v156, v156 row_ror:2 row_mask:0xf bank_mask:0xf bound_ctrl:1
	v_pk_add_f32 v[190:191], v[190:191], v[118:119] op_sel:[0,1] op_sel_hi:[1,1] neg_lo:[0,1] neg_hi:[0,1]
	v_add_f32_dpp v157, v157, v157 row_ror:2 row_mask:0xf bank_mask:0xf bound_ctrl:1
	v_pk_add_f32 v[184:185], v[184:185], v[118:119] op_sel_hi:[1,0] neg_lo:[0,1] neg_hi:[0,1]
	v_add_f32_dpp v156, v156, v156 row_ror:1 row_mask:0xf bank_mask:0xf bound_ctrl:1
	v_pk_add_f32 v[192:193], v[192:193], v[118:119] op_sel:[0,1] op_sel_hi:[1,1] neg_lo:[0,1] neg_hi:[0,1]
	v_add_f32_dpp v157, v157, v157 row_ror:1 row_mask:0xf bank_mask:0xf bound_ctrl:1
	s_waitcnt lgkmcnt(10)
	v_pk_fma_f32 v[178:179], v[72:73], v[178:179], v[118:119] op_sel_hi:[1,1,0]
	s_and_saveexec_b64 s[8:9], s[38:39]
	ds_write_b32 v103, v156 offset:36992
	ds_write_b32 v103, v157 offset:37056
	s_mov_b64 exec, s[8:9]
	v_pk_fma_f32 v[186:187], v[72:73], v[186:187], v[118:119] op_sel:[0,0,1] op_sel_hi:[1,1,1]
	v_pk_fma_f32 v[180:181], v[74:75], v[180:181], v[118:119] op_sel_hi:[1,1,0]
	v_pk_fma_f32 v[188:189], v[74:75], v[188:189], v[118:119] op_sel:[0,0,1] op_sel_hi:[1,1,1]
	s_waitcnt lgkmcnt(11)
	v_pk_fma_f32 v[182:183], v[76:77], v[182:183], v[118:119] op_sel_hi:[1,1,0]
	v_pk_fma_f32 v[190:191], v[76:77], v[190:191], v[118:119] op_sel:[0,0,1] op_sel_hi:[1,1,1]
	v_pk_fma_f32 v[184:185], v[78:79], v[184:185], v[118:119] op_sel_hi:[1,1,0]
	v_pk_fma_f32 v[192:193], v[78:79], v[192:193], v[118:119] op_sel:[0,0,1] op_sel_hi:[1,1,1]
	s_waitcnt lgkmcnt(10)
	v_pk_fma_f32 v[146:147], v[64:65], v[178:179], v[196:197]
	v_pk_fma_f32 v[150:151], v[64:65], v[186:187], v[196:197]
	v_pk_fma_f32 v[148:149], v[66:67], v[180:181], v[196:197]
	v_pk_fma_f32 v[152:153], v[66:67], v[188:189], v[196:197]
	s_waitcnt lgkmcnt(9)
	v_pk_fma_f32 v[146:147], v[68:69], v[182:183], v[146:147]
	v_pk_fma_f32 v[150:151], v[68:69], v[190:191], v[150:151]
	v_pk_fma_f32 v[148:149], v[70:71], v[184:185], v[148:149]
	v_pk_fma_f32 v[152:153], v[70:71], v[192:193], v[152:153]
	v_add_f32_e32 v146, v146, v147
	v_add_f32_e32 v148, v148, v149
	v_add_f32_e32 v150, v150, v151
	v_add_f32_e32 v152, v152, v153
	v_add_f32_e32 v154, v146, v148
	v_add_f32_e32 v155, v150, v152
	ds_read2_b32 v[118:119], v194 offset0:128 offset1:144
	ds_read_b128 v[72:75], v145 offset:10240
	ds_read_b128 v[76:79], v145 offset:10496
	ds_read_b128 v[64:67], v145 offset:2048
	ds_read_b128 v[68:71], v145 offset:2304
	s_waitcnt lgkmcnt(11)
	v_pk_add_f32 v[178:179], v[178:179], v[120:121] op_sel_hi:[1,0] neg_lo:[0,1] neg_hi:[0,1]
	v_add_f32_dpp v154, v154, v154 row_ror:8 row_mask:0xf bank_mask:0xf bound_ctrl:1
	v_pk_add_f32 v[186:187], v[186:187], v[120:121] op_sel:[0,1] op_sel_hi:[1,1] neg_lo:[0,1] neg_hi:[0,1]
	v_add_f32_dpp v155, v155, v155 row_ror:8 row_mask:0xf bank_mask:0xf bound_ctrl:1
	v_pk_add_f32 v[180:181], v[180:181], v[120:121] op_sel_hi:[1,0] neg_lo:[0,1] neg_hi:[0,1]
	v_add_f32_dpp v154, v154, v154 row_ror:4 row_mask:0xf bank_mask:0xf bound_ctrl:1
	v_pk_add_f32 v[188:189], v[188:189], v[120:121] op_sel:[0,1] op_sel_hi:[1,1] neg_lo:[0,1] neg_hi:[0,1]
	v_add_f32_dpp v155, v155, v155 row_ror:4 row_mask:0xf bank_mask:0xf bound_ctrl:1
	v_pk_add_f32 v[182:183], v[182:183], v[120:121] op_sel_hi:[1,0] neg_lo:[0,1] neg_hi:[0,1]
	v_add_f32_dpp v154, v154, v154 row_ror:2 row_mask:0xf bank_mask:0xf bound_ctrl:1
	v_pk_add_f32 v[190:191], v[190:191], v[120:121] op_sel:[0,1] op_sel_hi:[1,1] neg_lo:[0,1] neg_hi:[0,1]
	v_add_f32_dpp v155, v155, v155 row_ror:2 row_mask:0xf bank_mask:0xf bound_ctrl:1
	v_pk_add_f32 v[184:185], v[184:185], v[120:121] op_sel_hi:[1,0] neg_lo:[0,1] neg_hi:[0,1]
	v_add_f32_dpp v154, v154, v154 row_ror:1 row_mask:0xf bank_mask:0xf bound_ctrl:1
	v_pk_add_f32 v[192:193], v[192:193], v[120:121] op_sel:[0,1] op_sel_hi:[1,1] neg_lo:[0,1] neg_hi:[0,1]
	v_add_f32_dpp v155, v155, v155 row_ror:1 row_mask:0xf bank_mask:0xf bound_ctrl:1
	s_waitcnt lgkmcnt(10)
	v_pk_fma_f32 v[178:179], v[88:89], v[178:179], v[120:121] op_sel_hi:[1,1,0]
	s_and_saveexec_b64 s[8:9], s[38:39]
	ds_write_b32 v103, v154 offset:37120
	ds_write_b32 v103, v155 offset:37184
	s_mov_b64 exec, s[8:9]
	v_pk_fma_f32 v[186:187], v[88:89], v[186:187], v[120:121] op_sel:[0,0,1] op_sel_hi:[1,1,1]
	v_pk_fma_f32 v[180:181], v[90:91], v[180:181], v[120:121] op_sel_hi:[1,1,0]
	v_pk_fma_f32 v[188:189], v[90:91], v[188:189], v[120:121] op_sel:[0,0,1] op_sel_hi:[1,1,1]
	s_waitcnt lgkmcnt(11)
	v_pk_fma_f32 v[182:183], v[92:93], v[182:183], v[120:121] op_sel_hi:[1,1,0]
	v_pk_fma_f32 v[190:191], v[92:93], v[190:191], v[120:121] op_sel:[0,0,1] op_sel_hi:[1,1,1]
	v_pk_fma_f32 v[184:185], v[94:95], v[184:185], v[120:121] op_sel_hi:[1,1,0]
	v_pk_fma_f32 v[192:193], v[94:95], v[192:193], v[120:121] op_sel:[0,0,1] op_sel_hi:[1,1,1]
	s_waitcnt lgkmcnt(10)
	v_pk_fma_f32 v[146:147], v[80:81], v[178:179], v[196:197]
	v_pk_fma_f32 v[150:151], v[80:81], v[186:187], v[196:197]
	v_pk_fma_f32 v[148:149], v[82:83], v[180:181], v[196:197]
	v_pk_fma_f32 v[152:153], v[82:83], v[188:189], v[196:197]
	s_waitcnt lgkmcnt(9)
	v_pk_fma_f32 v[146:147], v[84:85], v[182:183], v[146:147]
	v_pk_fma_f32 v[150:151], v[84:85], v[190:191], v[150:151]
	v_pk_fma_f32 v[148:149], v[86:87], v[184:185], v[148:149]
	v_pk_fma_f32 v[152:153], v[86:87], v[192:193], v[152:153]
	v_add_f32_e32 v146, v146, v147
	v_add_f32_e32 v148, v148, v149
	v_add_f32_e32 v150, v150, v151
	v_add_f32_e32 v152, v152, v153
	v_add_f32_e32 v156, v146, v148
	v_add_f32_e32 v157, v150, v152
	ds_read2_b32 v[120:121], v194 offset0:160 offset1:176
	ds_read_b128 v[88:91], v145 offset:10752
	ds_read_b128 v[92:95], v145 offset:11008
	ds_read_b128 v[80:83], v145 offset:2560
	ds_read_b128 v[84:87], v145 offset:2816
	s_waitcnt lgkmcnt(11)
	v_pk_add_f32 v[178:179], v[178:179], v[118:119] op_sel_hi:[1,0] neg_lo:[0,1] neg_hi:[0,1]
	v_add_f32_dpp v156, v156, v156 row_ror:8 row_mask:0xf bank_mask:0xf bound_ctrl:1
	v_pk_add_f32 v[186:187], v[186:187], v[118:119] op_sel:[0,1] op_sel_hi:[1,1] neg_lo:[0,1] neg_hi:[0,1]
	v_add_f32_dpp v157, v157, v157 row_ror:8 row_mask:0xf bank_mask:0xf bound_ctrl:1
	v_pk_add_f32 v[180:181], v[180:181], v[118:119] op_sel_hi:[1,0] neg_lo:[0,1] neg_hi:[0,1]
	v_add_f32_dpp v156, v156, v156 row_ror:4 row_mask:0xf bank_mask:0xf bound_ctrl:1
	v_pk_add_f32 v[188:189], v[188:189], v[118:119] op_sel:[0,1] op_sel_hi:[1,1] neg_lo:[0,1] neg_hi:[0,1]
	v_add_f32_dpp v157, v157, v157 row_ror:4 row_mask:0xf bank_mask:0xf bound_ctrl:1
	v_pk_add_f32 v[182:183], v[182:183], v[118:119] op_sel_hi:[1,0] neg_lo:[0,1] neg_hi:[0,1]
	v_add_f32_dpp v156, v156, v156 row_ror:2 row_mask:0xf bank_mask:0xf bound_ctrl:1
	v_pk_add_f32 v[190:191], v[190:191], v[118:119] op_sel:[0,1] op_sel_hi:[1,1] neg_lo:[0,1] neg_hi:[0,1]
	v_add_f32_dpp v157, v157, v157 row_ror:2 row_mask:0xf bank_mask:0xf bound_ctrl:1
	v_pk_add_f32 v[184:185], v[184:185], v[118:119] op_sel_hi:[1,0] neg_lo:[0,1] neg_hi:[0,1]
	v_add_f32_dpp v156, v156, v156 row_ror:1 row_mask:0xf bank_mask:0xf bound_ctrl:1
	v_pk_add_f32 v[192:193], v[192:193], v[118:119] op_sel:[0,1] op_sel_hi:[1,1] neg_lo:[0,1] neg_hi:[0,1]
	v_add_f32_dpp v157, v157, v157 row_ror:1 row_mask:0xf bank_mask:0xf bound_ctrl:1
	s_waitcnt lgkmcnt(10)
	v_pk_fma_f32 v[178:179], v[72:73], v[178:179], v[118:119] op_sel_hi:[1,1,0]
	s_and_saveexec_b64 s[8:9], s[38:39]
	ds_write_b32 v103, v156 offset:37248
	ds_write_b32 v103, v157 offset:37312
	s_mov_b64 exec, s[8:9]
	v_pk_fma_f32 v[186:187], v[72:73], v[186:187], v[118:119] op_sel:[0,0,1] op_sel_hi:[1,1,1]
	v_pk_fma_f32 v[180:181], v[74:75], v[180:181], v[118:119] op_sel_hi:[1,1,0]
	v_pk_fma_f32 v[188:189], v[74:75], v[188:189], v[118:119] op_sel:[0,0,1] op_sel_hi:[1,1,1]
	s_waitcnt lgkmcnt(11)
	v_pk_fma_f32 v[182:183], v[76:77], v[182:183], v[118:119] op_sel_hi:[1,1,0]
	v_pk_fma_f32 v[190:191], v[76:77], v[190:191], v[118:119] op_sel:[0,0,1] op_sel_hi:[1,1,1]
	v_pk_fma_f32 v[184:185], v[78:79], v[184:185], v[118:119] op_sel_hi:[1,1,0]
	v_pk_fma_f32 v[192:193], v[78:79], v[192:193], v[118:119] op_sel:[0,0,1] op_sel_hi:[1,1,1]
	s_waitcnt lgkmcnt(10)
	v_pk_fma_f32 v[146:147], v[64:65], v[178:179], v[196:197]
	v_pk_fma_f32 v[150:151], v[64:65], v[186:187], v[196:197]
	v_pk_fma_f32 v[148:149], v[66:67], v[180:181], v[196:197]
	v_pk_fma_f32 v[152:153], v[66:67], v[188:189], v[196:197]
	s_waitcnt lgkmcnt(9)
	v_pk_fma_f32 v[146:147], v[68:69], v[182:183], v[146:147]
	v_pk_fma_f32 v[150:151], v[68:69], v[190:191], v[150:151]
	v_pk_fma_f32 v[148:149], v[70:71], v[184:185], v[148:149]
	v_pk_fma_f32 v[152:153], v[70:71], v[192:193], v[152:153]
	v_add_f32_e32 v146, v146, v147
	v_add_f32_e32 v148, v148, v149
	v_add_f32_e32 v150, v150, v151
	v_add_f32_e32 v152, v152, v153
	v_add_f32_e32 v154, v146, v148
	v_add_f32_e32 v155, v150, v152
	ds_read2_b32 v[118:119], v194 offset0:192 offset1:208
	ds_read_b128 v[72:75], v145 offset:11264
	ds_read_b128 v[76:79], v145 offset:11520
	ds_read_b128 v[64:67], v145 offset:3072
	ds_read_b128 v[68:71], v145 offset:3328
	s_waitcnt lgkmcnt(11)
	v_pk_add_f32 v[178:179], v[178:179], v[120:121] op_sel_hi:[1,0] neg_lo:[0,1] neg_hi:[0,1]
	v_add_f32_dpp v154, v154, v154 row_ror:8 row_mask:0xf bank_mask:0xf bound_ctrl:1
	v_pk_add_f32 v[186:187], v[186:187], v[120:121] op_sel:[0,1] op_sel_hi:[1,1] neg_lo:[0,1] neg_hi:[0,1]
	v_add_f32_dpp v155, v155, v155 row_ror:8 row_mask:0xf bank_mask:0xf bound_ctrl:1
	v_pk_add_f32 v[180:181], v[180:181], v[120:121] op_sel_hi:[1,0] neg_lo:[0,1] neg_hi:[0,1]
	v_add_f32_dpp v154, v154, v154 row_ror:4 row_mask:0xf bank_mask:0xf bound_ctrl:1
	v_pk_add_f32 v[188:189], v[188:189], v[120:121] op_sel:[0,1] op_sel_hi:[1,1] neg_lo:[0,1] neg_hi:[0,1]
	v_add_f32_dpp v155, v155, v155 row_ror:4 row_mask:0xf bank_mask:0xf bound_ctrl:1
	v_pk_add_f32 v[182:183], v[182:183], v[120:121] op_sel_hi:[1,0] neg_lo:[0,1] neg_hi:[0,1]
	v_add_f32_dpp v154, v154, v154 row_ror:2 row_mask:0xf bank_mask:0xf bound_ctrl:1
	v_pk_add_f32 v[190:191], v[190:191], v[120:121] op_sel:[0,1] op_sel_hi:[1,1] neg_lo:[0,1] neg_hi:[0,1]
	v_add_f32_dpp v155, v155, v155 row_ror:2 row_mask:0xf bank_mask:0xf bound_ctrl:1
	v_pk_add_f32 v[184:185], v[184:185], v[120:121] op_sel_hi:[1,0] neg_lo:[0,1] neg_hi:[0,1]
	v_add_f32_dpp v154, v154, v154 row_ror:1 row_mask:0xf bank_mask:0xf bound_ctrl:1
	v_pk_add_f32 v[192:193], v[192:193], v[120:121] op_sel:[0,1] op_sel_hi:[1,1] neg_lo:[0,1] neg_hi:[0,1]
	v_add_f32_dpp v155, v155, v155 row_ror:1 row_mask:0xf bank_mask:0xf bound_ctrl:1
	s_waitcnt lgkmcnt(10)
	v_pk_fma_f32 v[178:179], v[88:89], v[178:179], v[120:121] op_sel_hi:[1,1,0]
	s_and_saveexec_b64 s[8:9], s[38:39]
	ds_write_b32 v103, v154 offset:37376
	ds_write_b32 v103, v155 offset:37440
	s_mov_b64 exec, s[8:9]
	v_pk_fma_f32 v[186:187], v[88:89], v[186:187], v[120:121] op_sel:[0,0,1] op_sel_hi:[1,1,1]
	v_pk_fma_f32 v[180:181], v[90:91], v[180:181], v[120:121] op_sel_hi:[1,1,0]
	v_pk_fma_f32 v[188:189], v[90:91], v[188:189], v[120:121] op_sel:[0,0,1] op_sel_hi:[1,1,1]
	s_waitcnt lgkmcnt(11)
	v_pk_fma_f32 v[182:183], v[92:93], v[182:183], v[120:121] op_sel_hi:[1,1,0]
	v_pk_fma_f32 v[190:191], v[92:93], v[190:191], v[120:121] op_sel:[0,0,1] op_sel_hi:[1,1,1]
	v_pk_fma_f32 v[184:185], v[94:95], v[184:185], v[120:121] op_sel_hi:[1,1,0]
	v_pk_fma_f32 v[192:193], v[94:95], v[192:193], v[120:121] op_sel:[0,0,1] op_sel_hi:[1,1,1]
	s_waitcnt lgkmcnt(10)
	v_pk_fma_f32 v[146:147], v[80:81], v[178:179], v[196:197]
	v_pk_fma_f32 v[150:151], v[80:81], v[186:187], v[196:197]
	v_pk_fma_f32 v[148:149], v[82:83], v[180:181], v[196:197]
	v_pk_fma_f32 v[152:153], v[82:83], v[188:189], v[196:197]
	s_waitcnt lgkmcnt(9)
	v_pk_fma_f32 v[146:147], v[84:85], v[182:183], v[146:147]
	v_pk_fma_f32 v[150:151], v[84:85], v[190:191], v[150:151]
	v_pk_fma_f32 v[148:149], v[86:87], v[184:185], v[148:149]
	v_pk_fma_f32 v[152:153], v[86:87], v[192:193], v[152:153]
	v_add_f32_e32 v146, v146, v147
	v_add_f32_e32 v148, v148, v149
	v_add_f32_e32 v150, v150, v151
	v_add_f32_e32 v152, v152, v153
	v_add_f32_e32 v156, v146, v148
	v_add_f32_e32 v157, v150, v152
	ds_read2_b32 v[120:121], v194 offset0:224 offset1:240
	ds_read_b128 v[88:91], v145 offset:11776
	ds_read_b128 v[92:95], v145 offset:12032
	ds_read_b128 v[80:83], v145 offset:3584
	ds_read_b128 v[84:87], v145 offset:3840
	s_waitcnt lgkmcnt(11)
	v_pk_add_f32 v[178:179], v[178:179], v[118:119] op_sel_hi:[1,0] neg_lo:[0,1] neg_hi:[0,1]
	v_add_f32_dpp v156, v156, v156 row_ror:8 row_mask:0xf bank_mask:0xf bound_ctrl:1
	v_pk_add_f32 v[186:187], v[186:187], v[118:119] op_sel:[0,1] op_sel_hi:[1,1] neg_lo:[0,1] neg_hi:[0,1]
	v_add_f32_dpp v157, v157, v157 row_ror:8 row_mask:0xf bank_mask:0xf bound_ctrl:1
	v_pk_add_f32 v[180:181], v[180:181], v[118:119] op_sel_hi:[1,0] neg_lo:[0,1] neg_hi:[0,1]
	v_add_f32_dpp v156, v156, v156 row_ror:4 row_mask:0xf bank_mask:0xf bound_ctrl:1
	v_pk_add_f32 v[188:189], v[188:189], v[118:119] op_sel:[0,1] op_sel_hi:[1,1] neg_lo:[0,1] neg_hi:[0,1]
	v_add_f32_dpp v157, v157, v157 row_ror:4 row_mask:0xf bank_mask:0xf bound_ctrl:1
	v_pk_add_f32 v[182:183], v[182:183], v[118:119] op_sel_hi:[1,0] neg_lo:[0,1] neg_hi:[0,1]
	v_add_f32_dpp v156, v156, v156 row_ror:2 row_mask:0xf bank_mask:0xf bound_ctrl:1
	v_pk_add_f32 v[190:191], v[190:191], v[118:119] op_sel:[0,1] op_sel_hi:[1,1] neg_lo:[0,1] neg_hi:[0,1]
	v_add_f32_dpp v157, v157, v157 row_ror:2 row_mask:0xf bank_mask:0xf bound_ctrl:1
	v_pk_add_f32 v[184:185], v[184:185], v[118:119] op_sel_hi:[1,0] neg_lo:[0,1] neg_hi:[0,1]
	v_add_f32_dpp v156, v156, v156 row_ror:1 row_mask:0xf bank_mask:0xf bound_ctrl:1
	v_pk_add_f32 v[192:193], v[192:193], v[118:119] op_sel:[0,1] op_sel_hi:[1,1] neg_lo:[0,1] neg_hi:[0,1]
	v_add_f32_dpp v157, v157, v157 row_ror:1 row_mask:0xf bank_mask:0xf bound_ctrl:1
	s_waitcnt lgkmcnt(10)
	v_pk_fma_f32 v[178:179], v[72:73], v[178:179], v[118:119] op_sel_hi:[1,1,0]
	s_and_saveexec_b64 s[8:9], s[38:39]
	ds_write_b32 v103, v156 offset:37504
	ds_write_b32 v103, v157 offset:37568
	s_mov_b64 exec, s[8:9]
	v_pk_fma_f32 v[186:187], v[72:73], v[186:187], v[118:119] op_sel:[0,0,1] op_sel_hi:[1,1,1]
	v_pk_fma_f32 v[180:181], v[74:75], v[180:181], v[118:119] op_sel_hi:[1,1,0]
	v_pk_fma_f32 v[188:189], v[74:75], v[188:189], v[118:119] op_sel:[0,0,1] op_sel_hi:[1,1,1]
	s_waitcnt lgkmcnt(11)
	v_pk_fma_f32 v[182:183], v[76:77], v[182:183], v[118:119] op_sel_hi:[1,1,0]
	v_pk_fma_f32 v[190:191], v[76:77], v[190:191], v[118:119] op_sel:[0,0,1] op_sel_hi:[1,1,1]
	v_pk_fma_f32 v[184:185], v[78:79], v[184:185], v[118:119] op_sel_hi:[1,1,0]
	v_pk_fma_f32 v[192:193], v[78:79], v[192:193], v[118:119] op_sel:[0,0,1] op_sel_hi:[1,1,1]
	s_waitcnt lgkmcnt(10)
	v_pk_fma_f32 v[146:147], v[64:65], v[178:179], v[196:197]
	v_pk_fma_f32 v[150:151], v[64:65], v[186:187], v[196:197]
	v_pk_fma_f32 v[148:149], v[66:67], v[180:181], v[196:197]
	v_pk_fma_f32 v[152:153], v[66:67], v[188:189], v[196:197]
	s_waitcnt lgkmcnt(9)
	v_pk_fma_f32 v[146:147], v[68:69], v[182:183], v[146:147]
	v_pk_fma_f32 v[150:151], v[68:69], v[190:191], v[150:151]
	v_pk_fma_f32 v[148:149], v[70:71], v[184:185], v[148:149]
	v_pk_fma_f32 v[152:153], v[70:71], v[192:193], v[152:153]
	v_add_f32_e32 v146, v146, v147
	v_add_f32_e32 v148, v148, v149
	v_add_f32_e32 v150, v150, v151
	v_add_f32_e32 v152, v152, v153
	v_add_f32_e32 v154, v146, v148
	v_add_f32_e32 v155, v150, v152
	ds_read2_b32 v[118:119], v195 offset0:0 offset1:16
	ds_read_b128 v[72:75], v145 offset:12288
	ds_read_b128 v[76:79], v145 offset:12544
	ds_read_b128 v[64:67], v145 offset:4096
	ds_read_b128 v[68:71], v145 offset:4352
	s_waitcnt lgkmcnt(11)
	v_pk_add_f32 v[178:179], v[178:179], v[120:121] op_sel_hi:[1,0] neg_lo:[0,1] neg_hi:[0,1]
	v_add_f32_dpp v154, v154, v154 row_ror:8 row_mask:0xf bank_mask:0xf bound_ctrl:1
	v_pk_add_f32 v[186:187], v[186:187], v[120:121] op_sel:[0,1] op_sel_hi:[1,1] neg_lo:[0,1] neg_hi:[0,1]
	v_add_f32_dpp v155, v155, v155 row_ror:8 row_mask:0xf bank_mask:0xf bound_ctrl:1
	v_pk_add_f32 v[180:181], v[180:181], v[120:121] op_sel_hi:[1,0] neg_lo:[0,1] neg_hi:[0,1]
	v_add_f32_dpp v154, v154, v154 row_ror:4 row_mask:0xf bank_mask:0xf bound_ctrl:1
	v_pk_add_f32 v[188:189], v[188:189], v[120:121] op_sel:[0,1] op_sel_hi:[1,1] neg_lo:[0,1] neg_hi:[0,1]
	v_add_f32_dpp v155, v155, v155 row_ror:4 row_mask:0xf bank_mask:0xf bound_ctrl:1
	v_pk_add_f32 v[182:183], v[182:183], v[120:121] op_sel_hi:[1,0] neg_lo:[0,1] neg_hi:[0,1]
	v_add_f32_dpp v154, v154, v154 row_ror:2 row_mask:0xf bank_mask:0xf bound_ctrl:1
	v_pk_add_f32 v[190:191], v[190:191], v[120:121] op_sel:[0,1] op_sel_hi:[1,1] neg_lo:[0,1] neg_hi:[0,1]
	v_add_f32_dpp v155, v155, v155 row_ror:2 row_mask:0xf bank_mask:0xf bound_ctrl:1
	v_pk_add_f32 v[184:185], v[184:185], v[120:121] op_sel_hi:[1,0] neg_lo:[0,1] neg_hi:[0,1]
	v_add_f32_dpp v154, v154, v154 row_ror:1 row_mask:0xf bank_mask:0xf bound_ctrl:1
	v_pk_add_f32 v[192:193], v[192:193], v[120:121] op_sel:[0,1] op_sel_hi:[1,1] neg_lo:[0,1] neg_hi:[0,1]
	v_add_f32_dpp v155, v155, v155 row_ror:1 row_mask:0xf bank_mask:0xf bound_ctrl:1
	s_waitcnt lgkmcnt(10)
	v_pk_fma_f32 v[178:179], v[88:89], v[178:179], v[120:121] op_sel_hi:[1,1,0]
	s_and_saveexec_b64 s[8:9], s[38:39]
	ds_write_b32 v103, v154 offset:37632
	ds_write_b32 v103, v155 offset:37696
	s_mov_b64 exec, s[8:9]
	v_pk_fma_f32 v[186:187], v[88:89], v[186:187], v[120:121] op_sel:[0,0,1] op_sel_hi:[1,1,1]
	v_pk_fma_f32 v[180:181], v[90:91], v[180:181], v[120:121] op_sel_hi:[1,1,0]
	v_pk_fma_f32 v[188:189], v[90:91], v[188:189], v[120:121] op_sel:[0,0,1] op_sel_hi:[1,1,1]
	s_waitcnt lgkmcnt(11)
	v_pk_fma_f32 v[182:183], v[92:93], v[182:183], v[120:121] op_sel_hi:[1,1,0]
	v_pk_fma_f32 v[190:191], v[92:93], v[190:191], v[120:121] op_sel:[0,0,1] op_sel_hi:[1,1,1]
	v_pk_fma_f32 v[184:185], v[94:95], v[184:185], v[120:121] op_sel_hi:[1,1,0]
	v_pk_fma_f32 v[192:193], v[94:95], v[192:193], v[120:121] op_sel:[0,0,1] op_sel_hi:[1,1,1]
	s_waitcnt lgkmcnt(10)
	v_pk_fma_f32 v[146:147], v[80:81], v[178:179], v[196:197]
	v_pk_fma_f32 v[150:151], v[80:81], v[186:187], v[196:197]
	v_pk_fma_f32 v[148:149], v[82:83], v[180:181], v[196:197]
	v_pk_fma_f32 v[152:153], v[82:83], v[188:189], v[196:197]
	s_waitcnt lgkmcnt(9)
	v_pk_fma_f32 v[146:147], v[84:85], v[182:183], v[146:147]
	v_pk_fma_f32 v[150:151], v[84:85], v[190:191], v[150:151]
	v_pk_fma_f32 v[148:149], v[86:87], v[184:185], v[148:149]
	v_pk_fma_f32 v[152:153], v[86:87], v[192:193], v[152:153]
	v_add_f32_e32 v146, v146, v147
	v_add_f32_e32 v148, v148, v149
	v_add_f32_e32 v150, v150, v151
	v_add_f32_e32 v152, v152, v153
	v_add_f32_e32 v156, v146, v148
	v_add_f32_e32 v157, v150, v152
	ds_read2_b32 v[120:121], v195 offset0:32 offset1:48
	ds_read_b128 v[88:91], v145 offset:12800
	ds_read_b128 v[92:95], v145 offset:13056
	ds_read_b128 v[80:83], v145 offset:4608
	ds_read_b128 v[84:87], v145 offset:4864
	s_waitcnt lgkmcnt(11)
	v_pk_add_f32 v[178:179], v[178:179], v[118:119] op_sel_hi:[1,0] neg_lo:[0,1] neg_hi:[0,1]
	v_add_f32_dpp v156, v156, v156 row_ror:8 row_mask:0xf bank_mask:0xf bound_ctrl:1
	v_pk_add_f32 v[186:187], v[186:187], v[118:119] op_sel:[0,1] op_sel_hi:[1,1] neg_lo:[0,1] neg_hi:[0,1]
	v_add_f32_dpp v157, v157, v157 row_ror:8 row_mask:0xf bank_mask:0xf bound_ctrl:1
	v_pk_add_f32 v[180:181], v[180:181], v[118:119] op_sel_hi:[1,0] neg_lo:[0,1] neg_hi:[0,1]
	v_add_f32_dpp v156, v156, v156 row_ror:4 row_mask:0xf bank_mask:0xf bound_ctrl:1
	v_pk_add_f32 v[188:189], v[188:189], v[118:119] op_sel:[0,1] op_sel_hi:[1,1] neg_lo:[0,1] neg_hi:[0,1]
	v_add_f32_dpp v157, v157, v157 row_ror:4 row_mask:0xf bank_mask:0xf bound_ctrl:1
	v_pk_add_f32 v[182:183], v[182:183], v[118:119] op_sel_hi:[1,0] neg_lo:[0,1] neg_hi:[0,1]
	v_add_f32_dpp v156, v156, v156 row_ror:2 row_mask:0xf bank_mask:0xf bound_ctrl:1
	v_pk_add_f32 v[190:191], v[190:191], v[118:119] op_sel:[0,1] op_sel_hi:[1,1] neg_lo:[0,1] neg_hi:[0,1]
	v_add_f32_dpp v157, v157, v157 row_ror:2 row_mask:0xf bank_mask:0xf bound_ctrl:1
	v_pk_add_f32 v[184:185], v[184:185], v[118:119] op_sel_hi:[1,0] neg_lo:[0,1] neg_hi:[0,1]
	v_add_f32_dpp v156, v156, v156 row_ror:1 row_mask:0xf bank_mask:0xf bound_ctrl:1
	v_pk_add_f32 v[192:193], v[192:193], v[118:119] op_sel:[0,1] op_sel_hi:[1,1] neg_lo:[0,1] neg_hi:[0,1]
	v_add_f32_dpp v157, v157, v157 row_ror:1 row_mask:0xf bank_mask:0xf bound_ctrl:1
	s_waitcnt lgkmcnt(10)
	v_pk_fma_f32 v[178:179], v[72:73], v[178:179], v[118:119] op_sel_hi:[1,1,0]
	s_and_saveexec_b64 s[8:9], s[38:39]
	ds_write_b32 v103, v156 offset:37760
	ds_write_b32 v103, v157 offset:37824
	s_mov_b64 exec, s[8:9]
	v_pk_fma_f32 v[186:187], v[72:73], v[186:187], v[118:119] op_sel:[0,0,1] op_sel_hi:[1,1,1]
	v_pk_fma_f32 v[180:181], v[74:75], v[180:181], v[118:119] op_sel_hi:[1,1,0]
	v_pk_fma_f32 v[188:189], v[74:75], v[188:189], v[118:119] op_sel:[0,0,1] op_sel_hi:[1,1,1]
	s_waitcnt lgkmcnt(11)
	v_pk_fma_f32 v[182:183], v[76:77], v[182:183], v[118:119] op_sel_hi:[1,1,0]
	v_pk_fma_f32 v[190:191], v[76:77], v[190:191], v[118:119] op_sel:[0,0,1] op_sel_hi:[1,1,1]
	v_pk_fma_f32 v[184:185], v[78:79], v[184:185], v[118:119] op_sel_hi:[1,1,0]
	v_pk_fma_f32 v[192:193], v[78:79], v[192:193], v[118:119] op_sel:[0,0,1] op_sel_hi:[1,1,1]
	s_waitcnt lgkmcnt(10)
	v_pk_fma_f32 v[146:147], v[64:65], v[178:179], v[196:197]
	v_pk_fma_f32 v[150:151], v[64:65], v[186:187], v[196:197]
	v_pk_fma_f32 v[148:149], v[66:67], v[180:181], v[196:197]
	v_pk_fma_f32 v[152:153], v[66:67], v[188:189], v[196:197]
	s_waitcnt lgkmcnt(9)
	v_pk_fma_f32 v[146:147], v[68:69], v[182:183], v[146:147]
	v_pk_fma_f32 v[150:151], v[68:69], v[190:191], v[150:151]
	v_pk_fma_f32 v[148:149], v[70:71], v[184:185], v[148:149]
	v_pk_fma_f32 v[152:153], v[70:71], v[192:193], v[152:153]
	v_add_f32_e32 v146, v146, v147
	v_add_f32_e32 v148, v148, v149
	v_add_f32_e32 v150, v150, v151
	v_add_f32_e32 v152, v152, v153
	v_add_f32_e32 v154, v146, v148
	v_add_f32_e32 v155, v150, v152
	ds_read2_b32 v[118:119], v195 offset0:64 offset1:80
	ds_read_b128 v[72:75], v145 offset:13312
	ds_read_b128 v[76:79], v145 offset:13568
	ds_read_b128 v[64:67], v145 offset:5120
	ds_read_b128 v[68:71], v145 offset:5376
	s_waitcnt lgkmcnt(11)
	v_pk_add_f32 v[178:179], v[178:179], v[120:121] op_sel_hi:[1,0] neg_lo:[0,1] neg_hi:[0,1]
	v_add_f32_dpp v154, v154, v154 row_ror:8 row_mask:0xf bank_mask:0xf bound_ctrl:1
	v_pk_add_f32 v[186:187], v[186:187], v[120:121] op_sel:[0,1] op_sel_hi:[1,1] neg_lo:[0,1] neg_hi:[0,1]
	v_add_f32_dpp v155, v155, v155 row_ror:8 row_mask:0xf bank_mask:0xf bound_ctrl:1
	v_pk_add_f32 v[180:181], v[180:181], v[120:121] op_sel_hi:[1,0] neg_lo:[0,1] neg_hi:[0,1]
	v_add_f32_dpp v154, v154, v154 row_ror:4 row_mask:0xf bank_mask:0xf bound_ctrl:1
	v_pk_add_f32 v[188:189], v[188:189], v[120:121] op_sel:[0,1] op_sel_hi:[1,1] neg_lo:[0,1] neg_hi:[0,1]
	v_add_f32_dpp v155, v155, v155 row_ror:4 row_mask:0xf bank_mask:0xf bound_ctrl:1
	v_pk_add_f32 v[182:183], v[182:183], v[120:121] op_sel_hi:[1,0] neg_lo:[0,1] neg_hi:[0,1]
	v_add_f32_dpp v154, v154, v154 row_ror:2 row_mask:0xf bank_mask:0xf bound_ctrl:1
	v_pk_add_f32 v[190:191], v[190:191], v[120:121] op_sel:[0,1] op_sel_hi:[1,1] neg_lo:[0,1] neg_hi:[0,1]
	v_add_f32_dpp v155, v155, v155 row_ror:2 row_mask:0xf bank_mask:0xf bound_ctrl:1
	v_pk_add_f32 v[184:185], v[184:185], v[120:121] op_sel_hi:[1,0] neg_lo:[0,1] neg_hi:[0,1]
	v_add_f32_dpp v154, v154, v154 row_ror:1 row_mask:0xf bank_mask:0xf bound_ctrl:1
	v_pk_add_f32 v[192:193], v[192:193], v[120:121] op_sel:[0,1] op_sel_hi:[1,1] neg_lo:[0,1] neg_hi:[0,1]
	v_add_f32_dpp v155, v155, v155 row_ror:1 row_mask:0xf bank_mask:0xf bound_ctrl:1
	s_waitcnt lgkmcnt(10)
	v_pk_fma_f32 v[178:179], v[88:89], v[178:179], v[120:121] op_sel_hi:[1,1,0]
	s_and_saveexec_b64 s[8:9], s[38:39]
	ds_write_b32 v103, v154 offset:37888
	ds_write_b32 v103, v155 offset:37952
	s_mov_b64 exec, s[8:9]
	v_pk_fma_f32 v[186:187], v[88:89], v[186:187], v[120:121] op_sel:[0,0,1] op_sel_hi:[1,1,1]
	v_pk_fma_f32 v[180:181], v[90:91], v[180:181], v[120:121] op_sel_hi:[1,1,0]
	v_pk_fma_f32 v[188:189], v[90:91], v[188:189], v[120:121] op_sel:[0,0,1] op_sel_hi:[1,1,1]
	s_waitcnt lgkmcnt(11)
	v_pk_fma_f32 v[182:183], v[92:93], v[182:183], v[120:121] op_sel_hi:[1,1,0]
	v_pk_fma_f32 v[190:191], v[92:93], v[190:191], v[120:121] op_sel:[0,0,1] op_sel_hi:[1,1,1]
	v_pk_fma_f32 v[184:185], v[94:95], v[184:185], v[120:121] op_sel_hi:[1,1,0]
	v_pk_fma_f32 v[192:193], v[94:95], v[192:193], v[120:121] op_sel:[0,0,1] op_sel_hi:[1,1,1]
	s_waitcnt lgkmcnt(10)
	v_pk_fma_f32 v[146:147], v[80:81], v[178:179], v[196:197]
	v_pk_fma_f32 v[150:151], v[80:81], v[186:187], v[196:197]
	v_pk_fma_f32 v[148:149], v[82:83], v[180:181], v[196:197]
	v_pk_fma_f32 v[152:153], v[82:83], v[188:189], v[196:197]
	s_waitcnt lgkmcnt(9)
	v_pk_fma_f32 v[146:147], v[84:85], v[182:183], v[146:147]
	v_pk_fma_f32 v[150:151], v[84:85], v[190:191], v[150:151]
	v_pk_fma_f32 v[148:149], v[86:87], v[184:185], v[148:149]
	v_pk_fma_f32 v[152:153], v[86:87], v[192:193], v[152:153]
	v_add_f32_e32 v146, v146, v147
	v_add_f32_e32 v148, v148, v149
	v_add_f32_e32 v150, v150, v151
	v_add_f32_e32 v152, v152, v153
	v_add_f32_e32 v156, v146, v148
	v_add_f32_e32 v157, v150, v152
	ds_read2_b32 v[120:121], v195 offset0:96 offset1:112
	ds_read_b128 v[88:91], v145 offset:13824
	ds_read_b128 v[92:95], v145 offset:14080
	ds_read_b128 v[80:83], v145 offset:5632
	ds_read_b128 v[84:87], v145 offset:5888
	s_waitcnt lgkmcnt(11)
	v_pk_add_f32 v[178:179], v[178:179], v[118:119] op_sel_hi:[1,0] neg_lo:[0,1] neg_hi:[0,1]
	v_add_f32_dpp v156, v156, v156 row_ror:8 row_mask:0xf bank_mask:0xf bound_ctrl:1
	v_pk_add_f32 v[186:187], v[186:187], v[118:119] op_sel:[0,1] op_sel_hi:[1,1] neg_lo:[0,1] neg_hi:[0,1]
	v_add_f32_dpp v157, v157, v157 row_ror:8 row_mask:0xf bank_mask:0xf bound_ctrl:1
	v_pk_add_f32 v[180:181], v[180:181], v[118:119] op_sel_hi:[1,0] neg_lo:[0,1] neg_hi:[0,1]
	v_add_f32_dpp v156, v156, v156 row_ror:4 row_mask:0xf bank_mask:0xf bound_ctrl:1
	v_pk_add_f32 v[188:189], v[188:189], v[118:119] op_sel:[0,1] op_sel_hi:[1,1] neg_lo:[0,1] neg_hi:[0,1]
	v_add_f32_dpp v157, v157, v157 row_ror:4 row_mask:0xf bank_mask:0xf bound_ctrl:1
	v_pk_add_f32 v[182:183], v[182:183], v[118:119] op_sel_hi:[1,0] neg_lo:[0,1] neg_hi:[0,1]
	v_add_f32_dpp v156, v156, v156 row_ror:2 row_mask:0xf bank_mask:0xf bound_ctrl:1
	v_pk_add_f32 v[190:191], v[190:191], v[118:119] op_sel:[0,1] op_sel_hi:[1,1] neg_lo:[0,1] neg_hi:[0,1]
	v_add_f32_dpp v157, v157, v157 row_ror:2 row_mask:0xf bank_mask:0xf bound_ctrl:1
	v_pk_add_f32 v[184:185], v[184:185], v[118:119] op_sel_hi:[1,0] neg_lo:[0,1] neg_hi:[0,1]
	v_add_f32_dpp v156, v156, v156 row_ror:1 row_mask:0xf bank_mask:0xf bound_ctrl:1
	v_pk_add_f32 v[192:193], v[192:193], v[118:119] op_sel:[0,1] op_sel_hi:[1,1] neg_lo:[0,1] neg_hi:[0,1]
	v_add_f32_dpp v157, v157, v157 row_ror:1 row_mask:0xf bank_mask:0xf bound_ctrl:1
	s_waitcnt lgkmcnt(10)
	v_pk_fma_f32 v[178:179], v[72:73], v[178:179], v[118:119] op_sel_hi:[1,1,0]
	s_and_saveexec_b64 s[8:9], s[38:39]
	ds_write_b32 v103, v156 offset:38016
	ds_write_b32 v103, v157 offset:38080
	s_mov_b64 exec, s[8:9]
	v_pk_fma_f32 v[186:187], v[72:73], v[186:187], v[118:119] op_sel:[0,0,1] op_sel_hi:[1,1,1]
	v_pk_fma_f32 v[180:181], v[74:75], v[180:181], v[118:119] op_sel_hi:[1,1,0]
	v_pk_fma_f32 v[188:189], v[74:75], v[188:189], v[118:119] op_sel:[0,0,1] op_sel_hi:[1,1,1]
	s_waitcnt lgkmcnt(11)
	v_pk_fma_f32 v[182:183], v[76:77], v[182:183], v[118:119] op_sel_hi:[1,1,0]
	v_pk_fma_f32 v[190:191], v[76:77], v[190:191], v[118:119] op_sel:[0,0,1] op_sel_hi:[1,1,1]
	v_pk_fma_f32 v[184:185], v[78:79], v[184:185], v[118:119] op_sel_hi:[1,1,0]
	v_pk_fma_f32 v[192:193], v[78:79], v[192:193], v[118:119] op_sel:[0,0,1] op_sel_hi:[1,1,1]
	s_waitcnt lgkmcnt(10)
	v_pk_fma_f32 v[146:147], v[64:65], v[178:179], v[196:197]
	v_pk_fma_f32 v[150:151], v[64:65], v[186:187], v[196:197]
	v_pk_fma_f32 v[148:149], v[66:67], v[180:181], v[196:197]
	v_pk_fma_f32 v[152:153], v[66:67], v[188:189], v[196:197]
	s_waitcnt lgkmcnt(9)
	v_pk_fma_f32 v[146:147], v[68:69], v[182:183], v[146:147]
	v_pk_fma_f32 v[150:151], v[68:69], v[190:191], v[150:151]
	v_pk_fma_f32 v[148:149], v[70:71], v[184:185], v[148:149]
	v_pk_fma_f32 v[152:153], v[70:71], v[192:193], v[152:153]
	v_add_f32_e32 v146, v146, v147
	v_add_f32_e32 v148, v148, v149
	v_add_f32_e32 v150, v150, v151
	v_add_f32_e32 v152, v152, v153
	v_add_f32_e32 v154, v146, v148
	v_add_f32_e32 v155, v150, v152
	ds_read2_b32 v[118:119], v195 offset0:128 offset1:144
	ds_read_b128 v[72:75], v145 offset:14336
	ds_read_b128 v[76:79], v145 offset:14592
	ds_read_b128 v[64:67], v145 offset:6144
	ds_read_b128 v[68:71], v145 offset:6400
	s_waitcnt lgkmcnt(11)
	v_pk_add_f32 v[178:179], v[178:179], v[120:121] op_sel_hi:[1,0] neg_lo:[0,1] neg_hi:[0,1]
	v_add_f32_dpp v154, v154, v154 row_ror:8 row_mask:0xf bank_mask:0xf bound_ctrl:1
	v_pk_add_f32 v[186:187], v[186:187], v[120:121] op_sel:[0,1] op_sel_hi:[1,1] neg_lo:[0,1] neg_hi:[0,1]
	v_add_f32_dpp v155, v155, v155 row_ror:8 row_mask:0xf bank_mask:0xf bound_ctrl:1
	v_pk_add_f32 v[180:181], v[180:181], v[120:121] op_sel_hi:[1,0] neg_lo:[0,1] neg_hi:[0,1]
	v_add_f32_dpp v154, v154, v154 row_ror:4 row_mask:0xf bank_mask:0xf bound_ctrl:1
	v_pk_add_f32 v[188:189], v[188:189], v[120:121] op_sel:[0,1] op_sel_hi:[1,1] neg_lo:[0,1] neg_hi:[0,1]
	v_add_f32_dpp v155, v155, v155 row_ror:4 row_mask:0xf bank_mask:0xf bound_ctrl:1
	v_pk_add_f32 v[182:183], v[182:183], v[120:121] op_sel_hi:[1,0] neg_lo:[0,1] neg_hi:[0,1]
	v_add_f32_dpp v154, v154, v154 row_ror:2 row_mask:0xf bank_mask:0xf bound_ctrl:1
	v_pk_add_f32 v[190:191], v[190:191], v[120:121] op_sel:[0,1] op_sel_hi:[1,1] neg_lo:[0,1] neg_hi:[0,1]
	v_add_f32_dpp v155, v155, v155 row_ror:2 row_mask:0xf bank_mask:0xf bound_ctrl:1
	v_pk_add_f32 v[184:185], v[184:185], v[120:121] op_sel_hi:[1,0] neg_lo:[0,1] neg_hi:[0,1]
	v_add_f32_dpp v154, v154, v154 row_ror:1 row_mask:0xf bank_mask:0xf bound_ctrl:1
	v_pk_add_f32 v[192:193], v[192:193], v[120:121] op_sel:[0,1] op_sel_hi:[1,1] neg_lo:[0,1] neg_hi:[0,1]
	v_add_f32_dpp v155, v155, v155 row_ror:1 row_mask:0xf bank_mask:0xf bound_ctrl:1
	s_waitcnt lgkmcnt(10)
	v_pk_fma_f32 v[178:179], v[88:89], v[178:179], v[120:121] op_sel_hi:[1,1,0]
	s_and_saveexec_b64 s[8:9], s[38:39]
	ds_write_b32 v103, v154 offset:38144
	ds_write_b32 v103, v155 offset:38208
	s_mov_b64 exec, s[8:9]
	v_pk_fma_f32 v[186:187], v[88:89], v[186:187], v[120:121] op_sel:[0,0,1] op_sel_hi:[1,1,1]
	v_pk_fma_f32 v[180:181], v[90:91], v[180:181], v[120:121] op_sel_hi:[1,1,0]
	v_pk_fma_f32 v[188:189], v[90:91], v[188:189], v[120:121] op_sel:[0,0,1] op_sel_hi:[1,1,1]
	s_waitcnt lgkmcnt(11)
	v_pk_fma_f32 v[182:183], v[92:93], v[182:183], v[120:121] op_sel_hi:[1,1,0]
	v_pk_fma_f32 v[190:191], v[92:93], v[190:191], v[120:121] op_sel:[0,0,1] op_sel_hi:[1,1,1]
	v_pk_fma_f32 v[184:185], v[94:95], v[184:185], v[120:121] op_sel_hi:[1,1,0]
	v_pk_fma_f32 v[192:193], v[94:95], v[192:193], v[120:121] op_sel:[0,0,1] op_sel_hi:[1,1,1]
	s_waitcnt lgkmcnt(10)
	v_pk_fma_f32 v[146:147], v[80:81], v[178:179], v[196:197]
	v_pk_fma_f32 v[150:151], v[80:81], v[186:187], v[196:197]
	v_pk_fma_f32 v[148:149], v[82:83], v[180:181], v[196:197]
	v_pk_fma_f32 v[152:153], v[82:83], v[188:189], v[196:197]
	s_waitcnt lgkmcnt(9)
	v_pk_fma_f32 v[146:147], v[84:85], v[182:183], v[146:147]
	v_pk_fma_f32 v[150:151], v[84:85], v[190:191], v[150:151]
	v_pk_fma_f32 v[148:149], v[86:87], v[184:185], v[148:149]
	v_pk_fma_f32 v[152:153], v[86:87], v[192:193], v[152:153]
	v_add_f32_e32 v146, v146, v147
	v_add_f32_e32 v148, v148, v149
	v_add_f32_e32 v150, v150, v151
	v_add_f32_e32 v152, v152, v153
	v_add_f32_e32 v156, v146, v148
	v_add_f32_e32 v157, v150, v152
	ds_read2_b32 v[120:121], v195 offset0:160 offset1:176
	ds_read_b128 v[88:91], v145 offset:14848
	ds_read_b128 v[92:95], v145 offset:15104
	ds_read_b128 v[80:83], v145 offset:6656
	ds_read_b128 v[84:87], v145 offset:6912
	s_waitcnt lgkmcnt(11)
	v_pk_add_f32 v[178:179], v[178:179], v[118:119] op_sel_hi:[1,0] neg_lo:[0,1] neg_hi:[0,1]
	v_add_f32_dpp v156, v156, v156 row_ror:8 row_mask:0xf bank_mask:0xf bound_ctrl:1
	v_pk_add_f32 v[186:187], v[186:187], v[118:119] op_sel:[0,1] op_sel_hi:[1,1] neg_lo:[0,1] neg_hi:[0,1]
	v_add_f32_dpp v157, v157, v157 row_ror:8 row_mask:0xf bank_mask:0xf bound_ctrl:1
	v_pk_add_f32 v[180:181], v[180:181], v[118:119] op_sel_hi:[1,0] neg_lo:[0,1] neg_hi:[0,1]
	v_add_f32_dpp v156, v156, v156 row_ror:4 row_mask:0xf bank_mask:0xf bound_ctrl:1
	v_pk_add_f32 v[188:189], v[188:189], v[118:119] op_sel:[0,1] op_sel_hi:[1,1] neg_lo:[0,1] neg_hi:[0,1]
	v_add_f32_dpp v157, v157, v157 row_ror:4 row_mask:0xf bank_mask:0xf bound_ctrl:1
	v_pk_add_f32 v[182:183], v[182:183], v[118:119] op_sel_hi:[1,0] neg_lo:[0,1] neg_hi:[0,1]
	v_add_f32_dpp v156, v156, v156 row_ror:2 row_mask:0xf bank_mask:0xf bound_ctrl:1
	v_pk_add_f32 v[190:191], v[190:191], v[118:119] op_sel:[0,1] op_sel_hi:[1,1] neg_lo:[0,1] neg_hi:[0,1]
	v_add_f32_dpp v157, v157, v157 row_ror:2 row_mask:0xf bank_mask:0xf bound_ctrl:1
	v_pk_add_f32 v[184:185], v[184:185], v[118:119] op_sel_hi:[1,0] neg_lo:[0,1] neg_hi:[0,1]
	v_add_f32_dpp v156, v156, v156 row_ror:1 row_mask:0xf bank_mask:0xf bound_ctrl:1
	v_pk_add_f32 v[192:193], v[192:193], v[118:119] op_sel:[0,1] op_sel_hi:[1,1] neg_lo:[0,1] neg_hi:[0,1]
	v_add_f32_dpp v157, v157, v157 row_ror:1 row_mask:0xf bank_mask:0xf bound_ctrl:1
	s_waitcnt lgkmcnt(10)
	v_pk_fma_f32 v[178:179], v[72:73], v[178:179], v[118:119] op_sel_hi:[1,1,0]
	s_and_saveexec_b64 s[8:9], s[38:39]
	ds_write_b32 v103, v156 offset:38272
	ds_write_b32 v103, v157 offset:38336
	s_mov_b64 exec, s[8:9]
	v_pk_fma_f32 v[186:187], v[72:73], v[186:187], v[118:119] op_sel:[0,0,1] op_sel_hi:[1,1,1]
	v_pk_fma_f32 v[180:181], v[74:75], v[180:181], v[118:119] op_sel_hi:[1,1,0]
	v_pk_fma_f32 v[188:189], v[74:75], v[188:189], v[118:119] op_sel:[0,0,1] op_sel_hi:[1,1,1]
	s_waitcnt lgkmcnt(11)
	v_pk_fma_f32 v[182:183], v[76:77], v[182:183], v[118:119] op_sel_hi:[1,1,0]
	v_pk_fma_f32 v[190:191], v[76:77], v[190:191], v[118:119] op_sel:[0,0,1] op_sel_hi:[1,1,1]
	v_pk_fma_f32 v[184:185], v[78:79], v[184:185], v[118:119] op_sel_hi:[1,1,0]
	v_pk_fma_f32 v[192:193], v[78:79], v[192:193], v[118:119] op_sel:[0,0,1] op_sel_hi:[1,1,1]
	s_waitcnt lgkmcnt(10)
	v_pk_fma_f32 v[146:147], v[64:65], v[178:179], v[196:197]
	v_pk_fma_f32 v[150:151], v[64:65], v[186:187], v[196:197]
	v_pk_fma_f32 v[148:149], v[66:67], v[180:181], v[196:197]
	v_pk_fma_f32 v[152:153], v[66:67], v[188:189], v[196:197]
	s_waitcnt lgkmcnt(9)
	v_pk_fma_f32 v[146:147], v[68:69], v[182:183], v[146:147]
	v_pk_fma_f32 v[150:151], v[68:69], v[190:191], v[150:151]
	v_pk_fma_f32 v[148:149], v[70:71], v[184:185], v[148:149]
	v_pk_fma_f32 v[152:153], v[70:71], v[192:193], v[152:153]
	v_add_f32_e32 v146, v146, v147
	v_add_f32_e32 v148, v148, v149
	v_add_f32_e32 v150, v150, v151
	v_add_f32_e32 v152, v152, v153
	v_add_f32_e32 v154, v146, v148
	v_add_f32_e32 v155, v150, v152
	ds_read2_b32 v[118:119], v195 offset0:192 offset1:208
	ds_read_b128 v[72:75], v145 offset:15360
	ds_read_b128 v[76:79], v145 offset:15616
	ds_read_b128 v[64:67], v145 offset:7168
	ds_read_b128 v[68:71], v145 offset:7424
	s_waitcnt lgkmcnt(11)
	v_pk_add_f32 v[178:179], v[178:179], v[120:121] op_sel_hi:[1,0] neg_lo:[0,1] neg_hi:[0,1]
	v_add_f32_dpp v154, v154, v154 row_ror:8 row_mask:0xf bank_mask:0xf bound_ctrl:1
	v_pk_add_f32 v[186:187], v[186:187], v[120:121] op_sel:[0,1] op_sel_hi:[1,1] neg_lo:[0,1] neg_hi:[0,1]
	v_add_f32_dpp v155, v155, v155 row_ror:8 row_mask:0xf bank_mask:0xf bound_ctrl:1
	v_pk_add_f32 v[180:181], v[180:181], v[120:121] op_sel_hi:[1,0] neg_lo:[0,1] neg_hi:[0,1]
	v_add_f32_dpp v154, v154, v154 row_ror:4 row_mask:0xf bank_mask:0xf bound_ctrl:1
	v_pk_add_f32 v[188:189], v[188:189], v[120:121] op_sel:[0,1] op_sel_hi:[1,1] neg_lo:[0,1] neg_hi:[0,1]
	v_add_f32_dpp v155, v155, v155 row_ror:4 row_mask:0xf bank_mask:0xf bound_ctrl:1
	v_pk_add_f32 v[182:183], v[182:183], v[120:121] op_sel_hi:[1,0] neg_lo:[0,1] neg_hi:[0,1]
	v_add_f32_dpp v154, v154, v154 row_ror:2 row_mask:0xf bank_mask:0xf bound_ctrl:1
	v_pk_add_f32 v[190:191], v[190:191], v[120:121] op_sel:[0,1] op_sel_hi:[1,1] neg_lo:[0,1] neg_hi:[0,1]
	v_add_f32_dpp v155, v155, v155 row_ror:2 row_mask:0xf bank_mask:0xf bound_ctrl:1
	v_pk_add_f32 v[184:185], v[184:185], v[120:121] op_sel_hi:[1,0] neg_lo:[0,1] neg_hi:[0,1]
	v_add_f32_dpp v154, v154, v154 row_ror:1 row_mask:0xf bank_mask:0xf bound_ctrl:1
	v_pk_add_f32 v[192:193], v[192:193], v[120:121] op_sel:[0,1] op_sel_hi:[1,1] neg_lo:[0,1] neg_hi:[0,1]
	v_add_f32_dpp v155, v155, v155 row_ror:1 row_mask:0xf bank_mask:0xf bound_ctrl:1
	s_waitcnt lgkmcnt(10)
	v_pk_fma_f32 v[178:179], v[88:89], v[178:179], v[120:121] op_sel_hi:[1,1,0]
	s_and_saveexec_b64 s[8:9], s[38:39]
	ds_write_b32 v103, v154 offset:38400
	ds_write_b32 v103, v155 offset:38464
	s_mov_b64 exec, s[8:9]
	v_pk_fma_f32 v[186:187], v[88:89], v[186:187], v[120:121] op_sel:[0,0,1] op_sel_hi:[1,1,1]
	v_pk_fma_f32 v[180:181], v[90:91], v[180:181], v[120:121] op_sel_hi:[1,1,0]
	v_pk_fma_f32 v[188:189], v[90:91], v[188:189], v[120:121] op_sel:[0,0,1] op_sel_hi:[1,1,1]
	s_waitcnt lgkmcnt(11)
	v_pk_fma_f32 v[182:183], v[92:93], v[182:183], v[120:121] op_sel_hi:[1,1,0]
	v_pk_fma_f32 v[190:191], v[92:93], v[190:191], v[120:121] op_sel:[0,0,1] op_sel_hi:[1,1,1]
	v_pk_fma_f32 v[184:185], v[94:95], v[184:185], v[120:121] op_sel_hi:[1,1,0]
	v_pk_fma_f32 v[192:193], v[94:95], v[192:193], v[120:121] op_sel:[0,0,1] op_sel_hi:[1,1,1]
	s_waitcnt lgkmcnt(10)
	v_pk_fma_f32 v[146:147], v[80:81], v[178:179], v[196:197]
	v_pk_fma_f32 v[150:151], v[80:81], v[186:187], v[196:197]
	v_pk_fma_f32 v[148:149], v[82:83], v[180:181], v[196:197]
	v_pk_fma_f32 v[152:153], v[82:83], v[188:189], v[196:197]
	s_waitcnt lgkmcnt(9)
	v_pk_fma_f32 v[146:147], v[84:85], v[182:183], v[146:147]
	v_pk_fma_f32 v[150:151], v[84:85], v[190:191], v[150:151]
	v_pk_fma_f32 v[148:149], v[86:87], v[184:185], v[148:149]
	v_pk_fma_f32 v[152:153], v[86:87], v[192:193], v[152:153]
	v_add_f32_e32 v146, v146, v147
	v_add_f32_e32 v148, v148, v149
	v_add_f32_e32 v150, v150, v151
	v_add_f32_e32 v152, v152, v153
	v_add_f32_e32 v156, v146, v148
	v_add_f32_e32 v157, v150, v152
	ds_read2_b32 v[120:121], v195 offset0:224 offset1:240
	ds_read_b128 v[88:91], v145 offset:15872
	ds_read_b128 v[92:95], v145 offset:16128
	ds_read_b128 v[80:83], v145 offset:7680
	ds_read_b128 v[84:87], v145 offset:7936
	s_waitcnt lgkmcnt(11)
	v_pk_add_f32 v[178:179], v[178:179], v[118:119] op_sel_hi:[1,0] neg_lo:[0,1] neg_hi:[0,1]
	v_add_f32_dpp v156, v156, v156 row_ror:8 row_mask:0xf bank_mask:0xf bound_ctrl:1
	v_pk_add_f32 v[186:187], v[186:187], v[118:119] op_sel:[0,1] op_sel_hi:[1,1] neg_lo:[0,1] neg_hi:[0,1]
	v_add_f32_dpp v157, v157, v157 row_ror:8 row_mask:0xf bank_mask:0xf bound_ctrl:1
	v_pk_add_f32 v[180:181], v[180:181], v[118:119] op_sel_hi:[1,0] neg_lo:[0,1] neg_hi:[0,1]
	v_add_f32_dpp v156, v156, v156 row_ror:4 row_mask:0xf bank_mask:0xf bound_ctrl:1
	v_pk_add_f32 v[188:189], v[188:189], v[118:119] op_sel:[0,1] op_sel_hi:[1,1] neg_lo:[0,1] neg_hi:[0,1]
	v_add_f32_dpp v157, v157, v157 row_ror:4 row_mask:0xf bank_mask:0xf bound_ctrl:1
	v_pk_add_f32 v[182:183], v[182:183], v[118:119] op_sel_hi:[1,0] neg_lo:[0,1] neg_hi:[0,1]
	v_add_f32_dpp v156, v156, v156 row_ror:2 row_mask:0xf bank_mask:0xf bound_ctrl:1
	v_pk_add_f32 v[190:191], v[190:191], v[118:119] op_sel:[0,1] op_sel_hi:[1,1] neg_lo:[0,1] neg_hi:[0,1]
	v_add_f32_dpp v157, v157, v157 row_ror:2 row_mask:0xf bank_mask:0xf bound_ctrl:1
	v_pk_add_f32 v[184:185], v[184:185], v[118:119] op_sel_hi:[1,0] neg_lo:[0,1] neg_hi:[0,1]
	v_add_f32_dpp v156, v156, v156 row_ror:1 row_mask:0xf bank_mask:0xf bound_ctrl:1
	v_pk_add_f32 v[192:193], v[192:193], v[118:119] op_sel:[0,1] op_sel_hi:[1,1] neg_lo:[0,1] neg_hi:[0,1]
	v_add_f32_dpp v157, v157, v157 row_ror:1 row_mask:0xf bank_mask:0xf bound_ctrl:1
	s_waitcnt lgkmcnt(10)
	v_pk_fma_f32 v[178:179], v[72:73], v[178:179], v[118:119] op_sel_hi:[1,1,0]
	s_and_saveexec_b64 s[8:9], s[38:39]
	ds_write_b32 v103, v156 offset:38528
	ds_write_b32 v103, v157 offset:38592
	s_mov_b64 exec, s[8:9]
	v_pk_fma_f32 v[186:187], v[72:73], v[186:187], v[118:119] op_sel:[0,0,1] op_sel_hi:[1,1,1]
	v_pk_fma_f32 v[180:181], v[74:75], v[180:181], v[118:119] op_sel_hi:[1,1,0]
	v_pk_fma_f32 v[188:189], v[74:75], v[188:189], v[118:119] op_sel:[0,0,1] op_sel_hi:[1,1,1]
	s_waitcnt lgkmcnt(11)
	v_pk_fma_f32 v[182:183], v[76:77], v[182:183], v[118:119] op_sel_hi:[1,1,0]
	v_pk_fma_f32 v[190:191], v[76:77], v[190:191], v[118:119] op_sel:[0,0,1] op_sel_hi:[1,1,1]
	v_pk_fma_f32 v[184:185], v[78:79], v[184:185], v[118:119] op_sel_hi:[1,1,0]
	v_pk_fma_f32 v[192:193], v[78:79], v[192:193], v[118:119] op_sel:[0,0,1] op_sel_hi:[1,1,1]
	s_waitcnt lgkmcnt(10)
	v_pk_fma_f32 v[146:147], v[64:65], v[178:179], v[196:197]
	v_pk_fma_f32 v[150:151], v[64:65], v[186:187], v[196:197]
	v_pk_fma_f32 v[148:149], v[66:67], v[180:181], v[196:197]
	v_pk_fma_f32 v[152:153], v[66:67], v[188:189], v[196:197]
	s_waitcnt lgkmcnt(9)
	v_pk_fma_f32 v[146:147], v[68:69], v[182:183], v[146:147]
	v_pk_fma_f32 v[150:151], v[68:69], v[190:191], v[150:151]
	v_pk_fma_f32 v[148:149], v[70:71], v[184:185], v[148:149]
	v_pk_fma_f32 v[152:153], v[70:71], v[192:193], v[152:153]
	v_add_f32_e32 v146, v146, v147
	v_add_f32_e32 v148, v148, v149
	v_add_f32_e32 v150, v150, v151
	v_add_f32_e32 v152, v152, v153
	v_add_f32_e32 v154, v146, v148
	v_add_f32_e32 v155, v150, v152
	s_waitcnt lgkmcnt(6)
	v_pk_add_f32 v[178:179], v[178:179], v[120:121] op_sel_hi:[1,0] neg_lo:[0,1] neg_hi:[0,1]
	v_add_f32_dpp v154, v154, v154 row_ror:8 row_mask:0xf bank_mask:0xf bound_ctrl:1
	v_pk_add_f32 v[186:187], v[186:187], v[120:121] op_sel:[0,1] op_sel_hi:[1,1] neg_lo:[0,1] neg_hi:[0,1]
	v_add_f32_dpp v155, v155, v155 row_ror:8 row_mask:0xf bank_mask:0xf bound_ctrl:1
	v_pk_add_f32 v[180:181], v[180:181], v[120:121] op_sel_hi:[1,0] neg_lo:[0,1] neg_hi:[0,1]
	v_add_f32_dpp v154, v154, v154 row_ror:4 row_mask:0xf bank_mask:0xf bound_ctrl:1
	v_pk_add_f32 v[188:189], v[188:189], v[120:121] op_sel:[0,1] op_sel_hi:[1,1] neg_lo:[0,1] neg_hi:[0,1]
	v_add_f32_dpp v155, v155, v155 row_ror:4 row_mask:0xf bank_mask:0xf bound_ctrl:1
	v_pk_add_f32 v[182:183], v[182:183], v[120:121] op_sel_hi:[1,0] neg_lo:[0,1] neg_hi:[0,1]
	v_add_f32_dpp v154, v154, v154 row_ror:2 row_mask:0xf bank_mask:0xf bound_ctrl:1
	v_pk_add_f32 v[190:191], v[190:191], v[120:121] op_sel:[0,1] op_sel_hi:[1,1] neg_lo:[0,1] neg_hi:[0,1]
	v_add_f32_dpp v155, v155, v155 row_ror:2 row_mask:0xf bank_mask:0xf bound_ctrl:1
	v_pk_add_f32 v[184:185], v[184:185], v[120:121] op_sel_hi:[1,0] neg_lo:[0,1] neg_hi:[0,1]
	v_add_f32_dpp v154, v154, v154 row_ror:1 row_mask:0xf bank_mask:0xf bound_ctrl:1
	v_pk_add_f32 v[192:193], v[192:193], v[120:121] op_sel:[0,1] op_sel_hi:[1,1] neg_lo:[0,1] neg_hi:[0,1]
	v_add_f32_dpp v155, v155, v155 row_ror:1 row_mask:0xf bank_mask:0xf bound_ctrl:1
	s_waitcnt lgkmcnt(5)
	v_pk_fma_f32 v[178:179], v[88:89], v[178:179], v[120:121] op_sel_hi:[1,1,0]
	s_and_saveexec_b64 s[8:9], s[38:39]
	ds_write_b32 v103, v154 offset:38656
	ds_write_b32 v103, v155 offset:38720
	s_mov_b64 exec, s[8:9]
	v_pk_fma_f32 v[186:187], v[88:89], v[186:187], v[120:121] op_sel:[0,0,1] op_sel_hi:[1,1,1]
	v_pk_fma_f32 v[180:181], v[90:91], v[180:181], v[120:121] op_sel_hi:[1,1,0]
	v_pk_fma_f32 v[188:189], v[90:91], v[188:189], v[120:121] op_sel:[0,0,1] op_sel_hi:[1,1,1]
	s_waitcnt lgkmcnt(6)
	v_pk_fma_f32 v[182:183], v[92:93], v[182:183], v[120:121] op_sel_hi:[1,1,0]
	v_pk_fma_f32 v[190:191], v[92:93], v[190:191], v[120:121] op_sel:[0,0,1] op_sel_hi:[1,1,1]
	v_pk_fma_f32 v[184:185], v[94:95], v[184:185], v[120:121] op_sel_hi:[1,1,0]
	v_pk_fma_f32 v[192:193], v[94:95], v[192:193], v[120:121] op_sel:[0,0,1] op_sel_hi:[1,1,1]
	s_waitcnt lgkmcnt(5)
	v_pk_fma_f32 v[146:147], v[80:81], v[178:179], v[196:197]
	v_pk_fma_f32 v[150:151], v[80:81], v[186:187], v[196:197]
	v_pk_fma_f32 v[148:149], v[82:83], v[180:181], v[196:197]
	v_pk_fma_f32 v[152:153], v[82:83], v[188:189], v[196:197]
	s_waitcnt lgkmcnt(4)
	v_pk_fma_f32 v[146:147], v[84:85], v[182:183], v[146:147]
	v_pk_fma_f32 v[150:151], v[84:85], v[190:191], v[150:151]
	v_pk_fma_f32 v[148:149], v[86:87], v[184:185], v[148:149]
	v_pk_fma_f32 v[152:153], v[86:87], v[192:193], v[152:153]
	v_add_f32_e32 v146, v146, v147
	v_add_f32_e32 v148, v148, v149
	v_add_f32_e32 v150, v150, v151
	v_add_f32_e32 v152, v152, v153
	v_add_f32_e32 v156, v146, v148
	v_add_f32_e32 v157, v150, v152
	s_nop 0
	v_add_f32_dpp v156, v156, v156 row_ror:8 row_mask:0xf bank_mask:0xf bound_ctrl:1
	v_add_f32_dpp v157, v157, v157 row_ror:8 row_mask:0xf bank_mask:0xf bound_ctrl:1
	s_nop 0
	v_add_f32_dpp v156, v156, v156 row_ror:4 row_mask:0xf bank_mask:0xf bound_ctrl:1
	v_add_f32_dpp v157, v157, v157 row_ror:4 row_mask:0xf bank_mask:0xf bound_ctrl:1
	s_nop 0
	v_add_f32_dpp v156, v156, v156 row_ror:2 row_mask:0xf bank_mask:0xf bound_ctrl:1
	v_add_f32_dpp v157, v157, v157 row_ror:2 row_mask:0xf bank_mask:0xf bound_ctrl:1
	s_nop 0
	v_add_f32_dpp v156, v156, v156 row_ror:1 row_mask:0xf bank_mask:0xf bound_ctrl:1
	v_add_f32_dpp v157, v157, v157 row_ror:1 row_mask:0xf bank_mask:0xf bound_ctrl:1
	s_and_saveexec_b64 s[8:9], s[38:39]
	ds_write_b32 v103, v156 offset:38784
	ds_write_b32 v103, v157 offset:38848
	s_mov_b64 exec, s[8:9]
	s_waitcnt vmcnt(5)
	v_mul_f32_e32 v64, 0xbfb8aa3b, v44
	v_mul_f32_e32 v65, 0xbfb8aa3b, v45
	v_exp_f32_e32 v64, v64
	v_exp_f32_e32 v65, v65
	v_mul_f32_e32 v66, 0xbfb8aa3b, v46
	v_mul_f32_e32 v67, 0xbfb8aa3b, v47
	v_exp_f32_e32 v66, v66
	v_pk_add_f32 v[64:65], v[64:65], 1.0 op_sel_hi:[1,0]
	v_exp_f32_e32 v67, v67
	v_div_scale_f32 v80, s[8:9], v65, v65, v45
	v_rcp_f32_e32 v81, v80
	v_pk_add_f32 v[66:67], v[66:67], 1.0 op_sel_hi:[1,0]
	v_mul_f32_e32 v72, 0xbfb8aa3b, v48
	v_mul_f32_e32 v73, 0xbfb8aa3b, v49
	v_fma_f32 v82, -v80, v81, 1.0
	v_fmac_f32_e32 v81, v82, v81
	v_div_scale_f32 v82, vcc, v45, v65, v45
	v_mul_f32_e32 v83, v82, v81
	v_fma_f32 v88, -v80, v83, v82
	v_fmac_f32_e32 v83, v88, v81
	v_fma_f32 v80, -v80, v83, v82
	v_div_fmas_f32 v80, v80, v81, v83
	v_div_fixup_f32 v65, v80, v65, v45
	v_div_scale_f32 v80, s[8:9], v64, v64, v44
	v_rcp_f32_e32 v81, v80
	v_exp_f32_e32 v72, v72
	v_exp_f32_e32 v73, v73
	v_mul_f32_e32 v74, 0xbfb8aa3b, v50
	v_fma_f32 v82, -v80, v81, 1.0
	v_fmac_f32_e32 v81, v82, v81
	v_div_scale_f32 v82, vcc, v44, v64, v44
	v_mul_f32_e32 v83, v82, v81
	v_fma_f32 v88, -v80, v83, v82
	v_fmac_f32_e32 v83, v88, v81
	v_fma_f32 v80, -v80, v83, v82
	v_div_fmas_f32 v80, v80, v81, v83
	v_div_fixup_f32 v64, v80, v64, v44
	v_div_scale_f32 v80, s[8:9], v67, v67, v47
	v_rcp_f32_e32 v81, v80
	v_pk_mul_f32 v[64:65], v[64:65], s[18:19] op_sel_hi:[1,0]
	v_mul_f32_e32 v75, 0xbfb8aa3b, v51
	v_exp_f32_e32 v74, v74
	v_fma_f32 v82, -v80, v81, 1.0
	v_fmac_f32_e32 v81, v82, v81
	v_div_scale_f32 v82, vcc, v47, v67, v47
	v_mul_f32_e32 v83, v82, v81
	v_fma_f32 v88, -v80, v83, v82
	v_fmac_f32_e32 v83, v88, v81
	v_fma_f32 v80, -v80, v83, v82
	v_div_fmas_f32 v80, v80, v81, v83
	v_div_fixup_f32 v67, v80, v67, v47
	v_div_scale_f32 v80, s[8:9], v66, v66, v46
	v_rcp_f32_e32 v81, v80
	v_exp_f32_e32 v75, v75
	s_cmpk_gt_u32 s48, 0x78
	v_fma_f32 v82, -v80, v81, 1.0
	v_fmac_f32_e32 v81, v82, v81
	v_div_scale_f32 v82, vcc, v46, v66, v46
	v_mul_f32_e32 v83, v82, v81
	v_fma_f32 v88, -v80, v83, v82
	v_fmac_f32_e32 v83, v88, v81
	v_fma_f32 v80, -v80, v83, v82
	v_div_fmas_f32 v80, v80, v81, v83
	v_div_fixup_f32 v66, v80, v66, v46
	v_pk_mul_f32 v[66:67], v[66:67], s[18:19] op_sel_hi:[1,0]
	ds_write_b128 v141, v[64:67] offset:18432
	v_pk_add_f32 v[64:65], v[72:73], 1.0 op_sel_hi:[1,0]
	v_div_scale_f32 v66, s[8:9], v65, v65, 1.0
	v_rcp_f32_e32 v67, v66
	s_nop 0
	v_fma_f32 v72, -v66, v67, 1.0
	v_fmac_f32_e32 v67, v72, v67
	v_div_scale_f32 v72, vcc, 1.0, v65, 1.0
	v_mul_f32_e32 v73, v72, v67
	v_fma_f32 v80, -v66, v73, v72
	v_fmac_f32_e32 v73, v80, v67
	v_fma_f32 v66, -v66, v73, v72
	v_div_fmas_f32 v66, v66, v67, v73
	v_div_fixup_f32 v65, v66, v65, 1.0
	v_div_scale_f32 v66, s[8:9], v64, v64, 1.0
	v_rcp_f32_e32 v67, v66
	s_nop 0
	v_fma_f32 v72, -v66, v67, 1.0
	v_fmac_f32_e32 v67, v72, v67
	v_div_scale_f32 v72, vcc, 1.0, v64, 1.0
	v_mul_f32_e32 v73, v72, v67
	v_fma_f32 v80, -v66, v73, v72
	v_fmac_f32_e32 v73, v80, v67
	v_fma_f32 v66, -v66, v73, v72
	v_div_fmas_f32 v66, v66, v67, v73
	v_div_fixup_f32 v64, v66, v64, 1.0
	v_pk_add_f32 v[66:67], v[74:75], 1.0 op_sel_hi:[1,0]
	v_pk_fma_f32 v[64:65], v[110:111], v[64:65], v[104:105]
	v_div_scale_f32 v72, s[8:9], v67, v67, 1.0
	v_rcp_f32_e32 v73, v72
	s_nop 0
	v_fma_f32 v74, -v72, v73, 1.0
	v_fmac_f32_e32 v73, v74, v73
	v_div_scale_f32 v74, vcc, 1.0, v67, 1.0
	v_mul_f32_e32 v75, v74, v73
	v_fma_f32 v80, -v72, v75, v74
	v_fmac_f32_e32 v75, v80, v73
	v_fma_f32 v72, -v72, v75, v74
	v_div_fmas_f32 v72, v72, v73, v75
	v_div_fixup_f32 v67, v72, v67, 1.0
	v_div_scale_f32 v72, s[8:9], v66, v66, 1.0
	v_rcp_f32_e32 v73, v72
	s_nop 0
	v_fma_f32 v74, -v72, v73, 1.0
	v_fmac_f32_e32 v73, v74, v73
	v_div_scale_f32 v74, vcc, 1.0, v66, 1.0
	v_mul_f32_e32 v75, v74, v73
	v_fma_f32 v80, -v72, v75, v74
	v_fmac_f32_e32 v75, v80, v73
	v_fma_f32 v72, -v72, v75, v74
	v_div_fmas_f32 v72, v72, v73, v75
	v_div_fixup_f32 v66, v72, v66, 1.0
	v_pk_fma_f32 v[66:67], v[112:113], v[66:67], v[106:107]
	ds_write_b128 v141, v[64:67] offset:26624
	ds_write_b32 v134, v133 offset:34816
	v_mul_f32_e32 v64, 0xbfb8aa3b, v56
	v_mul_f32_e32 v65, 0xbfb8aa3b, v57
	v_exp_f32_e32 v64, v64
	v_exp_f32_e32 v65, v65
	v_mul_f32_e32 v66, 0xbfb8aa3b, v58
	v_mul_f32_e32 v67, 0xbfb8aa3b, v59
	v_exp_f32_e32 v66, v66
	v_pk_add_f32 v[64:65], v[64:65], 1.0 op_sel_hi:[1,0]
	v_exp_f32_e32 v67, v67
	v_div_scale_f32 v80, s[8:9], v65, v65, v57
	v_rcp_f32_e32 v81, v80
	v_pk_add_f32 v[66:67], v[66:67], 1.0 op_sel_hi:[1,0]
	s_waitcnt vmcnt(4)
	v_mul_f32_e32 v72, 0xbfb8aa3b, v60
	v_mul_f32_e32 v73, 0xbfb8aa3b, v61
	v_fma_f32 v82, -v80, v81, 1.0
	v_fmac_f32_e32 v81, v82, v81
	v_div_scale_f32 v82, vcc, v57, v65, v57
	v_mul_f32_e32 v83, v82, v81
	v_fma_f32 v88, -v80, v83, v82
	v_fmac_f32_e32 v83, v88, v81
	v_fma_f32 v80, -v80, v83, v82
	v_div_fmas_f32 v80, v80, v81, v83
	v_div_fixup_f32 v65, v80, v65, v57
	v_div_scale_f32 v80, s[8:9], v64, v64, v56
	v_rcp_f32_e32 v81, v80
	v_exp_f32_e32 v72, v72
	v_exp_f32_e32 v73, v73
	v_mul_f32_e32 v74, 0xbfb8aa3b, v62
	v_fma_f32 v82, -v80, v81, 1.0
	v_fmac_f32_e32 v81, v82, v81
	v_div_scale_f32 v82, vcc, v56, v64, v56
	v_mul_f32_e32 v83, v82, v81
	v_fma_f32 v88, -v80, v83, v82
	v_fmac_f32_e32 v83, v88, v81
	v_fma_f32 v80, -v80, v83, v82
	v_div_fmas_f32 v80, v80, v81, v83
	v_div_fixup_f32 v64, v80, v64, v56
	v_div_scale_f32 v80, s[8:9], v67, v67, v59
	v_rcp_f32_e32 v81, v80
	v_pk_mul_f32 v[64:65], v[64:65], s[18:19] op_sel_hi:[1,0]
	v_mul_f32_e32 v75, 0xbfb8aa3b, v63
	v_exp_f32_e32 v74, v74
	v_fma_f32 v82, -v80, v81, 1.0
	v_fmac_f32_e32 v81, v82, v81
	v_div_scale_f32 v82, vcc, v59, v67, v59
	v_mul_f32_e32 v83, v82, v81
	v_fma_f32 v88, -v80, v83, v82
	v_fmac_f32_e32 v83, v88, v81
	v_fma_f32 v80, -v80, v83, v82
	v_div_fmas_f32 v80, v80, v81, v83
	v_div_fixup_f32 v67, v80, v67, v59
	v_div_scale_f32 v80, s[8:9], v66, v66, v58
	v_rcp_f32_e32 v81, v80
	v_exp_f32_e32 v75, v75
	v_fma_f32 v82, -v80, v81, 1.0
	v_fmac_f32_e32 v81, v82, v81
	v_div_scale_f32 v82, vcc, v58, v66, v58
	v_mul_f32_e32 v83, v82, v81
	v_fma_f32 v88, -v80, v83, v82
	v_fmac_f32_e32 v83, v88, v81
	v_fma_f32 v80, -v80, v83, v82
	v_div_fmas_f32 v80, v80, v81, v83
	v_div_fixup_f32 v66, v80, v66, v58
	v_pk_mul_f32 v[66:67], v[66:67], s[18:19] op_sel_hi:[1,0]
	ds_write_b128 v144, v[64:67] offset:18432
	v_pk_add_f32 v[64:65], v[72:73], 1.0 op_sel_hi:[1,0]
	v_div_scale_f32 v66, s[8:9], v65, v65, 1.0
	v_rcp_f32_e32 v67, v66
	s_nop 0
	v_fma_f32 v72, -v66, v67, 1.0
	v_fmac_f32_e32 v67, v72, v67
	v_div_scale_f32 v72, vcc, 1.0, v65, 1.0
	v_mul_f32_e32 v73, v72, v67
	v_fma_f32 v80, -v66, v73, v72
	v_fmac_f32_e32 v73, v80, v67
	v_fma_f32 v66, -v66, v73, v72
	v_div_fmas_f32 v66, v66, v67, v73
	v_div_fixup_f32 v65, v66, v65, 1.0
	v_div_scale_f32 v66, s[8:9], v64, v64, 1.0
	v_rcp_f32_e32 v67, v66
	s_nop 0
	v_fma_f32 v72, -v66, v67, 1.0
	v_fmac_f32_e32 v67, v72, v67
	v_div_scale_f32 v72, vcc, 1.0, v64, 1.0
	v_mul_f32_e32 v73, v72, v67
	v_fma_f32 v80, -v66, v73, v72
	v_fmac_f32_e32 v73, v80, v67
	v_fma_f32 v66, -v66, v73, v72
	v_div_fmas_f32 v66, v66, v67, v73
	v_div_fixup_f32 v64, v66, v64, 1.0
	v_pk_add_f32 v[66:67], v[74:75], 1.0 op_sel_hi:[1,0]
	v_pk_fma_f32 v[64:65], v[110:111], v[64:65], v[104:105]
	v_div_scale_f32 v72, s[8:9], v67, v67, 1.0
	v_rcp_f32_e32 v73, v72
	s_nop 0
	v_fma_f32 v74, -v72, v73, 1.0
	v_fmac_f32_e32 v73, v74, v73
	v_div_scale_f32 v74, vcc, 1.0, v67, 1.0
	v_mul_f32_e32 v75, v74, v73
	v_fma_f32 v80, -v72, v75, v74
	v_fmac_f32_e32 v75, v80, v73
	v_fma_f32 v72, -v72, v75, v74
	v_div_fmas_f32 v72, v72, v73, v75
	v_div_fixup_f32 v67, v72, v67, 1.0
	v_div_scale_f32 v72, s[8:9], v66, v66, 1.0
	v_rcp_f32_e32 v73, v72
	s_nop 0
	v_fma_f32 v74, -v72, v73, 1.0
	v_fmac_f32_e32 v73, v74, v73
	v_div_scale_f32 v74, vcc, 1.0, v66, 1.0
	v_mul_f32_e32 v75, v74, v73
	v_fma_f32 v80, -v72, v75, v74
	v_fmac_f32_e32 v75, v80, v73
	v_fma_f32 v72, -v72, v75, v74
	v_div_fmas_f32 v72, v72, v73, v75
	v_div_fixup_f32 v66, v72, v66, 1.0
	v_pk_fma_f32 v[66:67], v[112:113], v[66:67], v[106:107]
	ds_write_b128 v144, v[64:67] offset:26624
	ds_write_b32 v134, v135 offset:35840
	s_waitcnt lgkmcnt(0)
	s_barrier
	s_cbranch_scc1 .LBB0_1393
	v_add_u32_e32 v44, 0x70, v98
	v_mov_b64_e32 v[56:57], s[30:31]
	v_mad_i64_i32 v[44:45], s[8:9], v44, s25, v[56:57]
	s_lshl_b32 s94, s46, 2
	v_lshl_add_u64 v[58:59], v[44:45], 0, s[94:95]
	v_mov_b32_e32 v117, v140
	v_lshl_add_u64 v[44:45], v[58:59], 0, v[116:117]
	v_add_co_u32_e32 v46, vcc, 0x4000, v44
	s_lshl_b32 s8, s42, 2
	s_nop 0
	v_addc_co_u32_e32 v47, vcc, 0, v45, vcc
	s_mov_b32 s9, s95
	v_add_co_u32_e32 v48, vcc, 0x5000, v44
	v_lshl_add_u64 v[58:59], v[58:59], 0, s[8:9]
	v_mov_b32_e32 v115, v140
	v_add_u32_e32 v60, 0x70, v96
	v_addc_co_u32_e32 v49, vcc, 0, v45, vcc
	v_lshl_add_u64 v[58:59], v[58:59], 0, v[114:115]
	v_mad_i64_i32 v[56:57], s[22:23], v60, s25, v[56:57]
	v_add_co_u32_e32 v58, vcc, s81, v58
	v_lshl_add_u64 v[60:61], v[56:57], 0, s[94:95]
	s_nop 0
	v_addc_co_u32_e32 v59, vcc, 0, v59, vcc
	v_lshl_add_u64 v[62:63], v[60:61], 0, v[116:117]
	v_add_co_u32_e32 v56, vcc, s80, v62
	v_lshl_add_u64 v[60:61], v[60:61], 0, s[8:9]
	s_nop 0
	v_addc_co_u32_e32 v57, vcc, 0, v63, vcc
	v_add_co_u32_e32 v62, vcc, 0x5000, v62
	v_lshl_add_u64 v[60:61], v[60:61], 0, v[114:115]
	s_nop 0
	v_addc_co_u32_e32 v63, vcc, 0, v63, vcc
	v_add_co_u32_e32 v64, vcc, 0x6000, v60
	global_load_dwordx4 v[44:47], v[46:47], off offset:32
	s_nop 0
	global_load_dwordx4 v[48:51], v[48:49], off offset:32
	s_nop 0
	global_load_dword v133, v[58:59], off offset:32
	s_nop 0
	global_load_dwordx4 v[56:59], v[56:57], off offset:32
	v_addc_co_u32_e32 v65, vcc, 0, v61, vcc
	global_load_dwordx4 v[60:63], v[62:63], off offset:32
	s_nop 0
	global_load_dword v135, v[64:65], off offset:32
.LBB0_1393:
	ds_read2st64_b32 v[64:65], v134 offset0:144 offset1:148
	v_add_u32_e32 v66, 32, v98
	v_ashrrev_i32_e32 v67, 31, v66
	v_lshlrev_b64 v[66:67], 12, v[66:67]
	v_lshl_add_u64 v[66:67], v[108:109], 0, v[66:67]
	s_waitcnt lgkmcnt(0)
	global_store_dword v[66:67], v64, off
	v_add_u32_e32 v66, 32, v96
	v_ashrrev_i32_e32 v67, 31, v66
	v_lshlrev_b64 v[66:67], 12, v[66:67]
	v_lshl_add_u64 v[66:67], v[108:109], 0, v[66:67]
	global_store_dword v[66:67], v65, off
	v_mov_b32_e32 v196, 0
	v_mov_b32_e32 v197, 0
	v_add_u32_e32 v194, 0x8800, v103
	v_add_u32_e32 v195, 0x8c00, v103
	ds_read2_b32 v[118:119], v194 offset0:0 offset1:16
	ds_read_b128 v[72:75], v145 offset:26624
	ds_read_b128 v[76:79], v145 offset:26880
	ds_read_b128 v[64:67], v145 offset:18432
	ds_read_b128 v[68:71], v145 offset:18688
	ds_read2_b32 v[120:121], v194 offset0:32 offset1:48
	ds_read_b128 v[88:91], v145 offset:27136
	ds_read_b128 v[92:95], v145 offset:27392
	ds_read_b128 v[80:83], v145 offset:18944
	ds_read_b128 v[84:87], v145 offset:19200
	s_waitcnt lgkmcnt(9)
	v_pk_add_f32 v[178:179], v[178:179], v[118:119] op_sel_hi:[1,0] neg_lo:[0,1] neg_hi:[0,1]
	v_pk_add_f32 v[186:187], v[186:187], v[118:119] op_sel:[0,1] op_sel_hi:[1,1] neg_lo:[0,1] neg_hi:[0,1]
	v_pk_add_f32 v[180:181], v[180:181], v[118:119] op_sel_hi:[1,0] neg_lo:[0,1] neg_hi:[0,1]
	v_pk_add_f32 v[188:189], v[188:189], v[118:119] op_sel:[0,1] op_sel_hi:[1,1] neg_lo:[0,1] neg_hi:[0,1]
	v_pk_add_f32 v[182:183], v[182:183], v[118:119] op_sel_hi:[1,0] neg_lo:[0,1] neg_hi:[0,1]
	v_pk_add_f32 v[190:191], v[190:191], v[118:119] op_sel:[0,1] op_sel_hi:[1,1] neg_lo:[0,1] neg_hi:[0,1]
	v_pk_add_f32 v[184:185], v[184:185], v[118:119] op_sel_hi:[1,0] neg_lo:[0,1] neg_hi:[0,1]
	v_pk_add_f32 v[192:193], v[192:193], v[118:119] op_sel:[0,1] op_sel_hi:[1,1] neg_lo:[0,1] neg_hi:[0,1]
	s_waitcnt lgkmcnt(8)
	v_pk_fma_f32 v[178:179], v[72:73], v[178:179], v[118:119] op_sel_hi:[1,1,0]
	v_pk_fma_f32 v[186:187], v[72:73], v[186:187], v[118:119] op_sel:[0,0,1] op_sel_hi:[1,1,1]
	v_pk_fma_f32 v[180:181], v[74:75], v[180:181], v[118:119] op_sel_hi:[1,1,0]
	v_pk_fma_f32 v[188:189], v[74:75], v[188:189], v[118:119] op_sel:[0,0,1] op_sel_hi:[1,1,1]
	s_waitcnt lgkmcnt(7)
	v_pk_fma_f32 v[182:183], v[76:77], v[182:183], v[118:119] op_sel_hi:[1,1,0]
	v_pk_fma_f32 v[190:191], v[76:77], v[190:191], v[118:119] op_sel:[0,0,1] op_sel_hi:[1,1,1]
	v_pk_fma_f32 v[184:185], v[78:79], v[184:185], v[118:119] op_sel_hi:[1,1,0]
	v_pk_fma_f32 v[192:193], v[78:79], v[192:193], v[118:119] op_sel:[0,0,1] op_sel_hi:[1,1,1]
	s_waitcnt lgkmcnt(6)
	v_pk_fma_f32 v[146:147], v[64:65], v[178:179], v[196:197]
	v_pk_fma_f32 v[150:151], v[64:65], v[186:187], v[196:197]
	v_pk_fma_f32 v[148:149], v[66:67], v[180:181], v[196:197]
	v_pk_fma_f32 v[152:153], v[66:67], v[188:189], v[196:197]
	s_waitcnt lgkmcnt(5)
	v_pk_fma_f32 v[146:147], v[68:69], v[182:183], v[146:147]
	v_pk_fma_f32 v[150:151], v[68:69], v[190:191], v[150:151]
	v_pk_fma_f32 v[148:149], v[70:71], v[184:185], v[148:149]
	v_pk_fma_f32 v[152:153], v[70:71], v[192:193], v[152:153]
	v_add_f32_e32 v146, v146, v147
	v_add_f32_e32 v148, v148, v149
	v_add_f32_e32 v150, v150, v151
	v_add_f32_e32 v152, v152, v153
	v_add_f32_e32 v154, v146, v148
	v_add_f32_e32 v155, v150, v152
	ds_read2_b32 v[118:119], v194 offset0:64 offset1:80
	ds_read_b128 v[72:75], v145 offset:27648
	ds_read_b128 v[76:79], v145 offset:27904
	ds_read_b128 v[64:67], v145 offset:19456
	ds_read_b128 v[68:71], v145 offset:19712
	s_waitcnt lgkmcnt(9)
	v_pk_add_f32 v[178:179], v[178:179], v[120:121] op_sel_hi:[1,0] neg_lo:[0,1] neg_hi:[0,1]
	v_add_f32_dpp v154, v154, v154 row_ror:8 row_mask:0xf bank_mask:0xf bound_ctrl:1
	v_pk_add_f32 v[186:187], v[186:187], v[120:121] op_sel:[0,1] op_sel_hi:[1,1] neg_lo:[0,1] neg_hi:[0,1]
	v_add_f32_dpp v155, v155, v155 row_ror:8 row_mask:0xf bank_mask:0xf bound_ctrl:1
	v_pk_add_f32 v[180:181], v[180:181], v[120:121] op_sel_hi:[1,0] neg_lo:[0,1] neg_hi:[0,1]
	v_add_f32_dpp v154, v154, v154 row_ror:4 row_mask:0xf bank_mask:0xf bound_ctrl:1
	v_pk_add_f32 v[188:189], v[188:189], v[120:121] op_sel:[0,1] op_sel_hi:[1,1] neg_lo:[0,1] neg_hi:[0,1]
	v_add_f32_dpp v155, v155, v155 row_ror:4 row_mask:0xf bank_mask:0xf bound_ctrl:1
	v_pk_add_f32 v[182:183], v[182:183], v[120:121] op_sel_hi:[1,0] neg_lo:[0,1] neg_hi:[0,1]
	v_add_f32_dpp v154, v154, v154 row_ror:2 row_mask:0xf bank_mask:0xf bound_ctrl:1
	v_pk_add_f32 v[190:191], v[190:191], v[120:121] op_sel:[0,1] op_sel_hi:[1,1] neg_lo:[0,1] neg_hi:[0,1]
	v_add_f32_dpp v155, v155, v155 row_ror:2 row_mask:0xf bank_mask:0xf bound_ctrl:1
	v_pk_add_f32 v[184:185], v[184:185], v[120:121] op_sel_hi:[1,0] neg_lo:[0,1] neg_hi:[0,1]
	v_add_f32_dpp v154, v154, v154 row_ror:1 row_mask:0xf bank_mask:0xf bound_ctrl:1
	v_pk_add_f32 v[192:193], v[192:193], v[120:121] op_sel:[0,1] op_sel_hi:[1,1] neg_lo:[0,1] neg_hi:[0,1]
	v_add_f32_dpp v155, v155, v155 row_ror:1 row_mask:0xf bank_mask:0xf bound_ctrl:1
	s_waitcnt lgkmcnt(8)
	v_pk_fma_f32 v[178:179], v[88:89], v[178:179], v[120:121] op_sel_hi:[1,1,0]
	s_and_saveexec_b64 s[8:9], s[38:39]
	ds_write_b32 v103, v154 offset:38912
	ds_write_b32 v103, v155 offset:38976
	s_mov_b64 exec, s[8:9]
	v_pk_fma_f32 v[186:187], v[88:89], v[186:187], v[120:121] op_sel:[0,0,1] op_sel_hi:[1,1,1]
	v_pk_fma_f32 v[180:181], v[90:91], v[180:181], v[120:121] op_sel_hi:[1,1,0]
	v_pk_fma_f32 v[188:189], v[90:91], v[188:189], v[120:121] op_sel:[0,0,1] op_sel_hi:[1,1,1]
	s_waitcnt lgkmcnt(9)
	v_pk_fma_f32 v[182:183], v[92:93], v[182:183], v[120:121] op_sel_hi:[1,1,0]
	v_pk_fma_f32 v[190:191], v[92:93], v[190:191], v[120:121] op_sel:[0,0,1] op_sel_hi:[1,1,1]
	v_pk_fma_f32 v[184:185], v[94:95], v[184:185], v[120:121] op_sel_hi:[1,1,0]
	v_pk_fma_f32 v[192:193], v[94:95], v[192:193], v[120:121] op_sel:[0,0,1] op_sel_hi:[1,1,1]
	s_waitcnt lgkmcnt(8)
	v_pk_fma_f32 v[146:147], v[80:81], v[178:179], v[196:197]
	v_pk_fma_f32 v[150:151], v[80:81], v[186:187], v[196:197]
	v_pk_fma_f32 v[148:149], v[82:83], v[180:181], v[196:197]
	v_pk_fma_f32 v[152:153], v[82:83], v[188:189], v[196:197]
	s_waitcnt lgkmcnt(7)
	v_pk_fma_f32 v[146:147], v[84:85], v[182:183], v[146:147]
	v_pk_fma_f32 v[150:151], v[84:85], v[190:191], v[150:151]
	v_pk_fma_f32 v[148:149], v[86:87], v[184:185], v[148:149]
	v_pk_fma_f32 v[152:153], v[86:87], v[192:193], v[152:153]
	v_add_f32_e32 v146, v146, v147
	v_add_f32_e32 v148, v148, v149
	v_add_f32_e32 v150, v150, v151
	v_add_f32_e32 v152, v152, v153
	v_add_f32_e32 v156, v146, v148
	v_add_f32_e32 v157, v150, v152
	ds_read2_b32 v[120:121], v194 offset0:96 offset1:112
	ds_read_b128 v[88:91], v145 offset:28160
	ds_read_b128 v[92:95], v145 offset:28416
	ds_read_b128 v[80:83], v145 offset:19968
	ds_read_b128 v[84:87], v145 offset:20224
	s_waitcnt lgkmcnt(11)
	v_pk_add_f32 v[178:179], v[178:179], v[118:119] op_sel_hi:[1,0] neg_lo:[0,1] neg_hi:[0,1]
	v_add_f32_dpp v156, v156, v156 row_ror:8 row_mask:0xf bank_mask:0xf bound_ctrl:1
	v_pk_add_f32 v[186:187], v[186:187], v[118:119] op_sel:[0,1] op_sel_hi:[1,1] neg_lo:[0,1] neg_hi:[0,1]
	v_add_f32_dpp v157, v157, v157 row_ror:8 row_mask:0xf bank_mask:0xf bound_ctrl:1
	v_pk_add_f32 v[180:181], v[180:181], v[118:119] op_sel_hi:[1,0] neg_lo:[0,1] neg_hi:[0,1]
	v_add_f32_dpp v156, v156, v156 row_ror:4 row_mask:0xf bank_mask:0xf bound_ctrl:1
	v_pk_add_f32 v[188:189], v[188:189], v[118:119] op_sel:[0,1] op_sel_hi:[1,1] neg_lo:[0,1] neg_hi:[0,1]
	v_add_f32_dpp v157, v157, v157 row_ror:4 row_mask:0xf bank_mask:0xf bound_ctrl:1
	v_pk_add_f32 v[182:183], v[182:183], v[118:119] op_sel_hi:[1,0] neg_lo:[0,1] neg_hi:[0,1]
	v_add_f32_dpp v156, v156, v156 row_ror:2 row_mask:0xf bank_mask:0xf bound_ctrl:1
	v_pk_add_f32 v[190:191], v[190:191], v[118:119] op_sel:[0,1] op_sel_hi:[1,1] neg_lo:[0,1] neg_hi:[0,1]
	v_add_f32_dpp v157, v157, v157 row_ror:2 row_mask:0xf bank_mask:0xf bound_ctrl:1
	v_pk_add_f32 v[184:185], v[184:185], v[118:119] op_sel_hi:[1,0] neg_lo:[0,1] neg_hi:[0,1]
	v_add_f32_dpp v156, v156, v156 row_ror:1 row_mask:0xf bank_mask:0xf bound_ctrl:1
	v_pk_add_f32 v[192:193], v[192:193], v[118:119] op_sel:[0,1] op_sel_hi:[1,1] neg_lo:[0,1] neg_hi:[0,1]
	v_add_f32_dpp v157, v157, v157 row_ror:1 row_mask:0xf bank_mask:0xf bound_ctrl:1
	s_waitcnt lgkmcnt(10)
	v_pk_fma_f32 v[178:179], v[72:73], v[178:179], v[118:119] op_sel_hi:[1,1,0]
	s_and_saveexec_b64 s[8:9], s[38:39]
	ds_write_b32 v103, v156 offset:39040
	ds_write_b32 v103, v157 offset:39104
	s_mov_b64 exec, s[8:9]
	v_pk_fma_f32 v[186:187], v[72:73], v[186:187], v[118:119] op_sel:[0,0,1] op_sel_hi:[1,1,1]
	v_pk_fma_f32 v[180:181], v[74:75], v[180:181], v[118:119] op_sel_hi:[1,1,0]
	v_pk_fma_f32 v[188:189], v[74:75], v[188:189], v[118:119] op_sel:[0,0,1] op_sel_hi:[1,1,1]
	s_waitcnt lgkmcnt(11)
	v_pk_fma_f32 v[182:183], v[76:77], v[182:183], v[118:119] op_sel_hi:[1,1,0]
	v_pk_fma_f32 v[190:191], v[76:77], v[190:191], v[118:119] op_sel:[0,0,1] op_sel_hi:[1,1,1]
	v_pk_fma_f32 v[184:185], v[78:79], v[184:185], v[118:119] op_sel_hi:[1,1,0]
	v_pk_fma_f32 v[192:193], v[78:79], v[192:193], v[118:119] op_sel:[0,0,1] op_sel_hi:[1,1,1]
	s_waitcnt lgkmcnt(10)
	v_pk_fma_f32 v[146:147], v[64:65], v[178:179], v[196:197]
	v_pk_fma_f32 v[150:151], v[64:65], v[186:187], v[196:197]
	v_pk_fma_f32 v[148:149], v[66:67], v[180:181], v[196:197]
	v_pk_fma_f32 v[152:153], v[66:67], v[188:189], v[196:197]
	s_waitcnt lgkmcnt(9)
	v_pk_fma_f32 v[146:147], v[68:69], v[182:183], v[146:147]
	v_pk_fma_f32 v[150:151], v[68:69], v[190:191], v[150:151]
	v_pk_fma_f32 v[148:149], v[70:71], v[184:185], v[148:149]
	v_pk_fma_f32 v[152:153], v[70:71], v[192:193], v[152:153]
	v_add_f32_e32 v146, v146, v147
	v_add_f32_e32 v148, v148, v149
	v_add_f32_e32 v150, v150, v151
	v_add_f32_e32 v152, v152, v153
	v_add_f32_e32 v154, v146, v148
	v_add_f32_e32 v155, v150, v152
	ds_read2_b32 v[118:119], v194 offset0:128 offset1:144
	ds_read_b128 v[72:75], v145 offset:28672
	ds_read_b128 v[76:79], v145 offset:28928
	ds_read_b128 v[64:67], v145 offset:20480
	ds_read_b128 v[68:71], v145 offset:20736
	s_waitcnt lgkmcnt(11)
	v_pk_add_f32 v[178:179], v[178:179], v[120:121] op_sel_hi:[1,0] neg_lo:[0,1] neg_hi:[0,1]
	v_add_f32_dpp v154, v154, v154 row_ror:8 row_mask:0xf bank_mask:0xf bound_ctrl:1
	v_pk_add_f32 v[186:187], v[186:187], v[120:121] op_sel:[0,1] op_sel_hi:[1,1] neg_lo:[0,1] neg_hi:[0,1]
	v_add_f32_dpp v155, v155, v155 row_ror:8 row_mask:0xf bank_mask:0xf bound_ctrl:1
	v_pk_add_f32 v[180:181], v[180:181], v[120:121] op_sel_hi:[1,0] neg_lo:[0,1] neg_hi:[0,1]
	v_add_f32_dpp v154, v154, v154 row_ror:4 row_mask:0xf bank_mask:0xf bound_ctrl:1
	v_pk_add_f32 v[188:189], v[188:189], v[120:121] op_sel:[0,1] op_sel_hi:[1,1] neg_lo:[0,1] neg_hi:[0,1]
	v_add_f32_dpp v155, v155, v155 row_ror:4 row_mask:0xf bank_mask:0xf bound_ctrl:1
	v_pk_add_f32 v[182:183], v[182:183], v[120:121] op_sel_hi:[1,0] neg_lo:[0,1] neg_hi:[0,1]
	v_add_f32_dpp v154, v154, v154 row_ror:2 row_mask:0xf bank_mask:0xf bound_ctrl:1
	v_pk_add_f32 v[190:191], v[190:191], v[120:121] op_sel:[0,1] op_sel_hi:[1,1] neg_lo:[0,1] neg_hi:[0,1]
	v_add_f32_dpp v155, v155, v155 row_ror:2 row_mask:0xf bank_mask:0xf bound_ctrl:1
	v_pk_add_f32 v[184:185], v[184:185], v[120:121] op_sel_hi:[1,0] neg_lo:[0,1] neg_hi:[0,1]
	v_add_f32_dpp v154, v154, v154 row_ror:1 row_mask:0xf bank_mask:0xf bound_ctrl:1
	v_pk_add_f32 v[192:193], v[192:193], v[120:121] op_sel:[0,1] op_sel_hi:[1,1] neg_lo:[0,1] neg_hi:[0,1]
	v_add_f32_dpp v155, v155, v155 row_ror:1 row_mask:0xf bank_mask:0xf bound_ctrl:1
	s_waitcnt lgkmcnt(10)
	v_pk_fma_f32 v[178:179], v[88:89], v[178:179], v[120:121] op_sel_hi:[1,1,0]
	s_and_saveexec_b64 s[8:9], s[38:39]
	ds_write_b32 v103, v154 offset:39168
	ds_write_b32 v103, v155 offset:39232
	s_mov_b64 exec, s[8:9]
	v_pk_fma_f32 v[186:187], v[88:89], v[186:187], v[120:121] op_sel:[0,0,1] op_sel_hi:[1,1,1]
	v_pk_fma_f32 v[180:181], v[90:91], v[180:181], v[120:121] op_sel_hi:[1,1,0]
	v_pk_fma_f32 v[188:189], v[90:91], v[188:189], v[120:121] op_sel:[0,0,1] op_sel_hi:[1,1,1]
	s_waitcnt lgkmcnt(11)
	v_pk_fma_f32 v[182:183], v[92:93], v[182:183], v[120:121] op_sel_hi:[1,1,0]
	v_pk_fma_f32 v[190:191], v[92:93], v[190:191], v[120:121] op_sel:[0,0,1] op_sel_hi:[1,1,1]
	v_pk_fma_f32 v[184:185], v[94:95], v[184:185], v[120:121] op_sel_hi:[1,1,0]
	v_pk_fma_f32 v[192:193], v[94:95], v[192:193], v[120:121] op_sel:[0,0,1] op_sel_hi:[1,1,1]
	s_waitcnt lgkmcnt(10)
	v_pk_fma_f32 v[146:147], v[80:81], v[178:179], v[196:197]
	v_pk_fma_f32 v[150:151], v[80:81], v[186:187], v[196:197]
	v_pk_fma_f32 v[148:149], v[82:83], v[180:181], v[196:197]
	v_pk_fma_f32 v[152:153], v[82:83], v[188:189], v[196:197]
	s_waitcnt lgkmcnt(9)
	v_pk_fma_f32 v[146:147], v[84:85], v[182:183], v[146:147]
	v_pk_fma_f32 v[150:151], v[84:85], v[190:191], v[150:151]
	v_pk_fma_f32 v[148:149], v[86:87], v[184:185], v[148:149]
	v_pk_fma_f32 v[152:153], v[86:87], v[192:193], v[152:153]
	v_add_f32_e32 v146, v146, v147
	v_add_f32_e32 v148, v148, v149
	v_add_f32_e32 v150, v150, v151
	v_add_f32_e32 v152, v152, v153
	v_add_f32_e32 v156, v146, v148
	v_add_f32_e32 v157, v150, v152
	ds_read2_b32 v[120:121], v194 offset0:160 offset1:176
	ds_read_b128 v[88:91], v145 offset:29184
	ds_read_b128 v[92:95], v145 offset:29440
	ds_read_b128 v[80:83], v145 offset:20992
	ds_read_b128 v[84:87], v145 offset:21248
	s_waitcnt lgkmcnt(11)
	v_pk_add_f32 v[178:179], v[178:179], v[118:119] op_sel_hi:[1,0] neg_lo:[0,1] neg_hi:[0,1]
	v_add_f32_dpp v156, v156, v156 row_ror:8 row_mask:0xf bank_mask:0xf bound_ctrl:1
	v_pk_add_f32 v[186:187], v[186:187], v[118:119] op_sel:[0,1] op_sel_hi:[1,1] neg_lo:[0,1] neg_hi:[0,1]
	v_add_f32_dpp v157, v157, v157 row_ror:8 row_mask:0xf bank_mask:0xf bound_ctrl:1
	v_pk_add_f32 v[180:181], v[180:181], v[118:119] op_sel_hi:[1,0] neg_lo:[0,1] neg_hi:[0,1]
	v_add_f32_dpp v156, v156, v156 row_ror:4 row_mask:0xf bank_mask:0xf bound_ctrl:1
	v_pk_add_f32 v[188:189], v[188:189], v[118:119] op_sel:[0,1] op_sel_hi:[1,1] neg_lo:[0,1] neg_hi:[0,1]
	v_add_f32_dpp v157, v157, v157 row_ror:4 row_mask:0xf bank_mask:0xf bound_ctrl:1
	v_pk_add_f32 v[182:183], v[182:183], v[118:119] op_sel_hi:[1,0] neg_lo:[0,1] neg_hi:[0,1]
	v_add_f32_dpp v156, v156, v156 row_ror:2 row_mask:0xf bank_mask:0xf bound_ctrl:1
	v_pk_add_f32 v[190:191], v[190:191], v[118:119] op_sel:[0,1] op_sel_hi:[1,1] neg_lo:[0,1] neg_hi:[0,1]
	v_add_f32_dpp v157, v157, v157 row_ror:2 row_mask:0xf bank_mask:0xf bound_ctrl:1
	v_pk_add_f32 v[184:185], v[184:185], v[118:119] op_sel_hi:[1,0] neg_lo:[0,1] neg_hi:[0,1]
	v_add_f32_dpp v156, v156, v156 row_ror:1 row_mask:0xf bank_mask:0xf bound_ctrl:1
	v_pk_add_f32 v[192:193], v[192:193], v[118:119] op_sel:[0,1] op_sel_hi:[1,1] neg_lo:[0,1] neg_hi:[0,1]
	v_add_f32_dpp v157, v157, v157 row_ror:1 row_mask:0xf bank_mask:0xf bound_ctrl:1
	s_waitcnt lgkmcnt(10)
	v_pk_fma_f32 v[178:179], v[72:73], v[178:179], v[118:119] op_sel_hi:[1,1,0]
	s_and_saveexec_b64 s[8:9], s[38:39]
	ds_write_b32 v103, v156 offset:39296
	ds_write_b32 v103, v157 offset:39360
	s_mov_b64 exec, s[8:9]
	v_pk_fma_f32 v[186:187], v[72:73], v[186:187], v[118:119] op_sel:[0,0,1] op_sel_hi:[1,1,1]
	v_pk_fma_f32 v[180:181], v[74:75], v[180:181], v[118:119] op_sel_hi:[1,1,0]
	v_pk_fma_f32 v[188:189], v[74:75], v[188:189], v[118:119] op_sel:[0,0,1] op_sel_hi:[1,1,1]
	s_waitcnt lgkmcnt(11)
	v_pk_fma_f32 v[182:183], v[76:77], v[182:183], v[118:119] op_sel_hi:[1,1,0]
	v_pk_fma_f32 v[190:191], v[76:77], v[190:191], v[118:119] op_sel:[0,0,1] op_sel_hi:[1,1,1]
	v_pk_fma_f32 v[184:185], v[78:79], v[184:185], v[118:119] op_sel_hi:[1,1,0]
	v_pk_fma_f32 v[192:193], v[78:79], v[192:193], v[118:119] op_sel:[0,0,1] op_sel_hi:[1,1,1]
	s_waitcnt lgkmcnt(10)
	v_pk_fma_f32 v[146:147], v[64:65], v[178:179], v[196:197]
	v_pk_fma_f32 v[150:151], v[64:65], v[186:187], v[196:197]
	v_pk_fma_f32 v[148:149], v[66:67], v[180:181], v[196:197]
	v_pk_fma_f32 v[152:153], v[66:67], v[188:189], v[196:197]
	s_waitcnt lgkmcnt(9)
	v_pk_fma_f32 v[146:147], v[68:69], v[182:183], v[146:147]
	v_pk_fma_f32 v[150:151], v[68:69], v[190:191], v[150:151]
	v_pk_fma_f32 v[148:149], v[70:71], v[184:185], v[148:149]
	v_pk_fma_f32 v[152:153], v[70:71], v[192:193], v[152:153]
	v_add_f32_e32 v146, v146, v147
	v_add_f32_e32 v148, v148, v149
	v_add_f32_e32 v150, v150, v151
	v_add_f32_e32 v152, v152, v153
	v_add_f32_e32 v154, v146, v148
	v_add_f32_e32 v155, v150, v152
	ds_read2_b32 v[118:119], v194 offset0:192 offset1:208
	ds_read_b128 v[72:75], v145 offset:29696
	ds_read_b128 v[76:79], v145 offset:29952
	ds_read_b128 v[64:67], v145 offset:21504
	ds_read_b128 v[68:71], v145 offset:21760
	s_waitcnt lgkmcnt(11)
	v_pk_add_f32 v[178:179], v[178:179], v[120:121] op_sel_hi:[1,0] neg_lo:[0,1] neg_hi:[0,1]
	v_add_f32_dpp v154, v154, v154 row_ror:8 row_mask:0xf bank_mask:0xf bound_ctrl:1
	v_pk_add_f32 v[186:187], v[186:187], v[120:121] op_sel:[0,1] op_sel_hi:[1,1] neg_lo:[0,1] neg_hi:[0,1]
	v_add_f32_dpp v155, v155, v155 row_ror:8 row_mask:0xf bank_mask:0xf bound_ctrl:1
	v_pk_add_f32 v[180:181], v[180:181], v[120:121] op_sel_hi:[1,0] neg_lo:[0,1] neg_hi:[0,1]
	v_add_f32_dpp v154, v154, v154 row_ror:4 row_mask:0xf bank_mask:0xf bound_ctrl:1
	v_pk_add_f32 v[188:189], v[188:189], v[120:121] op_sel:[0,1] op_sel_hi:[1,1] neg_lo:[0,1] neg_hi:[0,1]
	v_add_f32_dpp v155, v155, v155 row_ror:4 row_mask:0xf bank_mask:0xf bound_ctrl:1
	v_pk_add_f32 v[182:183], v[182:183], v[120:121] op_sel_hi:[1,0] neg_lo:[0,1] neg_hi:[0,1]
	v_add_f32_dpp v154, v154, v154 row_ror:2 row_mask:0xf bank_mask:0xf bound_ctrl:1
	v_pk_add_f32 v[190:191], v[190:191], v[120:121] op_sel:[0,1] op_sel_hi:[1,1] neg_lo:[0,1] neg_hi:[0,1]
	v_add_f32_dpp v155, v155, v155 row_ror:2 row_mask:0xf bank_mask:0xf bound_ctrl:1
	v_pk_add_f32 v[184:185], v[184:185], v[120:121] op_sel_hi:[1,0] neg_lo:[0,1] neg_hi:[0,1]
	v_add_f32_dpp v154, v154, v154 row_ror:1 row_mask:0xf bank_mask:0xf bound_ctrl:1
	v_pk_add_f32 v[192:193], v[192:193], v[120:121] op_sel:[0,1] op_sel_hi:[1,1] neg_lo:[0,1] neg_hi:[0,1]
	v_add_f32_dpp v155, v155, v155 row_ror:1 row_mask:0xf bank_mask:0xf bound_ctrl:1
	s_waitcnt lgkmcnt(10)
	v_pk_fma_f32 v[178:179], v[88:89], v[178:179], v[120:121] op_sel_hi:[1,1,0]
	s_and_saveexec_b64 s[8:9], s[38:39]
	ds_write_b32 v103, v154 offset:39424
	ds_write_b32 v103, v155 offset:39488
	s_mov_b64 exec, s[8:9]
	v_pk_fma_f32 v[186:187], v[88:89], v[186:187], v[120:121] op_sel:[0,0,1] op_sel_hi:[1,1,1]
	v_pk_fma_f32 v[180:181], v[90:91], v[180:181], v[120:121] op_sel_hi:[1,1,0]
	v_pk_fma_f32 v[188:189], v[90:91], v[188:189], v[120:121] op_sel:[0,0,1] op_sel_hi:[1,1,1]
	s_waitcnt lgkmcnt(11)
	v_pk_fma_f32 v[182:183], v[92:93], v[182:183], v[120:121] op_sel_hi:[1,1,0]
	v_pk_fma_f32 v[190:191], v[92:93], v[190:191], v[120:121] op_sel:[0,0,1] op_sel_hi:[1,1,1]
	v_pk_fma_f32 v[184:185], v[94:95], v[184:185], v[120:121] op_sel_hi:[1,1,0]
	v_pk_fma_f32 v[192:193], v[94:95], v[192:193], v[120:121] op_sel:[0,0,1] op_sel_hi:[1,1,1]
	s_waitcnt lgkmcnt(10)
	v_pk_fma_f32 v[146:147], v[80:81], v[178:179], v[196:197]
	v_pk_fma_f32 v[150:151], v[80:81], v[186:187], v[196:197]
	v_pk_fma_f32 v[148:149], v[82:83], v[180:181], v[196:197]
	v_pk_fma_f32 v[152:153], v[82:83], v[188:189], v[196:197]
	s_waitcnt lgkmcnt(9)
	v_pk_fma_f32 v[146:147], v[84:85], v[182:183], v[146:147]
	v_pk_fma_f32 v[150:151], v[84:85], v[190:191], v[150:151]
	v_pk_fma_f32 v[148:149], v[86:87], v[184:185], v[148:149]
	v_pk_fma_f32 v[152:153], v[86:87], v[192:193], v[152:153]
	v_add_f32_e32 v146, v146, v147
	v_add_f32_e32 v148, v148, v149
	v_add_f32_e32 v150, v150, v151
	v_add_f32_e32 v152, v152, v153
	v_add_f32_e32 v156, v146, v148
	v_add_f32_e32 v157, v150, v152
	ds_read2_b32 v[120:121], v194 offset0:224 offset1:240
	ds_read_b128 v[88:91], v145 offset:30208
	ds_read_b128 v[92:95], v145 offset:30464
	ds_read_b128 v[80:83], v145 offset:22016
	ds_read_b128 v[84:87], v145 offset:22272
	s_waitcnt lgkmcnt(11)
	v_pk_add_f32 v[178:179], v[178:179], v[118:119] op_sel_hi:[1,0] neg_lo:[0,1] neg_hi:[0,1]
	v_add_f32_dpp v156, v156, v156 row_ror:8 row_mask:0xf bank_mask:0xf bound_ctrl:1
	v_pk_add_f32 v[186:187], v[186:187], v[118:119] op_sel:[0,1] op_sel_hi:[1,1] neg_lo:[0,1] neg_hi:[0,1]
	v_add_f32_dpp v157, v157, v157 row_ror:8 row_mask:0xf bank_mask:0xf bound_ctrl:1
	v_pk_add_f32 v[180:181], v[180:181], v[118:119] op_sel_hi:[1,0] neg_lo:[0,1] neg_hi:[0,1]
	v_add_f32_dpp v156, v156, v156 row_ror:4 row_mask:0xf bank_mask:0xf bound_ctrl:1
	v_pk_add_f32 v[188:189], v[188:189], v[118:119] op_sel:[0,1] op_sel_hi:[1,1] neg_lo:[0,1] neg_hi:[0,1]
	v_add_f32_dpp v157, v157, v157 row_ror:4 row_mask:0xf bank_mask:0xf bound_ctrl:1
	v_pk_add_f32 v[182:183], v[182:183], v[118:119] op_sel_hi:[1,0] neg_lo:[0,1] neg_hi:[0,1]
	v_add_f32_dpp v156, v156, v156 row_ror:2 row_mask:0xf bank_mask:0xf bound_ctrl:1
	v_pk_add_f32 v[190:191], v[190:191], v[118:119] op_sel:[0,1] op_sel_hi:[1,1] neg_lo:[0,1] neg_hi:[0,1]
	v_add_f32_dpp v157, v157, v157 row_ror:2 row_mask:0xf bank_mask:0xf bound_ctrl:1
	v_pk_add_f32 v[184:185], v[184:185], v[118:119] op_sel_hi:[1,0] neg_lo:[0,1] neg_hi:[0,1]
	v_add_f32_dpp v156, v156, v156 row_ror:1 row_mask:0xf bank_mask:0xf bound_ctrl:1
	v_pk_add_f32 v[192:193], v[192:193], v[118:119] op_sel:[0,1] op_sel_hi:[1,1] neg_lo:[0,1] neg_hi:[0,1]
	v_add_f32_dpp v157, v157, v157 row_ror:1 row_mask:0xf bank_mask:0xf bound_ctrl:1
	s_waitcnt lgkmcnt(10)
	v_pk_fma_f32 v[178:179], v[72:73], v[178:179], v[118:119] op_sel_hi:[1,1,0]
	s_and_saveexec_b64 s[8:9], s[38:39]
	ds_write_b32 v103, v156 offset:39552
	ds_write_b32 v103, v157 offset:39616
	s_mov_b64 exec, s[8:9]
	v_pk_fma_f32 v[186:187], v[72:73], v[186:187], v[118:119] op_sel:[0,0,1] op_sel_hi:[1,1,1]
	v_pk_fma_f32 v[180:181], v[74:75], v[180:181], v[118:119] op_sel_hi:[1,1,0]
	v_pk_fma_f32 v[188:189], v[74:75], v[188:189], v[118:119] op_sel:[0,0,1] op_sel_hi:[1,1,1]
	s_waitcnt lgkmcnt(11)
	v_pk_fma_f32 v[182:183], v[76:77], v[182:183], v[118:119] op_sel_hi:[1,1,0]
	v_pk_fma_f32 v[190:191], v[76:77], v[190:191], v[118:119] op_sel:[0,0,1] op_sel_hi:[1,1,1]
	v_pk_fma_f32 v[184:185], v[78:79], v[184:185], v[118:119] op_sel_hi:[1,1,0]
	v_pk_fma_f32 v[192:193], v[78:79], v[192:193], v[118:119] op_sel:[0,0,1] op_sel_hi:[1,1,1]
	s_waitcnt lgkmcnt(10)
	v_pk_fma_f32 v[146:147], v[64:65], v[178:179], v[196:197]
	v_pk_fma_f32 v[150:151], v[64:65], v[186:187], v[196:197]
	v_pk_fma_f32 v[148:149], v[66:67], v[180:181], v[196:197]
	v_pk_fma_f32 v[152:153], v[66:67], v[188:189], v[196:197]
	s_waitcnt lgkmcnt(9)
	v_pk_fma_f32 v[146:147], v[68:69], v[182:183], v[146:147]
	v_pk_fma_f32 v[150:151], v[68:69], v[190:191], v[150:151]
	v_pk_fma_f32 v[148:149], v[70:71], v[184:185], v[148:149]
	v_pk_fma_f32 v[152:153], v[70:71], v[192:193], v[152:153]
	v_add_f32_e32 v146, v146, v147
	v_add_f32_e32 v148, v148, v149
	v_add_f32_e32 v150, v150, v151
	v_add_f32_e32 v152, v152, v153
	v_add_f32_e32 v154, v146, v148
	v_add_f32_e32 v155, v150, v152
	ds_read2_b32 v[118:119], v195 offset0:0 offset1:16
	ds_read_b128 v[72:75], v145 offset:30720
	ds_read_b128 v[76:79], v145 offset:30976
	ds_read_b128 v[64:67], v145 offset:22528
	ds_read_b128 v[68:71], v145 offset:22784
	s_waitcnt lgkmcnt(11)
	v_pk_add_f32 v[178:179], v[178:179], v[120:121] op_sel_hi:[1,0] neg_lo:[0,1] neg_hi:[0,1]
	v_add_f32_dpp v154, v154, v154 row_ror:8 row_mask:0xf bank_mask:0xf bound_ctrl:1
	v_pk_add_f32 v[186:187], v[186:187], v[120:121] op_sel:[0,1] op_sel_hi:[1,1] neg_lo:[0,1] neg_hi:[0,1]
	v_add_f32_dpp v155, v155, v155 row_ror:8 row_mask:0xf bank_mask:0xf bound_ctrl:1
	v_pk_add_f32 v[180:181], v[180:181], v[120:121] op_sel_hi:[1,0] neg_lo:[0,1] neg_hi:[0,1]
	v_add_f32_dpp v154, v154, v154 row_ror:4 row_mask:0xf bank_mask:0xf bound_ctrl:1
	v_pk_add_f32 v[188:189], v[188:189], v[120:121] op_sel:[0,1] op_sel_hi:[1,1] neg_lo:[0,1] neg_hi:[0,1]
	v_add_f32_dpp v155, v155, v155 row_ror:4 row_mask:0xf bank_mask:0xf bound_ctrl:1
	v_pk_add_f32 v[182:183], v[182:183], v[120:121] op_sel_hi:[1,0] neg_lo:[0,1] neg_hi:[0,1]
	v_add_f32_dpp v154, v154, v154 row_ror:2 row_mask:0xf bank_mask:0xf bound_ctrl:1
	v_pk_add_f32 v[190:191], v[190:191], v[120:121] op_sel:[0,1] op_sel_hi:[1,1] neg_lo:[0,1] neg_hi:[0,1]
	v_add_f32_dpp v155, v155, v155 row_ror:2 row_mask:0xf bank_mask:0xf bound_ctrl:1
	v_pk_add_f32 v[184:185], v[184:185], v[120:121] op_sel_hi:[1,0] neg_lo:[0,1] neg_hi:[0,1]
	v_add_f32_dpp v154, v154, v154 row_ror:1 row_mask:0xf bank_mask:0xf bound_ctrl:1
	v_pk_add_f32 v[192:193], v[192:193], v[120:121] op_sel:[0,1] op_sel_hi:[1,1] neg_lo:[0,1] neg_hi:[0,1]
	v_add_f32_dpp v155, v155, v155 row_ror:1 row_mask:0xf bank_mask:0xf bound_ctrl:1
	s_waitcnt lgkmcnt(10)
	v_pk_fma_f32 v[178:179], v[88:89], v[178:179], v[120:121] op_sel_hi:[1,1,0]
	s_and_saveexec_b64 s[8:9], s[38:39]
	ds_write_b32 v103, v154 offset:39680
	ds_write_b32 v103, v155 offset:39744
	s_mov_b64 exec, s[8:9]
	v_pk_fma_f32 v[186:187], v[88:89], v[186:187], v[120:121] op_sel:[0,0,1] op_sel_hi:[1,1,1]
	v_pk_fma_f32 v[180:181], v[90:91], v[180:181], v[120:121] op_sel_hi:[1,1,0]
	v_pk_fma_f32 v[188:189], v[90:91], v[188:189], v[120:121] op_sel:[0,0,1] op_sel_hi:[1,1,1]
	s_waitcnt lgkmcnt(11)
	v_pk_fma_f32 v[182:183], v[92:93], v[182:183], v[120:121] op_sel_hi:[1,1,0]
	v_pk_fma_f32 v[190:191], v[92:93], v[190:191], v[120:121] op_sel:[0,0,1] op_sel_hi:[1,1,1]
	v_pk_fma_f32 v[184:185], v[94:95], v[184:185], v[120:121] op_sel_hi:[1,1,0]
	v_pk_fma_f32 v[192:193], v[94:95], v[192:193], v[120:121] op_sel:[0,0,1] op_sel_hi:[1,1,1]
	s_waitcnt lgkmcnt(10)
	v_pk_fma_f32 v[146:147], v[80:81], v[178:179], v[196:197]
	v_pk_fma_f32 v[150:151], v[80:81], v[186:187], v[196:197]
	v_pk_fma_f32 v[148:149], v[82:83], v[180:181], v[196:197]
	v_pk_fma_f32 v[152:153], v[82:83], v[188:189], v[196:197]
	s_waitcnt lgkmcnt(9)
	v_pk_fma_f32 v[146:147], v[84:85], v[182:183], v[146:147]
	v_pk_fma_f32 v[150:151], v[84:85], v[190:191], v[150:151]
	v_pk_fma_f32 v[148:149], v[86:87], v[184:185], v[148:149]
	v_pk_fma_f32 v[152:153], v[86:87], v[192:193], v[152:153]
	v_add_f32_e32 v146, v146, v147
	v_add_f32_e32 v148, v148, v149
	v_add_f32_e32 v150, v150, v151
	v_add_f32_e32 v152, v152, v153
	v_add_f32_e32 v156, v146, v148
	v_add_f32_e32 v157, v150, v152
	ds_read2_b32 v[120:121], v195 offset0:32 offset1:48
	ds_read_b128 v[88:91], v145 offset:31232
	ds_read_b128 v[92:95], v145 offset:31488
	ds_read_b128 v[80:83], v145 offset:23040
	ds_read_b128 v[84:87], v145 offset:23296
	s_waitcnt lgkmcnt(11)
	v_pk_add_f32 v[178:179], v[178:179], v[118:119] op_sel_hi:[1,0] neg_lo:[0,1] neg_hi:[0,1]
	v_add_f32_dpp v156, v156, v156 row_ror:8 row_mask:0xf bank_mask:0xf bound_ctrl:1
	v_pk_add_f32 v[186:187], v[186:187], v[118:119] op_sel:[0,1] op_sel_hi:[1,1] neg_lo:[0,1] neg_hi:[0,1]
	v_add_f32_dpp v157, v157, v157 row_ror:8 row_mask:0xf bank_mask:0xf bound_ctrl:1
	v_pk_add_f32 v[180:181], v[180:181], v[118:119] op_sel_hi:[1,0] neg_lo:[0,1] neg_hi:[0,1]
	v_add_f32_dpp v156, v156, v156 row_ror:4 row_mask:0xf bank_mask:0xf bound_ctrl:1
	v_pk_add_f32 v[188:189], v[188:189], v[118:119] op_sel:[0,1] op_sel_hi:[1,1] neg_lo:[0,1] neg_hi:[0,1]
	v_add_f32_dpp v157, v157, v157 row_ror:4 row_mask:0xf bank_mask:0xf bound_ctrl:1
	v_pk_add_f32 v[182:183], v[182:183], v[118:119] op_sel_hi:[1,0] neg_lo:[0,1] neg_hi:[0,1]
	v_add_f32_dpp v156, v156, v156 row_ror:2 row_mask:0xf bank_mask:0xf bound_ctrl:1
	v_pk_add_f32 v[190:191], v[190:191], v[118:119] op_sel:[0,1] op_sel_hi:[1,1] neg_lo:[0,1] neg_hi:[0,1]
	v_add_f32_dpp v157, v157, v157 row_ror:2 row_mask:0xf bank_mask:0xf bound_ctrl:1
	v_pk_add_f32 v[184:185], v[184:185], v[118:119] op_sel_hi:[1,0] neg_lo:[0,1] neg_hi:[0,1]
	v_add_f32_dpp v156, v156, v156 row_ror:1 row_mask:0xf bank_mask:0xf bound_ctrl:1
	v_pk_add_f32 v[192:193], v[192:193], v[118:119] op_sel:[0,1] op_sel_hi:[1,1] neg_lo:[0,1] neg_hi:[0,1]
	v_add_f32_dpp v157, v157, v157 row_ror:1 row_mask:0xf bank_mask:0xf bound_ctrl:1
	s_waitcnt lgkmcnt(10)
	v_pk_fma_f32 v[178:179], v[72:73], v[178:179], v[118:119] op_sel_hi:[1,1,0]
	s_and_saveexec_b64 s[8:9], s[38:39]
	ds_write_b32 v103, v156 offset:39808
	ds_write_b32 v103, v157 offset:39872
	s_mov_b64 exec, s[8:9]
	v_pk_fma_f32 v[186:187], v[72:73], v[186:187], v[118:119] op_sel:[0,0,1] op_sel_hi:[1,1,1]
	v_pk_fma_f32 v[180:181], v[74:75], v[180:181], v[118:119] op_sel_hi:[1,1,0]
	v_pk_fma_f32 v[188:189], v[74:75], v[188:189], v[118:119] op_sel:[0,0,1] op_sel_hi:[1,1,1]
	s_waitcnt lgkmcnt(11)
	v_pk_fma_f32 v[182:183], v[76:77], v[182:183], v[118:119] op_sel_hi:[1,1,0]
	v_pk_fma_f32 v[190:191], v[76:77], v[190:191], v[118:119] op_sel:[0,0,1] op_sel_hi:[1,1,1]
	v_pk_fma_f32 v[184:185], v[78:79], v[184:185], v[118:119] op_sel_hi:[1,1,0]
	v_pk_fma_f32 v[192:193], v[78:79], v[192:193], v[118:119] op_sel:[0,0,1] op_sel_hi:[1,1,1]
	s_waitcnt lgkmcnt(10)
	v_pk_fma_f32 v[146:147], v[64:65], v[178:179], v[196:197]
	v_pk_fma_f32 v[150:151], v[64:65], v[186:187], v[196:197]
	v_pk_fma_f32 v[148:149], v[66:67], v[180:181], v[196:197]
	v_pk_fma_f32 v[152:153], v[66:67], v[188:189], v[196:197]
	s_waitcnt lgkmcnt(9)
	v_pk_fma_f32 v[146:147], v[68:69], v[182:183], v[146:147]
	v_pk_fma_f32 v[150:151], v[68:69], v[190:191], v[150:151]
	v_pk_fma_f32 v[148:149], v[70:71], v[184:185], v[148:149]
	v_pk_fma_f32 v[152:153], v[70:71], v[192:193], v[152:153]
	v_add_f32_e32 v146, v146, v147
	v_add_f32_e32 v148, v148, v149
	v_add_f32_e32 v150, v150, v151
	v_add_f32_e32 v152, v152, v153
	v_add_f32_e32 v154, v146, v148
	v_add_f32_e32 v155, v150, v152
	ds_read2_b32 v[118:119], v195 offset0:64 offset1:80
	ds_read_b128 v[72:75], v145 offset:31744
	ds_read_b128 v[76:79], v145 offset:32000
	ds_read_b128 v[64:67], v145 offset:23552
	ds_read_b128 v[68:71], v145 offset:23808
	s_waitcnt lgkmcnt(11)
	v_pk_add_f32 v[178:179], v[178:179], v[120:121] op_sel_hi:[1,0] neg_lo:[0,1] neg_hi:[0,1]
	v_add_f32_dpp v154, v154, v154 row_ror:8 row_mask:0xf bank_mask:0xf bound_ctrl:1
	v_pk_add_f32 v[186:187], v[186:187], v[120:121] op_sel:[0,1] op_sel_hi:[1,1] neg_lo:[0,1] neg_hi:[0,1]
	v_add_f32_dpp v155, v155, v155 row_ror:8 row_mask:0xf bank_mask:0xf bound_ctrl:1
	v_pk_add_f32 v[180:181], v[180:181], v[120:121] op_sel_hi:[1,0] neg_lo:[0,1] neg_hi:[0,1]
	v_add_f32_dpp v154, v154, v154 row_ror:4 row_mask:0xf bank_mask:0xf bound_ctrl:1
	v_pk_add_f32 v[188:189], v[188:189], v[120:121] op_sel:[0,1] op_sel_hi:[1,1] neg_lo:[0,1] neg_hi:[0,1]
	v_add_f32_dpp v155, v155, v155 row_ror:4 row_mask:0xf bank_mask:0xf bound_ctrl:1
	v_pk_add_f32 v[182:183], v[182:183], v[120:121] op_sel_hi:[1,0] neg_lo:[0,1] neg_hi:[0,1]
	v_add_f32_dpp v154, v154, v154 row_ror:2 row_mask:0xf bank_mask:0xf bound_ctrl:1
	v_pk_add_f32 v[190:191], v[190:191], v[120:121] op_sel:[0,1] op_sel_hi:[1,1] neg_lo:[0,1] neg_hi:[0,1]
	v_add_f32_dpp v155, v155, v155 row_ror:2 row_mask:0xf bank_mask:0xf bound_ctrl:1
	v_pk_add_f32 v[184:185], v[184:185], v[120:121] op_sel_hi:[1,0] neg_lo:[0,1] neg_hi:[0,1]
	v_add_f32_dpp v154, v154, v154 row_ror:1 row_mask:0xf bank_mask:0xf bound_ctrl:1
	v_pk_add_f32 v[192:193], v[192:193], v[120:121] op_sel:[0,1] op_sel_hi:[1,1] neg_lo:[0,1] neg_hi:[0,1]
	v_add_f32_dpp v155, v155, v155 row_ror:1 row_mask:0xf bank_mask:0xf bound_ctrl:1
	s_waitcnt lgkmcnt(10)
	v_pk_fma_f32 v[178:179], v[88:89], v[178:179], v[120:121] op_sel_hi:[1,1,0]
	s_and_saveexec_b64 s[8:9], s[38:39]
	ds_write_b32 v103, v154 offset:39936
	ds_write_b32 v103, v155 offset:40000
	s_mov_b64 exec, s[8:9]
	v_pk_fma_f32 v[186:187], v[88:89], v[186:187], v[120:121] op_sel:[0,0,1] op_sel_hi:[1,1,1]
	v_pk_fma_f32 v[180:181], v[90:91], v[180:181], v[120:121] op_sel_hi:[1,1,0]
	v_pk_fma_f32 v[188:189], v[90:91], v[188:189], v[120:121] op_sel:[0,0,1] op_sel_hi:[1,1,1]
	s_waitcnt lgkmcnt(11)
	v_pk_fma_f32 v[182:183], v[92:93], v[182:183], v[120:121] op_sel_hi:[1,1,0]
	v_pk_fma_f32 v[190:191], v[92:93], v[190:191], v[120:121] op_sel:[0,0,1] op_sel_hi:[1,1,1]
	v_pk_fma_f32 v[184:185], v[94:95], v[184:185], v[120:121] op_sel_hi:[1,1,0]
	v_pk_fma_f32 v[192:193], v[94:95], v[192:193], v[120:121] op_sel:[0,0,1] op_sel_hi:[1,1,1]
	s_waitcnt lgkmcnt(10)
	v_pk_fma_f32 v[146:147], v[80:81], v[178:179], v[196:197]
	v_pk_fma_f32 v[150:151], v[80:81], v[186:187], v[196:197]
	v_pk_fma_f32 v[148:149], v[82:83], v[180:181], v[196:197]
	v_pk_fma_f32 v[152:153], v[82:83], v[188:189], v[196:197]
	s_waitcnt lgkmcnt(9)
	v_pk_fma_f32 v[146:147], v[84:85], v[182:183], v[146:147]
	v_pk_fma_f32 v[150:151], v[84:85], v[190:191], v[150:151]
	v_pk_fma_f32 v[148:149], v[86:87], v[184:185], v[148:149]
	v_pk_fma_f32 v[152:153], v[86:87], v[192:193], v[152:153]
	v_add_f32_e32 v146, v146, v147
	v_add_f32_e32 v148, v148, v149
	v_add_f32_e32 v150, v150, v151
	v_add_f32_e32 v152, v152, v153
	v_add_f32_e32 v156, v146, v148
	v_add_f32_e32 v157, v150, v152
	ds_read2_b32 v[120:121], v195 offset0:96 offset1:112
	ds_read_b128 v[88:91], v145 offset:32256
	ds_read_b128 v[92:95], v145 offset:32512
	ds_read_b128 v[80:83], v145 offset:24064
	ds_read_b128 v[84:87], v145 offset:24320
	s_waitcnt lgkmcnt(11)
	v_pk_add_f32 v[178:179], v[178:179], v[118:119] op_sel_hi:[1,0] neg_lo:[0,1] neg_hi:[0,1]
	v_add_f32_dpp v156, v156, v156 row_ror:8 row_mask:0xf bank_mask:0xf bound_ctrl:1
	v_pk_add_f32 v[186:187], v[186:187], v[118:119] op_sel:[0,1] op_sel_hi:[1,1] neg_lo:[0,1] neg_hi:[0,1]
	v_add_f32_dpp v157, v157, v157 row_ror:8 row_mask:0xf bank_mask:0xf bound_ctrl:1
	v_pk_add_f32 v[180:181], v[180:181], v[118:119] op_sel_hi:[1,0] neg_lo:[0,1] neg_hi:[0,1]
	v_add_f32_dpp v156, v156, v156 row_ror:4 row_mask:0xf bank_mask:0xf bound_ctrl:1
	v_pk_add_f32 v[188:189], v[188:189], v[118:119] op_sel:[0,1] op_sel_hi:[1,1] neg_lo:[0,1] neg_hi:[0,1]
	v_add_f32_dpp v157, v157, v157 row_ror:4 row_mask:0xf bank_mask:0xf bound_ctrl:1
	v_pk_add_f32 v[182:183], v[182:183], v[118:119] op_sel_hi:[1,0] neg_lo:[0,1] neg_hi:[0,1]
	v_add_f32_dpp v156, v156, v156 row_ror:2 row_mask:0xf bank_mask:0xf bound_ctrl:1
	v_pk_add_f32 v[190:191], v[190:191], v[118:119] op_sel:[0,1] op_sel_hi:[1,1] neg_lo:[0,1] neg_hi:[0,1]
	v_add_f32_dpp v157, v157, v157 row_ror:2 row_mask:0xf bank_mask:0xf bound_ctrl:1
	v_pk_add_f32 v[184:185], v[184:185], v[118:119] op_sel_hi:[1,0] neg_lo:[0,1] neg_hi:[0,1]
	v_add_f32_dpp v156, v156, v156 row_ror:1 row_mask:0xf bank_mask:0xf bound_ctrl:1
	v_pk_add_f32 v[192:193], v[192:193], v[118:119] op_sel:[0,1] op_sel_hi:[1,1] neg_lo:[0,1] neg_hi:[0,1]
	v_add_f32_dpp v157, v157, v157 row_ror:1 row_mask:0xf bank_mask:0xf bound_ctrl:1
	s_waitcnt lgkmcnt(10)
	v_pk_fma_f32 v[178:179], v[72:73], v[178:179], v[118:119] op_sel_hi:[1,1,0]
	s_and_saveexec_b64 s[8:9], s[38:39]
	ds_write_b32 v103, v156 offset:40064
	ds_write_b32 v103, v157 offset:40128
	s_mov_b64 exec, s[8:9]
	v_pk_fma_f32 v[186:187], v[72:73], v[186:187], v[118:119] op_sel:[0,0,1] op_sel_hi:[1,1,1]
	v_pk_fma_f32 v[180:181], v[74:75], v[180:181], v[118:119] op_sel_hi:[1,1,0]
	v_pk_fma_f32 v[188:189], v[74:75], v[188:189], v[118:119] op_sel:[0,0,1] op_sel_hi:[1,1,1]
	s_waitcnt lgkmcnt(11)
	v_pk_fma_f32 v[182:183], v[76:77], v[182:183], v[118:119] op_sel_hi:[1,1,0]
	v_pk_fma_f32 v[190:191], v[76:77], v[190:191], v[118:119] op_sel:[0,0,1] op_sel_hi:[1,1,1]
	v_pk_fma_f32 v[184:185], v[78:79], v[184:185], v[118:119] op_sel_hi:[1,1,0]
	v_pk_fma_f32 v[192:193], v[78:79], v[192:193], v[118:119] op_sel:[0,0,1] op_sel_hi:[1,1,1]
	s_waitcnt lgkmcnt(10)
	v_pk_fma_f32 v[146:147], v[64:65], v[178:179], v[196:197]
	v_pk_fma_f32 v[150:151], v[64:65], v[186:187], v[196:197]
	v_pk_fma_f32 v[148:149], v[66:67], v[180:181], v[196:197]
	v_pk_fma_f32 v[152:153], v[66:67], v[188:189], v[196:197]
	s_waitcnt lgkmcnt(9)
	v_pk_fma_f32 v[146:147], v[68:69], v[182:183], v[146:147]
	v_pk_fma_f32 v[150:151], v[68:69], v[190:191], v[150:151]
	v_pk_fma_f32 v[148:149], v[70:71], v[184:185], v[148:149]
	v_pk_fma_f32 v[152:153], v[70:71], v[192:193], v[152:153]
	v_add_f32_e32 v146, v146, v147
	v_add_f32_e32 v148, v148, v149
	v_add_f32_e32 v150, v150, v151
	v_add_f32_e32 v152, v152, v153
	v_add_f32_e32 v154, v146, v148
	v_add_f32_e32 v155, v150, v152
	ds_read2_b32 v[118:119], v195 offset0:128 offset1:144
	ds_read_b128 v[72:75], v145 offset:32768
	ds_read_b128 v[76:79], v145 offset:33024
	ds_read_b128 v[64:67], v145 offset:24576
	ds_read_b128 v[68:71], v145 offset:24832
	s_waitcnt lgkmcnt(11)
	v_pk_add_f32 v[178:179], v[178:179], v[120:121] op_sel_hi:[1,0] neg_lo:[0,1] neg_hi:[0,1]
	v_add_f32_dpp v154, v154, v154 row_ror:8 row_mask:0xf bank_mask:0xf bound_ctrl:1
	v_pk_add_f32 v[186:187], v[186:187], v[120:121] op_sel:[0,1] op_sel_hi:[1,1] neg_lo:[0,1] neg_hi:[0,1]
	v_add_f32_dpp v155, v155, v155 row_ror:8 row_mask:0xf bank_mask:0xf bound_ctrl:1
	v_pk_add_f32 v[180:181], v[180:181], v[120:121] op_sel_hi:[1,0] neg_lo:[0,1] neg_hi:[0,1]
	v_add_f32_dpp v154, v154, v154 row_ror:4 row_mask:0xf bank_mask:0xf bound_ctrl:1
	v_pk_add_f32 v[188:189], v[188:189], v[120:121] op_sel:[0,1] op_sel_hi:[1,1] neg_lo:[0,1] neg_hi:[0,1]
	v_add_f32_dpp v155, v155, v155 row_ror:4 row_mask:0xf bank_mask:0xf bound_ctrl:1
	v_pk_add_f32 v[182:183], v[182:183], v[120:121] op_sel_hi:[1,0] neg_lo:[0,1] neg_hi:[0,1]
	v_add_f32_dpp v154, v154, v154 row_ror:2 row_mask:0xf bank_mask:0xf bound_ctrl:1
	v_pk_add_f32 v[190:191], v[190:191], v[120:121] op_sel:[0,1] op_sel_hi:[1,1] neg_lo:[0,1] neg_hi:[0,1]
	v_add_f32_dpp v155, v155, v155 row_ror:2 row_mask:0xf bank_mask:0xf bound_ctrl:1
	v_pk_add_f32 v[184:185], v[184:185], v[120:121] op_sel_hi:[1,0] neg_lo:[0,1] neg_hi:[0,1]
	v_add_f32_dpp v154, v154, v154 row_ror:1 row_mask:0xf bank_mask:0xf bound_ctrl:1
	v_pk_add_f32 v[192:193], v[192:193], v[120:121] op_sel:[0,1] op_sel_hi:[1,1] neg_lo:[0,1] neg_hi:[0,1]
	v_add_f32_dpp v155, v155, v155 row_ror:1 row_mask:0xf bank_mask:0xf bound_ctrl:1
	s_waitcnt lgkmcnt(10)
	v_pk_fma_f32 v[178:179], v[88:89], v[178:179], v[120:121] op_sel_hi:[1,1,0]
	s_and_saveexec_b64 s[8:9], s[38:39]
	ds_write_b32 v103, v154 offset:40192
	ds_write_b32 v103, v155 offset:40256
	s_mov_b64 exec, s[8:9]
	v_pk_fma_f32 v[186:187], v[88:89], v[186:187], v[120:121] op_sel:[0,0,1] op_sel_hi:[1,1,1]
	v_pk_fma_f32 v[180:181], v[90:91], v[180:181], v[120:121] op_sel_hi:[1,1,0]
	v_pk_fma_f32 v[188:189], v[90:91], v[188:189], v[120:121] op_sel:[0,0,1] op_sel_hi:[1,1,1]
	s_waitcnt lgkmcnt(11)
	v_pk_fma_f32 v[182:183], v[92:93], v[182:183], v[120:121] op_sel_hi:[1,1,0]
	v_pk_fma_f32 v[190:191], v[92:93], v[190:191], v[120:121] op_sel:[0,0,1] op_sel_hi:[1,1,1]
	v_pk_fma_f32 v[184:185], v[94:95], v[184:185], v[120:121] op_sel_hi:[1,1,0]
	v_pk_fma_f32 v[192:193], v[94:95], v[192:193], v[120:121] op_sel:[0,0,1] op_sel_hi:[1,1,1]
	s_waitcnt lgkmcnt(10)
	v_pk_fma_f32 v[146:147], v[80:81], v[178:179], v[196:197]
	v_pk_fma_f32 v[150:151], v[80:81], v[186:187], v[196:197]
	v_pk_fma_f32 v[148:149], v[82:83], v[180:181], v[196:197]
	v_pk_fma_f32 v[152:153], v[82:83], v[188:189], v[196:197]
	s_waitcnt lgkmcnt(9)
	v_pk_fma_f32 v[146:147], v[84:85], v[182:183], v[146:147]
	v_pk_fma_f32 v[150:151], v[84:85], v[190:191], v[150:151]
	v_pk_fma_f32 v[148:149], v[86:87], v[184:185], v[148:149]
	v_pk_fma_f32 v[152:153], v[86:87], v[192:193], v[152:153]
	v_add_f32_e32 v146, v146, v147
	v_add_f32_e32 v148, v148, v149
	v_add_f32_e32 v150, v150, v151
	v_add_f32_e32 v152, v152, v153
	v_add_f32_e32 v156, v146, v148
	v_add_f32_e32 v157, v150, v152
	ds_read2_b32 v[120:121], v195 offset0:160 offset1:176
	ds_read_b128 v[88:91], v145 offset:33280
	ds_read_b128 v[92:95], v145 offset:33536
	ds_read_b128 v[80:83], v145 offset:25088
	ds_read_b128 v[84:87], v145 offset:25344
	s_waitcnt lgkmcnt(11)
	v_pk_add_f32 v[178:179], v[178:179], v[118:119] op_sel_hi:[1,0] neg_lo:[0,1] neg_hi:[0,1]
	v_add_f32_dpp v156, v156, v156 row_ror:8 row_mask:0xf bank_mask:0xf bound_ctrl:1
	v_pk_add_f32 v[186:187], v[186:187], v[118:119] op_sel:[0,1] op_sel_hi:[1,1] neg_lo:[0,1] neg_hi:[0,1]
	v_add_f32_dpp v157, v157, v157 row_ror:8 row_mask:0xf bank_mask:0xf bound_ctrl:1
	v_pk_add_f32 v[180:181], v[180:181], v[118:119] op_sel_hi:[1,0] neg_lo:[0,1] neg_hi:[0,1]
	v_add_f32_dpp v156, v156, v156 row_ror:4 row_mask:0xf bank_mask:0xf bound_ctrl:1
	v_pk_add_f32 v[188:189], v[188:189], v[118:119] op_sel:[0,1] op_sel_hi:[1,1] neg_lo:[0,1] neg_hi:[0,1]
	v_add_f32_dpp v157, v157, v157 row_ror:4 row_mask:0xf bank_mask:0xf bound_ctrl:1
	v_pk_add_f32 v[182:183], v[182:183], v[118:119] op_sel_hi:[1,0] neg_lo:[0,1] neg_hi:[0,1]
	v_add_f32_dpp v156, v156, v156 row_ror:2 row_mask:0xf bank_mask:0xf bound_ctrl:1
	v_pk_add_f32 v[190:191], v[190:191], v[118:119] op_sel:[0,1] op_sel_hi:[1,1] neg_lo:[0,1] neg_hi:[0,1]
	v_add_f32_dpp v157, v157, v157 row_ror:2 row_mask:0xf bank_mask:0xf bound_ctrl:1
	v_pk_add_f32 v[184:185], v[184:185], v[118:119] op_sel_hi:[1,0] neg_lo:[0,1] neg_hi:[0,1]
	v_add_f32_dpp v156, v156, v156 row_ror:1 row_mask:0xf bank_mask:0xf bound_ctrl:1
	v_pk_add_f32 v[192:193], v[192:193], v[118:119] op_sel:[0,1] op_sel_hi:[1,1] neg_lo:[0,1] neg_hi:[0,1]
	v_add_f32_dpp v157, v157, v157 row_ror:1 row_mask:0xf bank_mask:0xf bound_ctrl:1
	s_waitcnt lgkmcnt(10)
	v_pk_fma_f32 v[178:179], v[72:73], v[178:179], v[118:119] op_sel_hi:[1,1,0]
	s_and_saveexec_b64 s[8:9], s[38:39]
	ds_write_b32 v103, v156 offset:40320
	ds_write_b32 v103, v157 offset:40384
	s_mov_b64 exec, s[8:9]
	v_pk_fma_f32 v[186:187], v[72:73], v[186:187], v[118:119] op_sel:[0,0,1] op_sel_hi:[1,1,1]
	v_pk_fma_f32 v[180:181], v[74:75], v[180:181], v[118:119] op_sel_hi:[1,1,0]
	v_pk_fma_f32 v[188:189], v[74:75], v[188:189], v[118:119] op_sel:[0,0,1] op_sel_hi:[1,1,1]
	s_waitcnt lgkmcnt(11)
	v_pk_fma_f32 v[182:183], v[76:77], v[182:183], v[118:119] op_sel_hi:[1,1,0]
	v_pk_fma_f32 v[190:191], v[76:77], v[190:191], v[118:119] op_sel:[0,0,1] op_sel_hi:[1,1,1]
	v_pk_fma_f32 v[184:185], v[78:79], v[184:185], v[118:119] op_sel_hi:[1,1,0]
	v_pk_fma_f32 v[192:193], v[78:79], v[192:193], v[118:119] op_sel:[0,0,1] op_sel_hi:[1,1,1]
	s_waitcnt lgkmcnt(10)
	v_pk_fma_f32 v[146:147], v[64:65], v[178:179], v[196:197]
	v_pk_fma_f32 v[150:151], v[64:65], v[186:187], v[196:197]
	v_pk_fma_f32 v[148:149], v[66:67], v[180:181], v[196:197]
	v_pk_fma_f32 v[152:153], v[66:67], v[188:189], v[196:197]
	s_waitcnt lgkmcnt(9)
	v_pk_fma_f32 v[146:147], v[68:69], v[182:183], v[146:147]
	v_pk_fma_f32 v[150:151], v[68:69], v[190:191], v[150:151]
	v_pk_fma_f32 v[148:149], v[70:71], v[184:185], v[148:149]
	v_pk_fma_f32 v[152:153], v[70:71], v[192:193], v[152:153]
	v_add_f32_e32 v146, v146, v147
	v_add_f32_e32 v148, v148, v149
	v_add_f32_e32 v150, v150, v151
	v_add_f32_e32 v152, v152, v153
	v_add_f32_e32 v154, v146, v148
	v_add_f32_e32 v155, v150, v152
	ds_read2_b32 v[118:119], v195 offset0:192 offset1:208
	ds_read_b128 v[72:75], v145 offset:33792
	ds_read_b128 v[76:79], v145 offset:34048
	ds_read_b128 v[64:67], v145 offset:25600
	ds_read_b128 v[68:71], v145 offset:25856
	s_waitcnt lgkmcnt(11)
	v_pk_add_f32 v[178:179], v[178:179], v[120:121] op_sel_hi:[1,0] neg_lo:[0,1] neg_hi:[0,1]
	v_add_f32_dpp v154, v154, v154 row_ror:8 row_mask:0xf bank_mask:0xf bound_ctrl:1
	v_pk_add_f32 v[186:187], v[186:187], v[120:121] op_sel:[0,1] op_sel_hi:[1,1] neg_lo:[0,1] neg_hi:[0,1]
	v_add_f32_dpp v155, v155, v155 row_ror:8 row_mask:0xf bank_mask:0xf bound_ctrl:1
	v_pk_add_f32 v[180:181], v[180:181], v[120:121] op_sel_hi:[1,0] neg_lo:[0,1] neg_hi:[0,1]
	v_add_f32_dpp v154, v154, v154 row_ror:4 row_mask:0xf bank_mask:0xf bound_ctrl:1
	v_pk_add_f32 v[188:189], v[188:189], v[120:121] op_sel:[0,1] op_sel_hi:[1,1] neg_lo:[0,1] neg_hi:[0,1]
	v_add_f32_dpp v155, v155, v155 row_ror:4 row_mask:0xf bank_mask:0xf bound_ctrl:1
	v_pk_add_f32 v[182:183], v[182:183], v[120:121] op_sel_hi:[1,0] neg_lo:[0,1] neg_hi:[0,1]
	v_add_f32_dpp v154, v154, v154 row_ror:2 row_mask:0xf bank_mask:0xf bound_ctrl:1
	v_pk_add_f32 v[190:191], v[190:191], v[120:121] op_sel:[0,1] op_sel_hi:[1,1] neg_lo:[0,1] neg_hi:[0,1]
	v_add_f32_dpp v155, v155, v155 row_ror:2 row_mask:0xf bank_mask:0xf bound_ctrl:1
	v_pk_add_f32 v[184:185], v[184:185], v[120:121] op_sel_hi:[1,0] neg_lo:[0,1] neg_hi:[0,1]
	v_add_f32_dpp v154, v154, v154 row_ror:1 row_mask:0xf bank_mask:0xf bound_ctrl:1
	v_pk_add_f32 v[192:193], v[192:193], v[120:121] op_sel:[0,1] op_sel_hi:[1,1] neg_lo:[0,1] neg_hi:[0,1]
	v_add_f32_dpp v155, v155, v155 row_ror:1 row_mask:0xf bank_mask:0xf bound_ctrl:1
	s_waitcnt lgkmcnt(10)
	v_pk_fma_f32 v[178:179], v[88:89], v[178:179], v[120:121] op_sel_hi:[1,1,0]
	s_and_saveexec_b64 s[8:9], s[38:39]
	ds_write_b32 v103, v154 offset:40448
	ds_write_b32 v103, v155 offset:40512
	s_mov_b64 exec, s[8:9]
	v_pk_fma_f32 v[186:187], v[88:89], v[186:187], v[120:121] op_sel:[0,0,1] op_sel_hi:[1,1,1]
	v_pk_fma_f32 v[180:181], v[90:91], v[180:181], v[120:121] op_sel_hi:[1,1,0]
	v_pk_fma_f32 v[188:189], v[90:91], v[188:189], v[120:121] op_sel:[0,0,1] op_sel_hi:[1,1,1]
	s_waitcnt lgkmcnt(11)
	v_pk_fma_f32 v[182:183], v[92:93], v[182:183], v[120:121] op_sel_hi:[1,1,0]
	v_pk_fma_f32 v[190:191], v[92:93], v[190:191], v[120:121] op_sel:[0,0,1] op_sel_hi:[1,1,1]
	v_pk_fma_f32 v[184:185], v[94:95], v[184:185], v[120:121] op_sel_hi:[1,1,0]
	v_pk_fma_f32 v[192:193], v[94:95], v[192:193], v[120:121] op_sel:[0,0,1] op_sel_hi:[1,1,1]
	s_waitcnt lgkmcnt(10)
	v_pk_fma_f32 v[146:147], v[80:81], v[178:179], v[196:197]
	v_pk_fma_f32 v[150:151], v[80:81], v[186:187], v[196:197]
	v_pk_fma_f32 v[148:149], v[82:83], v[180:181], v[196:197]
	v_pk_fma_f32 v[152:153], v[82:83], v[188:189], v[196:197]
	s_waitcnt lgkmcnt(9)
	v_pk_fma_f32 v[146:147], v[84:85], v[182:183], v[146:147]
	v_pk_fma_f32 v[150:151], v[84:85], v[190:191], v[150:151]
	v_pk_fma_f32 v[148:149], v[86:87], v[184:185], v[148:149]
	v_pk_fma_f32 v[152:153], v[86:87], v[192:193], v[152:153]
	v_add_f32_e32 v146, v146, v147
	v_add_f32_e32 v148, v148, v149
	v_add_f32_e32 v150, v150, v151
	v_add_f32_e32 v152, v152, v153
	v_add_f32_e32 v156, v146, v148
	v_add_f32_e32 v157, v150, v152
	ds_read2_b32 v[120:121], v195 offset0:224 offset1:240
	ds_read_b128 v[88:91], v145 offset:34304
	ds_read_b128 v[92:95], v145 offset:34560
	ds_read_b128 v[80:83], v145 offset:26112
	ds_read_b128 v[84:87], v145 offset:26368
	s_waitcnt lgkmcnt(11)
	v_pk_add_f32 v[178:179], v[178:179], v[118:119] op_sel_hi:[1,0] neg_lo:[0,1] neg_hi:[0,1]
	v_add_f32_dpp v156, v156, v156 row_ror:8 row_mask:0xf bank_mask:0xf bound_ctrl:1
	v_pk_add_f32 v[186:187], v[186:187], v[118:119] op_sel:[0,1] op_sel_hi:[1,1] neg_lo:[0,1] neg_hi:[0,1]
	v_add_f32_dpp v157, v157, v157 row_ror:8 row_mask:0xf bank_mask:0xf bound_ctrl:1
	v_pk_add_f32 v[180:181], v[180:181], v[118:119] op_sel_hi:[1,0] neg_lo:[0,1] neg_hi:[0,1]
	v_add_f32_dpp v156, v156, v156 row_ror:4 row_mask:0xf bank_mask:0xf bound_ctrl:1
	v_pk_add_f32 v[188:189], v[188:189], v[118:119] op_sel:[0,1] op_sel_hi:[1,1] neg_lo:[0,1] neg_hi:[0,1]
	v_add_f32_dpp v157, v157, v157 row_ror:4 row_mask:0xf bank_mask:0xf bound_ctrl:1
	v_pk_add_f32 v[182:183], v[182:183], v[118:119] op_sel_hi:[1,0] neg_lo:[0,1] neg_hi:[0,1]
	v_add_f32_dpp v156, v156, v156 row_ror:2 row_mask:0xf bank_mask:0xf bound_ctrl:1
	v_pk_add_f32 v[190:191], v[190:191], v[118:119] op_sel:[0,1] op_sel_hi:[1,1] neg_lo:[0,1] neg_hi:[0,1]
	v_add_f32_dpp v157, v157, v157 row_ror:2 row_mask:0xf bank_mask:0xf bound_ctrl:1
	v_pk_add_f32 v[184:185], v[184:185], v[118:119] op_sel_hi:[1,0] neg_lo:[0,1] neg_hi:[0,1]
	v_add_f32_dpp v156, v156, v156 row_ror:1 row_mask:0xf bank_mask:0xf bound_ctrl:1
	v_pk_add_f32 v[192:193], v[192:193], v[118:119] op_sel:[0,1] op_sel_hi:[1,1] neg_lo:[0,1] neg_hi:[0,1]
	v_add_f32_dpp v157, v157, v157 row_ror:1 row_mask:0xf bank_mask:0xf bound_ctrl:1
	s_waitcnt lgkmcnt(10)
	v_pk_fma_f32 v[178:179], v[72:73], v[178:179], v[118:119] op_sel_hi:[1,1,0]
	s_and_saveexec_b64 s[8:9], s[38:39]
	ds_write_b32 v103, v156 offset:40576
	ds_write_b32 v103, v157 offset:40640
	s_mov_b64 exec, s[8:9]
	v_pk_fma_f32 v[186:187], v[72:73], v[186:187], v[118:119] op_sel:[0,0,1] op_sel_hi:[1,1,1]
	v_pk_fma_f32 v[180:181], v[74:75], v[180:181], v[118:119] op_sel_hi:[1,1,0]
	v_pk_fma_f32 v[188:189], v[74:75], v[188:189], v[118:119] op_sel:[0,0,1] op_sel_hi:[1,1,1]
	s_waitcnt lgkmcnt(11)
	v_pk_fma_f32 v[182:183], v[76:77], v[182:183], v[118:119] op_sel_hi:[1,1,0]
	v_pk_fma_f32 v[190:191], v[76:77], v[190:191], v[118:119] op_sel:[0,0,1] op_sel_hi:[1,1,1]
	v_pk_fma_f32 v[184:185], v[78:79], v[184:185], v[118:119] op_sel_hi:[1,1,0]
	v_pk_fma_f32 v[192:193], v[78:79], v[192:193], v[118:119] op_sel:[0,0,1] op_sel_hi:[1,1,1]
	s_waitcnt lgkmcnt(10)
	v_pk_fma_f32 v[146:147], v[64:65], v[178:179], v[196:197]
	v_pk_fma_f32 v[150:151], v[64:65], v[186:187], v[196:197]
	v_pk_fma_f32 v[148:149], v[66:67], v[180:181], v[196:197]
	v_pk_fma_f32 v[152:153], v[66:67], v[188:189], v[196:197]
	s_waitcnt lgkmcnt(9)
	v_pk_fma_f32 v[146:147], v[68:69], v[182:183], v[146:147]
	v_pk_fma_f32 v[150:151], v[68:69], v[190:191], v[150:151]
	v_pk_fma_f32 v[148:149], v[70:71], v[184:185], v[148:149]
	v_pk_fma_f32 v[152:153], v[70:71], v[192:193], v[152:153]
	v_add_f32_e32 v146, v146, v147
	v_add_f32_e32 v148, v148, v149
	v_add_f32_e32 v150, v150, v151
	v_add_f32_e32 v152, v152, v153
	v_add_f32_e32 v154, v146, v148
	v_add_f32_e32 v155, v150, v152
	s_waitcnt lgkmcnt(6)
	v_pk_add_f32 v[178:179], v[178:179], v[120:121] op_sel_hi:[1,0] neg_lo:[0,1] neg_hi:[0,1]
	v_add_f32_dpp v154, v154, v154 row_ror:8 row_mask:0xf bank_mask:0xf bound_ctrl:1
	v_pk_add_f32 v[186:187], v[186:187], v[120:121] op_sel:[0,1] op_sel_hi:[1,1] neg_lo:[0,1] neg_hi:[0,1]
	v_add_f32_dpp v155, v155, v155 row_ror:8 row_mask:0xf bank_mask:0xf bound_ctrl:1
	v_pk_add_f32 v[180:181], v[180:181], v[120:121] op_sel_hi:[1,0] neg_lo:[0,1] neg_hi:[0,1]
	v_add_f32_dpp v154, v154, v154 row_ror:4 row_mask:0xf bank_mask:0xf bound_ctrl:1
	v_pk_add_f32 v[188:189], v[188:189], v[120:121] op_sel:[0,1] op_sel_hi:[1,1] neg_lo:[0,1] neg_hi:[0,1]
	v_add_f32_dpp v155, v155, v155 row_ror:4 row_mask:0xf bank_mask:0xf bound_ctrl:1
	v_pk_add_f32 v[182:183], v[182:183], v[120:121] op_sel_hi:[1,0] neg_lo:[0,1] neg_hi:[0,1]
	v_add_f32_dpp v154, v154, v154 row_ror:2 row_mask:0xf bank_mask:0xf bound_ctrl:1
	v_pk_add_f32 v[190:191], v[190:191], v[120:121] op_sel:[0,1] op_sel_hi:[1,1] neg_lo:[0,1] neg_hi:[0,1]
	v_add_f32_dpp v155, v155, v155 row_ror:2 row_mask:0xf bank_mask:0xf bound_ctrl:1
	v_pk_add_f32 v[184:185], v[184:185], v[120:121] op_sel_hi:[1,0] neg_lo:[0,1] neg_hi:[0,1]
	v_add_f32_dpp v154, v154, v154 row_ror:1 row_mask:0xf bank_mask:0xf bound_ctrl:1
	v_pk_add_f32 v[192:193], v[192:193], v[120:121] op_sel:[0,1] op_sel_hi:[1,1] neg_lo:[0,1] neg_hi:[0,1]
	v_add_f32_dpp v155, v155, v155 row_ror:1 row_mask:0xf bank_mask:0xf bound_ctrl:1
	s_waitcnt lgkmcnt(5)
	v_pk_fma_f32 v[178:179], v[88:89], v[178:179], v[120:121] op_sel_hi:[1,1,0]
	s_and_saveexec_b64 s[8:9], s[38:39]
	ds_write_b32 v103, v154 offset:40704
	ds_write_b32 v103, v155 offset:40768
	s_mov_b64 exec, s[8:9]
	v_pk_fma_f32 v[186:187], v[88:89], v[186:187], v[120:121] op_sel:[0,0,1] op_sel_hi:[1,1,1]
	v_pk_fma_f32 v[180:181], v[90:91], v[180:181], v[120:121] op_sel_hi:[1,1,0]
	v_pk_fma_f32 v[188:189], v[90:91], v[188:189], v[120:121] op_sel:[0,0,1] op_sel_hi:[1,1,1]
	s_waitcnt lgkmcnt(6)
	v_pk_fma_f32 v[182:183], v[92:93], v[182:183], v[120:121] op_sel_hi:[1,1,0]
	v_pk_fma_f32 v[190:191], v[92:93], v[190:191], v[120:121] op_sel:[0,0,1] op_sel_hi:[1,1,1]
	v_pk_fma_f32 v[184:185], v[94:95], v[184:185], v[120:121] op_sel_hi:[1,1,0]
	v_pk_fma_f32 v[192:193], v[94:95], v[192:193], v[120:121] op_sel:[0,0,1] op_sel_hi:[1,1,1]
	s_waitcnt lgkmcnt(5)
	v_pk_fma_f32 v[146:147], v[80:81], v[178:179], v[196:197]
	v_pk_fma_f32 v[150:151], v[80:81], v[186:187], v[196:197]
	v_pk_fma_f32 v[148:149], v[82:83], v[180:181], v[196:197]
	v_pk_fma_f32 v[152:153], v[82:83], v[188:189], v[196:197]
	s_waitcnt lgkmcnt(4)
	v_pk_fma_f32 v[146:147], v[84:85], v[182:183], v[146:147]
	v_pk_fma_f32 v[150:151], v[84:85], v[190:191], v[150:151]
	v_pk_fma_f32 v[148:149], v[86:87], v[184:185], v[148:149]
	v_pk_fma_f32 v[152:153], v[86:87], v[192:193], v[152:153]
	v_add_f32_e32 v146, v146, v147
	v_add_f32_e32 v148, v148, v149
	v_add_f32_e32 v150, v150, v151
	v_add_f32_e32 v152, v152, v153
	v_add_f32_e32 v156, v146, v148
	v_add_f32_e32 v157, v150, v152
	s_nop 0
	v_add_f32_dpp v156, v156, v156 row_ror:8 row_mask:0xf bank_mask:0xf bound_ctrl:1
	v_add_f32_dpp v157, v157, v157 row_ror:8 row_mask:0xf bank_mask:0xf bound_ctrl:1
	s_nop 0
	v_add_f32_dpp v156, v156, v156 row_ror:4 row_mask:0xf bank_mask:0xf bound_ctrl:1
	v_add_f32_dpp v157, v157, v157 row_ror:4 row_mask:0xf bank_mask:0xf bound_ctrl:1
	s_nop 0
	v_add_f32_dpp v156, v156, v156 row_ror:2 row_mask:0xf bank_mask:0xf bound_ctrl:1
	v_add_f32_dpp v157, v157, v157 row_ror:2 row_mask:0xf bank_mask:0xf bound_ctrl:1
	s_nop 0
	v_add_f32_dpp v156, v156, v156 row_ror:1 row_mask:0xf bank_mask:0xf bound_ctrl:1
	v_add_f32_dpp v157, v157, v157 row_ror:1 row_mask:0xf bank_mask:0xf bound_ctrl:1
	s_and_saveexec_b64 s[8:9], s[38:39]
	ds_write_b32 v103, v156 offset:40832
	ds_write_b32 v103, v157 offset:40896
	s_mov_b64 exec, s[8:9]
	s_waitcnt lgkmcnt(0)
	v_mov_b32_e32 v118, v178
	v_mov_b32_e32 v119, v179
	v_mov_b32_e32 v88, v180
	v_mov_b32_e32 v89, v181
	v_mov_b32_e32 v90, v182
	v_mov_b32_e32 v80, v183
	v_mov_b32_e32 v81, v184
	v_mov_b32_e32 v82, v185
	v_mov_b32_e32 v146, v186
	v_mov_b32_e32 v120, v187
	v_mov_b32_e32 v121, v188
	v_mov_b32_e32 v91, v189
	v_mov_b32_e32 v147, v190
	v_mov_b32_e32 v148, v191
	v_mov_b32_e32 v149, v192
	v_mov_b32_e32 v83, v193
	s_branch .LBB0_1284

.LBB0_1454:
	s_or_b64 exec, exec, s[8:9]
	s_waitcnt lgkmcnt(0)
	s_barrier
	v_mov_b32_e32 v196, v64
	v_mov_b32_e32 v197, v65
	v_mov_b32_e32 v198, v66
	v_mov_b32_e32 v199, v67
	v_mov_b32_e32 v200, v76
	v_mov_b32_e32 v201, v77
	v_mov_b32_e32 v202, v78
	v_mov_b32_e32 v203, v79
	v_mov_b32_e32 v204, v72
	v_mov_b32_e32 v205, v73
	v_mov_b32_e32 v206, v74
	v_mov_b32_e32 v207, v75
	v_mov_b32_e32 v208, v68
	v_mov_b32_e32 v209, v69
	v_mov_b32_e32 v210, v70
	v_mov_b32_e32 v211, v71
	v_mov_b32_e32 v192, 0
	v_mov_b32_e32 v193, 0
	ds_read_b128 v[80:83], v188 offset:8192
	ds_read_b128 v[84:87], v188 offset:8448
	ds_read_b128 v[88:91], v188 offset:8704
	ds_read_b128 v[92:95], v188 offset:8960
	ds_read_b32 v134, v140 offset:35136
	ds_read_b32 v135, v189 offset:16384
	ds_read_b32 v132, v140 offset:35072
	ds_read_b128 v[64:67], v188
	ds_read_b128 v[68:71], v188 offset:256
	ds_read_b128 v[72:75], v188 offset:512
	ds_read_b128 v[76:79], v188 offset:768
	ds_read_b128 v[112:115], v188 offset:9216
	ds_read_b128 v[116:119], v188 offset:9472
	ds_read_b128 v[120:123], v188 offset:9728
	ds_read_b128 v[124:127], v188 offset:9984
	ds_read_b32 v154, v140 offset:35140
	ds_read_b32 v155, v189 offset:16448
	ds_read_b32 v152, v140 offset:35076
	ds_read_b128 v[96:99], v188 offset:1024
	ds_read_b128 v[100:103], v188 offset:1280
	ds_read_b128 v[104:107], v188 offset:1536
	ds_read_b128 v[108:111], v188 offset:1792
	s_waitcnt lgkmcnt(15)
	v_mul_f32_e32 v133, v134, v135
	v_pk_mul_f32 v[80:81], v[80:81], v[132:133] op_sel:[0,1] op_sel_hi:[1,1]
	v_pk_mul_f32 v[82:83], v[82:83], v[132:133] op_sel:[0,1] op_sel_hi:[1,1]
	v_pk_mul_f32 v[84:85], v[84:85], v[132:133] op_sel:[0,1] op_sel_hi:[1,1]
	v_pk_mul_f32 v[86:87], v[86:87], v[132:133] op_sel:[0,1] op_sel_hi:[1,1]
	v_pk_mul_f32 v[88:89], v[88:89], v[132:133] op_sel:[0,1] op_sel_hi:[1,1]
	v_pk_mul_f32 v[90:91], v[90:91], v[132:133] op_sel:[0,1] op_sel_hi:[1,1]
	v_pk_mul_f32 v[92:93], v[92:93], v[132:133] op_sel:[0,1] op_sel_hi:[1,1]
	v_pk_mul_f32 v[94:95], v[94:95], v[132:133] op_sel:[0,1] op_sel_hi:[1,1]
	v_pk_fma_f32 v[196:197], v[132:133], v[196:197], v[80:81] op_sel_hi:[0,1,1]
	v_pk_fma_f32 v[198:199], v[132:133], v[198:199], v[82:83] op_sel_hi:[0,1,1]
	v_pk_fma_f32 v[200:201], v[132:133], v[200:201], v[84:85] op_sel_hi:[0,1,1]
	v_pk_fma_f32 v[202:203], v[132:133], v[202:203], v[86:87] op_sel_hi:[0,1,1]
	v_pk_fma_f32 v[204:205], v[132:133], v[204:205], v[88:89] op_sel_hi:[0,1,1]
	v_pk_fma_f32 v[206:207], v[132:133], v[206:207], v[90:91] op_sel_hi:[0,1,1]
	v_pk_fma_f32 v[208:209], v[132:133], v[208:209], v[92:93] op_sel_hi:[0,1,1]
	v_pk_fma_f32 v[210:211], v[132:133], v[210:211], v[94:95] op_sel_hi:[0,1,1]
	s_waitcnt lgkmcnt(14)
	v_pk_fma_f32 v[128:129], v[64:65], v[196:197], v[192:193]
	v_pk_fma_f32 v[130:131], v[66:67], v[198:199], v[192:193]
	s_waitcnt lgkmcnt(13)
	v_pk_fma_f32 v[128:129], v[68:69], v[200:201], v[128:129]
	v_pk_fma_f32 v[130:131], v[70:71], v[202:203], v[130:131]
	s_waitcnt lgkmcnt(12)
	v_pk_fma_f32 v[128:129], v[72:73], v[204:205], v[128:129]
	v_pk_fma_f32 v[130:131], v[74:75], v[206:207], v[130:131]
	s_waitcnt lgkmcnt(11)
	v_pk_fma_f32 v[128:129], v[76:77], v[208:209], v[128:129]
	v_pk_fma_f32 v[130:131], v[78:79], v[210:211], v[130:131]
	v_add_f32_e32 v128, v128, v129
	v_add_f32_e32 v130, v130, v131
	v_add_f32_e32 v190, v128, v130
	ds_read_b128 v[80:83], v188 offset:10240
	ds_read_b128 v[84:87], v188 offset:10496
	ds_read_b128 v[88:91], v188 offset:10752
	ds_read_b128 v[92:95], v188 offset:11008
	ds_read_b32 v134, v140 offset:35144
	ds_read_b32 v135, v189 offset:16512
	ds_read_b32 v132, v140 offset:35080
	ds_read_b128 v[64:67], v188 offset:2048
	ds_read_b128 v[68:71], v188 offset:2304
	ds_read_b128 v[72:75], v188 offset:2560
	ds_read_b128 v[76:79], v188 offset:2816
	s_waitcnt lgkmcnt(15)
	v_mul_f32_e32 v153, v154, v155
	v_pk_mul_f32 v[112:113], v[112:113], v[152:153] op_sel:[0,1] op_sel_hi:[1,1]
	v_add_f32_dpp v190, v190, v190 row_ror:8 row_mask:0xf bank_mask:0xf bound_ctrl:1
	v_pk_mul_f32 v[114:115], v[114:115], v[152:153] op_sel:[0,1] op_sel_hi:[1,1]
	v_pk_mul_f32 v[116:117], v[116:117], v[152:153] op_sel:[0,1] op_sel_hi:[1,1]
	v_add_f32_dpp v190, v190, v190 row_ror:4 row_mask:0xf bank_mask:0xf bound_ctrl:1
	v_pk_mul_f32 v[118:119], v[118:119], v[152:153] op_sel:[0,1] op_sel_hi:[1,1]
	v_pk_mul_f32 v[120:121], v[120:121], v[152:153] op_sel:[0,1] op_sel_hi:[1,1]
	v_add_f32_dpp v190, v190, v190 row_ror:2 row_mask:0xf bank_mask:0xf bound_ctrl:1
	v_pk_mul_f32 v[122:123], v[122:123], v[152:153] op_sel:[0,1] op_sel_hi:[1,1]
	v_pk_mul_f32 v[124:125], v[124:125], v[152:153] op_sel:[0,1] op_sel_hi:[1,1]
	v_add_f32_dpp v190, v190, v190 row_ror:1 row_mask:0xf bank_mask:0xf bound_ctrl:1
	v_pk_mul_f32 v[126:127], v[126:127], v[152:153] op_sel:[0,1] op_sel_hi:[1,1]
	v_pk_fma_f32 v[196:197], v[152:153], v[196:197], v[112:113] op_sel_hi:[0,1,1]
	s_and_saveexec_b64 s[8:9], s[44:45]
	ds_write_b32 v189, v190 offset:34048
	s_mov_b64 exec, s[8:9]
	v_pk_fma_f32 v[198:199], v[152:153], v[198:199], v[114:115] op_sel_hi:[0,1,1]
	v_pk_fma_f32 v[200:201], v[152:153], v[200:201], v[116:117] op_sel_hi:[0,1,1]
	v_pk_fma_f32 v[202:203], v[152:153], v[202:203], v[118:119] op_sel_hi:[0,1,1]
	v_pk_fma_f32 v[204:205], v[152:153], v[204:205], v[120:121] op_sel_hi:[0,1,1]
	v_pk_fma_f32 v[206:207], v[152:153], v[206:207], v[122:123] op_sel_hi:[0,1,1]
	v_pk_fma_f32 v[208:209], v[152:153], v[208:209], v[124:125] op_sel_hi:[0,1,1]
	v_pk_fma_f32 v[210:211], v[152:153], v[210:211], v[126:127] op_sel_hi:[0,1,1]
	s_waitcnt lgkmcnt(15)
	v_pk_fma_f32 v[128:129], v[96:97], v[196:197], v[192:193]
	v_pk_fma_f32 v[130:131], v[98:99], v[198:199], v[192:193]
	s_waitcnt lgkmcnt(14)
	v_pk_fma_f32 v[128:129], v[100:101], v[200:201], v[128:129]
	v_pk_fma_f32 v[130:131], v[102:103], v[202:203], v[130:131]
	s_waitcnt lgkmcnt(13)
	v_pk_fma_f32 v[128:129], v[104:105], v[204:205], v[128:129]
	v_pk_fma_f32 v[130:131], v[106:107], v[206:207], v[130:131]
	s_waitcnt lgkmcnt(12)
	v_pk_fma_f32 v[128:129], v[108:109], v[208:209], v[128:129]
	v_pk_fma_f32 v[130:131], v[110:111], v[210:211], v[130:131]
	v_add_f32_e32 v128, v128, v129
	v_add_f32_e32 v130, v130, v131
	v_add_f32_e32 v191, v128, v130
	ds_read_b128 v[112:115], v188 offset:11264
	ds_read_b128 v[116:119], v188 offset:11520
	ds_read_b128 v[120:123], v188 offset:11776
	ds_read_b128 v[124:127], v188 offset:12032
	ds_read_b32 v154, v140 offset:35148
	ds_read_b32 v155, v189 offset:16576
	ds_read_b32 v152, v140 offset:35084
	ds_read_b128 v[96:99], v188 offset:3072
	ds_read_b128 v[100:103], v188 offset:3328
	ds_read_b128 v[104:107], v188 offset:3584
	ds_read_b128 v[108:111], v188 offset:3840
	s_waitcnt lgkmcnt(15)
	v_mul_f32_e32 v133, v134, v135
	v_pk_mul_f32 v[80:81], v[80:81], v[132:133] op_sel:[0,1] op_sel_hi:[1,1]
	v_add_f32_dpp v191, v191, v191 row_ror:8 row_mask:0xf bank_mask:0xf bound_ctrl:1
	v_pk_mul_f32 v[82:83], v[82:83], v[132:133] op_sel:[0,1] op_sel_hi:[1,1]
	v_pk_mul_f32 v[84:85], v[84:85], v[132:133] op_sel:[0,1] op_sel_hi:[1,1]
	v_add_f32_dpp v191, v191, v191 row_ror:4 row_mask:0xf bank_mask:0xf bound_ctrl:1
	v_pk_mul_f32 v[86:87], v[86:87], v[132:133] op_sel:[0,1] op_sel_hi:[1,1]
	v_pk_mul_f32 v[88:89], v[88:89], v[132:133] op_sel:[0,1] op_sel_hi:[1,1]
	v_add_f32_dpp v191, v191, v191 row_ror:2 row_mask:0xf bank_mask:0xf bound_ctrl:1
	v_pk_mul_f32 v[90:91], v[90:91], v[132:133] op_sel:[0,1] op_sel_hi:[1,1]
	v_pk_mul_f32 v[92:93], v[92:93], v[132:133] op_sel:[0,1] op_sel_hi:[1,1]
	v_add_f32_dpp v191, v191, v191 row_ror:1 row_mask:0xf bank_mask:0xf bound_ctrl:1
	v_pk_mul_f32 v[94:95], v[94:95], v[132:133] op_sel:[0,1] op_sel_hi:[1,1]
	v_pk_fma_f32 v[196:197], v[132:133], v[196:197], v[80:81] op_sel_hi:[0,1,1]
	s_and_saveexec_b64 s[8:9], s[44:45]
	ds_write_b32 v189, v191 offset:34112
	s_mov_b64 exec, s[8:9]
	v_pk_fma_f32 v[198:199], v[132:133], v[198:199], v[82:83] op_sel_hi:[0,1,1]
	v_pk_fma_f32 v[200:201], v[132:133], v[200:201], v[84:85] op_sel_hi:[0,1,1]
	v_pk_fma_f32 v[202:203], v[132:133], v[202:203], v[86:87] op_sel_hi:[0,1,1]
	v_pk_fma_f32 v[204:205], v[132:133], v[204:205], v[88:89] op_sel_hi:[0,1,1]
	v_pk_fma_f32 v[206:207], v[132:133], v[206:207], v[90:91] op_sel_hi:[0,1,1]
	v_pk_fma_f32 v[208:209], v[132:133], v[208:209], v[92:93] op_sel_hi:[0,1,1]
	v_pk_fma_f32 v[210:211], v[132:133], v[210:211], v[94:95] op_sel_hi:[0,1,1]
	s_waitcnt lgkmcnt(15)
	v_pk_fma_f32 v[128:129], v[64:65], v[196:197], v[192:193]
	v_pk_fma_f32 v[130:131], v[66:67], v[198:199], v[192:193]
	v_pk_fma_f32 v[128:129], v[68:69], v[200:201], v[128:129]
	v_pk_fma_f32 v[130:131], v[70:71], v[202:203], v[130:131]
	s_waitcnt lgkmcnt(14)
	v_pk_fma_f32 v[128:129], v[72:73], v[204:205], v[128:129]
	v_pk_fma_f32 v[130:131], v[74:75], v[206:207], v[130:131]
	s_waitcnt lgkmcnt(13)
	v_pk_fma_f32 v[128:129], v[76:77], v[208:209], v[128:129]
	v_pk_fma_f32 v[130:131], v[78:79], v[210:211], v[130:131]
	v_add_f32_e32 v128, v128, v129
	v_add_f32_e32 v130, v130, v131
	v_add_f32_e32 v190, v128, v130
	ds_read_b128 v[80:83], v188 offset:12288
	ds_read_b128 v[84:87], v188 offset:12544
	ds_read_b128 v[88:91], v188 offset:12800
	ds_read_b128 v[92:95], v188 offset:13056
	ds_read_b32 v134, v140 offset:35152
	ds_read_b32 v135, v189 offset:16640
	ds_read_b32 v132, v140 offset:35088
	ds_read_b128 v[64:67], v188 offset:4096
	ds_read_b128 v[68:71], v188 offset:4352
	ds_read_b128 v[72:75], v188 offset:4608
	ds_read_b128 v[76:79], v188 offset:4864
	s_waitcnt lgkmcnt(15)
	v_mul_f32_e32 v153, v154, v155
	v_pk_mul_f32 v[112:113], v[112:113], v[152:153] op_sel:[0,1] op_sel_hi:[1,1]
	v_add_f32_dpp v190, v190, v190 row_ror:8 row_mask:0xf bank_mask:0xf bound_ctrl:1
	v_pk_mul_f32 v[114:115], v[114:115], v[152:153] op_sel:[0,1] op_sel_hi:[1,1]
	v_pk_mul_f32 v[116:117], v[116:117], v[152:153] op_sel:[0,1] op_sel_hi:[1,1]
	v_add_f32_dpp v190, v190, v190 row_ror:4 row_mask:0xf bank_mask:0xf bound_ctrl:1
	v_pk_mul_f32 v[118:119], v[118:119], v[152:153] op_sel:[0,1] op_sel_hi:[1,1]
	v_pk_mul_f32 v[120:121], v[120:121], v[152:153] op_sel:[0,1] op_sel_hi:[1,1]
	v_add_f32_dpp v190, v190, v190 row_ror:2 row_mask:0xf bank_mask:0xf bound_ctrl:1
	v_pk_mul_f32 v[122:123], v[122:123], v[152:153] op_sel:[0,1] op_sel_hi:[1,1]
	v_pk_mul_f32 v[124:125], v[124:125], v[152:153] op_sel:[0,1] op_sel_hi:[1,1]
	v_add_f32_dpp v190, v190, v190 row_ror:1 row_mask:0xf bank_mask:0xf bound_ctrl:1
	v_pk_mul_f32 v[126:127], v[126:127], v[152:153] op_sel:[0,1] op_sel_hi:[1,1]
	v_pk_fma_f32 v[196:197], v[152:153], v[196:197], v[112:113] op_sel_hi:[0,1,1]
	s_and_saveexec_b64 s[8:9], s[44:45]
	ds_write_b32 v189, v190 offset:34176
	s_mov_b64 exec, s[8:9]
	v_pk_fma_f32 v[198:199], v[152:153], v[198:199], v[114:115] op_sel_hi:[0,1,1]
	v_pk_fma_f32 v[200:201], v[152:153], v[200:201], v[116:117] op_sel_hi:[0,1,1]
	v_pk_fma_f32 v[202:203], v[152:153], v[202:203], v[118:119] op_sel_hi:[0,1,1]
	v_pk_fma_f32 v[204:205], v[152:153], v[204:205], v[120:121] op_sel_hi:[0,1,1]
	v_pk_fma_f32 v[206:207], v[152:153], v[206:207], v[122:123] op_sel_hi:[0,1,1]
	v_pk_fma_f32 v[208:209], v[152:153], v[208:209], v[124:125] op_sel_hi:[0,1,1]
	v_pk_fma_f32 v[210:211], v[152:153], v[210:211], v[126:127] op_sel_hi:[0,1,1]
	s_waitcnt lgkmcnt(15)
	v_pk_fma_f32 v[128:129], v[96:97], v[196:197], v[192:193]
	v_pk_fma_f32 v[130:131], v[98:99], v[198:199], v[192:193]
	v_pk_fma_f32 v[128:129], v[100:101], v[200:201], v[128:129]
	v_pk_fma_f32 v[130:131], v[102:103], v[202:203], v[130:131]
	s_waitcnt lgkmcnt(14)
	v_pk_fma_f32 v[128:129], v[104:105], v[204:205], v[128:129]
	v_pk_fma_f32 v[130:131], v[106:107], v[206:207], v[130:131]
	s_waitcnt lgkmcnt(13)
	v_pk_fma_f32 v[128:129], v[108:109], v[208:209], v[128:129]
	v_pk_fma_f32 v[130:131], v[110:111], v[210:211], v[130:131]
	v_add_f32_e32 v128, v128, v129
	v_add_f32_e32 v130, v130, v131
	v_add_f32_e32 v191, v128, v130
	ds_read_b128 v[112:115], v188 offset:13312
	ds_read_b128 v[116:119], v188 offset:13568
	ds_read_b128 v[120:123], v188 offset:13824
	ds_read_b128 v[124:127], v188 offset:14080
	ds_read_b32 v154, v140 offset:35156
	ds_read_b32 v155, v189 offset:16704
	ds_read_b32 v152, v140 offset:35092
	ds_read_b128 v[96:99], v188 offset:5120
	ds_read_b128 v[100:103], v188 offset:5376
	ds_read_b128 v[104:107], v188 offset:5632
	ds_read_b128 v[108:111], v188 offset:5888
	s_waitcnt lgkmcnt(15)
	v_mul_f32_e32 v133, v134, v135
	v_pk_mul_f32 v[80:81], v[80:81], v[132:133] op_sel:[0,1] op_sel_hi:[1,1]
	v_add_f32_dpp v191, v191, v191 row_ror:8 row_mask:0xf bank_mask:0xf bound_ctrl:1
	v_pk_mul_f32 v[82:83], v[82:83], v[132:133] op_sel:[0,1] op_sel_hi:[1,1]
	v_pk_mul_f32 v[84:85], v[84:85], v[132:133] op_sel:[0,1] op_sel_hi:[1,1]
	v_add_f32_dpp v191, v191, v191 row_ror:4 row_mask:0xf bank_mask:0xf bound_ctrl:1
	v_pk_mul_f32 v[86:87], v[86:87], v[132:133] op_sel:[0,1] op_sel_hi:[1,1]
	v_pk_mul_f32 v[88:89], v[88:89], v[132:133] op_sel:[0,1] op_sel_hi:[1,1]
	v_add_f32_dpp v191, v191, v191 row_ror:2 row_mask:0xf bank_mask:0xf bound_ctrl:1
	v_pk_mul_f32 v[90:91], v[90:91], v[132:133] op_sel:[0,1] op_sel_hi:[1,1]
	v_pk_mul_f32 v[92:93], v[92:93], v[132:133] op_sel:[0,1] op_sel_hi:[1,1]
	v_add_f32_dpp v191, v191, v191 row_ror:1 row_mask:0xf bank_mask:0xf bound_ctrl:1
	v_pk_mul_f32 v[94:95], v[94:95], v[132:133] op_sel:[0,1] op_sel_hi:[1,1]
	v_pk_fma_f32 v[196:197], v[132:133], v[196:197], v[80:81] op_sel_hi:[0,1,1]
	s_and_saveexec_b64 s[8:9], s[44:45]
	ds_write_b32 v189, v191 offset:34240
	s_mov_b64 exec, s[8:9]
	v_pk_fma_f32 v[198:199], v[132:133], v[198:199], v[82:83] op_sel_hi:[0,1,1]
	v_pk_fma_f32 v[200:201], v[132:133], v[200:201], v[84:85] op_sel_hi:[0,1,1]
	v_pk_fma_f32 v[202:203], v[132:133], v[202:203], v[86:87] op_sel_hi:[0,1,1]
	v_pk_fma_f32 v[204:205], v[132:133], v[204:205], v[88:89] op_sel_hi:[0,1,1]
	v_pk_fma_f32 v[206:207], v[132:133], v[206:207], v[90:91] op_sel_hi:[0,1,1]
	v_pk_fma_f32 v[208:209], v[132:133], v[208:209], v[92:93] op_sel_hi:[0,1,1]
	v_pk_fma_f32 v[210:211], v[132:133], v[210:211], v[94:95] op_sel_hi:[0,1,1]
	s_waitcnt lgkmcnt(15)
	v_pk_fma_f32 v[128:129], v[64:65], v[196:197], v[192:193]
	v_pk_fma_f32 v[130:131], v[66:67], v[198:199], v[192:193]
	v_pk_fma_f32 v[128:129], v[68:69], v[200:201], v[128:129]
	v_pk_fma_f32 v[130:131], v[70:71], v[202:203], v[130:131]
	s_waitcnt lgkmcnt(14)
	v_pk_fma_f32 v[128:129], v[72:73], v[204:205], v[128:129]
	v_pk_fma_f32 v[130:131], v[74:75], v[206:207], v[130:131]
	s_waitcnt lgkmcnt(13)
	v_pk_fma_f32 v[128:129], v[76:77], v[208:209], v[128:129]
	v_pk_fma_f32 v[130:131], v[78:79], v[210:211], v[130:131]
	v_add_f32_e32 v128, v128, v129
	v_add_f32_e32 v130, v130, v131
	v_add_f32_e32 v190, v128, v130
	ds_read_b128 v[80:83], v188 offset:14336
	ds_read_b128 v[84:87], v188 offset:14592
	ds_read_b128 v[88:91], v188 offset:14848
	ds_read_b128 v[92:95], v188 offset:15104
	ds_read_b32 v134, v140 offset:35160
	ds_read_b32 v135, v189 offset:16768
	ds_read_b32 v132, v140 offset:35096
	ds_read_b128 v[64:67], v188 offset:6144
	ds_read_b128 v[68:71], v188 offset:6400
	ds_read_b128 v[72:75], v188 offset:6656
	ds_read_b128 v[76:79], v188 offset:6912
	s_waitcnt lgkmcnt(15)
	v_mul_f32_e32 v153, v154, v155
	v_pk_mul_f32 v[112:113], v[112:113], v[152:153] op_sel:[0,1] op_sel_hi:[1,1]
	v_add_f32_dpp v190, v190, v190 row_ror:8 row_mask:0xf bank_mask:0xf bound_ctrl:1
	v_pk_mul_f32 v[114:115], v[114:115], v[152:153] op_sel:[0,1] op_sel_hi:[1,1]
	v_pk_mul_f32 v[116:117], v[116:117], v[152:153] op_sel:[0,1] op_sel_hi:[1,1]
	v_add_f32_dpp v190, v190, v190 row_ror:4 row_mask:0xf bank_mask:0xf bound_ctrl:1
	v_pk_mul_f32 v[118:119], v[118:119], v[152:153] op_sel:[0,1] op_sel_hi:[1,1]
	v_pk_mul_f32 v[120:121], v[120:121], v[152:153] op_sel:[0,1] op_sel_hi:[1,1]
	v_add_f32_dpp v190, v190, v190 row_ror:2 row_mask:0xf bank_mask:0xf bound_ctrl:1
	v_pk_mul_f32 v[122:123], v[122:123], v[152:153] op_sel:[0,1] op_sel_hi:[1,1]
	v_pk_mul_f32 v[124:125], v[124:125], v[152:153] op_sel:[0,1] op_sel_hi:[1,1]
	v_add_f32_dpp v190, v190, v190 row_ror:1 row_mask:0xf bank_mask:0xf bound_ctrl:1
	v_pk_mul_f32 v[126:127], v[126:127], v[152:153] op_sel:[0,1] op_sel_hi:[1,1]
	v_pk_fma_f32 v[196:197], v[152:153], v[196:197], v[112:113] op_sel_hi:[0,1,1]
	s_and_saveexec_b64 s[8:9], s[44:45]
	ds_write_b32 v189, v190 offset:34304
	s_mov_b64 exec, s[8:9]
	v_pk_fma_f32 v[198:199], v[152:153], v[198:199], v[114:115] op_sel_hi:[0,1,1]
	v_pk_fma_f32 v[200:201], v[152:153], v[200:201], v[116:117] op_sel_hi:[0,1,1]
	v_pk_fma_f32 v[202:203], v[152:153], v[202:203], v[118:119] op_sel_hi:[0,1,1]
	v_pk_fma_f32 v[204:205], v[152:153], v[204:205], v[120:121] op_sel_hi:[0,1,1]
	v_pk_fma_f32 v[206:207], v[152:153], v[206:207], v[122:123] op_sel_hi:[0,1,1]
	v_pk_fma_f32 v[208:209], v[152:153], v[208:209], v[124:125] op_sel_hi:[0,1,1]
	v_pk_fma_f32 v[210:211], v[152:153], v[210:211], v[126:127] op_sel_hi:[0,1,1]
	s_waitcnt lgkmcnt(15)
	v_pk_fma_f32 v[128:129], v[96:97], v[196:197], v[192:193]
	v_pk_fma_f32 v[130:131], v[98:99], v[198:199], v[192:193]
	v_pk_fma_f32 v[128:129], v[100:101], v[200:201], v[128:129]
	v_pk_fma_f32 v[130:131], v[102:103], v[202:203], v[130:131]
	s_waitcnt lgkmcnt(14)
	v_pk_fma_f32 v[128:129], v[104:105], v[204:205], v[128:129]
	v_pk_fma_f32 v[130:131], v[106:107], v[206:207], v[130:131]
	s_waitcnt lgkmcnt(13)
	v_pk_fma_f32 v[128:129], v[108:109], v[208:209], v[128:129]
	v_pk_fma_f32 v[130:131], v[110:111], v[210:211], v[130:131]
	v_add_f32_e32 v128, v128, v129
	v_add_f32_e32 v130, v130, v131
	v_add_f32_e32 v191, v128, v130
	ds_read_b128 v[112:115], v188 offset:15360
	ds_read_b128 v[116:119], v188 offset:15616
	ds_read_b128 v[120:123], v188 offset:15872
	ds_read_b128 v[124:127], v188 offset:16128
	ds_read_b32 v154, v140 offset:35164
	ds_read_b32 v155, v189 offset:16832
	ds_read_b32 v152, v140 offset:35100
	ds_read_b128 v[96:99], v188 offset:7168
	ds_read_b128 v[100:103], v188 offset:7424
	ds_read_b128 v[104:107], v188 offset:7680
	ds_read_b128 v[108:111], v188 offset:7936
	s_waitcnt lgkmcnt(15)
	v_mul_f32_e32 v133, v134, v135
	v_pk_mul_f32 v[80:81], v[80:81], v[132:133] op_sel:[0,1] op_sel_hi:[1,1]
	v_add_f32_dpp v191, v191, v191 row_ror:8 row_mask:0xf bank_mask:0xf bound_ctrl:1
	v_pk_mul_f32 v[82:83], v[82:83], v[132:133] op_sel:[0,1] op_sel_hi:[1,1]
	v_pk_mul_f32 v[84:85], v[84:85], v[132:133] op_sel:[0,1] op_sel_hi:[1,1]
	v_add_f32_dpp v191, v191, v191 row_ror:4 row_mask:0xf bank_mask:0xf bound_ctrl:1
	v_pk_mul_f32 v[86:87], v[86:87], v[132:133] op_sel:[0,1] op_sel_hi:[1,1]
	v_pk_mul_f32 v[88:89], v[88:89], v[132:133] op_sel:[0,1] op_sel_hi:[1,1]
	v_add_f32_dpp v191, v191, v191 row_ror:2 row_mask:0xf bank_mask:0xf bound_ctrl:1
	v_pk_mul_f32 v[90:91], v[90:91], v[132:133] op_sel:[0,1] op_sel_hi:[1,1]
	v_pk_mul_f32 v[92:93], v[92:93], v[132:133] op_sel:[0,1] op_sel_hi:[1,1]
	v_add_f32_dpp v191, v191, v191 row_ror:1 row_mask:0xf bank_mask:0xf bound_ctrl:1
	v_pk_mul_f32 v[94:95], v[94:95], v[132:133] op_sel:[0,1] op_sel_hi:[1,1]
	v_pk_fma_f32 v[196:197], v[132:133], v[196:197], v[80:81] op_sel_hi:[0,1,1]
	s_and_saveexec_b64 s[8:9], s[44:45]
	ds_write_b32 v189, v191 offset:34368
	s_mov_b64 exec, s[8:9]
	v_pk_fma_f32 v[198:199], v[132:133], v[198:199], v[82:83] op_sel_hi:[0,1,1]
	v_pk_fma_f32 v[200:201], v[132:133], v[200:201], v[84:85] op_sel_hi:[0,1,1]
	v_pk_fma_f32 v[202:203], v[132:133], v[202:203], v[86:87] op_sel_hi:[0,1,1]
	v_pk_fma_f32 v[204:205], v[132:133], v[204:205], v[88:89] op_sel_hi:[0,1,1]
	v_pk_fma_f32 v[206:207], v[132:133], v[206:207], v[90:91] op_sel_hi:[0,1,1]
	v_pk_fma_f32 v[208:209], v[132:133], v[208:209], v[92:93] op_sel_hi:[0,1,1]
	v_pk_fma_f32 v[210:211], v[132:133], v[210:211], v[94:95] op_sel_hi:[0,1,1]
	s_waitcnt lgkmcnt(15)
	v_pk_fma_f32 v[128:129], v[64:65], v[196:197], v[192:193]
	v_pk_fma_f32 v[130:131], v[66:67], v[198:199], v[192:193]
	v_pk_fma_f32 v[128:129], v[68:69], v[200:201], v[128:129]
	v_pk_fma_f32 v[130:131], v[70:71], v[202:203], v[130:131]
	s_waitcnt lgkmcnt(14)
	v_pk_fma_f32 v[128:129], v[72:73], v[204:205], v[128:129]
	v_pk_fma_f32 v[130:131], v[74:75], v[206:207], v[130:131]
	s_waitcnt lgkmcnt(13)
	v_pk_fma_f32 v[128:129], v[76:77], v[208:209], v[128:129]
	v_pk_fma_f32 v[130:131], v[78:79], v[210:211], v[130:131]
	v_add_f32_e32 v128, v128, v129
	v_add_f32_e32 v130, v130, v131
	v_add_f32_e32 v190, v128, v130
	s_waitcnt lgkmcnt(6)
	v_mul_f32_e32 v153, v154, v155
	v_pk_mul_f32 v[112:113], v[112:113], v[152:153] op_sel:[0,1] op_sel_hi:[1,1]
	v_add_f32_dpp v190, v190, v190 row_ror:8 row_mask:0xf bank_mask:0xf bound_ctrl:1
	v_pk_mul_f32 v[114:115], v[114:115], v[152:153] op_sel:[0,1] op_sel_hi:[1,1]
	v_pk_mul_f32 v[116:117], v[116:117], v[152:153] op_sel:[0,1] op_sel_hi:[1,1]
	v_add_f32_dpp v190, v190, v190 row_ror:4 row_mask:0xf bank_mask:0xf bound_ctrl:1
	v_pk_mul_f32 v[118:119], v[118:119], v[152:153] op_sel:[0,1] op_sel_hi:[1,1]
	v_pk_mul_f32 v[120:121], v[120:121], v[152:153] op_sel:[0,1] op_sel_hi:[1,1]
	v_add_f32_dpp v190, v190, v190 row_ror:2 row_mask:0xf bank_mask:0xf bound_ctrl:1
	v_pk_mul_f32 v[122:123], v[122:123], v[152:153] op_sel:[0,1] op_sel_hi:[1,1]
	v_pk_mul_f32 v[124:125], v[124:125], v[152:153] op_sel:[0,1] op_sel_hi:[1,1]
	v_add_f32_dpp v190, v190, v190 row_ror:1 row_mask:0xf bank_mask:0xf bound_ctrl:1
	v_pk_mul_f32 v[126:127], v[126:127], v[152:153] op_sel:[0,1] op_sel_hi:[1,1]
	s_waitcnt lgkmcnt(5)
	v_pk_fma_f32 v[196:197], v[152:153], v[196:197], v[112:113] op_sel_hi:[0,1,1]
	s_and_saveexec_b64 s[8:9], s[44:45]
	ds_write_b32 v189, v190 offset:34432
	s_mov_b64 exec, s[8:9]
	v_pk_fma_f32 v[198:199], v[152:153], v[198:199], v[114:115] op_sel_hi:[0,1,1]
	v_pk_fma_f32 v[200:201], v[152:153], v[200:201], v[116:117] op_sel_hi:[0,1,1]
	v_pk_fma_f32 v[202:203], v[152:153], v[202:203], v[118:119] op_sel_hi:[0,1,1]
	v_pk_fma_f32 v[204:205], v[152:153], v[204:205], v[120:121] op_sel_hi:[0,1,1]
	v_pk_fma_f32 v[206:207], v[152:153], v[206:207], v[122:123] op_sel_hi:[0,1,1]
	v_pk_fma_f32 v[208:209], v[152:153], v[208:209], v[124:125] op_sel_hi:[0,1,1]
	v_pk_fma_f32 v[210:211], v[152:153], v[210:211], v[126:127] op_sel_hi:[0,1,1]
	s_waitcnt lgkmcnt(5)
	v_pk_fma_f32 v[128:129], v[96:97], v[196:197], v[192:193]
	v_pk_fma_f32 v[130:131], v[98:99], v[198:199], v[192:193]
	s_waitcnt lgkmcnt(4)
	v_pk_fma_f32 v[128:129], v[100:101], v[200:201], v[128:129]
	v_pk_fma_f32 v[130:131], v[102:103], v[202:203], v[130:131]
	s_waitcnt lgkmcnt(3)
	v_pk_fma_f32 v[128:129], v[104:105], v[204:205], v[128:129]
	v_pk_fma_f32 v[130:131], v[106:107], v[206:207], v[130:131]
	s_waitcnt lgkmcnt(2)
	v_pk_fma_f32 v[128:129], v[108:109], v[208:209], v[128:129]
	v_pk_fma_f32 v[130:131], v[110:111], v[210:211], v[130:131]
	v_add_f32_e32 v128, v128, v129
	v_add_f32_e32 v130, v130, v131
	v_add_f32_e32 v191, v128, v130
	s_nop 1
	v_add_f32_dpp v191, v191, v191 row_ror:8 row_mask:0xf bank_mask:0xf bound_ctrl:1
	s_nop 1
	v_add_f32_dpp v191, v191, v191 row_ror:4 row_mask:0xf bank_mask:0xf bound_ctrl:1
	s_nop 1
	v_add_f32_dpp v191, v191, v191 row_ror:2 row_mask:0xf bank_mask:0xf bound_ctrl:1
	s_nop 1
	v_add_f32_dpp v191, v191, v191 row_ror:1 row_mask:0xf bank_mask:0xf bound_ctrl:1
	s_and_saveexec_b64 s[8:9], s[44:45]
	ds_write_b32 v189, v191 offset:34496
	s_mov_b64 exec, s[8:9]
	s_waitcnt vmcnt(11)
	ds_write_b128 v185, v[16:19] offset:17024
	s_waitcnt vmcnt(9)
	ds_write_b128 v186, v[24:27] offset:17024
	ds_write_b128 v185, v[20:23] offset:25216
	s_waitcnt vmcnt(8)
	ds_write_b128 v186, v[28:31] offset:25216
	s_and_saveexec_b64 s[8:9], s[42:43]
	ds_write_b32 v144, v184 offset:33408
	s_or_b64 exec, exec, s[8:9]
	s_and_saveexec_b64 s[8:9], s[40:41]
	s_cbranch_execz .LBB0_1474
	v_add_f32_e32 v64, v156, v157
	v_mul_f32_e64 v65, |v64|, s62
	v_exp_f32_e32 v65, v65
	v_min_f32_e32 v64, 0, v64
	v_add_f32_e32 v65, 1.0, v65
	v_cmp_gt_f32_e32 vcc, s5, v65
	s_nop 1
	v_cndmask_b32_e64 v66, 0, 32, vcc
	v_ldexp_f32 v65, v65, v66
	v_log_f32_e32 v65, v65
	v_cndmask_b32_e32 v67, 0, v171, vcc
	v_add_f32_e32 v66, v145, v179
	v_mul_f32_e32 v68, 0x3f317217, v65
	v_fma_f32 v68, v65, s76, -v68
	v_fmac_f32_e32 v68, 0x3377d1cf, v65
	v_fmac_f32_e32 v68, 0x3f317217, v65
	v_cmp_lt_f32_e64 vcc, |v65|, s77
	s_nop 1
	v_cndmask_b32_e32 v65, v65, v68, vcc
	v_sub_f32_e32 v65, v65, v67
	v_sub_f32_e32 v64, v64, v65
	v_add_u32_e32 v65, 0x8400, v144
	ds_write2_b32 v65, v66, v64 offset0:32 offset1:48

.LBB0_1485:
	s_or_b64 exec, exec, s[8:9]
	s_waitcnt lgkmcnt(0)
	s_barrier
	v_mov_b32_e32 v192, 0
	v_mov_b32_e32 v193, 0
	ds_read_b128 v[80:83], v188 offset:25216
	ds_read_b128 v[84:87], v188 offset:25472
	ds_read_b128 v[88:91], v188 offset:25728
	ds_read_b128 v[92:95], v188 offset:25984
	ds_read_b32 v134, v140 offset:35136
	ds_read_b32 v135, v189 offset:33408
	ds_read_b32 v132, v140 offset:35072
	ds_read_b128 v[64:67], v188 offset:17024
	ds_read_b128 v[68:71], v188 offset:17280
	ds_read_b128 v[72:75], v188 offset:17536
	ds_read_b128 v[76:79], v188 offset:17792
	ds_read_b128 v[112:115], v188 offset:26240
	ds_read_b128 v[116:119], v188 offset:26496
	ds_read_b128 v[120:123], v188 offset:26752
	ds_read_b128 v[124:127], v188 offset:27008
	ds_read_b32 v154, v140 offset:35140
	ds_read_b32 v155, v189 offset:33472
	ds_read_b32 v152, v140 offset:35076
	ds_read_b128 v[96:99], v188 offset:18048
	ds_read_b128 v[100:103], v188 offset:18304
	ds_read_b128 v[104:107], v188 offset:18560
	ds_read_b128 v[108:111], v188 offset:18816
	s_waitcnt lgkmcnt(15)
	v_mul_f32_e32 v133, v134, v135
	v_pk_mul_f32 v[80:81], v[80:81], v[132:133] op_sel:[0,1] op_sel_hi:[1,1]
	v_pk_mul_f32 v[82:83], v[82:83], v[132:133] op_sel:[0,1] op_sel_hi:[1,1]
	v_pk_mul_f32 v[84:85], v[84:85], v[132:133] op_sel:[0,1] op_sel_hi:[1,1]
	v_pk_mul_f32 v[86:87], v[86:87], v[132:133] op_sel:[0,1] op_sel_hi:[1,1]
	v_pk_mul_f32 v[88:89], v[88:89], v[132:133] op_sel:[0,1] op_sel_hi:[1,1]
	v_pk_mul_f32 v[90:91], v[90:91], v[132:133] op_sel:[0,1] op_sel_hi:[1,1]
	v_pk_mul_f32 v[92:93], v[92:93], v[132:133] op_sel:[0,1] op_sel_hi:[1,1]
	v_pk_mul_f32 v[94:95], v[94:95], v[132:133] op_sel:[0,1] op_sel_hi:[1,1]
	v_pk_fma_f32 v[196:197], v[132:133], v[196:197], v[80:81] op_sel_hi:[0,1,1]
	v_pk_fma_f32 v[198:199], v[132:133], v[198:199], v[82:83] op_sel_hi:[0,1,1]
	v_pk_fma_f32 v[200:201], v[132:133], v[200:201], v[84:85] op_sel_hi:[0,1,1]
	v_pk_fma_f32 v[202:203], v[132:133], v[202:203], v[86:87] op_sel_hi:[0,1,1]
	v_pk_fma_f32 v[204:205], v[132:133], v[204:205], v[88:89] op_sel_hi:[0,1,1]
	v_pk_fma_f32 v[206:207], v[132:133], v[206:207], v[90:91] op_sel_hi:[0,1,1]
	v_pk_fma_f32 v[208:209], v[132:133], v[208:209], v[92:93] op_sel_hi:[0,1,1]
	v_pk_fma_f32 v[210:211], v[132:133], v[210:211], v[94:95] op_sel_hi:[0,1,1]
	s_waitcnt lgkmcnt(14)
	v_pk_fma_f32 v[128:129], v[64:65], v[196:197], v[192:193]
	v_pk_fma_f32 v[130:131], v[66:67], v[198:199], v[192:193]
	s_waitcnt lgkmcnt(13)
	v_pk_fma_f32 v[128:129], v[68:69], v[200:201], v[128:129]
	v_pk_fma_f32 v[130:131], v[70:71], v[202:203], v[130:131]
	s_waitcnt lgkmcnt(12)
	v_pk_fma_f32 v[128:129], v[72:73], v[204:205], v[128:129]
	v_pk_fma_f32 v[130:131], v[74:75], v[206:207], v[130:131]
	s_waitcnt lgkmcnt(11)
	v_pk_fma_f32 v[128:129], v[76:77], v[208:209], v[128:129]
	v_pk_fma_f32 v[130:131], v[78:79], v[210:211], v[130:131]
	v_add_f32_e32 v128, v128, v129
	v_add_f32_e32 v130, v130, v131
	v_add_f32_e32 v190, v128, v130
	ds_read_b128 v[80:83], v188 offset:27264
	ds_read_b128 v[84:87], v188 offset:27520
	ds_read_b128 v[88:91], v188 offset:27776
	ds_read_b128 v[92:95], v188 offset:28032
	ds_read_b32 v134, v140 offset:35144
	ds_read_b32 v135, v189 offset:33536
	ds_read_b32 v132, v140 offset:35080
	ds_read_b128 v[64:67], v188 offset:19072
	ds_read_b128 v[68:71], v188 offset:19328
	ds_read_b128 v[72:75], v188 offset:19584
	ds_read_b128 v[76:79], v188 offset:19840
	s_waitcnt lgkmcnt(15)
	v_mul_f32_e32 v153, v154, v155
	v_pk_mul_f32 v[112:113], v[112:113], v[152:153] op_sel:[0,1] op_sel_hi:[1,1]
	v_add_f32_dpp v190, v190, v190 row_ror:8 row_mask:0xf bank_mask:0xf bound_ctrl:1
	v_pk_mul_f32 v[114:115], v[114:115], v[152:153] op_sel:[0,1] op_sel_hi:[1,1]
	v_pk_mul_f32 v[116:117], v[116:117], v[152:153] op_sel:[0,1] op_sel_hi:[1,1]
	v_add_f32_dpp v190, v190, v190 row_ror:4 row_mask:0xf bank_mask:0xf bound_ctrl:1
	v_pk_mul_f32 v[118:119], v[118:119], v[152:153] op_sel:[0,1] op_sel_hi:[1,1]
	v_pk_mul_f32 v[120:121], v[120:121], v[152:153] op_sel:[0,1] op_sel_hi:[1,1]
	v_add_f32_dpp v190, v190, v190 row_ror:2 row_mask:0xf bank_mask:0xf bound_ctrl:1
	v_pk_mul_f32 v[122:123], v[122:123], v[152:153] op_sel:[0,1] op_sel_hi:[1,1]
	v_pk_mul_f32 v[124:125], v[124:125], v[152:153] op_sel:[0,1] op_sel_hi:[1,1]
	v_add_f32_dpp v190, v190, v190 row_ror:1 row_mask:0xf bank_mask:0xf bound_ctrl:1
	v_pk_mul_f32 v[126:127], v[126:127], v[152:153] op_sel:[0,1] op_sel_hi:[1,1]
	v_pk_fma_f32 v[196:197], v[152:153], v[196:197], v[112:113] op_sel_hi:[0,1,1]
	s_and_saveexec_b64 s[8:9], s[44:45]
	ds_write_b32 v189, v190 offset:34560
	s_mov_b64 exec, s[8:9]
	v_pk_fma_f32 v[198:199], v[152:153], v[198:199], v[114:115] op_sel_hi:[0,1,1]
	v_pk_fma_f32 v[200:201], v[152:153], v[200:201], v[116:117] op_sel_hi:[0,1,1]
	v_pk_fma_f32 v[202:203], v[152:153], v[202:203], v[118:119] op_sel_hi:[0,1,1]
	v_pk_fma_f32 v[204:205], v[152:153], v[204:205], v[120:121] op_sel_hi:[0,1,1]
	v_pk_fma_f32 v[206:207], v[152:153], v[206:207], v[122:123] op_sel_hi:[0,1,1]
	v_pk_fma_f32 v[208:209], v[152:153], v[208:209], v[124:125] op_sel_hi:[0,1,1]
	v_pk_fma_f32 v[210:211], v[152:153], v[210:211], v[126:127] op_sel_hi:[0,1,1]
	s_waitcnt lgkmcnt(15)
	v_pk_fma_f32 v[128:129], v[96:97], v[196:197], v[192:193]
	v_pk_fma_f32 v[130:131], v[98:99], v[198:199], v[192:193]
	s_waitcnt lgkmcnt(14)
	v_pk_fma_f32 v[128:129], v[100:101], v[200:201], v[128:129]
	v_pk_fma_f32 v[130:131], v[102:103], v[202:203], v[130:131]
	s_waitcnt lgkmcnt(13)
	v_pk_fma_f32 v[128:129], v[104:105], v[204:205], v[128:129]
	v_pk_fma_f32 v[130:131], v[106:107], v[206:207], v[130:131]
	s_waitcnt lgkmcnt(12)
	v_pk_fma_f32 v[128:129], v[108:109], v[208:209], v[128:129]
	v_pk_fma_f32 v[130:131], v[110:111], v[210:211], v[130:131]
	v_add_f32_e32 v128, v128, v129
	v_add_f32_e32 v130, v130, v131
	v_add_f32_e32 v191, v128, v130
	ds_read_b128 v[112:115], v188 offset:28288
	ds_read_b128 v[116:119], v188 offset:28544
	ds_read_b128 v[120:123], v188 offset:28800
	ds_read_b128 v[124:127], v188 offset:29056
	ds_read_b32 v154, v140 offset:35148
	ds_read_b32 v155, v189 offset:33600
	ds_read_b32 v152, v140 offset:35084
	ds_read_b128 v[96:99], v188 offset:20096
	ds_read_b128 v[100:103], v188 offset:20352
	ds_read_b128 v[104:107], v188 offset:20608
	ds_read_b128 v[108:111], v188 offset:20864
	s_waitcnt lgkmcnt(15)
	v_mul_f32_e32 v133, v134, v135
	v_pk_mul_f32 v[80:81], v[80:81], v[132:133] op_sel:[0,1] op_sel_hi:[1,1]
	v_add_f32_dpp v191, v191, v191 row_ror:8 row_mask:0xf bank_mask:0xf bound_ctrl:1
	v_pk_mul_f32 v[82:83], v[82:83], v[132:133] op_sel:[0,1] op_sel_hi:[1,1]
	v_pk_mul_f32 v[84:85], v[84:85], v[132:133] op_sel:[0,1] op_sel_hi:[1,1]
	v_add_f32_dpp v191, v191, v191 row_ror:4 row_mask:0xf bank_mask:0xf bound_ctrl:1
	v_pk_mul_f32 v[86:87], v[86:87], v[132:133] op_sel:[0,1] op_sel_hi:[1,1]
	v_pk_mul_f32 v[88:89], v[88:89], v[132:133] op_sel:[0,1] op_sel_hi:[1,1]
	v_add_f32_dpp v191, v191, v191 row_ror:2 row_mask:0xf bank_mask:0xf bound_ctrl:1
	v_pk_mul_f32 v[90:91], v[90:91], v[132:133] op_sel:[0,1] op_sel_hi:[1,1]
	v_pk_mul_f32 v[92:93], v[92:93], v[132:133] op_sel:[0,1] op_sel_hi:[1,1]
	v_add_f32_dpp v191, v191, v191 row_ror:1 row_mask:0xf bank_mask:0xf bound_ctrl:1
	v_pk_mul_f32 v[94:95], v[94:95], v[132:133] op_sel:[0,1] op_sel_hi:[1,1]
	v_pk_fma_f32 v[196:197], v[132:133], v[196:197], v[80:81] op_sel_hi:[0,1,1]
	s_and_saveexec_b64 s[8:9], s[44:45]
	ds_write_b32 v189, v191 offset:34624
	s_mov_b64 exec, s[8:9]
	v_pk_fma_f32 v[198:199], v[132:133], v[198:199], v[82:83] op_sel_hi:[0,1,1]
	v_pk_fma_f32 v[200:201], v[132:133], v[200:201], v[84:85] op_sel_hi:[0,1,1]
	v_pk_fma_f32 v[202:203], v[132:133], v[202:203], v[86:87] op_sel_hi:[0,1,1]
	v_pk_fma_f32 v[204:205], v[132:133], v[204:205], v[88:89] op_sel_hi:[0,1,1]
	v_pk_fma_f32 v[206:207], v[132:133], v[206:207], v[90:91] op_sel_hi:[0,1,1]
	v_pk_fma_f32 v[208:209], v[132:133], v[208:209], v[92:93] op_sel_hi:[0,1,1]
	v_pk_fma_f32 v[210:211], v[132:133], v[210:211], v[94:95] op_sel_hi:[0,1,1]
	s_waitcnt lgkmcnt(15)
	v_pk_fma_f32 v[128:129], v[64:65], v[196:197], v[192:193]
	v_pk_fma_f32 v[130:131], v[66:67], v[198:199], v[192:193]
	v_pk_fma_f32 v[128:129], v[68:69], v[200:201], v[128:129]
	v_pk_fma_f32 v[130:131], v[70:71], v[202:203], v[130:131]
	s_waitcnt lgkmcnt(14)
	v_pk_fma_f32 v[128:129], v[72:73], v[204:205], v[128:129]
	v_pk_fma_f32 v[130:131], v[74:75], v[206:207], v[130:131]
	s_waitcnt lgkmcnt(13)
	v_pk_fma_f32 v[128:129], v[76:77], v[208:209], v[128:129]
	v_pk_fma_f32 v[130:131], v[78:79], v[210:211], v[130:131]
	v_add_f32_e32 v128, v128, v129
	v_add_f32_e32 v130, v130, v131
	v_add_f32_e32 v190, v128, v130
	ds_read_b128 v[80:83], v188 offset:29312
	ds_read_b128 v[84:87], v188 offset:29568
	ds_read_b128 v[88:91], v188 offset:29824
	ds_read_b128 v[92:95], v188 offset:30080
	ds_read_b32 v134, v140 offset:35152
	ds_read_b32 v135, v189 offset:33664
	ds_read_b32 v132, v140 offset:35088
	ds_read_b128 v[64:67], v188 offset:21120
	ds_read_b128 v[68:71], v188 offset:21376
	ds_read_b128 v[72:75], v188 offset:21632
	ds_read_b128 v[76:79], v188 offset:21888
	s_waitcnt lgkmcnt(15)
	v_mul_f32_e32 v153, v154, v155
	v_pk_mul_f32 v[112:113], v[112:113], v[152:153] op_sel:[0,1] op_sel_hi:[1,1]
	v_add_f32_dpp v190, v190, v190 row_ror:8 row_mask:0xf bank_mask:0xf bound_ctrl:1
	v_pk_mul_f32 v[114:115], v[114:115], v[152:153] op_sel:[0,1] op_sel_hi:[1,1]
	v_pk_mul_f32 v[116:117], v[116:117], v[152:153] op_sel:[0,1] op_sel_hi:[1,1]
	v_add_f32_dpp v190, v190, v190 row_ror:4 row_mask:0xf bank_mask:0xf bound_ctrl:1
	v_pk_mul_f32 v[118:119], v[118:119], v[152:153] op_sel:[0,1] op_sel_hi:[1,1]
	v_pk_mul_f32 v[120:121], v[120:121], v[152:153] op_sel:[0,1] op_sel_hi:[1,1]
	v_add_f32_dpp v190, v190, v190 row_ror:2 row_mask:0xf bank_mask:0xf bound_ctrl:1
	v_pk_mul_f32 v[122:123], v[122:123], v[152:153] op_sel:[0,1] op_sel_hi:[1,1]
	v_pk_mul_f32 v[124:125], v[124:125], v[152:153] op_sel:[0,1] op_sel_hi:[1,1]
	v_add_f32_dpp v190, v190, v190 row_ror:1 row_mask:0xf bank_mask:0xf bound_ctrl:1
	v_pk_mul_f32 v[126:127], v[126:127], v[152:153] op_sel:[0,1] op_sel_hi:[1,1]
	v_pk_fma_f32 v[196:197], v[152:153], v[196:197], v[112:113] op_sel_hi:[0,1,1]
	s_and_saveexec_b64 s[8:9], s[44:45]
	ds_write_b32 v189, v190 offset:34688
	s_mov_b64 exec, s[8:9]
	v_pk_fma_f32 v[198:199], v[152:153], v[198:199], v[114:115] op_sel_hi:[0,1,1]
	v_pk_fma_f32 v[200:201], v[152:153], v[200:201], v[116:117] op_sel_hi:[0,1,1]
	v_pk_fma_f32 v[202:203], v[152:153], v[202:203], v[118:119] op_sel_hi:[0,1,1]
	v_pk_fma_f32 v[204:205], v[152:153], v[204:205], v[120:121] op_sel_hi:[0,1,1]
	v_pk_fma_f32 v[206:207], v[152:153], v[206:207], v[122:123] op_sel_hi:[0,1,1]
	v_pk_fma_f32 v[208:209], v[152:153], v[208:209], v[124:125] op_sel_hi:[0,1,1]
	v_pk_fma_f32 v[210:211], v[152:153], v[210:211], v[126:127] op_sel_hi:[0,1,1]
	s_waitcnt lgkmcnt(15)
	v_pk_fma_f32 v[128:129], v[96:97], v[196:197], v[192:193]
	v_pk_fma_f32 v[130:131], v[98:99], v[198:199], v[192:193]
	v_pk_fma_f32 v[128:129], v[100:101], v[200:201], v[128:129]
	v_pk_fma_f32 v[130:131], v[102:103], v[202:203], v[130:131]
	s_waitcnt lgkmcnt(14)
	v_pk_fma_f32 v[128:129], v[104:105], v[204:205], v[128:129]
	v_pk_fma_f32 v[130:131], v[106:107], v[206:207], v[130:131]
	s_waitcnt lgkmcnt(13)
	v_pk_fma_f32 v[128:129], v[108:109], v[208:209], v[128:129]
	v_pk_fma_f32 v[130:131], v[110:111], v[210:211], v[130:131]
	v_add_f32_e32 v128, v128, v129
	v_add_f32_e32 v130, v130, v131
	v_add_f32_e32 v191, v128, v130
	ds_read_b128 v[112:115], v188 offset:30336
	ds_read_b128 v[116:119], v188 offset:30592
	ds_read_b128 v[120:123], v188 offset:30848
	ds_read_b128 v[124:127], v188 offset:31104
	ds_read_b32 v154, v140 offset:35156
	ds_read_b32 v155, v189 offset:33728
	ds_read_b32 v152, v140 offset:35092
	ds_read_b128 v[96:99], v188 offset:22144
	ds_read_b128 v[100:103], v188 offset:22400
	ds_read_b128 v[104:107], v188 offset:22656
	ds_read_b128 v[108:111], v188 offset:22912
	s_waitcnt lgkmcnt(15)
	v_mul_f32_e32 v133, v134, v135
	v_pk_mul_f32 v[80:81], v[80:81], v[132:133] op_sel:[0,1] op_sel_hi:[1,1]
	v_add_f32_dpp v191, v191, v191 row_ror:8 row_mask:0xf bank_mask:0xf bound_ctrl:1
	v_pk_mul_f32 v[82:83], v[82:83], v[132:133] op_sel:[0,1] op_sel_hi:[1,1]
	v_pk_mul_f32 v[84:85], v[84:85], v[132:133] op_sel:[0,1] op_sel_hi:[1,1]
	v_add_f32_dpp v191, v191, v191 row_ror:4 row_mask:0xf bank_mask:0xf bound_ctrl:1
	v_pk_mul_f32 v[86:87], v[86:87], v[132:133] op_sel:[0,1] op_sel_hi:[1,1]
	v_pk_mul_f32 v[88:89], v[88:89], v[132:133] op_sel:[0,1] op_sel_hi:[1,1]
	v_add_f32_dpp v191, v191, v191 row_ror:2 row_mask:0xf bank_mask:0xf bound_ctrl:1
	v_pk_mul_f32 v[90:91], v[90:91], v[132:133] op_sel:[0,1] op_sel_hi:[1,1]
	v_pk_mul_f32 v[92:93], v[92:93], v[132:133] op_sel:[0,1] op_sel_hi:[1,1]
	v_add_f32_dpp v191, v191, v191 row_ror:1 row_mask:0xf bank_mask:0xf bound_ctrl:1
	v_pk_mul_f32 v[94:95], v[94:95], v[132:133] op_sel:[0,1] op_sel_hi:[1,1]
	v_pk_fma_f32 v[196:197], v[132:133], v[196:197], v[80:81] op_sel_hi:[0,1,1]
	s_and_saveexec_b64 s[8:9], s[44:45]
	ds_write_b32 v189, v191 offset:34752
	s_mov_b64 exec, s[8:9]
	v_pk_fma_f32 v[198:199], v[132:133], v[198:199], v[82:83] op_sel_hi:[0,1,1]
	v_pk_fma_f32 v[200:201], v[132:133], v[200:201], v[84:85] op_sel_hi:[0,1,1]
	v_pk_fma_f32 v[202:203], v[132:133], v[202:203], v[86:87] op_sel_hi:[0,1,1]
	v_pk_fma_f32 v[204:205], v[132:133], v[204:205], v[88:89] op_sel_hi:[0,1,1]
	v_pk_fma_f32 v[206:207], v[132:133], v[206:207], v[90:91] op_sel_hi:[0,1,1]
	v_pk_fma_f32 v[208:209], v[132:133], v[208:209], v[92:93] op_sel_hi:[0,1,1]
	v_pk_fma_f32 v[210:211], v[132:133], v[210:211], v[94:95] op_sel_hi:[0,1,1]
	s_waitcnt lgkmcnt(15)
	v_pk_fma_f32 v[128:129], v[64:65], v[196:197], v[192:193]
	v_pk_fma_f32 v[130:131], v[66:67], v[198:199], v[192:193]
	v_pk_fma_f32 v[128:129], v[68:69], v[200:201], v[128:129]
	v_pk_fma_f32 v[130:131], v[70:71], v[202:203], v[130:131]
	s_waitcnt lgkmcnt(14)
	v_pk_fma_f32 v[128:129], v[72:73], v[204:205], v[128:129]
	v_pk_fma_f32 v[130:131], v[74:75], v[206:207], v[130:131]
	s_waitcnt lgkmcnt(13)
	v_pk_fma_f32 v[128:129], v[76:77], v[208:209], v[128:129]
	v_pk_fma_f32 v[130:131], v[78:79], v[210:211], v[130:131]
	v_add_f32_e32 v128, v128, v129
	v_add_f32_e32 v130, v130, v131
	v_add_f32_e32 v190, v128, v130
	ds_read_b128 v[80:83], v188 offset:31360
	ds_read_b128 v[84:87], v188 offset:31616
	ds_read_b128 v[88:91], v188 offset:31872
	ds_read_b128 v[92:95], v188 offset:32128
	ds_read_b32 v134, v140 offset:35160
	ds_read_b32 v135, v189 offset:33792
	ds_read_b32 v132, v140 offset:35096
	ds_read_b128 v[64:67], v188 offset:23168
	ds_read_b128 v[68:71], v188 offset:23424
	ds_read_b128 v[72:75], v188 offset:23680
	ds_read_b128 v[76:79], v188 offset:23936
	s_waitcnt lgkmcnt(15)
	v_mul_f32_e32 v153, v154, v155
	v_pk_mul_f32 v[112:113], v[112:113], v[152:153] op_sel:[0,1] op_sel_hi:[1,1]
	v_add_f32_dpp v190, v190, v190 row_ror:8 row_mask:0xf bank_mask:0xf bound_ctrl:1
	v_pk_mul_f32 v[114:115], v[114:115], v[152:153] op_sel:[0,1] op_sel_hi:[1,1]
	v_pk_mul_f32 v[116:117], v[116:117], v[152:153] op_sel:[0,1] op_sel_hi:[1,1]
	v_add_f32_dpp v190, v190, v190 row_ror:4 row_mask:0xf bank_mask:0xf bound_ctrl:1
	v_pk_mul_f32 v[118:119], v[118:119], v[152:153] op_sel:[0,1] op_sel_hi:[1,1]
	v_pk_mul_f32 v[120:121], v[120:121], v[152:153] op_sel:[0,1] op_sel_hi:[1,1]
	v_add_f32_dpp v190, v190, v190 row_ror:2 row_mask:0xf bank_mask:0xf bound_ctrl:1
	v_pk_mul_f32 v[122:123], v[122:123], v[152:153] op_sel:[0,1] op_sel_hi:[1,1]
	v_pk_mul_f32 v[124:125], v[124:125], v[152:153] op_sel:[0,1] op_sel_hi:[1,1]
	v_add_f32_dpp v190, v190, v190 row_ror:1 row_mask:0xf bank_mask:0xf bound_ctrl:1
	v_pk_mul_f32 v[126:127], v[126:127], v[152:153] op_sel:[0,1] op_sel_hi:[1,1]
	v_pk_fma_f32 v[196:197], v[152:153], v[196:197], v[112:113] op_sel_hi:[0,1,1]
	s_and_saveexec_b64 s[8:9], s[44:45]
	ds_write_b32 v189, v190 offset:34816
	s_mov_b64 exec, s[8:9]
	v_pk_fma_f32 v[198:199], v[152:153], v[198:199], v[114:115] op_sel_hi:[0,1,1]
	v_pk_fma_f32 v[200:201], v[152:153], v[200:201], v[116:117] op_sel_hi:[0,1,1]
	v_pk_fma_f32 v[202:203], v[152:153], v[202:203], v[118:119] op_sel_hi:[0,1,1]
	v_pk_fma_f32 v[204:205], v[152:153], v[204:205], v[120:121] op_sel_hi:[0,1,1]
	v_pk_fma_f32 v[206:207], v[152:153], v[206:207], v[122:123] op_sel_hi:[0,1,1]
	v_pk_fma_f32 v[208:209], v[152:153], v[208:209], v[124:125] op_sel_hi:[0,1,1]
	v_pk_fma_f32 v[210:211], v[152:153], v[210:211], v[126:127] op_sel_hi:[0,1,1]
	s_waitcnt lgkmcnt(15)
	v_pk_fma_f32 v[128:129], v[96:97], v[196:197], v[192:193]
	v_pk_fma_f32 v[130:131], v[98:99], v[198:199], v[192:193]
	v_pk_fma_f32 v[128:129], v[100:101], v[200:201], v[128:129]
	v_pk_fma_f32 v[130:131], v[102:103], v[202:203], v[130:131]
	s_waitcnt lgkmcnt(14)
	v_pk_fma_f32 v[128:129], v[104:105], v[204:205], v[128:129]
	v_pk_fma_f32 v[130:131], v[106:107], v[206:207], v[130:131]
	s_waitcnt lgkmcnt(13)
	v_pk_fma_f32 v[128:129], v[108:109], v[208:209], v[128:129]
	v_pk_fma_f32 v[130:131], v[110:111], v[210:211], v[130:131]
	v_add_f32_e32 v128, v128, v129
	v_add_f32_e32 v130, v130, v131
	v_add_f32_e32 v191, v128, v130
	ds_read_b128 v[112:115], v188 offset:32384
	ds_read_b128 v[116:119], v188 offset:32640
	ds_read_b128 v[120:123], v188 offset:32896
	ds_read_b128 v[124:127], v188 offset:33152
	ds_read_b32 v154, v140 offset:35164
	ds_read_b32 v155, v189 offset:33856
	ds_read_b32 v152, v140 offset:35100
	ds_read_b128 v[96:99], v188 offset:24192
	ds_read_b128 v[100:103], v188 offset:24448
	ds_read_b128 v[104:107], v188 offset:24704
	ds_read_b128 v[108:111], v188 offset:24960
	s_waitcnt lgkmcnt(15)
	v_mul_f32_e32 v133, v134, v135
	v_pk_mul_f32 v[80:81], v[80:81], v[132:133] op_sel:[0,1] op_sel_hi:[1,1]
	v_add_f32_dpp v191, v191, v191 row_ror:8 row_mask:0xf bank_mask:0xf bound_ctrl:1
	v_pk_mul_f32 v[82:83], v[82:83], v[132:133] op_sel:[0,1] op_sel_hi:[1,1]
	v_pk_mul_f32 v[84:85], v[84:85], v[132:133] op_sel:[0,1] op_sel_hi:[1,1]
	v_add_f32_dpp v191, v191, v191 row_ror:4 row_mask:0xf bank_mask:0xf bound_ctrl:1
	v_pk_mul_f32 v[86:87], v[86:87], v[132:133] op_sel:[0,1] op_sel_hi:[1,1]
	v_pk_mul_f32 v[88:89], v[88:89], v[132:133] op_sel:[0,1] op_sel_hi:[1,1]
	v_add_f32_dpp v191, v191, v191 row_ror:2 row_mask:0xf bank_mask:0xf bound_ctrl:1
	v_pk_mul_f32 v[90:91], v[90:91], v[132:133] op_sel:[0,1] op_sel_hi:[1,1]
	v_pk_mul_f32 v[92:93], v[92:93], v[132:133] op_sel:[0,1] op_sel_hi:[1,1]
	v_add_f32_dpp v191, v191, v191 row_ror:1 row_mask:0xf bank_mask:0xf bound_ctrl:1
	v_pk_mul_f32 v[94:95], v[94:95], v[132:133] op_sel:[0,1] op_sel_hi:[1,1]
	v_pk_fma_f32 v[196:197], v[132:133], v[196:197], v[80:81] op_sel_hi:[0,1,1]
	s_and_saveexec_b64 s[8:9], s[44:45]
	ds_write_b32 v189, v191 offset:34880
	s_mov_b64 exec, s[8:9]
	v_pk_fma_f32 v[198:199], v[132:133], v[198:199], v[82:83] op_sel_hi:[0,1,1]
	v_pk_fma_f32 v[200:201], v[132:133], v[200:201], v[84:85] op_sel_hi:[0,1,1]
	v_pk_fma_f32 v[202:203], v[132:133], v[202:203], v[86:87] op_sel_hi:[0,1,1]
	v_pk_fma_f32 v[204:205], v[132:133], v[204:205], v[88:89] op_sel_hi:[0,1,1]
	v_pk_fma_f32 v[206:207], v[132:133], v[206:207], v[90:91] op_sel_hi:[0,1,1]
	v_pk_fma_f32 v[208:209], v[132:133], v[208:209], v[92:93] op_sel_hi:[0,1,1]
	v_pk_fma_f32 v[210:211], v[132:133], v[210:211], v[94:95] op_sel_hi:[0,1,1]
	s_waitcnt lgkmcnt(15)
	v_pk_fma_f32 v[128:129], v[64:65], v[196:197], v[192:193]
	v_pk_fma_f32 v[130:131], v[66:67], v[198:199], v[192:193]
	v_pk_fma_f32 v[128:129], v[68:69], v[200:201], v[128:129]
	v_pk_fma_f32 v[130:131], v[70:71], v[202:203], v[130:131]
	s_waitcnt lgkmcnt(14)
	v_pk_fma_f32 v[128:129], v[72:73], v[204:205], v[128:129]
	v_pk_fma_f32 v[130:131], v[74:75], v[206:207], v[130:131]
	s_waitcnt lgkmcnt(13)
	v_pk_fma_f32 v[128:129], v[76:77], v[208:209], v[128:129]
	v_pk_fma_f32 v[130:131], v[78:79], v[210:211], v[130:131]
	v_add_f32_e32 v128, v128, v129
	v_add_f32_e32 v130, v130, v131
	v_add_f32_e32 v190, v128, v130
	s_waitcnt lgkmcnt(6)
	v_mul_f32_e32 v153, v154, v155
	v_pk_mul_f32 v[112:113], v[112:113], v[152:153] op_sel:[0,1] op_sel_hi:[1,1]
	v_add_f32_dpp v190, v190, v190 row_ror:8 row_mask:0xf bank_mask:0xf bound_ctrl:1
	v_pk_mul_f32 v[114:115], v[114:115], v[152:153] op_sel:[0,1] op_sel_hi:[1,1]
	v_pk_mul_f32 v[116:117], v[116:117], v[152:153] op_sel:[0,1] op_sel_hi:[1,1]
	v_add_f32_dpp v190, v190, v190 row_ror:4 row_mask:0xf bank_mask:0xf bound_ctrl:1
	v_pk_mul_f32 v[118:119], v[118:119], v[152:153] op_sel:[0,1] op_sel_hi:[1,1]
	v_pk_mul_f32 v[120:121], v[120:121], v[152:153] op_sel:[0,1] op_sel_hi:[1,1]
	v_add_f32_dpp v190, v190, v190 row_ror:2 row_mask:0xf bank_mask:0xf bound_ctrl:1
	v_pk_mul_f32 v[122:123], v[122:123], v[152:153] op_sel:[0,1] op_sel_hi:[1,1]
	v_pk_mul_f32 v[124:125], v[124:125], v[152:153] op_sel:[0,1] op_sel_hi:[1,1]
	v_add_f32_dpp v190, v190, v190 row_ror:1 row_mask:0xf bank_mask:0xf bound_ctrl:1
	v_pk_mul_f32 v[126:127], v[126:127], v[152:153] op_sel:[0,1] op_sel_hi:[1,1]
	s_waitcnt lgkmcnt(5)
	v_pk_fma_f32 v[196:197], v[152:153], v[196:197], v[112:113] op_sel_hi:[0,1,1]
	s_and_saveexec_b64 s[8:9], s[44:45]
	ds_write_b32 v189, v190 offset:34944
	s_mov_b64 exec, s[8:9]
	v_pk_fma_f32 v[198:199], v[152:153], v[198:199], v[114:115] op_sel_hi:[0,1,1]
	v_pk_fma_f32 v[200:201], v[152:153], v[200:201], v[116:117] op_sel_hi:[0,1,1]
	v_pk_fma_f32 v[202:203], v[152:153], v[202:203], v[118:119] op_sel_hi:[0,1,1]
	v_pk_fma_f32 v[204:205], v[152:153], v[204:205], v[120:121] op_sel_hi:[0,1,1]
	v_pk_fma_f32 v[206:207], v[152:153], v[206:207], v[122:123] op_sel_hi:[0,1,1]
	v_pk_fma_f32 v[208:209], v[152:153], v[208:209], v[124:125] op_sel_hi:[0,1,1]
	v_pk_fma_f32 v[210:211], v[152:153], v[210:211], v[126:127] op_sel_hi:[0,1,1]
	s_waitcnt lgkmcnt(5)
	v_pk_fma_f32 v[128:129], v[96:97], v[196:197], v[192:193]
	v_pk_fma_f32 v[130:131], v[98:99], v[198:199], v[192:193]
	s_waitcnt lgkmcnt(4)
	v_pk_fma_f32 v[128:129], v[100:101], v[200:201], v[128:129]
	v_pk_fma_f32 v[130:131], v[102:103], v[202:203], v[130:131]
	s_waitcnt lgkmcnt(3)
	v_pk_fma_f32 v[128:129], v[104:105], v[204:205], v[128:129]
	v_pk_fma_f32 v[130:131], v[106:107], v[206:207], v[130:131]
	s_waitcnt lgkmcnt(2)
	v_pk_fma_f32 v[128:129], v[108:109], v[208:209], v[128:129]
	v_pk_fma_f32 v[130:131], v[110:111], v[210:211], v[130:131]
	v_add_f32_e32 v128, v128, v129
	v_add_f32_e32 v130, v130, v131
	v_add_f32_e32 v191, v128, v130
	s_nop 1
	v_add_f32_dpp v191, v191, v191 row_ror:8 row_mask:0xf bank_mask:0xf bound_ctrl:1
	s_nop 1
	v_add_f32_dpp v191, v191, v191 row_ror:4 row_mask:0xf bank_mask:0xf bound_ctrl:1
	s_nop 1
	v_add_f32_dpp v191, v191, v191 row_ror:2 row_mask:0xf bank_mask:0xf bound_ctrl:1
	s_nop 1
	v_add_f32_dpp v191, v191, v191 row_ror:1 row_mask:0xf bank_mask:0xf bound_ctrl:1
	s_and_saveexec_b64 s[8:9], s[44:45]
	ds_write_b32 v189, v191 offset:35008
	s_mov_b64 exec, s[8:9]
	s_waitcnt vmcnt(7)
	ds_write_b128 v185, v[32:35]
	s_waitcnt vmcnt(5)
	ds_write_b128 v186, v[40:43]
	ds_write_b128 v185, v[36:39] offset:8192
	s_waitcnt vmcnt(4)
	ds_write_b128 v186, v[44:47] offset:8192
	s_and_saveexec_b64 s[8:9], s[42:43]
	ds_write_b32 v144, v184 offset:16384
	s_or_b64 exec, exec, s[8:9]
	s_and_saveexec_b64 s[8:9], s[40:41]
	s_cbranch_execz .LBB0_1505
	v_add_f32_e32 v64, v156, v182
	v_mul_f32_e64 v65, |v64|, s62
	v_exp_f32_e32 v65, v65
	v_min_f32_e32 v64, 0, v64
	v_add_f32_e32 v65, 1.0, v65
	v_cmp_gt_f32_e32 vcc, s5, v65
	s_nop 1
	v_cndmask_b32_e64 v66, 0, 32, vcc
	v_ldexp_f32 v65, v65, v66
	v_log_f32_e32 v65, v65
	v_cndmask_b32_e32 v67, 0, v171, vcc
	v_add_f32_e32 v66, v145, v180
	v_mul_f32_e32 v68, 0x3f317217, v65
	v_fma_f32 v68, v65, s76, -v68
	v_fmac_f32_e32 v68, 0x3377d1cf, v65
	v_fmac_f32_e32 v68, 0x3f317217, v65
	v_cmp_lt_f32_e64 vcc, |v65|, s77
	s_nop 1
	v_cndmask_b32_e32 v65, v65, v68, vcc
	v_sub_f32_e32 v65, v65, v67
	v_sub_f32_e32 v64, v64, v65
	v_add_u32_e32 v65, 0x4000, v144
	ds_write2_b32 v65, v66, v64 offset0:128 offset1:144

.LBB0_1516:
	s_or_b64 exec, exec, s[8:9]
	s_waitcnt lgkmcnt(0)
	s_barrier
	v_mov_b32_e32 v192, 0
	v_mov_b32_e32 v193, 0
	ds_read_b128 v[80:83], v188 offset:8192
	ds_read_b128 v[84:87], v188 offset:8448
	ds_read_b128 v[88:91], v188 offset:8704
	ds_read_b128 v[92:95], v188 offset:8960
	ds_read_b32 v134, v140 offset:35136
	ds_read_b32 v135, v189 offset:16384
	ds_read_b32 v132, v140 offset:35072
	ds_read_b128 v[64:67], v188
	ds_read_b128 v[68:71], v188 offset:256
	ds_read_b128 v[72:75], v188 offset:512
	ds_read_b128 v[76:79], v188 offset:768
	ds_read_b128 v[112:115], v188 offset:9216
	ds_read_b128 v[116:119], v188 offset:9472
	ds_read_b128 v[120:123], v188 offset:9728
	ds_read_b128 v[124:127], v188 offset:9984
	ds_read_b32 v154, v140 offset:35140
	ds_read_b32 v155, v189 offset:16448
	ds_read_b32 v152, v140 offset:35076
	ds_read_b128 v[96:99], v188 offset:1024
	ds_read_b128 v[100:103], v188 offset:1280
	ds_read_b128 v[104:107], v188 offset:1536
	ds_read_b128 v[108:111], v188 offset:1792
	s_waitcnt lgkmcnt(15)
	v_mul_f32_e32 v133, v134, v135
	v_pk_mul_f32 v[80:81], v[80:81], v[132:133] op_sel:[0,1] op_sel_hi:[1,1]
	v_pk_mul_f32 v[82:83], v[82:83], v[132:133] op_sel:[0,1] op_sel_hi:[1,1]
	v_pk_mul_f32 v[84:85], v[84:85], v[132:133] op_sel:[0,1] op_sel_hi:[1,1]
	v_pk_mul_f32 v[86:87], v[86:87], v[132:133] op_sel:[0,1] op_sel_hi:[1,1]
	v_pk_mul_f32 v[88:89], v[88:89], v[132:133] op_sel:[0,1] op_sel_hi:[1,1]
	v_pk_mul_f32 v[90:91], v[90:91], v[132:133] op_sel:[0,1] op_sel_hi:[1,1]
	v_pk_mul_f32 v[92:93], v[92:93], v[132:133] op_sel:[0,1] op_sel_hi:[1,1]
	v_pk_mul_f32 v[94:95], v[94:95], v[132:133] op_sel:[0,1] op_sel_hi:[1,1]
	v_pk_fma_f32 v[196:197], v[132:133], v[196:197], v[80:81] op_sel_hi:[0,1,1]
	v_pk_fma_f32 v[198:199], v[132:133], v[198:199], v[82:83] op_sel_hi:[0,1,1]
	v_pk_fma_f32 v[200:201], v[132:133], v[200:201], v[84:85] op_sel_hi:[0,1,1]
	v_pk_fma_f32 v[202:203], v[132:133], v[202:203], v[86:87] op_sel_hi:[0,1,1]
	v_pk_fma_f32 v[204:205], v[132:133], v[204:205], v[88:89] op_sel_hi:[0,1,1]
	v_pk_fma_f32 v[206:207], v[132:133], v[206:207], v[90:91] op_sel_hi:[0,1,1]
	v_pk_fma_f32 v[208:209], v[132:133], v[208:209], v[92:93] op_sel_hi:[0,1,1]
	v_pk_fma_f32 v[210:211], v[132:133], v[210:211], v[94:95] op_sel_hi:[0,1,1]
	s_waitcnt lgkmcnt(14)
	v_pk_fma_f32 v[128:129], v[64:65], v[196:197], v[192:193]
	v_pk_fma_f32 v[130:131], v[66:67], v[198:199], v[192:193]
	s_waitcnt lgkmcnt(13)
	v_pk_fma_f32 v[128:129], v[68:69], v[200:201], v[128:129]
	v_pk_fma_f32 v[130:131], v[70:71], v[202:203], v[130:131]
	s_waitcnt lgkmcnt(12)
	v_pk_fma_f32 v[128:129], v[72:73], v[204:205], v[128:129]
	v_pk_fma_f32 v[130:131], v[74:75], v[206:207], v[130:131]
	s_waitcnt lgkmcnt(11)
	v_pk_fma_f32 v[128:129], v[76:77], v[208:209], v[128:129]
	v_pk_fma_f32 v[130:131], v[78:79], v[210:211], v[130:131]
	v_add_f32_e32 v128, v128, v129
	v_add_f32_e32 v130, v130, v131
	v_add_f32_e32 v190, v128, v130
	ds_read_b128 v[80:83], v188 offset:10240
	ds_read_b128 v[84:87], v188 offset:10496
	ds_read_b128 v[88:91], v188 offset:10752
	ds_read_b128 v[92:95], v188 offset:11008
	ds_read_b32 v134, v140 offset:35144
	ds_read_b32 v135, v189 offset:16512
	ds_read_b32 v132, v140 offset:35080
	ds_read_b128 v[64:67], v188 offset:2048
	ds_read_b128 v[68:71], v188 offset:2304
	ds_read_b128 v[72:75], v188 offset:2560
	ds_read_b128 v[76:79], v188 offset:2816
	s_waitcnt lgkmcnt(15)
	v_mul_f32_e32 v153, v154, v155
	v_pk_mul_f32 v[112:113], v[112:113], v[152:153] op_sel:[0,1] op_sel_hi:[1,1]
	v_add_f32_dpp v190, v190, v190 row_ror:8 row_mask:0xf bank_mask:0xf bound_ctrl:1
	v_pk_mul_f32 v[114:115], v[114:115], v[152:153] op_sel:[0,1] op_sel_hi:[1,1]
	v_pk_mul_f32 v[116:117], v[116:117], v[152:153] op_sel:[0,1] op_sel_hi:[1,1]
	v_add_f32_dpp v190, v190, v190 row_ror:4 row_mask:0xf bank_mask:0xf bound_ctrl:1
	v_pk_mul_f32 v[118:119], v[118:119], v[152:153] op_sel:[0,1] op_sel_hi:[1,1]
	v_pk_mul_f32 v[120:121], v[120:121], v[152:153] op_sel:[0,1] op_sel_hi:[1,1]
	v_add_f32_dpp v190, v190, v190 row_ror:2 row_mask:0xf bank_mask:0xf bound_ctrl:1
	v_pk_mul_f32 v[122:123], v[122:123], v[152:153] op_sel:[0,1] op_sel_hi:[1,1]
	v_pk_mul_f32 v[124:125], v[124:125], v[152:153] op_sel:[0,1] op_sel_hi:[1,1]
	v_add_f32_dpp v190, v190, v190 row_ror:1 row_mask:0xf bank_mask:0xf bound_ctrl:1
	v_pk_mul_f32 v[126:127], v[126:127], v[152:153] op_sel:[0,1] op_sel_hi:[1,1]
	v_pk_fma_f32 v[196:197], v[152:153], v[196:197], v[112:113] op_sel_hi:[0,1,1]
	s_and_saveexec_b64 s[8:9], s[44:45]
	ds_write_b32 v189, v190 offset:34048
	s_mov_b64 exec, s[8:9]
	v_pk_fma_f32 v[198:199], v[152:153], v[198:199], v[114:115] op_sel_hi:[0,1,1]
	v_pk_fma_f32 v[200:201], v[152:153], v[200:201], v[116:117] op_sel_hi:[0,1,1]
	v_pk_fma_f32 v[202:203], v[152:153], v[202:203], v[118:119] op_sel_hi:[0,1,1]
	v_pk_fma_f32 v[204:205], v[152:153], v[204:205], v[120:121] op_sel_hi:[0,1,1]
	v_pk_fma_f32 v[206:207], v[152:153], v[206:207], v[122:123] op_sel_hi:[0,1,1]
	v_pk_fma_f32 v[208:209], v[152:153], v[208:209], v[124:125] op_sel_hi:[0,1,1]
	v_pk_fma_f32 v[210:211], v[152:153], v[210:211], v[126:127] op_sel_hi:[0,1,1]
	s_waitcnt lgkmcnt(15)
	v_pk_fma_f32 v[128:129], v[96:97], v[196:197], v[192:193]
	v_pk_fma_f32 v[130:131], v[98:99], v[198:199], v[192:193]
	s_waitcnt lgkmcnt(14)
	v_pk_fma_f32 v[128:129], v[100:101], v[200:201], v[128:129]
	v_pk_fma_f32 v[130:131], v[102:103], v[202:203], v[130:131]
	s_waitcnt lgkmcnt(13)
	v_pk_fma_f32 v[128:129], v[104:105], v[204:205], v[128:129]
	v_pk_fma_f32 v[130:131], v[106:107], v[206:207], v[130:131]
	s_waitcnt lgkmcnt(12)
	v_pk_fma_f32 v[128:129], v[108:109], v[208:209], v[128:129]
	v_pk_fma_f32 v[130:131], v[110:111], v[210:211], v[130:131]
	v_add_f32_e32 v128, v128, v129
	v_add_f32_e32 v130, v130, v131
	v_add_f32_e32 v191, v128, v130
	ds_read_b128 v[112:115], v188 offset:11264
	ds_read_b128 v[116:119], v188 offset:11520
	ds_read_b128 v[120:123], v188 offset:11776
	ds_read_b128 v[124:127], v188 offset:12032
	ds_read_b32 v154, v140 offset:35148
	ds_read_b32 v155, v189 offset:16576
	ds_read_b32 v152, v140 offset:35084
	ds_read_b128 v[96:99], v188 offset:3072
	ds_read_b128 v[100:103], v188 offset:3328
	ds_read_b128 v[104:107], v188 offset:3584
	ds_read_b128 v[108:111], v188 offset:3840
	s_waitcnt lgkmcnt(15)
	v_mul_f32_e32 v133, v134, v135
	v_pk_mul_f32 v[80:81], v[80:81], v[132:133] op_sel:[0,1] op_sel_hi:[1,1]
	v_add_f32_dpp v191, v191, v191 row_ror:8 row_mask:0xf bank_mask:0xf bound_ctrl:1
	v_pk_mul_f32 v[82:83], v[82:83], v[132:133] op_sel:[0,1] op_sel_hi:[1,1]
	v_pk_mul_f32 v[84:85], v[84:85], v[132:133] op_sel:[0,1] op_sel_hi:[1,1]
	v_add_f32_dpp v191, v191, v191 row_ror:4 row_mask:0xf bank_mask:0xf bound_ctrl:1
	v_pk_mul_f32 v[86:87], v[86:87], v[132:133] op_sel:[0,1] op_sel_hi:[1,1]
	v_pk_mul_f32 v[88:89], v[88:89], v[132:133] op_sel:[0,1] op_sel_hi:[1,1]
	v_add_f32_dpp v191, v191, v191 row_ror:2 row_mask:0xf bank_mask:0xf bound_ctrl:1
	v_pk_mul_f32 v[90:91], v[90:91], v[132:133] op_sel:[0,1] op_sel_hi:[1,1]
	v_pk_mul_f32 v[92:93], v[92:93], v[132:133] op_sel:[0,1] op_sel_hi:[1,1]
	v_add_f32_dpp v191, v191, v191 row_ror:1 row_mask:0xf bank_mask:0xf bound_ctrl:1
	v_pk_mul_f32 v[94:95], v[94:95], v[132:133] op_sel:[0,1] op_sel_hi:[1,1]
	v_pk_fma_f32 v[196:197], v[132:133], v[196:197], v[80:81] op_sel_hi:[0,1,1]
	s_and_saveexec_b64 s[8:9], s[44:45]
	ds_write_b32 v189, v191 offset:34112
	s_mov_b64 exec, s[8:9]
	v_pk_fma_f32 v[198:199], v[132:133], v[198:199], v[82:83] op_sel_hi:[0,1,1]
	v_pk_fma_f32 v[200:201], v[132:133], v[200:201], v[84:85] op_sel_hi:[0,1,1]
	v_pk_fma_f32 v[202:203], v[132:133], v[202:203], v[86:87] op_sel_hi:[0,1,1]
	v_pk_fma_f32 v[204:205], v[132:133], v[204:205], v[88:89] op_sel_hi:[0,1,1]
	v_pk_fma_f32 v[206:207], v[132:133], v[206:207], v[90:91] op_sel_hi:[0,1,1]
	v_pk_fma_f32 v[208:209], v[132:133], v[208:209], v[92:93] op_sel_hi:[0,1,1]
	v_pk_fma_f32 v[210:211], v[132:133], v[210:211], v[94:95] op_sel_hi:[0,1,1]
	s_waitcnt lgkmcnt(15)
	v_pk_fma_f32 v[128:129], v[64:65], v[196:197], v[192:193]
	v_pk_fma_f32 v[130:131], v[66:67], v[198:199], v[192:193]
	v_pk_fma_f32 v[128:129], v[68:69], v[200:201], v[128:129]
	v_pk_fma_f32 v[130:131], v[70:71], v[202:203], v[130:131]
	s_waitcnt lgkmcnt(14)
	v_pk_fma_f32 v[128:129], v[72:73], v[204:205], v[128:129]
	v_pk_fma_f32 v[130:131], v[74:75], v[206:207], v[130:131]
	s_waitcnt lgkmcnt(13)
	v_pk_fma_f32 v[128:129], v[76:77], v[208:209], v[128:129]
	v_pk_fma_f32 v[130:131], v[78:79], v[210:211], v[130:131]
	v_add_f32_e32 v128, v128, v129
	v_add_f32_e32 v130, v130, v131
	v_add_f32_e32 v190, v128, v130
	ds_read_b128 v[80:83], v188 offset:12288
	ds_read_b128 v[84:87], v188 offset:12544
	ds_read_b128 v[88:91], v188 offset:12800
	ds_read_b128 v[92:95], v188 offset:13056
	ds_read_b32 v134, v140 offset:35152
	ds_read_b32 v135, v189 offset:16640
	ds_read_b32 v132, v140 offset:35088
	ds_read_b128 v[64:67], v188 offset:4096
	ds_read_b128 v[68:71], v188 offset:4352
	ds_read_b128 v[72:75], v188 offset:4608
	ds_read_b128 v[76:79], v188 offset:4864
	s_waitcnt lgkmcnt(15)
	v_mul_f32_e32 v153, v154, v155
	v_pk_mul_f32 v[112:113], v[112:113], v[152:153] op_sel:[0,1] op_sel_hi:[1,1]
	v_add_f32_dpp v190, v190, v190 row_ror:8 row_mask:0xf bank_mask:0xf bound_ctrl:1
	v_pk_mul_f32 v[114:115], v[114:115], v[152:153] op_sel:[0,1] op_sel_hi:[1,1]
	v_pk_mul_f32 v[116:117], v[116:117], v[152:153] op_sel:[0,1] op_sel_hi:[1,1]
	v_add_f32_dpp v190, v190, v190 row_ror:4 row_mask:0xf bank_mask:0xf bound_ctrl:1
	v_pk_mul_f32 v[118:119], v[118:119], v[152:153] op_sel:[0,1] op_sel_hi:[1,1]
	v_pk_mul_f32 v[120:121], v[120:121], v[152:153] op_sel:[0,1] op_sel_hi:[1,1]
	v_add_f32_dpp v190, v190, v190 row_ror:2 row_mask:0xf bank_mask:0xf bound_ctrl:1
	v_pk_mul_f32 v[122:123], v[122:123], v[152:153] op_sel:[0,1] op_sel_hi:[1,1]
	v_pk_mul_f32 v[124:125], v[124:125], v[152:153] op_sel:[0,1] op_sel_hi:[1,1]
	v_add_f32_dpp v190, v190, v190 row_ror:1 row_mask:0xf bank_mask:0xf bound_ctrl:1
	v_pk_mul_f32 v[126:127], v[126:127], v[152:153] op_sel:[0,1] op_sel_hi:[1,1]
	v_pk_fma_f32 v[196:197], v[152:153], v[196:197], v[112:113] op_sel_hi:[0,1,1]
	s_and_saveexec_b64 s[8:9], s[44:45]
	ds_write_b32 v189, v190 offset:34176
	s_mov_b64 exec, s[8:9]
	v_pk_fma_f32 v[198:199], v[152:153], v[198:199], v[114:115] op_sel_hi:[0,1,1]
	v_pk_fma_f32 v[200:201], v[152:153], v[200:201], v[116:117] op_sel_hi:[0,1,1]
	v_pk_fma_f32 v[202:203], v[152:153], v[202:203], v[118:119] op_sel_hi:[0,1,1]
	v_pk_fma_f32 v[204:205], v[152:153], v[204:205], v[120:121] op_sel_hi:[0,1,1]
	v_pk_fma_f32 v[206:207], v[152:153], v[206:207], v[122:123] op_sel_hi:[0,1,1]
	v_pk_fma_f32 v[208:209], v[152:153], v[208:209], v[124:125] op_sel_hi:[0,1,1]
	v_pk_fma_f32 v[210:211], v[152:153], v[210:211], v[126:127] op_sel_hi:[0,1,1]
	s_waitcnt lgkmcnt(15)
	v_pk_fma_f32 v[128:129], v[96:97], v[196:197], v[192:193]
	v_pk_fma_f32 v[130:131], v[98:99], v[198:199], v[192:193]
	v_pk_fma_f32 v[128:129], v[100:101], v[200:201], v[128:129]
	v_pk_fma_f32 v[130:131], v[102:103], v[202:203], v[130:131]
	s_waitcnt lgkmcnt(14)
	v_pk_fma_f32 v[128:129], v[104:105], v[204:205], v[128:129]
	v_pk_fma_f32 v[130:131], v[106:107], v[206:207], v[130:131]
	s_waitcnt lgkmcnt(13)
	v_pk_fma_f32 v[128:129], v[108:109], v[208:209], v[128:129]
	v_pk_fma_f32 v[130:131], v[110:111], v[210:211], v[130:131]
	v_add_f32_e32 v128, v128, v129
	v_add_f32_e32 v130, v130, v131
	v_add_f32_e32 v191, v128, v130
	ds_read_b128 v[112:115], v188 offset:13312
	ds_read_b128 v[116:119], v188 offset:13568
	ds_read_b128 v[120:123], v188 offset:13824
	ds_read_b128 v[124:127], v188 offset:14080
	ds_read_b32 v154, v140 offset:35156
	ds_read_b32 v155, v189 offset:16704
	ds_read_b32 v152, v140 offset:35092
	ds_read_b128 v[96:99], v188 offset:5120
	ds_read_b128 v[100:103], v188 offset:5376
	ds_read_b128 v[104:107], v188 offset:5632
	ds_read_b128 v[108:111], v188 offset:5888
	s_waitcnt lgkmcnt(15)
	v_mul_f32_e32 v133, v134, v135
	v_pk_mul_f32 v[80:81], v[80:81], v[132:133] op_sel:[0,1] op_sel_hi:[1,1]
	v_add_f32_dpp v191, v191, v191 row_ror:8 row_mask:0xf bank_mask:0xf bound_ctrl:1
	v_pk_mul_f32 v[82:83], v[82:83], v[132:133] op_sel:[0,1] op_sel_hi:[1,1]
	v_pk_mul_f32 v[84:85], v[84:85], v[132:133] op_sel:[0,1] op_sel_hi:[1,1]
	v_add_f32_dpp v191, v191, v191 row_ror:4 row_mask:0xf bank_mask:0xf bound_ctrl:1
	v_pk_mul_f32 v[86:87], v[86:87], v[132:133] op_sel:[0,1] op_sel_hi:[1,1]
	v_pk_mul_f32 v[88:89], v[88:89], v[132:133] op_sel:[0,1] op_sel_hi:[1,1]
	v_add_f32_dpp v191, v191, v191 row_ror:2 row_mask:0xf bank_mask:0xf bound_ctrl:1
	v_pk_mul_f32 v[90:91], v[90:91], v[132:133] op_sel:[0,1] op_sel_hi:[1,1]
	v_pk_mul_f32 v[92:93], v[92:93], v[132:133] op_sel:[0,1] op_sel_hi:[1,1]
	v_add_f32_dpp v191, v191, v191 row_ror:1 row_mask:0xf bank_mask:0xf bound_ctrl:1
	v_pk_mul_f32 v[94:95], v[94:95], v[132:133] op_sel:[0,1] op_sel_hi:[1,1]
	v_pk_fma_f32 v[196:197], v[132:133], v[196:197], v[80:81] op_sel_hi:[0,1,1]
	s_and_saveexec_b64 s[8:9], s[44:45]
	ds_write_b32 v189, v191 offset:34240
	s_mov_b64 exec, s[8:9]
	v_pk_fma_f32 v[198:199], v[132:133], v[198:199], v[82:83] op_sel_hi:[0,1,1]
	v_pk_fma_f32 v[200:201], v[132:133], v[200:201], v[84:85] op_sel_hi:[0,1,1]
	v_pk_fma_f32 v[202:203], v[132:133], v[202:203], v[86:87] op_sel_hi:[0,1,1]
	v_pk_fma_f32 v[204:205], v[132:133], v[204:205], v[88:89] op_sel_hi:[0,1,1]
	v_pk_fma_f32 v[206:207], v[132:133], v[206:207], v[90:91] op_sel_hi:[0,1,1]
	v_pk_fma_f32 v[208:209], v[132:133], v[208:209], v[92:93] op_sel_hi:[0,1,1]
	v_pk_fma_f32 v[210:211], v[132:133], v[210:211], v[94:95] op_sel_hi:[0,1,1]
	s_waitcnt lgkmcnt(15)
	v_pk_fma_f32 v[128:129], v[64:65], v[196:197], v[192:193]
	v_pk_fma_f32 v[130:131], v[66:67], v[198:199], v[192:193]
	v_pk_fma_f32 v[128:129], v[68:69], v[200:201], v[128:129]
	v_pk_fma_f32 v[130:131], v[70:71], v[202:203], v[130:131]
	s_waitcnt lgkmcnt(14)
	v_pk_fma_f32 v[128:129], v[72:73], v[204:205], v[128:129]
	v_pk_fma_f32 v[130:131], v[74:75], v[206:207], v[130:131]
	s_waitcnt lgkmcnt(13)
	v_pk_fma_f32 v[128:129], v[76:77], v[208:209], v[128:129]
	v_pk_fma_f32 v[130:131], v[78:79], v[210:211], v[130:131]
	v_add_f32_e32 v128, v128, v129
	v_add_f32_e32 v130, v130, v131
	v_add_f32_e32 v190, v128, v130
	ds_read_b128 v[80:83], v188 offset:14336
	ds_read_b128 v[84:87], v188 offset:14592
	ds_read_b128 v[88:91], v188 offset:14848
	ds_read_b128 v[92:95], v188 offset:15104
	ds_read_b32 v134, v140 offset:35160
	ds_read_b32 v135, v189 offset:16768
	ds_read_b32 v132, v140 offset:35096
	ds_read_b128 v[64:67], v188 offset:6144
	ds_read_b128 v[68:71], v188 offset:6400
	ds_read_b128 v[72:75], v188 offset:6656
	ds_read_b128 v[76:79], v188 offset:6912
	s_waitcnt lgkmcnt(15)
	v_mul_f32_e32 v153, v154, v155
	v_pk_mul_f32 v[112:113], v[112:113], v[152:153] op_sel:[0,1] op_sel_hi:[1,1]
	v_add_f32_dpp v190, v190, v190 row_ror:8 row_mask:0xf bank_mask:0xf bound_ctrl:1
	v_pk_mul_f32 v[114:115], v[114:115], v[152:153] op_sel:[0,1] op_sel_hi:[1,1]
	v_pk_mul_f32 v[116:117], v[116:117], v[152:153] op_sel:[0,1] op_sel_hi:[1,1]
	v_add_f32_dpp v190, v190, v190 row_ror:4 row_mask:0xf bank_mask:0xf bound_ctrl:1
	v_pk_mul_f32 v[118:119], v[118:119], v[152:153] op_sel:[0,1] op_sel_hi:[1,1]
	v_pk_mul_f32 v[120:121], v[120:121], v[152:153] op_sel:[0,1] op_sel_hi:[1,1]
	v_add_f32_dpp v190, v190, v190 row_ror:2 row_mask:0xf bank_mask:0xf bound_ctrl:1
	v_pk_mul_f32 v[122:123], v[122:123], v[152:153] op_sel:[0,1] op_sel_hi:[1,1]
	v_pk_mul_f32 v[124:125], v[124:125], v[152:153] op_sel:[0,1] op_sel_hi:[1,1]
	v_add_f32_dpp v190, v190, v190 row_ror:1 row_mask:0xf bank_mask:0xf bound_ctrl:1
	v_pk_mul_f32 v[126:127], v[126:127], v[152:153] op_sel:[0,1] op_sel_hi:[1,1]
	v_pk_fma_f32 v[196:197], v[152:153], v[196:197], v[112:113] op_sel_hi:[0,1,1]
	s_and_saveexec_b64 s[8:9], s[44:45]
	ds_write_b32 v189, v190 offset:34304
	s_mov_b64 exec, s[8:9]
	v_pk_fma_f32 v[198:199], v[152:153], v[198:199], v[114:115] op_sel_hi:[0,1,1]
	v_pk_fma_f32 v[200:201], v[152:153], v[200:201], v[116:117] op_sel_hi:[0,1,1]
	v_pk_fma_f32 v[202:203], v[152:153], v[202:203], v[118:119] op_sel_hi:[0,1,1]
	v_pk_fma_f32 v[204:205], v[152:153], v[204:205], v[120:121] op_sel_hi:[0,1,1]
	v_pk_fma_f32 v[206:207], v[152:153], v[206:207], v[122:123] op_sel_hi:[0,1,1]
	v_pk_fma_f32 v[208:209], v[152:153], v[208:209], v[124:125] op_sel_hi:[0,1,1]
	v_pk_fma_f32 v[210:211], v[152:153], v[210:211], v[126:127] op_sel_hi:[0,1,1]
	s_waitcnt lgkmcnt(15)
	v_pk_fma_f32 v[128:129], v[96:97], v[196:197], v[192:193]
	v_pk_fma_f32 v[130:131], v[98:99], v[198:199], v[192:193]
	v_pk_fma_f32 v[128:129], v[100:101], v[200:201], v[128:129]
	v_pk_fma_f32 v[130:131], v[102:103], v[202:203], v[130:131]
	s_waitcnt lgkmcnt(14)
	v_pk_fma_f32 v[128:129], v[104:105], v[204:205], v[128:129]
	v_pk_fma_f32 v[130:131], v[106:107], v[206:207], v[130:131]
	s_waitcnt lgkmcnt(13)
	v_pk_fma_f32 v[128:129], v[108:109], v[208:209], v[128:129]
	v_pk_fma_f32 v[130:131], v[110:111], v[210:211], v[130:131]
	v_add_f32_e32 v128, v128, v129
	v_add_f32_e32 v130, v130, v131
	v_add_f32_e32 v191, v128, v130
	ds_read_b128 v[112:115], v188 offset:15360
	ds_read_b128 v[116:119], v188 offset:15616
	ds_read_b128 v[120:123], v188 offset:15872
	ds_read_b128 v[124:127], v188 offset:16128
	ds_read_b32 v154, v140 offset:35164
	ds_read_b32 v155, v189 offset:16832
	ds_read_b32 v152, v140 offset:35100
	ds_read_b128 v[96:99], v188 offset:7168
	ds_read_b128 v[100:103], v188 offset:7424
	ds_read_b128 v[104:107], v188 offset:7680
	ds_read_b128 v[108:111], v188 offset:7936
	s_waitcnt lgkmcnt(15)
	v_mul_f32_e32 v133, v134, v135
	v_pk_mul_f32 v[80:81], v[80:81], v[132:133] op_sel:[0,1] op_sel_hi:[1,1]
	v_add_f32_dpp v191, v191, v191 row_ror:8 row_mask:0xf bank_mask:0xf bound_ctrl:1
	v_pk_mul_f32 v[82:83], v[82:83], v[132:133] op_sel:[0,1] op_sel_hi:[1,1]
	v_pk_mul_f32 v[84:85], v[84:85], v[132:133] op_sel:[0,1] op_sel_hi:[1,1]
	v_add_f32_dpp v191, v191, v191 row_ror:4 row_mask:0xf bank_mask:0xf bound_ctrl:1
	v_pk_mul_f32 v[86:87], v[86:87], v[132:133] op_sel:[0,1] op_sel_hi:[1,1]
	v_pk_mul_f32 v[88:89], v[88:89], v[132:133] op_sel:[0,1] op_sel_hi:[1,1]
	v_add_f32_dpp v191, v191, v191 row_ror:2 row_mask:0xf bank_mask:0xf bound_ctrl:1
	v_pk_mul_f32 v[90:91], v[90:91], v[132:133] op_sel:[0,1] op_sel_hi:[1,1]
	v_pk_mul_f32 v[92:93], v[92:93], v[132:133] op_sel:[0,1] op_sel_hi:[1,1]
	v_add_f32_dpp v191, v191, v191 row_ror:1 row_mask:0xf bank_mask:0xf bound_ctrl:1
	v_pk_mul_f32 v[94:95], v[94:95], v[132:133] op_sel:[0,1] op_sel_hi:[1,1]
	v_pk_fma_f32 v[196:197], v[132:133], v[196:197], v[80:81] op_sel_hi:[0,1,1]
	s_and_saveexec_b64 s[8:9], s[44:45]
	ds_write_b32 v189, v191 offset:34368
	s_mov_b64 exec, s[8:9]
	v_pk_fma_f32 v[198:199], v[132:133], v[198:199], v[82:83] op_sel_hi:[0,1,1]
	v_pk_fma_f32 v[200:201], v[132:133], v[200:201], v[84:85] op_sel_hi:[0,1,1]
	v_pk_fma_f32 v[202:203], v[132:133], v[202:203], v[86:87] op_sel_hi:[0,1,1]
	v_pk_fma_f32 v[204:205], v[132:133], v[204:205], v[88:89] op_sel_hi:[0,1,1]
	v_pk_fma_f32 v[206:207], v[132:133], v[206:207], v[90:91] op_sel_hi:[0,1,1]
	v_pk_fma_f32 v[208:209], v[132:133], v[208:209], v[92:93] op_sel_hi:[0,1,1]
	v_pk_fma_f32 v[210:211], v[132:133], v[210:211], v[94:95] op_sel_hi:[0,1,1]
	s_waitcnt lgkmcnt(15)
	v_pk_fma_f32 v[128:129], v[64:65], v[196:197], v[192:193]
	v_pk_fma_f32 v[130:131], v[66:67], v[198:199], v[192:193]
	v_pk_fma_f32 v[128:129], v[68:69], v[200:201], v[128:129]
	v_pk_fma_f32 v[130:131], v[70:71], v[202:203], v[130:131]
	s_waitcnt lgkmcnt(14)
	v_pk_fma_f32 v[128:129], v[72:73], v[204:205], v[128:129]
	v_pk_fma_f32 v[130:131], v[74:75], v[206:207], v[130:131]
	s_waitcnt lgkmcnt(13)
	v_pk_fma_f32 v[128:129], v[76:77], v[208:209], v[128:129]
	v_pk_fma_f32 v[130:131], v[78:79], v[210:211], v[130:131]
	v_add_f32_e32 v128, v128, v129
	v_add_f32_e32 v130, v130, v131
	v_add_f32_e32 v190, v128, v130
	s_waitcnt lgkmcnt(6)
	v_mul_f32_e32 v153, v154, v155
	v_pk_mul_f32 v[112:113], v[112:113], v[152:153] op_sel:[0,1] op_sel_hi:[1,1]
	v_add_f32_dpp v190, v190, v190 row_ror:8 row_mask:0xf bank_mask:0xf bound_ctrl:1
	v_pk_mul_f32 v[114:115], v[114:115], v[152:153] op_sel:[0,1] op_sel_hi:[1,1]
	v_pk_mul_f32 v[116:117], v[116:117], v[152:153] op_sel:[0,1] op_sel_hi:[1,1]
	v_add_f32_dpp v190, v190, v190 row_ror:4 row_mask:0xf bank_mask:0xf bound_ctrl:1
	v_pk_mul_f32 v[118:119], v[118:119], v[152:153] op_sel:[0,1] op_sel_hi:[1,1]
	v_pk_mul_f32 v[120:121], v[120:121], v[152:153] op_sel:[0,1] op_sel_hi:[1,1]
	v_add_f32_dpp v190, v190, v190 row_ror:2 row_mask:0xf bank_mask:0xf bound_ctrl:1
	v_pk_mul_f32 v[122:123], v[122:123], v[152:153] op_sel:[0,1] op_sel_hi:[1,1]
	v_pk_mul_f32 v[124:125], v[124:125], v[152:153] op_sel:[0,1] op_sel_hi:[1,1]
	v_add_f32_dpp v190, v190, v190 row_ror:1 row_mask:0xf bank_mask:0xf bound_ctrl:1
	v_pk_mul_f32 v[126:127], v[126:127], v[152:153] op_sel:[0,1] op_sel_hi:[1,1]
	s_waitcnt lgkmcnt(5)
	v_pk_fma_f32 v[196:197], v[152:153], v[196:197], v[112:113] op_sel_hi:[0,1,1]
	s_and_saveexec_b64 s[8:9], s[44:45]
	ds_write_b32 v189, v190 offset:34432
	s_mov_b64 exec, s[8:9]
	v_pk_fma_f32 v[198:199], v[152:153], v[198:199], v[114:115] op_sel_hi:[0,1,1]
	v_pk_fma_f32 v[200:201], v[152:153], v[200:201], v[116:117] op_sel_hi:[0,1,1]
	v_pk_fma_f32 v[202:203], v[152:153], v[202:203], v[118:119] op_sel_hi:[0,1,1]
	v_pk_fma_f32 v[204:205], v[152:153], v[204:205], v[120:121] op_sel_hi:[0,1,1]
	v_pk_fma_f32 v[206:207], v[152:153], v[206:207], v[122:123] op_sel_hi:[0,1,1]
	v_pk_fma_f32 v[208:209], v[152:153], v[208:209], v[124:125] op_sel_hi:[0,1,1]
	v_pk_fma_f32 v[210:211], v[152:153], v[210:211], v[126:127] op_sel_hi:[0,1,1]
	s_waitcnt lgkmcnt(5)
	v_pk_fma_f32 v[128:129], v[96:97], v[196:197], v[192:193]
	v_pk_fma_f32 v[130:131], v[98:99], v[198:199], v[192:193]
	s_waitcnt lgkmcnt(4)
	v_pk_fma_f32 v[128:129], v[100:101], v[200:201], v[128:129]
	v_pk_fma_f32 v[130:131], v[102:103], v[202:203], v[130:131]
	s_waitcnt lgkmcnt(3)
	v_pk_fma_f32 v[128:129], v[104:105], v[204:205], v[128:129]
	v_pk_fma_f32 v[130:131], v[106:107], v[206:207], v[130:131]
	s_waitcnt lgkmcnt(2)
	v_pk_fma_f32 v[128:129], v[108:109], v[208:209], v[128:129]
	v_pk_fma_f32 v[130:131], v[110:111], v[210:211], v[130:131]
	v_add_f32_e32 v128, v128, v129
	v_add_f32_e32 v130, v130, v131
	v_add_f32_e32 v191, v128, v130
	s_nop 1
	v_add_f32_dpp v191, v191, v191 row_ror:8 row_mask:0xf bank_mask:0xf bound_ctrl:1
	s_nop 1
	v_add_f32_dpp v191, v191, v191 row_ror:4 row_mask:0xf bank_mask:0xf bound_ctrl:1
	s_nop 1
	v_add_f32_dpp v191, v191, v191 row_ror:2 row_mask:0xf bank_mask:0xf bound_ctrl:1
	s_nop 1
	v_add_f32_dpp v191, v191, v191 row_ror:1 row_mask:0xf bank_mask:0xf bound_ctrl:1
	s_and_saveexec_b64 s[8:9], s[44:45]
	ds_write_b32 v189, v191 offset:34496
	s_mov_b64 exec, s[8:9]
	s_waitcnt vmcnt(3)
	ds_write_b128 v185, v[48:51] offset:17024
	s_waitcnt vmcnt(1)
	ds_write_b128 v186, v[56:59] offset:17024
	ds_write_b128 v185, v[52:55] offset:25216
	s_waitcnt vmcnt(0)
	ds_write_b128 v186, v[60:63] offset:25216
	s_and_saveexec_b64 s[8:9], s[42:43]
	ds_write_b32 v144, v184 offset:33408
	s_or_b64 exec, exec, s[8:9]
	s_and_saveexec_b64 s[8:9], s[40:41]
	s_cbranch_execz .LBB0_1536
	v_add_f32_e32 v64, v156, v181
	v_mul_f32_e64 v65, |v64|, s62
	v_exp_f32_e32 v65, v65
	v_min_f32_e32 v64, 0, v64
	v_add_f32_e32 v65, 1.0, v65
	v_cmp_gt_f32_e32 vcc, s5, v65
	s_nop 1
	v_cndmask_b32_e64 v66, 0, 32, vcc
	v_ldexp_f32 v65, v65, v66
	v_log_f32_e32 v65, v65
	v_cndmask_b32_e32 v67, 0, v171, vcc
	v_add_f32_e32 v66, v145, v187
	v_mul_f32_e32 v68, 0x3f317217, v65
	v_fma_f32 v68, v65, s76, -v68
	v_fmac_f32_e32 v68, 0x3377d1cf, v65
	v_fmac_f32_e32 v68, 0x3f317217, v65
	v_cmp_lt_f32_e64 vcc, |v65|, s77
	s_nop 1
	v_cndmask_b32_e32 v65, v65, v68, vcc
	v_sub_f32_e32 v65, v65, v67
	v_sub_f32_e32 v64, v64, v65
	v_add_u32_e32 v65, 0x8400, v144
	ds_write2_b32 v65, v66, v64 offset0:32 offset1:48

.LBB0_1547:
	s_or_b64 exec, exec, s[8:9]
	s_waitcnt lgkmcnt(0)
	s_barrier
	v_mov_b32_e32 v192, 0
	v_mov_b32_e32 v193, 0
	ds_read_b128 v[80:83], v188 offset:25216
	ds_read_b128 v[84:87], v188 offset:25472
	ds_read_b128 v[88:91], v188 offset:25728
	ds_read_b128 v[92:95], v188 offset:25984
	ds_read_b32 v134, v140 offset:35136
	ds_read_b32 v135, v189 offset:33408
	ds_read_b32 v132, v140 offset:35072
	ds_read_b128 v[64:67], v188 offset:17024
	ds_read_b128 v[68:71], v188 offset:17280
	ds_read_b128 v[72:75], v188 offset:17536
	ds_read_b128 v[76:79], v188 offset:17792
	ds_read_b128 v[112:115], v188 offset:26240
	ds_read_b128 v[116:119], v188 offset:26496
	ds_read_b128 v[120:123], v188 offset:26752
	ds_read_b128 v[124:127], v188 offset:27008
	ds_read_b32 v154, v140 offset:35140
	ds_read_b32 v155, v189 offset:33472
	ds_read_b32 v152, v140 offset:35076
	ds_read_b128 v[96:99], v188 offset:18048
	ds_read_b128 v[100:103], v188 offset:18304
	ds_read_b128 v[104:107], v188 offset:18560
	ds_read_b128 v[108:111], v188 offset:18816
	s_waitcnt lgkmcnt(15)
	v_mul_f32_e32 v133, v134, v135
	v_pk_mul_f32 v[80:81], v[80:81], v[132:133] op_sel:[0,1] op_sel_hi:[1,1]
	v_pk_mul_f32 v[82:83], v[82:83], v[132:133] op_sel:[0,1] op_sel_hi:[1,1]
	v_pk_mul_f32 v[84:85], v[84:85], v[132:133] op_sel:[0,1] op_sel_hi:[1,1]
	v_pk_mul_f32 v[86:87], v[86:87], v[132:133] op_sel:[0,1] op_sel_hi:[1,1]
	v_pk_mul_f32 v[88:89], v[88:89], v[132:133] op_sel:[0,1] op_sel_hi:[1,1]
	v_pk_mul_f32 v[90:91], v[90:91], v[132:133] op_sel:[0,1] op_sel_hi:[1,1]
	v_pk_mul_f32 v[92:93], v[92:93], v[132:133] op_sel:[0,1] op_sel_hi:[1,1]
	v_pk_mul_f32 v[94:95], v[94:95], v[132:133] op_sel:[0,1] op_sel_hi:[1,1]
	v_pk_fma_f32 v[196:197], v[132:133], v[196:197], v[80:81] op_sel_hi:[0,1,1]
	v_pk_fma_f32 v[198:199], v[132:133], v[198:199], v[82:83] op_sel_hi:[0,1,1]
	v_pk_fma_f32 v[200:201], v[132:133], v[200:201], v[84:85] op_sel_hi:[0,1,1]
	v_pk_fma_f32 v[202:203], v[132:133], v[202:203], v[86:87] op_sel_hi:[0,1,1]
	v_pk_fma_f32 v[204:205], v[132:133], v[204:205], v[88:89] op_sel_hi:[0,1,1]
	v_pk_fma_f32 v[206:207], v[132:133], v[206:207], v[90:91] op_sel_hi:[0,1,1]
	v_pk_fma_f32 v[208:209], v[132:133], v[208:209], v[92:93] op_sel_hi:[0,1,1]
	v_pk_fma_f32 v[210:211], v[132:133], v[210:211], v[94:95] op_sel_hi:[0,1,1]
	s_waitcnt lgkmcnt(14)
	v_pk_fma_f32 v[128:129], v[64:65], v[196:197], v[192:193]
	v_pk_fma_f32 v[130:131], v[66:67], v[198:199], v[192:193]
	s_waitcnt lgkmcnt(13)
	v_pk_fma_f32 v[128:129], v[68:69], v[200:201], v[128:129]
	v_pk_fma_f32 v[130:131], v[70:71], v[202:203], v[130:131]
	s_waitcnt lgkmcnt(12)
	v_pk_fma_f32 v[128:129], v[72:73], v[204:205], v[128:129]
	v_pk_fma_f32 v[130:131], v[74:75], v[206:207], v[130:131]
	s_waitcnt lgkmcnt(11)
	v_pk_fma_f32 v[128:129], v[76:77], v[208:209], v[128:129]
	v_pk_fma_f32 v[130:131], v[78:79], v[210:211], v[130:131]
	v_add_f32_e32 v128, v128, v129
	v_add_f32_e32 v130, v130, v131
	v_add_f32_e32 v190, v128, v130
	ds_read_b128 v[80:83], v188 offset:27264
	ds_read_b128 v[84:87], v188 offset:27520
	ds_read_b128 v[88:91], v188 offset:27776
	ds_read_b128 v[92:95], v188 offset:28032
	ds_read_b32 v134, v140 offset:35144
	ds_read_b32 v135, v189 offset:33536
	ds_read_b32 v132, v140 offset:35080
	ds_read_b128 v[64:67], v188 offset:19072
	ds_read_b128 v[68:71], v188 offset:19328
	ds_read_b128 v[72:75], v188 offset:19584
	ds_read_b128 v[76:79], v188 offset:19840
	s_waitcnt lgkmcnt(15)
	v_mul_f32_e32 v153, v154, v155
	v_pk_mul_f32 v[112:113], v[112:113], v[152:153] op_sel:[0,1] op_sel_hi:[1,1]
	v_add_f32_dpp v190, v190, v190 row_ror:8 row_mask:0xf bank_mask:0xf bound_ctrl:1
	v_pk_mul_f32 v[114:115], v[114:115], v[152:153] op_sel:[0,1] op_sel_hi:[1,1]
	v_pk_mul_f32 v[116:117], v[116:117], v[152:153] op_sel:[0,1] op_sel_hi:[1,1]
	v_add_f32_dpp v190, v190, v190 row_ror:4 row_mask:0xf bank_mask:0xf bound_ctrl:1
	v_pk_mul_f32 v[118:119], v[118:119], v[152:153] op_sel:[0,1] op_sel_hi:[1,1]
	v_pk_mul_f32 v[120:121], v[120:121], v[152:153] op_sel:[0,1] op_sel_hi:[1,1]
	v_add_f32_dpp v190, v190, v190 row_ror:2 row_mask:0xf bank_mask:0xf bound_ctrl:1
	v_pk_mul_f32 v[122:123], v[122:123], v[152:153] op_sel:[0,1] op_sel_hi:[1,1]
	v_pk_mul_f32 v[124:125], v[124:125], v[152:153] op_sel:[0,1] op_sel_hi:[1,1]
	v_add_f32_dpp v190, v190, v190 row_ror:1 row_mask:0xf bank_mask:0xf bound_ctrl:1
	v_pk_mul_f32 v[126:127], v[126:127], v[152:153] op_sel:[0,1] op_sel_hi:[1,1]
	v_pk_fma_f32 v[196:197], v[152:153], v[196:197], v[112:113] op_sel_hi:[0,1,1]
	s_and_saveexec_b64 s[8:9], s[44:45]
	ds_write_b32 v189, v190 offset:34560
	s_mov_b64 exec, s[8:9]
	v_pk_fma_f32 v[198:199], v[152:153], v[198:199], v[114:115] op_sel_hi:[0,1,1]
	v_pk_fma_f32 v[200:201], v[152:153], v[200:201], v[116:117] op_sel_hi:[0,1,1]
	v_pk_fma_f32 v[202:203], v[152:153], v[202:203], v[118:119] op_sel_hi:[0,1,1]
	v_pk_fma_f32 v[204:205], v[152:153], v[204:205], v[120:121] op_sel_hi:[0,1,1]
	v_pk_fma_f32 v[206:207], v[152:153], v[206:207], v[122:123] op_sel_hi:[0,1,1]
	v_pk_fma_f32 v[208:209], v[152:153], v[208:209], v[124:125] op_sel_hi:[0,1,1]
	v_pk_fma_f32 v[210:211], v[152:153], v[210:211], v[126:127] op_sel_hi:[0,1,1]
	s_waitcnt lgkmcnt(15)
	v_pk_fma_f32 v[128:129], v[96:97], v[196:197], v[192:193]
	v_pk_fma_f32 v[130:131], v[98:99], v[198:199], v[192:193]
	s_waitcnt lgkmcnt(14)
	v_pk_fma_f32 v[128:129], v[100:101], v[200:201], v[128:129]
	v_pk_fma_f32 v[130:131], v[102:103], v[202:203], v[130:131]
	s_waitcnt lgkmcnt(13)
	v_pk_fma_f32 v[128:129], v[104:105], v[204:205], v[128:129]
	v_pk_fma_f32 v[130:131], v[106:107], v[206:207], v[130:131]
	s_waitcnt lgkmcnt(12)
	v_pk_fma_f32 v[128:129], v[108:109], v[208:209], v[128:129]
	v_pk_fma_f32 v[130:131], v[110:111], v[210:211], v[130:131]
	v_add_f32_e32 v128, v128, v129
	v_add_f32_e32 v130, v130, v131
	v_add_f32_e32 v191, v128, v130
	ds_read_b128 v[112:115], v188 offset:28288
	ds_read_b128 v[116:119], v188 offset:28544
	ds_read_b128 v[120:123], v188 offset:28800
	ds_read_b128 v[124:127], v188 offset:29056
	ds_read_b32 v154, v140 offset:35148
	ds_read_b32 v155, v189 offset:33600
	ds_read_b32 v152, v140 offset:35084
	ds_read_b128 v[96:99], v188 offset:20096
	ds_read_b128 v[100:103], v188 offset:20352
	ds_read_b128 v[104:107], v188 offset:20608
	ds_read_b128 v[108:111], v188 offset:20864
	s_waitcnt lgkmcnt(15)
	v_mul_f32_e32 v133, v134, v135
	v_pk_mul_f32 v[80:81], v[80:81], v[132:133] op_sel:[0,1] op_sel_hi:[1,1]
	v_add_f32_dpp v191, v191, v191 row_ror:8 row_mask:0xf bank_mask:0xf bound_ctrl:1
	v_pk_mul_f32 v[82:83], v[82:83], v[132:133] op_sel:[0,1] op_sel_hi:[1,1]
	v_pk_mul_f32 v[84:85], v[84:85], v[132:133] op_sel:[0,1] op_sel_hi:[1,1]
	v_add_f32_dpp v191, v191, v191 row_ror:4 row_mask:0xf bank_mask:0xf bound_ctrl:1
	v_pk_mul_f32 v[86:87], v[86:87], v[132:133] op_sel:[0,1] op_sel_hi:[1,1]
	v_pk_mul_f32 v[88:89], v[88:89], v[132:133] op_sel:[0,1] op_sel_hi:[1,1]
	v_add_f32_dpp v191, v191, v191 row_ror:2 row_mask:0xf bank_mask:0xf bound_ctrl:1
	v_pk_mul_f32 v[90:91], v[90:91], v[132:133] op_sel:[0,1] op_sel_hi:[1,1]
	v_pk_mul_f32 v[92:93], v[92:93], v[132:133] op_sel:[0,1] op_sel_hi:[1,1]
	v_add_f32_dpp v191, v191, v191 row_ror:1 row_mask:0xf bank_mask:0xf bound_ctrl:1
	v_pk_mul_f32 v[94:95], v[94:95], v[132:133] op_sel:[0,1] op_sel_hi:[1,1]
	v_pk_fma_f32 v[196:197], v[132:133], v[196:197], v[80:81] op_sel_hi:[0,1,1]
	s_and_saveexec_b64 s[8:9], s[44:45]
	ds_write_b32 v189, v191 offset:34624
	s_mov_b64 exec, s[8:9]
	v_pk_fma_f32 v[198:199], v[132:133], v[198:199], v[82:83] op_sel_hi:[0,1,1]
	v_pk_fma_f32 v[200:201], v[132:133], v[200:201], v[84:85] op_sel_hi:[0,1,1]
	v_pk_fma_f32 v[202:203], v[132:133], v[202:203], v[86:87] op_sel_hi:[0,1,1]
	v_pk_fma_f32 v[204:205], v[132:133], v[204:205], v[88:89] op_sel_hi:[0,1,1]
	v_pk_fma_f32 v[206:207], v[132:133], v[206:207], v[90:91] op_sel_hi:[0,1,1]
	v_pk_fma_f32 v[208:209], v[132:133], v[208:209], v[92:93] op_sel_hi:[0,1,1]
	v_pk_fma_f32 v[210:211], v[132:133], v[210:211], v[94:95] op_sel_hi:[0,1,1]
	s_waitcnt lgkmcnt(15)
	v_pk_fma_f32 v[128:129], v[64:65], v[196:197], v[192:193]
	v_pk_fma_f32 v[130:131], v[66:67], v[198:199], v[192:193]
	v_pk_fma_f32 v[128:129], v[68:69], v[200:201], v[128:129]
	v_pk_fma_f32 v[130:131], v[70:71], v[202:203], v[130:131]
	s_waitcnt lgkmcnt(14)
	v_pk_fma_f32 v[128:129], v[72:73], v[204:205], v[128:129]
	v_pk_fma_f32 v[130:131], v[74:75], v[206:207], v[130:131]
	s_waitcnt lgkmcnt(13)
	v_pk_fma_f32 v[128:129], v[76:77], v[208:209], v[128:129]
	v_pk_fma_f32 v[130:131], v[78:79], v[210:211], v[130:131]
	v_add_f32_e32 v128, v128, v129
	v_add_f32_e32 v130, v130, v131
	v_add_f32_e32 v190, v128, v130
	ds_read_b128 v[80:83], v188 offset:29312
	ds_read_b128 v[84:87], v188 offset:29568
	ds_read_b128 v[88:91], v188 offset:29824
	ds_read_b128 v[92:95], v188 offset:30080
	ds_read_b32 v134, v140 offset:35152
	ds_read_b32 v135, v189 offset:33664
	ds_read_b32 v132, v140 offset:35088
	ds_read_b128 v[64:67], v188 offset:21120
	ds_read_b128 v[68:71], v188 offset:21376
	ds_read_b128 v[72:75], v188 offset:21632
	ds_read_b128 v[76:79], v188 offset:21888
	s_waitcnt lgkmcnt(15)
	v_mul_f32_e32 v153, v154, v155
	v_pk_mul_f32 v[112:113], v[112:113], v[152:153] op_sel:[0,1] op_sel_hi:[1,1]
	v_add_f32_dpp v190, v190, v190 row_ror:8 row_mask:0xf bank_mask:0xf bound_ctrl:1
	v_pk_mul_f32 v[114:115], v[114:115], v[152:153] op_sel:[0,1] op_sel_hi:[1,1]
	v_pk_mul_f32 v[116:117], v[116:117], v[152:153] op_sel:[0,1] op_sel_hi:[1,1]
	v_add_f32_dpp v190, v190, v190 row_ror:4 row_mask:0xf bank_mask:0xf bound_ctrl:1
	v_pk_mul_f32 v[118:119], v[118:119], v[152:153] op_sel:[0,1] op_sel_hi:[1,1]
	v_pk_mul_f32 v[120:121], v[120:121], v[152:153] op_sel:[0,1] op_sel_hi:[1,1]
	v_add_f32_dpp v190, v190, v190 row_ror:2 row_mask:0xf bank_mask:0xf bound_ctrl:1
	v_pk_mul_f32 v[122:123], v[122:123], v[152:153] op_sel:[0,1] op_sel_hi:[1,1]
	v_pk_mul_f32 v[124:125], v[124:125], v[152:153] op_sel:[0,1] op_sel_hi:[1,1]
	v_add_f32_dpp v190, v190, v190 row_ror:1 row_mask:0xf bank_mask:0xf bound_ctrl:1
	v_pk_mul_f32 v[126:127], v[126:127], v[152:153] op_sel:[0,1] op_sel_hi:[1,1]
	v_pk_fma_f32 v[196:197], v[152:153], v[196:197], v[112:113] op_sel_hi:[0,1,1]
	s_and_saveexec_b64 s[8:9], s[44:45]
	ds_write_b32 v189, v190 offset:34688
	s_mov_b64 exec, s[8:9]
	v_pk_fma_f32 v[198:199], v[152:153], v[198:199], v[114:115] op_sel_hi:[0,1,1]
	v_pk_fma_f32 v[200:201], v[152:153], v[200:201], v[116:117] op_sel_hi:[0,1,1]
	v_pk_fma_f32 v[202:203], v[152:153], v[202:203], v[118:119] op_sel_hi:[0,1,1]
	v_pk_fma_f32 v[204:205], v[152:153], v[204:205], v[120:121] op_sel_hi:[0,1,1]
	v_pk_fma_f32 v[206:207], v[152:153], v[206:207], v[122:123] op_sel_hi:[0,1,1]
	v_pk_fma_f32 v[208:209], v[152:153], v[208:209], v[124:125] op_sel_hi:[0,1,1]
	v_pk_fma_f32 v[210:211], v[152:153], v[210:211], v[126:127] op_sel_hi:[0,1,1]
	s_waitcnt lgkmcnt(15)
	v_pk_fma_f32 v[128:129], v[96:97], v[196:197], v[192:193]
	v_pk_fma_f32 v[130:131], v[98:99], v[198:199], v[192:193]
	v_pk_fma_f32 v[128:129], v[100:101], v[200:201], v[128:129]
	v_pk_fma_f32 v[130:131], v[102:103], v[202:203], v[130:131]
	s_waitcnt lgkmcnt(14)
	v_pk_fma_f32 v[128:129], v[104:105], v[204:205], v[128:129]
	v_pk_fma_f32 v[130:131], v[106:107], v[206:207], v[130:131]
	s_waitcnt lgkmcnt(13)
	v_pk_fma_f32 v[128:129], v[108:109], v[208:209], v[128:129]
	v_pk_fma_f32 v[130:131], v[110:111], v[210:211], v[130:131]
	v_add_f32_e32 v128, v128, v129
	v_add_f32_e32 v130, v130, v131
	v_add_f32_e32 v191, v128, v130
	ds_read_b128 v[112:115], v188 offset:30336
	ds_read_b128 v[116:119], v188 offset:30592
	ds_read_b128 v[120:123], v188 offset:30848
	ds_read_b128 v[124:127], v188 offset:31104
	ds_read_b32 v154, v140 offset:35156
	ds_read_b32 v155, v189 offset:33728
	ds_read_b32 v152, v140 offset:35092
	ds_read_b128 v[96:99], v188 offset:22144
	ds_read_b128 v[100:103], v188 offset:22400
	ds_read_b128 v[104:107], v188 offset:22656
	ds_read_b128 v[108:111], v188 offset:22912
	s_waitcnt lgkmcnt(15)
	v_mul_f32_e32 v133, v134, v135
	v_pk_mul_f32 v[80:81], v[80:81], v[132:133] op_sel:[0,1] op_sel_hi:[1,1]
	v_add_f32_dpp v191, v191, v191 row_ror:8 row_mask:0xf bank_mask:0xf bound_ctrl:1
	v_pk_mul_f32 v[82:83], v[82:83], v[132:133] op_sel:[0,1] op_sel_hi:[1,1]
	v_pk_mul_f32 v[84:85], v[84:85], v[132:133] op_sel:[0,1] op_sel_hi:[1,1]
	v_add_f32_dpp v191, v191, v191 row_ror:4 row_mask:0xf bank_mask:0xf bound_ctrl:1
	v_pk_mul_f32 v[86:87], v[86:87], v[132:133] op_sel:[0,1] op_sel_hi:[1,1]
	v_pk_mul_f32 v[88:89], v[88:89], v[132:133] op_sel:[0,1] op_sel_hi:[1,1]
	v_add_f32_dpp v191, v191, v191 row_ror:2 row_mask:0xf bank_mask:0xf bound_ctrl:1
	v_pk_mul_f32 v[90:91], v[90:91], v[132:133] op_sel:[0,1] op_sel_hi:[1,1]
	v_pk_mul_f32 v[92:93], v[92:93], v[132:133] op_sel:[0,1] op_sel_hi:[1,1]
	v_add_f32_dpp v191, v191, v191 row_ror:1 row_mask:0xf bank_mask:0xf bound_ctrl:1
	v_pk_mul_f32 v[94:95], v[94:95], v[132:133] op_sel:[0,1] op_sel_hi:[1,1]
	v_pk_fma_f32 v[196:197], v[132:133], v[196:197], v[80:81] op_sel_hi:[0,1,1]
	s_and_saveexec_b64 s[8:9], s[44:45]
	ds_write_b32 v189, v191 offset:34752
	s_mov_b64 exec, s[8:9]
	v_pk_fma_f32 v[198:199], v[132:133], v[198:199], v[82:83] op_sel_hi:[0,1,1]
	v_pk_fma_f32 v[200:201], v[132:133], v[200:201], v[84:85] op_sel_hi:[0,1,1]
	v_pk_fma_f32 v[202:203], v[132:133], v[202:203], v[86:87] op_sel_hi:[0,1,1]
	v_pk_fma_f32 v[204:205], v[132:133], v[204:205], v[88:89] op_sel_hi:[0,1,1]
	v_pk_fma_f32 v[206:207], v[132:133], v[206:207], v[90:91] op_sel_hi:[0,1,1]
	v_pk_fma_f32 v[208:209], v[132:133], v[208:209], v[92:93] op_sel_hi:[0,1,1]
	v_pk_fma_f32 v[210:211], v[132:133], v[210:211], v[94:95] op_sel_hi:[0,1,1]
	s_waitcnt lgkmcnt(15)
	v_pk_fma_f32 v[128:129], v[64:65], v[196:197], v[192:193]
	v_pk_fma_f32 v[130:131], v[66:67], v[198:199], v[192:193]
	v_pk_fma_f32 v[128:129], v[68:69], v[200:201], v[128:129]
	v_pk_fma_f32 v[130:131], v[70:71], v[202:203], v[130:131]
	s_waitcnt lgkmcnt(14)
	v_pk_fma_f32 v[128:129], v[72:73], v[204:205], v[128:129]
	v_pk_fma_f32 v[130:131], v[74:75], v[206:207], v[130:131]
	s_waitcnt lgkmcnt(13)
	v_pk_fma_f32 v[128:129], v[76:77], v[208:209], v[128:129]
	v_pk_fma_f32 v[130:131], v[78:79], v[210:211], v[130:131]
	v_add_f32_e32 v128, v128, v129
	v_add_f32_e32 v130, v130, v131
	v_add_f32_e32 v190, v128, v130
	ds_read_b128 v[80:83], v188 offset:31360
	ds_read_b128 v[84:87], v188 offset:31616
	ds_read_b128 v[88:91], v188 offset:31872
	ds_read_b128 v[92:95], v188 offset:32128
	ds_read_b32 v134, v140 offset:35160
	ds_read_b32 v135, v189 offset:33792
	ds_read_b32 v132, v140 offset:35096
	ds_read_b128 v[64:67], v188 offset:23168
	ds_read_b128 v[68:71], v188 offset:23424
	ds_read_b128 v[72:75], v188 offset:23680
	ds_read_b128 v[76:79], v188 offset:23936
	s_waitcnt lgkmcnt(15)
	v_mul_f32_e32 v153, v154, v155
	v_pk_mul_f32 v[112:113], v[112:113], v[152:153] op_sel:[0,1] op_sel_hi:[1,1]
	v_add_f32_dpp v190, v190, v190 row_ror:8 row_mask:0xf bank_mask:0xf bound_ctrl:1
	v_pk_mul_f32 v[114:115], v[114:115], v[152:153] op_sel:[0,1] op_sel_hi:[1,1]
	v_pk_mul_f32 v[116:117], v[116:117], v[152:153] op_sel:[0,1] op_sel_hi:[1,1]
	v_add_f32_dpp v190, v190, v190 row_ror:4 row_mask:0xf bank_mask:0xf bound_ctrl:1
	v_pk_mul_f32 v[118:119], v[118:119], v[152:153] op_sel:[0,1] op_sel_hi:[1,1]
	v_pk_mul_f32 v[120:121], v[120:121], v[152:153] op_sel:[0,1] op_sel_hi:[1,1]
	v_add_f32_dpp v190, v190, v190 row_ror:2 row_mask:0xf bank_mask:0xf bound_ctrl:1
	v_pk_mul_f32 v[122:123], v[122:123], v[152:153] op_sel:[0,1] op_sel_hi:[1,1]
	v_pk_mul_f32 v[124:125], v[124:125], v[152:153] op_sel:[0,1] op_sel_hi:[1,1]
	v_add_f32_dpp v190, v190, v190 row_ror:1 row_mask:0xf bank_mask:0xf bound_ctrl:1
	v_pk_mul_f32 v[126:127], v[126:127], v[152:153] op_sel:[0,1] op_sel_hi:[1,1]
	v_pk_fma_f32 v[196:197], v[152:153], v[196:197], v[112:113] op_sel_hi:[0,1,1]
	s_and_saveexec_b64 s[8:9], s[44:45]
	ds_write_b32 v189, v190 offset:34816
	s_mov_b64 exec, s[8:9]
	v_pk_fma_f32 v[198:199], v[152:153], v[198:199], v[114:115] op_sel_hi:[0,1,1]
	v_pk_fma_f32 v[200:201], v[152:153], v[200:201], v[116:117] op_sel_hi:[0,1,1]
	v_pk_fma_f32 v[202:203], v[152:153], v[202:203], v[118:119] op_sel_hi:[0,1,1]
	v_pk_fma_f32 v[204:205], v[152:153], v[204:205], v[120:121] op_sel_hi:[0,1,1]
	v_pk_fma_f32 v[206:207], v[152:153], v[206:207], v[122:123] op_sel_hi:[0,1,1]
	v_pk_fma_f32 v[208:209], v[152:153], v[208:209], v[124:125] op_sel_hi:[0,1,1]
	v_pk_fma_f32 v[210:211], v[152:153], v[210:211], v[126:127] op_sel_hi:[0,1,1]
	s_waitcnt lgkmcnt(15)
	v_pk_fma_f32 v[128:129], v[96:97], v[196:197], v[192:193]
	v_pk_fma_f32 v[130:131], v[98:99], v[198:199], v[192:193]
	v_pk_fma_f32 v[128:129], v[100:101], v[200:201], v[128:129]
	v_pk_fma_f32 v[130:131], v[102:103], v[202:203], v[130:131]
	s_waitcnt lgkmcnt(14)
	v_pk_fma_f32 v[128:129], v[104:105], v[204:205], v[128:129]
	v_pk_fma_f32 v[130:131], v[106:107], v[206:207], v[130:131]
	s_waitcnt lgkmcnt(13)
	v_pk_fma_f32 v[128:129], v[108:109], v[208:209], v[128:129]
	v_pk_fma_f32 v[130:131], v[110:111], v[210:211], v[130:131]
	v_add_f32_e32 v128, v128, v129
	v_add_f32_e32 v130, v130, v131
	v_add_f32_e32 v191, v128, v130
	ds_read_b128 v[112:115], v188 offset:32384
	ds_read_b128 v[116:119], v188 offset:32640
	ds_read_b128 v[120:123], v188 offset:32896
	ds_read_b128 v[124:127], v188 offset:33152
	ds_read_b32 v154, v140 offset:35164
	ds_read_b32 v155, v189 offset:33856
	ds_read_b32 v152, v140 offset:35100
	ds_read_b128 v[96:99], v188 offset:24192
	ds_read_b128 v[100:103], v188 offset:24448
	ds_read_b128 v[104:107], v188 offset:24704
	ds_read_b128 v[108:111], v188 offset:24960
	s_waitcnt lgkmcnt(15)
	v_mul_f32_e32 v133, v134, v135
	v_pk_mul_f32 v[80:81], v[80:81], v[132:133] op_sel:[0,1] op_sel_hi:[1,1]
	v_add_f32_dpp v191, v191, v191 row_ror:8 row_mask:0xf bank_mask:0xf bound_ctrl:1
	v_pk_mul_f32 v[82:83], v[82:83], v[132:133] op_sel:[0,1] op_sel_hi:[1,1]
	v_pk_mul_f32 v[84:85], v[84:85], v[132:133] op_sel:[0,1] op_sel_hi:[1,1]
	v_add_f32_dpp v191, v191, v191 row_ror:4 row_mask:0xf bank_mask:0xf bound_ctrl:1
	v_pk_mul_f32 v[86:87], v[86:87], v[132:133] op_sel:[0,1] op_sel_hi:[1,1]
	v_pk_mul_f32 v[88:89], v[88:89], v[132:133] op_sel:[0,1] op_sel_hi:[1,1]
	v_add_f32_dpp v191, v191, v191 row_ror:2 row_mask:0xf bank_mask:0xf bound_ctrl:1
	v_pk_mul_f32 v[90:91], v[90:91], v[132:133] op_sel:[0,1] op_sel_hi:[1,1]
	v_pk_mul_f32 v[92:93], v[92:93], v[132:133] op_sel:[0,1] op_sel_hi:[1,1]
	v_add_f32_dpp v191, v191, v191 row_ror:1 row_mask:0xf bank_mask:0xf bound_ctrl:1
	v_pk_mul_f32 v[94:95], v[94:95], v[132:133] op_sel:[0,1] op_sel_hi:[1,1]
	v_pk_fma_f32 v[196:197], v[132:133], v[196:197], v[80:81] op_sel_hi:[0,1,1]
	s_and_saveexec_b64 s[8:9], s[44:45]
	ds_write_b32 v189, v191 offset:34880
	s_mov_b64 exec, s[8:9]
	v_pk_fma_f32 v[198:199], v[132:133], v[198:199], v[82:83] op_sel_hi:[0,1,1]
	v_pk_fma_f32 v[200:201], v[132:133], v[200:201], v[84:85] op_sel_hi:[0,1,1]
	v_pk_fma_f32 v[202:203], v[132:133], v[202:203], v[86:87] op_sel_hi:[0,1,1]
	v_pk_fma_f32 v[204:205], v[132:133], v[204:205], v[88:89] op_sel_hi:[0,1,1]
	v_pk_fma_f32 v[206:207], v[132:133], v[206:207], v[90:91] op_sel_hi:[0,1,1]
	v_pk_fma_f32 v[208:209], v[132:133], v[208:209], v[92:93] op_sel_hi:[0,1,1]
	v_pk_fma_f32 v[210:211], v[132:133], v[210:211], v[94:95] op_sel_hi:[0,1,1]
	s_waitcnt lgkmcnt(15)
	v_pk_fma_f32 v[128:129], v[64:65], v[196:197], v[192:193]
	v_pk_fma_f32 v[130:131], v[66:67], v[198:199], v[192:193]
	v_pk_fma_f32 v[128:129], v[68:69], v[200:201], v[128:129]
	v_pk_fma_f32 v[130:131], v[70:71], v[202:203], v[130:131]
	s_waitcnt lgkmcnt(14)
	v_pk_fma_f32 v[128:129], v[72:73], v[204:205], v[128:129]
	v_pk_fma_f32 v[130:131], v[74:75], v[206:207], v[130:131]
	s_waitcnt lgkmcnt(13)
	v_pk_fma_f32 v[128:129], v[76:77], v[208:209], v[128:129]
	v_pk_fma_f32 v[130:131], v[78:79], v[210:211], v[130:131]
	v_add_f32_e32 v128, v128, v129
	v_add_f32_e32 v130, v130, v131
	v_add_f32_e32 v190, v128, v130
	s_waitcnt lgkmcnt(6)
	v_mul_f32_e32 v153, v154, v155
	v_pk_mul_f32 v[112:113], v[112:113], v[152:153] op_sel:[0,1] op_sel_hi:[1,1]
	v_add_f32_dpp v190, v190, v190 row_ror:8 row_mask:0xf bank_mask:0xf bound_ctrl:1
	v_pk_mul_f32 v[114:115], v[114:115], v[152:153] op_sel:[0,1] op_sel_hi:[1,1]
	v_pk_mul_f32 v[116:117], v[116:117], v[152:153] op_sel:[0,1] op_sel_hi:[1,1]
	v_add_f32_dpp v190, v190, v190 row_ror:4 row_mask:0xf bank_mask:0xf bound_ctrl:1
	v_pk_mul_f32 v[118:119], v[118:119], v[152:153] op_sel:[0,1] op_sel_hi:[1,1]
	v_pk_mul_f32 v[120:121], v[120:121], v[152:153] op_sel:[0,1] op_sel_hi:[1,1]
	v_add_f32_dpp v190, v190, v190 row_ror:2 row_mask:0xf bank_mask:0xf bound_ctrl:1
	v_pk_mul_f32 v[122:123], v[122:123], v[152:153] op_sel:[0,1] op_sel_hi:[1,1]
	v_pk_mul_f32 v[124:125], v[124:125], v[152:153] op_sel:[0,1] op_sel_hi:[1,1]
	v_add_f32_dpp v190, v190, v190 row_ror:1 row_mask:0xf bank_mask:0xf bound_ctrl:1
	v_pk_mul_f32 v[126:127], v[126:127], v[152:153] op_sel:[0,1] op_sel_hi:[1,1]
	s_waitcnt lgkmcnt(5)
	v_pk_fma_f32 v[196:197], v[152:153], v[196:197], v[112:113] op_sel_hi:[0,1,1]
	s_and_saveexec_b64 s[8:9], s[44:45]
	ds_write_b32 v189, v190 offset:34944
	s_mov_b64 exec, s[8:9]
	v_pk_fma_f32 v[198:199], v[152:153], v[198:199], v[114:115] op_sel_hi:[0,1,1]
	v_pk_fma_f32 v[200:201], v[152:153], v[200:201], v[116:117] op_sel_hi:[0,1,1]
	v_pk_fma_f32 v[202:203], v[152:153], v[202:203], v[118:119] op_sel_hi:[0,1,1]
	v_pk_fma_f32 v[204:205], v[152:153], v[204:205], v[120:121] op_sel_hi:[0,1,1]
	v_pk_fma_f32 v[206:207], v[152:153], v[206:207], v[122:123] op_sel_hi:[0,1,1]
	v_pk_fma_f32 v[208:209], v[152:153], v[208:209], v[124:125] op_sel_hi:[0,1,1]
	v_pk_fma_f32 v[210:211], v[152:153], v[210:211], v[126:127] op_sel_hi:[0,1,1]
	s_waitcnt lgkmcnt(5)
	v_pk_fma_f32 v[128:129], v[96:97], v[196:197], v[192:193]
	v_pk_fma_f32 v[130:131], v[98:99], v[198:199], v[192:193]
	s_waitcnt lgkmcnt(4)
	v_pk_fma_f32 v[128:129], v[100:101], v[200:201], v[128:129]
	v_pk_fma_f32 v[130:131], v[102:103], v[202:203], v[130:131]
	s_waitcnt lgkmcnt(3)
	v_pk_fma_f32 v[128:129], v[104:105], v[204:205], v[128:129]
	v_pk_fma_f32 v[130:131], v[106:107], v[206:207], v[130:131]
	s_waitcnt lgkmcnt(2)
	v_pk_fma_f32 v[128:129], v[108:109], v[208:209], v[128:129]
	v_pk_fma_f32 v[130:131], v[110:111], v[210:211], v[130:131]
	v_add_f32_e32 v128, v128, v129
	v_add_f32_e32 v130, v130, v131
	v_add_f32_e32 v191, v128, v130
	s_nop 1
	v_add_f32_dpp v191, v191, v191 row_ror:8 row_mask:0xf bank_mask:0xf bound_ctrl:1
	s_nop 1
	v_add_f32_dpp v191, v191, v191 row_ror:4 row_mask:0xf bank_mask:0xf bound_ctrl:1
	s_nop 1
	v_add_f32_dpp v191, v191, v191 row_ror:2 row_mask:0xf bank_mask:0xf bound_ctrl:1
	s_nop 1
	v_add_f32_dpp v191, v191, v191 row_ror:1 row_mask:0xf bank_mask:0xf bound_ctrl:1
	s_and_saveexec_b64 s[8:9], s[44:45]
	ds_write_b32 v189, v191 offset:35008
	s_mov_b64 exec, s[8:9]
	s_waitcnt lgkmcnt(0)
	v_mov_b32_e32 v64, v196
	v_mov_b32_e32 v65, v197
	v_mov_b32_e32 v66, v198
	v_mov_b32_e32 v67, v199
	v_mov_b32_e32 v76, v200
	v_mov_b32_e32 v77, v201
	v_mov_b32_e32 v78, v202
	v_mov_b32_e32 v79, v203
	v_mov_b32_e32 v72, v204
	v_mov_b32_e32 v73, v205
	v_mov_b32_e32 v74, v206
	v_mov_b32_e32 v75, v207
	v_mov_b32_e32 v68, v208
	v_mov_b32_e32 v69, v209
	v_mov_b32_e32 v70, v210
	v_mov_b32_e32 v71, v211
	s_branch .LBB0_1438
